# GEMM phases: first MFMA right after barrier, drop redundant lgkmcnt wait and mid-block setprio pairs, barrier before setprio 0
# speedup vs baseline: 1.0024x; 1.0024x over previous
; #define PG8_STAGE(bufoff, gbase, voff) do { if constexpr (ABL & 1) break; glds16s<(bufoff)>((voff)[0], (const void*)(gbase), ldsbw); glds16s<(bufoff) + 8192>((voff)[1], (const void*)(gbase), ldsbw); } while (0)
; #define PG8_LDA(dst, b, h) do { if constexpr (ABL & 4) break; _Pragma("unroll") for (int m = 0; m < 4; ++m) _Pragma("unroll") for (int k = 0; k < 2; ++k) dst[m][k] = *(const LAS f16x8*)(lds + PG8_SA(b, h) + aoff + m * 2048 + k * 1024); } while (0)
; #define PG8_LDB(dst, b, h) do { if constexpr (ABL & 4) break; _Pragma("unroll") for (int n = 0; n < 2; ++n) _Pragma("unroll") for (int k = 0; k < 2; ++k) dst[n][k] = *(const LAS f16x8*)(lds + PG8_SB(b, h) + boff + n * 2048 + k * 1024); } while (0)
; #define PG8_MMAF(ai, bj, At, Bt) do { if (t == 0) PG8_MMA0(ai, bj, At, Bt); else PG8_MMA(ai, bj, At, Bt); } while (0)
; #define PG8_WAIT_V(n) asm volatile("s_waitcnt vmcnt(" #n ")" ::: "memory")
; #define PG8_WAIT_L(n) asm volatile("s_waitcnt lgkmcnt(" #n ")" ::: "memory")
; #define PG8_BAR __builtin_amdgcn_s_barrier()
; #define PG8_SCHED __builtin_amdgcn_sched_barrier(0)
;     ...
;         const char* nA = has_next ? (const char*)g.A + (size_t)nxt.pm * tstep : cA; const char* nB = has_next ? (const char*)g.Bt + (size_t)nxt.pn * tstep : cB;
;         for (int t = 0; t < nt; t += 2) {
;             const bool last = (t == nt - 2);
;             const char* a1 = cA + (size_t)(t + 1) * kstep;
;             const char* a2 = last ? nA : cA + (size_t)(t + 2) * kstep; const char* b2 = last ? nB : cB + (size_t)(t + 2) * kstep;
;             const char* a3 = a2 + kstep; const char* b3 = b2 + kstep;
;             if (last && has_next) S.a_ready(nxt);
;             if constexpr (SP2) {
;             PG8_LDB(B0, 0, 0); PG8_LDB(B1, 0, 1); PG8_SCHED; PG8_LDA(At, 0, 0); PG8_STAGE(PG8_SA(1, 1), a1 + hstep, voffA);
;             PG8_WAIT_V(8); PG8_WAIT_L(0); PG8_BAR; PG8_MMAF(0, 0, At, B0); PG8_MMAF(0, 1, At, B1); PG8_BAR; PG8_SCHED;
;             const bool fin = last && !has_next;
;             PG8_LDA(At, 0, 1); if (!fin) { PG8_STAGE(PG8_SB(0, 0), b2, voffB); PG8_STAGE(PG8_SB(0, 1), b2 + hstep, voffB); PG8_STAGE(PG8_SA(0, 0), a2, voffA); }
;             if (!fin) PG8_WAIT_V(8); else PG8_WAIT_V(2); PG8_WAIT_L(0); PG8_BAR; PG8_MMAF(1, 0, At, B0); PG8_MMAF(1, 1, At, B1); PG8_BAR; PG8_SCHED;
.LBB0_229:
	s_ashr_i32 s53, s52, 31
	s_lshl_b64 s[8:9], s[52:53], 19
	s_add_u32 s54, s74, s8
	s_addc_u32 s55, s75, s9
	s_and_b64 s[8:9], exec, s[4:5]
	ds_read_b128 v[2:5], v236
	ds_read_b128 v[6:9], v236 offset:1024
	ds_read_b128 v[10:13], v236 offset:2048
	ds_read_b128 v[14:17], v236 offset:3072
	ds_read_b128 v[18:21], v237
	ds_read_b128 v[22:25], v237 offset:1024
	ds_read_b128 v[26:29], v237 offset:2048
	ds_read_b128 v[30:33], v237 offset:3072
	s_cselect_b32 s11, s63, s55
	s_cselect_b32 s35, s62, s54
	s_ashr_i32 s1, s0, 31
	s_lshl_b64 s[8:9], s[0:1], 19
	s_add_u32 s56, s90, s8
	s_addc_u32 s57, s91, s9
	s_and_b64 s[8:9], exec, s[4:5]
	s_cselect_b32 s1, s7, s57
	s_cselect_b32 s46, s6, s56
	s_add_u32 s8, s62, 0x100
	s_addc_u32 s9, s63, 0
	s_add_u32 s64, s6, 0x100
	s_addc_u32 s65, s7, 0
	s_add_u32 s24, s62, 0x180
	s_addc_u32 s25, s63, 0
	ds_read_b128 v[34:37], v238
	ds_read_b128 v[38:41], v238 offset:1024
	ds_read_b128 v[42:45], v238 offset:2048
	ds_read_b128 v[46:49], v238 offset:3072
	ds_read_b128 v[50:53], v238 offset:4096
	ds_read_b128 v[54:57], v238 offset:5120
	ds_read_b128 v[58:61], v238 offset:6144
	ds_read_b128 v[62:65], v238 offset:7168
	s_add_u32 s26, s6, 0x180
	s_addc_u32 s27, s7, 0
	s_add_u32 s76, s62, 0x40080
	s_addc_u32 s77, s63, 0
	s_add_u32 m0, s28, 0xc000
	s_nop 0
	global_load_lds_dwordx4 v232, s[76:77]
	s_nop 0
	s_add_u32 m0, s28, 0xe000
	s_nop 0
	global_load_lds_dwordx4 v234, s[76:77]
	s_waitcnt vmcnt(8)
	s_waitcnt lgkmcnt(0)
	s_barrier
	v_mfma_f32_16x16x32_f16 v[86:89], v[10:13], v[50:53], 0
	s_setprio 1
	s_waitcnt lgkmcnt(2)
	v_mfma_f32_16x16x32_f16 v[90:93], v[14:17], v[54:57], v[86:89]
	s_waitcnt lgkmcnt(1)
	v_mfma_f32_16x16x32_f16 v[86:89], v[2:5], v[58:61], 0
	v_mfma_f32_16x16x32_f16 v[66:69], v[2:5], v[34:37], 0
	v_mfma_f32_16x16x32_f16 v[70:73], v[10:13], v[34:37], 0
	v_mfma_f32_16x16x32_f16 v[74:77], v[2:5], v[42:45], 0
	v_mfma_f32_16x16x32_f16 v[78:81], v[10:13], v[42:45], 0
	v_mfma_f32_16x16x32_f16 v[82:85], v[2:5], v[50:53], 0
	s_waitcnt lgkmcnt(0)
	v_mfma_f32_16x16x32_f16 v[94:97], v[6:9], v[62:65], v[86:89]
	v_mfma_f32_16x16x32_f16 v[86:89], v[10:13], v[58:61], 0
	v_mfma_f32_16x16x32_f16 v[66:69], v[6:9], v[38:41], v[66:69]
	v_mfma_f32_16x16x32_f16 v[70:73], v[14:17], v[38:41], v[70:73]
	v_mfma_f32_16x16x32_f16 v[74:77], v[6:9], v[46:49], v[74:77]
	v_mfma_f32_16x16x32_f16 v[78:81], v[14:17], v[46:49], v[78:81]
	v_mfma_f32_16x16x32_f16 v[82:85], v[6:9], v[54:57], v[82:85]
	v_mfma_f32_16x16x32_f16 v[106:109], v[14:17], v[62:65], v[86:89]
	v_mfma_f32_16x16x32_f16 v[86:89], v[18:21], v[34:37], 0
	v_mfma_f32_16x16x32_f16 v[34:37], v[26:29], v[34:37], 0
	v_mfma_f32_16x16x32_f16 v[110:113], v[22:25], v[38:41], v[86:89]
	v_mfma_f32_16x16x32_f16 v[34:37], v[30:33], v[38:41], v[34:37]
	v_mfma_f32_16x16x32_f16 v[38:41], v[18:21], v[42:45], 0
	v_mfma_f32_16x16x32_f16 v[42:45], v[26:29], v[42:45], 0
	v_mfma_f32_16x16x32_f16 v[38:41], v[22:25], v[46:49], v[38:41]
	v_mfma_f32_16x16x32_f16 v[42:45], v[30:33], v[46:49], v[42:45]
	v_mfma_f32_16x16x32_f16 v[46:49], v[18:21], v[50:53], 0
	v_mfma_f32_16x16x32_f16 v[50:53], v[26:29], v[50:53], 0
	v_mfma_f32_16x16x32_f16 v[46:49], v[22:25], v[54:57], v[46:49]
	v_mfma_f32_16x16x32_f16 v[54:57], v[30:33], v[54:57], v[50:53]
	v_mfma_f32_16x16x32_f16 v[50:53], v[18:21], v[58:61], 0
	v_mfma_f32_16x16x32_f16 v[130:133], v[22:25], v[62:65], v[50:53]
	v_mfma_f32_16x16x32_f16 v[50:53], v[26:29], v[58:61], 0
	v_mfma_f32_16x16x32_f16 v[62:65], v[30:33], v[62:65], v[50:53]
	s_barrier
	s_setprio 0
	s_nop 4
	ds_read_b128 v[50:53], v238 offset:16384
	ds_read_b128 v[58:61], v238 offset:17408
	ds_read_b128 v[86:89], v238 offset:18432
	ds_read_b128 v[98:101], v238 offset:19456
	ds_read_b128 v[102:105], v238 offset:20480
	ds_read_b128 v[114:117], v238 offset:21504
	ds_read_b128 v[118:121], v238 offset:22528
	ds_read_b128 v[122:125], v238 offset:23552
	s_add_u32 m0, s28, 0x10000
	s_nop 0
	global_load_lds_dwordx4 v233, s[64:65]
	s_nop 0
	s_add_u32 m0, s28, 0x12000
	s_nop 0
	global_load_lds_dwordx4 v235, s[64:65]
	s_add_u32 s64, s6, 0x40100
	s_addc_u32 s65, s7, 0
	s_add_u32 m0, s28, 0x14000
	s_nop 0
	global_load_lds_dwordx4 v233, s[64:65]
	s_nop 0
	s_add_u32 m0, s28, 0x16000
	s_nop 0
	global_load_lds_dwordx4 v235, s[64:65]
	s_nop 0
	s_add_u32 m0, s28, 0
	s_nop 0
	global_load_lds_dwordx4 v232, s[8:9]
	s_nop 0
	s_add_u32 m0, s28, 0x2000
	s_nop 0
	global_load_lds_dwordx4 v234, s[8:9]
	s_waitcnt vmcnt(8)
	s_waitcnt lgkmcnt(0)
	s_barrier
	v_mfma_f32_16x16x32_f16 v[126:129], v[2:5], v[50:53], 0
	s_setprio 1
	s_waitcnt lgkmcnt(6)
	v_mfma_f32_16x16x32_f16 v[134:137], v[6:9], v[58:61], v[126:129]
	v_mfma_f32_16x16x32_f16 v[126:129], v[10:13], v[50:53], 0
	v_mfma_f32_16x16x32_f16 v[138:141], v[14:17], v[58:61], v[126:129]
	s_waitcnt lgkmcnt(5)
	v_mfma_f32_16x16x32_f16 v[126:129], v[2:5], v[86:89], 0
	s_waitcnt lgkmcnt(4)
	v_mfma_f32_16x16x32_f16 v[142:145], v[6:9], v[98:101], v[126:129]
	v_mfma_f32_16x16x32_f16 v[126:129], v[10:13], v[86:89], 0
	v_mfma_f32_16x16x32_f16 v[146:149], v[14:17], v[98:101], v[126:129]
	s_waitcnt lgkmcnt(3)
	v_mfma_f32_16x16x32_f16 v[126:129], v[2:5], v[102:105], 0
	s_waitcnt lgkmcnt(1)
	v_mfma_f32_16x16x32_f16 v[2:5], v[2:5], v[118:121], 0
	v_mfma_f32_16x16x32_f16 v[150:153], v[6:9], v[114:117], v[126:129]
	s_waitcnt lgkmcnt(0)
	v_mfma_f32_16x16x32_f16 v[2:5], v[6:9], v[122:125], v[2:5]
	v_mfma_f32_16x16x32_f16 v[6:9], v[10:13], v[118:121], 0
	v_mfma_f32_16x16x32_f16 v[126:129], v[10:13], v[102:105], 0
	v_mfma_f32_16x16x32_f16 v[10:13], v[14:17], v[122:125], v[6:9]
	v_mfma_f32_16x16x32_f16 v[154:157], v[14:17], v[114:117], v[126:129]
	v_mfma_f32_16x16x32_f16 v[6:9], v[18:21], v[50:53], 0
	v_mfma_f32_16x16x32_f16 v[158:161], v[22:25], v[58:61], v[6:9]
	v_mfma_f32_16x16x32_f16 v[6:9], v[26:29], v[50:53], 0
	v_mfma_f32_16x16x32_f16 v[162:165], v[30:33], v[58:61], v[6:9]
	v_mfma_f32_16x16x32_f16 v[6:9], v[18:21], v[86:89], 0
	v_mfma_f32_16x16x32_f16 v[166:169], v[22:25], v[98:101], v[6:9]
	v_mfma_f32_16x16x32_f16 v[6:9], v[26:29], v[86:89], 0
	v_mfma_f32_16x16x32_f16 v[170:173], v[30:33], v[98:101], v[6:9]
	v_mfma_f32_16x16x32_f16 v[6:9], v[18:21], v[102:105], 0
	v_mfma_f32_16x16x32_f16 v[174:177], v[22:25], v[114:117], v[6:9]
	v_mfma_f32_16x16x32_f16 v[6:9], v[26:29], v[102:105], 0
	v_mfma_f32_16x16x32_f16 v[178:181], v[30:33], v[114:117], v[6:9]
	v_mfma_f32_16x16x32_f16 v[6:9], v[18:21], v[118:121], 0
	v_mfma_f32_16x16x32_f16 v[22:25], v[22:25], v[122:125], v[6:9]
	v_mfma_f32_16x16x32_f16 v[6:9], v[26:29], v[118:121], 0
	v_mfma_f32_16x16x32_f16 v[182:185], v[30:33], v[122:125], v[6:9]
	s_barrier
; #define PG8_STAGE(bufoff, gbase, voff) do { if constexpr (ABL & 1) break; glds16s<(bufoff)>((voff)[0], (const void*)(gbase), ldsbw); glds16s<(bufoff) + 8192>((voff)[1], (const void*)(gbase), ldsbw); } while (0)
; #define PG8_LDA(dst, b, h) do { if constexpr (ABL & 4) break; _Pragma("unroll") for (int m = 0; m < 4; ++m) _Pragma("unroll") for (int k = 0; k < 2; ++k) dst[m][k] = *(const LAS f16x8*)(lds + PG8_SA(b, h) + aoff + m * 2048 + k * 1024); } while (0)
; #define PG8_LDB(dst, b, h) do { if constexpr (ABL & 4) break; _Pragma("unroll") for (int n = 0; n < 2; ++n) _Pragma("unroll") for (int k = 0; k < 2; ++k) dst[n][k] = *(const LAS f16x8*)(lds + PG8_SB(b, h) + boff + n * 2048 + k * 1024); } while (0)
; #define PG8_MMA(ai, bj, At, Bt) do { if constexpr (ABL & 2) break; __builtin_amdgcn_s_setprio(1); _Pragma("unroll") for (int m = 0; m < 4; ++m) _Pragma("unroll") for (int n = 0; n < 2; ++n) _Pragma("unroll") for (int k = 0; k < 2; ++k) \
;         acc[ai][bj][m][n] = __builtin_amdgcn_mfma_f32_16x16x32_f16(Bt[n][k], At[m][k], acc[ai][bj][m][n], 0, 0, 0); __builtin_amdgcn_s_setprio(0); } while (0)
; #define PG8_MMAF(ai, bj, At, Bt) do { if (t == 0) PG8_MMA0(ai, bj, At, Bt); else PG8_MMA(ai, bj, At, Bt); } while (0)
; #define PG8_WAIT_V(n) asm volatile("s_waitcnt vmcnt(" #n ")" ::: "memory")
; #define PG8_WAIT_L(n) asm volatile("s_waitcnt lgkmcnt(" #n ")" ::: "memory")
; #define PG8_BAR __builtin_amdgcn_s_barrier()
; #define PG8_SCHED __builtin_amdgcn_sched_barrier(0)
;     ...
;             if (!fin) PG8_WAIT_V(8); else PG8_WAIT_V(2); PG8_WAIT_L(0); PG8_BAR; PG8_MMAF(1, 0, At, B0); PG8_MMAF(1, 1, At, B1); PG8_BAR; PG8_SCHED;
;             PG8_LDB(B0, 1, 0); PG8_LDB(B1, 1, 1); PG8_SCHED; PG8_LDA(At, 1, 0); if (!fin) PG8_STAGE(PG8_SA(0, 1), a2 + hstep, voffA);
;             if (!fin) PG8_WAIT_V(8); else PG8_WAIT_V(0); PG8_WAIT_L(0); PG8_BAR; PG8_MMA(0, 0, At, B0); PG8_MMA(0, 1, At, B1); PG8_BAR; PG8_SCHED;
;             PG8_LDA(At, 1, 1); if (!fin) { PG8_STAGE(PG8_SB(1, 0), b3, voffB); PG8_STAGE(PG8_SB(1, 1), b3 + hstep, voffB); PG8_STAGE(PG8_SA(1, 0), a3, voffA); }
;             if (!fin) PG8_WAIT_V(8); PG8_WAIT_L(0); PG8_BAR; PG8_MMA(1, 0, At, B0); PG8_MMA(1, 1, At, B1); PG8_BAR; PG8_SCHED;
	s_setprio 0
	s_nop 4
	ds_read_b128 v[6:9], v239
	ds_read_b128 v[26:29], v239 offset:1024
	ds_read_b128 v[186:189], v239 offset:2048
	ds_read_b128 v[190:193], v239 offset:3072
	ds_read_b128 v[206:209], v240
	ds_read_b128 v[210:213], v240 offset:1024
	ds_read_b128 v[214:217], v240 offset:2048
	ds_read_b128 v[218:221], v240 offset:3072
	ds_read_b128 v[14:17], v238 offset:32768
	ds_read_b128 v[18:21], v238 offset:33792
	ds_read_b128 v[30:33], v238 offset:34816
	ds_read_b128 v[222:225], v238 offset:35840
	ds_read_b128 v[226:229], v238 offset:36864
	ds_read_b128 v[242:245], v238 offset:37888
	ds_read_b128 v[246:249], v238 offset:38912
	ds_read_b128 v[250:253], v238 offset:39936
	s_add_u32 s62, s62, 0x40100
	s_addc_u32 s63, s63, 0
	s_add_u32 m0, s28, 0x4000
	s_nop 0
	global_load_lds_dwordx4 v232, s[62:63]
	s_nop 0
	s_add_u32 m0, s28, 0x6000
	s_nop 0
	global_load_lds_dwordx4 v234, s[62:63]
	s_waitcnt vmcnt(8)
	s_waitcnt lgkmcnt(0)
	s_barrier
	v_mfma_f32_16x16x32_f16 v[50:53], v[6:9], v[14:17], v[66:69]
	s_setprio 1
	s_waitcnt lgkmcnt(6)
	v_mfma_f32_16x16x32_f16 v[118:121], v[26:29], v[18:21], v[50:53]
	v_mfma_f32_16x16x32_f16 v[50:53], v[186:189], v[14:17], v[70:73]
	v_mfma_f32_16x16x32_f16 v[114:117], v[190:193], v[18:21], v[50:53]
	s_waitcnt lgkmcnt(5)
	v_mfma_f32_16x16x32_f16 v[50:53], v[6:9], v[30:33], v[74:77]
	s_waitcnt lgkmcnt(4)
	v_mfma_f32_16x16x32_f16 v[102:105], v[26:29], v[222:225], v[50:53]
	v_mfma_f32_16x16x32_f16 v[50:53], v[186:189], v[30:33], v[78:81]
	v_mfma_f32_16x16x32_f16 v[98:101], v[190:193], v[222:225], v[50:53]
	s_waitcnt lgkmcnt(3)
	v_mfma_f32_16x16x32_f16 v[50:53], v[6:9], v[226:229], v[82:85]
	s_waitcnt lgkmcnt(2)
	v_mfma_f32_16x16x32_f16 v[86:89], v[26:29], v[242:245], v[50:53]
	v_mfma_f32_16x16x32_f16 v[50:53], v[186:189], v[226:229], v[90:93]
	v_mfma_f32_16x16x32_f16 v[78:81], v[190:193], v[242:245], v[50:53]
	s_waitcnt lgkmcnt(1)
	v_mfma_f32_16x16x32_f16 v[50:53], v[6:9], v[246:249], v[94:97]
	s_waitcnt lgkmcnt(0)
	v_mfma_f32_16x16x32_f16 v[58:61], v[26:29], v[250:253], v[50:53]
	v_mfma_f32_16x16x32_f16 v[50:53], v[186:189], v[246:249], v[106:109]
	v_mfma_f32_16x16x32_f16 v[50:53], v[190:193], v[250:253], v[50:53]
	v_mfma_f32_16x16x32_f16 v[66:69], v[206:209], v[14:17], v[110:113]
	v_mfma_f32_16x16x32_f16 v[14:17], v[214:217], v[14:17], v[34:37]
	v_mfma_f32_16x16x32_f16 v[122:125], v[218:221], v[18:21], v[14:17]
	v_mfma_f32_16x16x32_f16 v[14:17], v[206:209], v[30:33], v[38:41]
	v_mfma_f32_16x16x32_f16 v[110:113], v[210:213], v[222:225], v[14:17]
	v_mfma_f32_16x16x32_f16 v[14:17], v[214:217], v[30:33], v[42:45]
	v_mfma_f32_16x16x32_f16 v[106:109], v[218:221], v[222:225], v[14:17]
	v_mfma_f32_16x16x32_f16 v[14:17], v[206:209], v[226:229], v[46:49]
	v_mfma_f32_16x16x32_f16 v[94:97], v[210:213], v[242:245], v[14:17]
	v_mfma_f32_16x16x32_f16 v[14:17], v[214:217], v[226:229], v[54:57]
	v_mfma_f32_16x16x32_f16 v[90:93], v[218:221], v[242:245], v[14:17]
	v_mfma_f32_16x16x32_f16 v[14:17], v[206:209], v[246:249], v[130:133]
	v_mfma_f32_16x16x32_f16 v[74:77], v[210:213], v[250:253], v[14:17]
	v_mfma_f32_16x16x32_f16 v[14:17], v[214:217], v[246:249], v[62:65]
	v_mfma_f32_16x16x32_f16 v[126:129], v[210:213], v[18:21], v[66:69]
	v_mfma_f32_16x16x32_f16 v[66:69], v[218:221], v[250:253], v[14:17]
	s_barrier
	s_setprio 0
	ds_read_b128 v[38:41], v238 offset:49152
	ds_read_b128 v[42:45], v238 offset:50176
	ds_read_b128 v[130:133], v238 offset:51200
	ds_read_b128 v[222:225], v238 offset:52224
	ds_read_b128 v[226:229], v238 offset:53248
	ds_read_b128 v[242:245], v238 offset:54272
	ds_read_b128 v[246:249], v238 offset:55296
	ds_read_b128 v[250:253], v238 offset:56320
	s_add_u32 m0, s28, 0x18000
	s_nop 0
	global_load_lds_dwordx4 v233, s[26:27]
	s_nop 0
	s_add_u32 m0, s28, 0x1a000
	s_nop 0
	global_load_lds_dwordx4 v235, s[26:27]
	s_add_u32 s26, s6, 0x40180
	s_addc_u32 s27, s7, 0
	s_add_u32 m0, s28, 0x1c000
	s_nop 0
	global_load_lds_dwordx4 v233, s[26:27]
	s_nop 0
	s_add_u32 m0, s28, 0x1e000
	s_nop 0
	global_load_lds_dwordx4 v235, s[26:27]
	s_nop 0
	s_add_u32 m0, s28, 0x8000
	s_nop 0
	global_load_lds_dwordx4 v232, s[24:25]
	s_nop 0
	s_add_u32 m0, s28, 0xa000
	s_nop 0
	global_load_lds_dwordx4 v234, s[24:25]
	s_waitcnt vmcnt(8)
	s_waitcnt lgkmcnt(0)
	s_barrier
	v_mfma_f32_16x16x32_f16 v[14:17], v[6:9], v[38:41], v[134:137]
	s_setprio 1
	s_waitcnt lgkmcnt(6)
	v_mfma_f32_16x16x32_f16 v[54:57], v[26:29], v[42:45], v[14:17]
	v_mfma_f32_16x16x32_f16 v[14:17], v[186:189], v[38:41], v[138:141]
	v_mfma_f32_16x16x32_f16 v[46:49], v[190:193], v[42:45], v[14:17]
	s_waitcnt lgkmcnt(5)
	v_mfma_f32_16x16x32_f16 v[14:17], v[6:9], v[130:133], v[142:145]
	s_waitcnt lgkmcnt(4)
	v_mfma_f32_16x16x32_f16 v[34:37], v[26:29], v[222:225], v[14:17]
	v_mfma_f32_16x16x32_f16 v[14:17], v[186:189], v[130:133], v[146:149]
	v_mfma_f32_16x16x32_f16 v[30:33], v[190:193], v[222:225], v[14:17]
	s_waitcnt lgkmcnt(3)
	v_mfma_f32_16x16x32_f16 v[14:17], v[6:9], v[226:229], v[150:153]
	s_waitcnt lgkmcnt(1)
	v_mfma_f32_16x16x32_f16 v[2:5], v[6:9], v[246:249], v[2:5]
	v_mfma_f32_16x16x32_f16 v[18:21], v[26:29], v[242:245], v[14:17]
	v_mfma_f32_16x16x32_f16 v[14:17], v[186:189], v[226:229], v[154:157]
	s_waitcnt lgkmcnt(0)
	v_mfma_f32_16x16x32_f16 v[6:9], v[26:29], v[250:253], v[2:5]
	v_mfma_f32_16x16x32_f16 v[2:5], v[186:189], v[246:249], v[10:13]
	v_mfma_f32_16x16x32_f16 v[14:17], v[190:193], v[242:245], v[14:17]
	v_mfma_f32_16x16x32_f16 v[2:5], v[190:193], v[250:253], v[2:5]
	v_mfma_f32_16x16x32_f16 v[10:13], v[206:209], v[38:41], v[158:161]
	v_mfma_f32_16x16x32_f16 v[82:85], v[210:213], v[42:45], v[10:13]
	v_mfma_f32_16x16x32_f16 v[10:13], v[214:217], v[38:41], v[162:165]
	v_mfma_f32_16x16x32_f16 v[70:73], v[218:221], v[42:45], v[10:13]
	v_mfma_f32_16x16x32_f16 v[10:13], v[206:209], v[130:133], v[166:169]
	v_mfma_f32_16x16x32_f16 v[62:65], v[210:213], v[222:225], v[10:13]
	v_mfma_f32_16x16x32_f16 v[10:13], v[214:217], v[130:133], v[170:173]
	v_mfma_f32_16x16x32_f16 v[42:45], v[218:221], v[222:225], v[10:13]
	v_mfma_f32_16x16x32_f16 v[10:13], v[206:209], v[226:229], v[174:177]
	v_mfma_f32_16x16x32_f16 v[38:41], v[210:213], v[242:245], v[10:13]
	v_mfma_f32_16x16x32_f16 v[10:13], v[214:217], v[226:229], v[178:181]
	v_mfma_f32_16x16x32_f16 v[26:29], v[218:221], v[242:245], v[10:13]
	v_mfma_f32_16x16x32_f16 v[10:13], v[206:209], v[246:249], v[22:25]
	v_mfma_f32_16x16x32_f16 v[22:25], v[210:213], v[250:253], v[10:13]
	v_mfma_f32_16x16x32_f16 v[10:13], v[214:217], v[246:249], v[182:185]
	v_mfma_f32_16x16x32_f16 v[10:13], v[218:221], v[250:253], v[10:13]
	s_barrier
	s_setprio 0
	s_add_u32 s53, s6, 0x200
	s_addc_u32 s61, s7, 0
	s_mov_b32 s64, 0
	s_branch .LBB0_231
; #define PG8_MMA(ai, bj, At, Bt) do { if constexpr (ABL & 2) break; __builtin_amdgcn_s_setprio(1); _Pragma("unroll") for (int m = 0; m < 4; ++m) _Pragma("unroll") for (int n = 0; n < 2; ++n) _Pragma("unroll") for (int k = 0; k < 2; ++k) \
;         acc[ai][bj][m][n] = __builtin_amdgcn_mfma_f32_16x16x32_f16(Bt[n][k], At[m][k], acc[ai][bj][m][n], 0, 0, 0); __builtin_amdgcn_s_setprio(0); } while (0)
; #define PG8_WAIT_V(n) asm volatile("s_waitcnt vmcnt(" #n ")" ::: "memory")
; #define PG8_WAIT_L(n) asm volatile("s_waitcnt lgkmcnt(" #n ")" ::: "memory")
; #define PG8_BAR __builtin_amdgcn_s_barrier()
; #define PG8_SCHED __builtin_amdgcn_sched_barrier(0)
;     ...
;         for (int t = 0; t < nt; t += 2) {
;     ...
;             if (!fin) PG8_WAIT_V(8); PG8_WAIT_L(0); PG8_BAR; PG8_MMA(1, 0, At, B0); PG8_MMA(1, 1, At, B1); PG8_BAR; PG8_SCHED;
.LBB0_230:
	s_waitcnt lgkmcnt(0)
	s_barrier
	v_mfma_f32_16x16x32_f16 v[54:57], v[154:157], v[186:189], v[54:57]
	s_setprio 1
	v_mfma_f32_16x16x32_f16 v[46:49], v[146:149], v[186:189], v[46:49]
	s_waitcnt lgkmcnt(5)
	v_mfma_f32_16x16x32_f16 v[34:37], v[154:157], v[178:181], v[34:37]
	v_mfma_f32_16x16x32_f16 v[30:33], v[146:149], v[178:181], v[30:33]
	s_waitcnt lgkmcnt(3)
	v_mfma_f32_16x16x32_f16 v[18:21], v[154:157], v[170:173], v[18:21]
	v_mfma_f32_16x16x32_f16 v[14:17], v[146:149], v[170:173], v[14:17]
	s_waitcnt lgkmcnt(1)
	v_mfma_f32_16x16x32_f16 v[6:9], v[154:157], v[162:165], v[6:9]
	v_mfma_f32_16x16x32_f16 v[2:5], v[146:149], v[162:165], v[2:5]
	v_mfma_f32_16x16x32_f16 v[54:57], v[158:161], v[190:193], v[54:57]
	v_mfma_f32_16x16x32_f16 v[46:49], v[150:153], v[190:193], v[46:49]
	v_mfma_f32_16x16x32_f16 v[34:37], v[158:161], v[182:185], v[34:37]
	v_mfma_f32_16x16x32_f16 v[30:33], v[150:153], v[182:185], v[30:33]
	v_mfma_f32_16x16x32_f16 v[18:21], v[158:161], v[174:177], v[18:21]
	v_mfma_f32_16x16x32_f16 v[14:17], v[150:153], v[174:177], v[14:17]
	s_waitcnt lgkmcnt(0)
	v_mfma_f32_16x16x32_f16 v[6:9], v[158:161], v[166:169], v[6:9]
	v_mfma_f32_16x16x32_f16 v[2:5], v[150:153], v[166:169], v[2:5]
	v_mfma_f32_16x16x32_f16 v[82:85], v[138:141], v[186:189], v[82:85]
	v_mfma_f32_16x16x32_f16 v[70:73], v[130:133], v[186:189], v[70:73]
	v_mfma_f32_16x16x32_f16 v[62:65], v[138:141], v[178:181], v[62:65]
	v_mfma_f32_16x16x32_f16 v[42:45], v[130:133], v[178:181], v[42:45]
	v_mfma_f32_16x16x32_f16 v[38:41], v[138:141], v[170:173], v[38:41]
	v_mfma_f32_16x16x32_f16 v[26:29], v[130:133], v[170:173], v[26:29]
	v_mfma_f32_16x16x32_f16 v[22:25], v[138:141], v[162:165], v[22:25]
	v_mfma_f32_16x16x32_f16 v[10:13], v[130:133], v[162:165], v[10:13]
	v_mfma_f32_16x16x32_f16 v[82:85], v[142:145], v[190:193], v[82:85]
	v_mfma_f32_16x16x32_f16 v[70:73], v[134:137], v[190:193], v[70:73]
	v_mfma_f32_16x16x32_f16 v[62:65], v[142:145], v[182:185], v[62:65]
	v_mfma_f32_16x16x32_f16 v[42:45], v[134:137], v[182:185], v[42:45]
	v_mfma_f32_16x16x32_f16 v[38:41], v[142:145], v[174:177], v[38:41]
	v_mfma_f32_16x16x32_f16 v[26:29], v[134:137], v[174:177], v[26:29]
	v_mfma_f32_16x16x32_f16 v[22:25], v[142:145], v[166:169], v[22:25]
	v_mfma_f32_16x16x32_f16 v[10:13], v[134:137], v[166:169], v[10:13]
	s_barrier
	s_setprio 0
	s_add_i32 s64, s64, 2
	s_add_u32 s53, s53, 0x100
	s_addc_u32 s61, s61, 0
	s_cmp_gt_u32 s64, 13
	s_cbranch_scc1 .LBB0_241
; #define PG8_STAGE(bufoff, gbase, voff) do { if constexpr (ABL & 1) break; glds16s<(bufoff)>((voff)[0], (const void*)(gbase), ldsbw); glds16s<(bufoff) + 8192>((voff)[1], (const void*)(gbase), ldsbw); } while (0)
; #define PG8_LDA(dst, b, h) do { if constexpr (ABL & 4) break; _Pragma("unroll") for (int m = 0; m < 4; ++m) _Pragma("unroll") for (int k = 0; k < 2; ++k) dst[m][k] = *(const LAS f16x8*)(lds + PG8_SA(b, h) + aoff + m * 2048 + k * 1024); } while (0)
; #define PG8_LDB(dst, b, h) do { if constexpr (ABL & 4) break; _Pragma("unroll") for (int n = 0; n < 2; ++n) _Pragma("unroll") for (int k = 0; k < 2; ++k) dst[n][k] = *(const LAS f16x8*)(lds + PG8_SB(b, h) + boff + n * 2048 + k * 1024); } while (0)
; #define PG8_MMAF(ai, bj, At, Bt) do { if (t == 0) PG8_MMA0(ai, bj, At, Bt); else PG8_MMA(ai, bj, At, Bt); } while (0)
; #define PG8_WAIT_V(n) asm volatile("s_waitcnt vmcnt(" #n ")" ::: "memory")
; #define PG8_WAIT_L(n) asm volatile("s_waitcnt lgkmcnt(" #n ")" ::: "memory")
; #define PG8_BAR __builtin_amdgcn_s_barrier()
; #define PG8_SCHED __builtin_amdgcn_sched_barrier(0)
;     ...
;             const bool last = (t == nt - 2);
;             const char* a1 = cA + (size_t)(t + 1) * kstep;
;             const char* a2 = last ? nA : cA + (size_t)(t + 2) * kstep; const char* b2 = last ? nB : cB + (size_t)(t + 2) * kstep;
;             const char* a3 = a2 + kstep; const char* b3 = b2 + kstep;
;             if (last && has_next) S.a_ready(nxt);
;             if constexpr (SP2) {
;             PG8_LDB(B0, 0, 0); PG8_LDB(B1, 0, 1); PG8_SCHED; PG8_LDA(At, 0, 0); PG8_STAGE(PG8_SA(1, 1), a1 + hstep, voffA);
;             PG8_WAIT_V(8); PG8_WAIT_L(0); PG8_BAR; PG8_MMAF(0, 0, At, B0); PG8_MMAF(0, 1, At, B1); PG8_BAR; PG8_SCHED;
;             const bool fin = last && !has_next;
;             PG8_LDA(At, 0, 1); if (!fin) { PG8_STAGE(PG8_SB(0, 0), b2, voffB); PG8_STAGE(PG8_SB(0, 1), b2 + hstep, voffB); PG8_STAGE(PG8_SA(0, 0), a2, voffA); }
.LBB0_231:
	ds_read_b128 v[146:149], v236
	ds_read_b128 v[150:153], v236 offset:1024
	ds_read_b128 v[154:157], v236 offset:2048
	ds_read_b128 v[158:161], v236 offset:3072
	ds_read_b128 v[130:133], v237
	ds_read_b128 v[134:137], v237 offset:1024
	ds_read_b128 v[138:141], v237 offset:2048
	ds_read_b128 v[142:145], v237 offset:3072
	s_mov_b64 s[6:7], s[8:9]
	s_add_u32 s8, s6, 0x100
	s_addc_u32 s9, s7, 0
	s_cmp_eq_u32 s64, 12
	s_cselect_b64 s[62:63], -1, 0
	s_and_b64 s[24:25], s[62:63], exec
	s_cselect_b32 s27, s11, s9
	s_cselect_b32 s26, s35, s8
	s_cselect_b32 s25, s1, s61
	s_cselect_b32 s24, s46, s53
	ds_read_b128 v[162:165], v238
	ds_read_b128 v[166:169], v238 offset:1024
	ds_read_b128 v[170:173], v238 offset:2048
	ds_read_b128 v[174:177], v238 offset:3072
	ds_read_b128 v[178:181], v238 offset:4096
	ds_read_b128 v[182:185], v238 offset:5120
	ds_read_b128 v[186:189], v238 offset:6144
	ds_read_b128 v[190:193], v238 offset:7168
	s_add_u32 s6, s6, 0x40080
	s_addc_u32 s7, s7, 0
	s_add_u32 m0, s28, 0xc000
	s_nop 0
	global_load_lds_dwordx4 v232, s[6:7]
	s_nop 0
	s_add_u32 m0, s28, 0xe000
	s_nop 0
	global_load_lds_dwordx4 v234, s[6:7]
	s_waitcnt vmcnt(8)
	s_waitcnt lgkmcnt(0)
	s_barrier
	v_mfma_f32_16x16x32_f16 v[118:121], v[146:149], v[162:165], v[118:121]
	s_setprio 1
	v_mfma_f32_16x16x32_f16 v[114:117], v[154:157], v[162:165], v[114:117]
	s_waitcnt lgkmcnt(5)
	v_mfma_f32_16x16x32_f16 v[102:105], v[146:149], v[170:173], v[102:105]
	v_mfma_f32_16x16x32_f16 v[98:101], v[154:157], v[170:173], v[98:101]
	s_waitcnt lgkmcnt(3)
	v_mfma_f32_16x16x32_f16 v[86:89], v[146:149], v[178:181], v[86:89]
	v_mfma_f32_16x16x32_f16 v[78:81], v[154:157], v[178:181], v[78:81]
	s_waitcnt lgkmcnt(1)
	v_mfma_f32_16x16x32_f16 v[58:61], v[146:149], v[186:189], v[58:61]
	v_mfma_f32_16x16x32_f16 v[50:53], v[154:157], v[186:189], v[50:53]
	v_mfma_f32_16x16x32_f16 v[118:121], v[150:153], v[166:169], v[118:121]
	v_mfma_f32_16x16x32_f16 v[114:117], v[158:161], v[166:169], v[114:117]
	v_mfma_f32_16x16x32_f16 v[102:105], v[150:153], v[174:177], v[102:105]
	v_mfma_f32_16x16x32_f16 v[98:101], v[158:161], v[174:177], v[98:101]
	v_mfma_f32_16x16x32_f16 v[86:89], v[150:153], v[182:185], v[86:89]
	v_mfma_f32_16x16x32_f16 v[78:81], v[158:161], v[182:185], v[78:81]
	s_waitcnt lgkmcnt(0)
	v_mfma_f32_16x16x32_f16 v[58:61], v[150:153], v[190:193], v[58:61]
	v_mfma_f32_16x16x32_f16 v[50:53], v[158:161], v[190:193], v[50:53]
	v_mfma_f32_16x16x32_f16 v[126:129], v[130:133], v[162:165], v[126:129]
	v_mfma_f32_16x16x32_f16 v[122:125], v[138:141], v[162:165], v[122:125]
	v_mfma_f32_16x16x32_f16 v[110:113], v[130:133], v[170:173], v[110:113]
	v_mfma_f32_16x16x32_f16 v[106:109], v[138:141], v[170:173], v[106:109]
	v_mfma_f32_16x16x32_f16 v[94:97], v[130:133], v[178:181], v[94:97]
	v_mfma_f32_16x16x32_f16 v[90:93], v[138:141], v[178:181], v[90:93]
	v_mfma_f32_16x16x32_f16 v[74:77], v[130:133], v[186:189], v[74:77]
	v_mfma_f32_16x16x32_f16 v[66:69], v[138:141], v[186:189], v[66:69]
	v_mfma_f32_16x16x32_f16 v[126:129], v[134:137], v[166:169], v[126:129]
	v_mfma_f32_16x16x32_f16 v[122:125], v[142:145], v[166:169], v[122:125]
	v_mfma_f32_16x16x32_f16 v[110:113], v[134:137], v[174:177], v[110:113]
	v_mfma_f32_16x16x32_f16 v[106:109], v[142:145], v[174:177], v[106:109]
	v_mfma_f32_16x16x32_f16 v[94:97], v[134:137], v[182:185], v[94:97]
	v_mfma_f32_16x16x32_f16 v[90:93], v[142:145], v[182:185], v[90:93]
	v_mfma_f32_16x16x32_f16 v[74:77], v[134:137], v[190:193], v[74:77]
	v_mfma_f32_16x16x32_f16 v[66:69], v[142:145], v[190:193], v[66:69]
	s_barrier
	s_setprio 0
	ds_read_b128 v[186:189], v238 offset:16384
	ds_read_b128 v[190:193], v238 offset:17408
	ds_read_b128 v[178:181], v238 offset:18432
	ds_read_b128 v[182:185], v238 offset:19456
	ds_read_b128 v[170:173], v238 offset:20480
	ds_read_b128 v[174:177], v238 offset:21504
	ds_read_b128 v[162:165], v238 offset:22528
	ds_read_b128 v[166:169], v238 offset:23552
	s_and_b64 s[6:7], s[4:5], s[62:63]
	s_mov_b64 s[62:63], -1
	s_and_b64 vcc, exec, s[6:7]
	s_cbranch_vccnz .LBB0_233
	s_add_u32 m0, s28, 0x10000
	s_nop 0
	global_load_lds_dwordx4 v233, s[24:25]
	s_nop 0
	s_add_u32 m0, s28, 0x12000
	s_nop 0
	global_load_lds_dwordx4 v235, s[24:25]
	s_add_u32 s62, s24, 0x40000
	s_addc_u32 s63, s25, 0
	s_add_u32 m0, s28, 0x14000
	s_nop 0
	global_load_lds_dwordx4 v233, s[62:63]
	s_nop 0
	s_add_u32 m0, s28, 0x16000
	s_nop 0
	global_load_lds_dwordx4 v235, s[62:63]
	s_mov_b64 s[62:63], 0
	s_add_u32 m0, s28, 0
	s_nop 0
	global_load_lds_dwordx4 v232, s[26:27]
	s_nop 0
	s_add_u32 m0, s28, 0x2000
	s_nop 0
	global_load_lds_dwordx4 v234, s[26:27]
	s_waitcnt vmcnt(8)

; #define PG8_STAGE(bufoff, gbase, voff) do { if constexpr (ABL & 1) break; glds16s<(bufoff)>((voff)[0], (const void*)(gbase), ldsbw); glds16s<(bufoff) + 8192>((voff)[1], (const void*)(gbase), ldsbw); } while (0)
; #define PG8_LDA(dst, b, h) do { if constexpr (ABL & 4) break; _Pragma("unroll") for (int m = 0; m < 4; ++m) _Pragma("unroll") for (int k = 0; k < 2; ++k) dst[m][k] = *(const LAS f16x8*)(lds + PG8_SA(b, h) + aoff + m * 2048 + k * 1024); } while (0)
; #define PG8_LDB(dst, b, h) do { if constexpr (ABL & 4) break; _Pragma("unroll") for (int n = 0; n < 2; ++n) _Pragma("unroll") for (int k = 0; k < 2; ++k) dst[n][k] = *(const LAS f16x8*)(lds + PG8_SB(b, h) + boff + n * 2048 + k * 1024); } while (0)
; #define PG8_MMA(ai, bj, At, Bt) do { if constexpr (ABL & 2) break; __builtin_amdgcn_s_setprio(1); _Pragma("unroll") for (int m = 0; m < 4; ++m) _Pragma("unroll") for (int n = 0; n < 2; ++n) _Pragma("unroll") for (int k = 0; k < 2; ++k) \
;         acc[ai][bj][m][n] = __builtin_amdgcn_mfma_f32_16x16x32_f16(Bt[n][k], At[m][k], acc[ai][bj][m][n], 0, 0, 0); __builtin_amdgcn_s_setprio(0); } while (0)
; #define PG8_MMAF(ai, bj, At, Bt) do { if (t == 0) PG8_MMA0(ai, bj, At, Bt); else PG8_MMA(ai, bj, At, Bt); } while (0)
; #define PG8_WAIT_V(n) asm volatile("s_waitcnt vmcnt(" #n ")" ::: "memory")
; #define PG8_WAIT_L(n) asm volatile("s_waitcnt lgkmcnt(" #n ")" ::: "memory")
; #define PG8_BAR __builtin_amdgcn_s_barrier()
; #define PG8_SCHED __builtin_amdgcn_sched_barrier(0)
;     ...
;             if (!fin) PG8_WAIT_V(8); else PG8_WAIT_V(2); PG8_WAIT_L(0); PG8_BAR; PG8_MMAF(1, 0, At, B0); PG8_MMAF(1, 1, At, B1); PG8_BAR; PG8_SCHED;
;             PG8_LDB(B0, 1, 0); PG8_LDB(B1, 1, 1); PG8_SCHED; PG8_LDA(At, 1, 0); if (!fin) PG8_STAGE(PG8_SA(0, 1), a2 + hstep, voffA);
;             if (!fin) PG8_WAIT_V(8); else PG8_WAIT_V(0); PG8_WAIT_L(0); PG8_BAR; PG8_MMA(0, 0, At, B0); PG8_MMA(0, 1, At, B1); PG8_BAR; PG8_SCHED;
.LBB0_235:
	s_waitcnt lgkmcnt(0)
	s_xor_b64 s[62:63], s[6:7], -1
	s_barrier
	v_mfma_f32_16x16x32_f16 v[54:57], v[146:149], v[186:189], v[54:57]
	s_setprio 1
	v_mfma_f32_16x16x32_f16 v[46:49], v[154:157], v[186:189], v[46:49]
	s_waitcnt lgkmcnt(5)
	v_mfma_f32_16x16x32_f16 v[34:37], v[146:149], v[178:181], v[34:37]
	v_mfma_f32_16x16x32_f16 v[30:33], v[154:157], v[178:181], v[30:33]
	s_waitcnt lgkmcnt(3)
	v_mfma_f32_16x16x32_f16 v[18:21], v[146:149], v[170:173], v[18:21]
	v_mfma_f32_16x16x32_f16 v[14:17], v[154:157], v[170:173], v[14:17]
	s_waitcnt lgkmcnt(1)
	v_mfma_f32_16x16x32_f16 v[6:9], v[146:149], v[162:165], v[6:9]
	v_mfma_f32_16x16x32_f16 v[2:5], v[154:157], v[162:165], v[2:5]
	v_mfma_f32_16x16x32_f16 v[54:57], v[150:153], v[190:193], v[54:57]
	v_mfma_f32_16x16x32_f16 v[46:49], v[158:161], v[190:193], v[46:49]
	v_mfma_f32_16x16x32_f16 v[34:37], v[150:153], v[182:185], v[34:37]
	v_mfma_f32_16x16x32_f16 v[30:33], v[158:161], v[182:185], v[30:33]
	v_mfma_f32_16x16x32_f16 v[18:21], v[150:153], v[174:177], v[18:21]
	v_mfma_f32_16x16x32_f16 v[14:17], v[158:161], v[174:177], v[14:17]
	s_waitcnt lgkmcnt(0)
	v_mfma_f32_16x16x32_f16 v[6:9], v[150:153], v[166:169], v[6:9]
	v_mfma_f32_16x16x32_f16 v[2:5], v[158:161], v[166:169], v[2:5]
	v_mfma_f32_16x16x32_f16 v[82:85], v[130:133], v[186:189], v[82:85]
	v_mfma_f32_16x16x32_f16 v[70:73], v[138:141], v[186:189], v[70:73]
	v_mfma_f32_16x16x32_f16 v[62:65], v[130:133], v[178:181], v[62:65]
	v_mfma_f32_16x16x32_f16 v[42:45], v[138:141], v[178:181], v[42:45]
	v_mfma_f32_16x16x32_f16 v[38:41], v[130:133], v[170:173], v[38:41]
	v_mfma_f32_16x16x32_f16 v[26:29], v[138:141], v[170:173], v[26:29]
	v_mfma_f32_16x16x32_f16 v[22:25], v[130:133], v[162:165], v[22:25]
	v_mfma_f32_16x16x32_f16 v[10:13], v[138:141], v[162:165], v[10:13]
	v_mfma_f32_16x16x32_f16 v[82:85], v[134:137], v[190:193], v[82:85]
	v_mfma_f32_16x16x32_f16 v[70:73], v[142:145], v[190:193], v[70:73]
	v_mfma_f32_16x16x32_f16 v[62:65], v[134:137], v[182:185], v[62:65]
	v_mfma_f32_16x16x32_f16 v[42:45], v[142:145], v[182:185], v[42:45]
	v_mfma_f32_16x16x32_f16 v[38:41], v[134:137], v[174:177], v[38:41]
	v_mfma_f32_16x16x32_f16 v[26:29], v[142:145], v[174:177], v[26:29]
	v_mfma_f32_16x16x32_f16 v[22:25], v[134:137], v[166:169], v[22:25]
	v_mfma_f32_16x16x32_f16 v[10:13], v[142:145], v[166:169], v[10:13]
	s_barrier
	s_setprio 0
	ds_read_b128 v[154:157], v239
	ds_read_b128 v[158:161], v239 offset:1024
	ds_read_b128 v[146:149], v239 offset:2048
	ds_read_b128 v[150:153], v239 offset:3072
	ds_read_b128 v[138:141], v240
	ds_read_b128 v[142:145], v240 offset:1024
	ds_read_b128 v[130:133], v240 offset:2048
	ds_read_b128 v[134:137], v240 offset:3072
	ds_read_b128 v[186:189], v238 offset:32768
	ds_read_b128 v[190:193], v238 offset:33792
	ds_read_b128 v[178:181], v238 offset:34816
	ds_read_b128 v[182:185], v238 offset:35840
	ds_read_b128 v[170:173], v238 offset:36864
	ds_read_b128 v[174:177], v238 offset:37888
	ds_read_b128 v[162:165], v238 offset:38912
	ds_read_b128 v[166:169], v238 offset:39936
	v_cndmask_b32_e64 v198, 0, 1, s[62:63]
	v_cmp_ne_u32_e64 s[6:7], 1, v198
	s_andn2_b64 vcc, exec, s[62:63]
	s_mov_b64 s[62:63], -1
	s_cbranch_vccnz .LBB0_237
	s_add_u32 s62, s26, 0x40000
	s_addc_u32 s63, s27, 0
	s_add_u32 m0, s28, 0x4000
	s_nop 0
	global_load_lds_dwordx4 v232, s[62:63]
	s_nop 0
	s_add_u32 m0, s28, 0x6000
	s_nop 0
	global_load_lds_dwordx4 v234, s[62:63]
	s_waitcnt vmcnt(8)
	s_mov_b64 s[62:63], 0

; #define PG8_STAGE(bufoff, gbase, voff) do { if constexpr (ABL & 1) break; glds16s<(bufoff)>((voff)[0], (const void*)(gbase), ldsbw); glds16s<(bufoff) + 8192>((voff)[1], (const void*)(gbase), ldsbw); } while (0)
; #define PG8_LDA(dst, b, h) do { if constexpr (ABL & 4) break; _Pragma("unroll") for (int m = 0; m < 4; ++m) _Pragma("unroll") for (int k = 0; k < 2; ++k) dst[m][k] = *(const LAS f16x8*)(lds + PG8_SA(b, h) + aoff + m * 2048 + k * 1024); } while (0)
; #define PG8_MMA(ai, bj, At, Bt) do { if constexpr (ABL & 2) break; __builtin_amdgcn_s_setprio(1); _Pragma("unroll") for (int m = 0; m < 4; ++m) _Pragma("unroll") for (int n = 0; n < 2; ++n) _Pragma("unroll") for (int k = 0; k < 2; ++k) \
;         acc[ai][bj][m][n] = __builtin_amdgcn_mfma_f32_16x16x32_f16(Bt[n][k], At[m][k], acc[ai][bj][m][n], 0, 0, 0); __builtin_amdgcn_s_setprio(0); } while (0)
; #define PG8_WAIT_V(n) asm volatile("s_waitcnt vmcnt(" #n ")" ::: "memory")
; #define PG8_WAIT_L(n) asm volatile("s_waitcnt lgkmcnt(" #n ")" ::: "memory")
; #define PG8_BAR __builtin_amdgcn_s_barrier()
; #define PG8_SCHED __builtin_amdgcn_sched_barrier(0)
;     ...
;             if (!fin) PG8_WAIT_V(8); else PG8_WAIT_V(0); PG8_WAIT_L(0); PG8_BAR; PG8_MMA(0, 0, At, B0); PG8_MMA(0, 1, At, B1); PG8_BAR; PG8_SCHED;
;             PG8_LDA(At, 1, 1); if (!fin) { PG8_STAGE(PG8_SB(1, 0), b3, voffB); PG8_STAGE(PG8_SB(1, 1), b3 + hstep, voffB); PG8_STAGE(PG8_SA(1, 0), a3, voffA); }
;             if (!fin) PG8_WAIT_V(8); PG8_WAIT_L(0); PG8_BAR; PG8_MMA(1, 0, At, B0); PG8_MMA(1, 1, At, B1); PG8_BAR; PG8_SCHED;
.LBB0_239:
	s_waitcnt lgkmcnt(0)
	s_barrier
	v_mfma_f32_16x16x32_f16 v[118:121], v[154:157], v[186:189], v[118:121]
	s_setprio 1
	v_mfma_f32_16x16x32_f16 v[114:117], v[146:149], v[186:189], v[114:117]
	s_waitcnt lgkmcnt(5)
	v_mfma_f32_16x16x32_f16 v[102:105], v[154:157], v[178:181], v[102:105]
	v_mfma_f32_16x16x32_f16 v[98:101], v[146:149], v[178:181], v[98:101]
	s_waitcnt lgkmcnt(3)
	v_mfma_f32_16x16x32_f16 v[86:89], v[154:157], v[170:173], v[86:89]
	v_mfma_f32_16x16x32_f16 v[78:81], v[146:149], v[170:173], v[78:81]
	s_waitcnt lgkmcnt(1)
	v_mfma_f32_16x16x32_f16 v[58:61], v[154:157], v[162:165], v[58:61]
	v_mfma_f32_16x16x32_f16 v[50:53], v[146:149], v[162:165], v[50:53]
	v_mfma_f32_16x16x32_f16 v[118:121], v[158:161], v[190:193], v[118:121]
	v_mfma_f32_16x16x32_f16 v[114:117], v[150:153], v[190:193], v[114:117]
	v_mfma_f32_16x16x32_f16 v[102:105], v[158:161], v[182:185], v[102:105]
	v_mfma_f32_16x16x32_f16 v[98:101], v[150:153], v[182:185], v[98:101]
	v_mfma_f32_16x16x32_f16 v[86:89], v[158:161], v[174:177], v[86:89]
	v_mfma_f32_16x16x32_f16 v[78:81], v[150:153], v[174:177], v[78:81]
	s_waitcnt lgkmcnt(0)
	v_mfma_f32_16x16x32_f16 v[58:61], v[158:161], v[166:169], v[58:61]
	v_mfma_f32_16x16x32_f16 v[50:53], v[150:153], v[166:169], v[50:53]
	v_mfma_f32_16x16x32_f16 v[126:129], v[138:141], v[186:189], v[126:129]
	v_mfma_f32_16x16x32_f16 v[122:125], v[130:133], v[186:189], v[122:125]
	v_mfma_f32_16x16x32_f16 v[110:113], v[138:141], v[178:181], v[110:113]
	v_mfma_f32_16x16x32_f16 v[106:109], v[130:133], v[178:181], v[106:109]
	v_mfma_f32_16x16x32_f16 v[94:97], v[138:141], v[170:173], v[94:97]
	v_mfma_f32_16x16x32_f16 v[90:93], v[130:133], v[170:173], v[90:93]
	v_mfma_f32_16x16x32_f16 v[74:77], v[138:141], v[162:165], v[74:77]
	v_mfma_f32_16x16x32_f16 v[66:69], v[130:133], v[162:165], v[66:69]
	v_mfma_f32_16x16x32_f16 v[126:129], v[142:145], v[190:193], v[126:129]
	v_mfma_f32_16x16x32_f16 v[122:125], v[134:137], v[190:193], v[122:125]
	v_mfma_f32_16x16x32_f16 v[110:113], v[142:145], v[182:185], v[110:113]
	v_mfma_f32_16x16x32_f16 v[106:109], v[134:137], v[182:185], v[106:109]
	v_mfma_f32_16x16x32_f16 v[94:97], v[142:145], v[174:177], v[94:97]
	v_mfma_f32_16x16x32_f16 v[90:93], v[134:137], v[174:177], v[90:93]
	v_mfma_f32_16x16x32_f16 v[74:77], v[142:145], v[166:169], v[74:77]
	v_mfma_f32_16x16x32_f16 v[66:69], v[134:137], v[166:169], v[66:69]
	s_barrier
	s_setprio 0
	ds_read_b128 v[186:189], v238 offset:49152
	ds_read_b128 v[190:193], v238 offset:50176
	ds_read_b128 v[178:181], v238 offset:51200
	ds_read_b128 v[182:185], v238 offset:52224
	ds_read_b128 v[170:173], v238 offset:53248
	ds_read_b128 v[174:177], v238 offset:54272
	ds_read_b128 v[162:165], v238 offset:55296
	ds_read_b128 v[166:169], v238 offset:56320
	s_and_b64 vcc, exec, s[6:7]
	s_cbranch_vccnz .LBB0_230
	s_add_u32 s6, s26, 0x80
	s_addc_u32 s7, s27, 0
	s_add_u32 s26, s24, 0x80
	s_addc_u32 s27, s25, 0
	s_add_u32 m0, s28, 0x18000
	s_nop 0
	global_load_lds_dwordx4 v233, s[26:27]
	s_nop 0
	s_add_u32 m0, s28, 0x1a000
	s_nop 0
	global_load_lds_dwordx4 v235, s[26:27]
	s_add_u32 s24, s24, 0x40080
	s_addc_u32 s25, s25, 0
	s_add_u32 m0, s28, 0x1c000
	s_nop 0
	global_load_lds_dwordx4 v233, s[24:25]
	s_nop 0
	s_add_u32 m0, s28, 0x1e000
	s_nop 0
	global_load_lds_dwordx4 v235, s[24:25]
	s_nop 0
	s_add_u32 m0, s28, 0x8000
	s_nop 0
	global_load_lds_dwordx4 v232, s[6:7]
	s_nop 0
	s_add_u32 m0, s28, 0xa000
	s_nop 0
	global_load_lds_dwordx4 v234, s[6:7]
	s_waitcnt vmcnt(8)
	s_branch .LBB0_230

; #define PG8_STAGE(bufoff, gbase, voff) do { if constexpr (ABL & 1) break; glds16s<(bufoff)>((voff)[0], (const void*)(gbase), ldsbw); glds16s<(bufoff) + 8192>((voff)[1], (const void*)(gbase), ldsbw); } while (0)
; #define PG8_LDA(dst, b, h) do { if constexpr (ABL & 4) break; _Pragma("unroll") for (int m = 0; m < 4; ++m) _Pragma("unroll") for (int k = 0; k < 2; ++k) dst[m][k] = *(const LAS f16x8*)(lds + PG8_SA(b, h) + aoff + m * 2048 + k * 1024); } while (0)
; #define PG8_LDB(dst, b, h) do { if constexpr (ABL & 4) break; _Pragma("unroll") for (int n = 0; n < 2; ++n) _Pragma("unroll") for (int k = 0; k < 2; ++k) dst[n][k] = *(const LAS f16x8*)(lds + PG8_SB(b, h) + boff + n * 2048 + k * 1024); } while (0)
; #define PG8_MMAF(ai, bj, At, Bt) do { if (t == 0) PG8_MMA0(ai, bj, At, Bt); else PG8_MMA(ai, bj, At, Bt); } while (0)
; #define PG8_WAIT_V(n) asm volatile("s_waitcnt vmcnt(" #n ")" ::: "memory")
; #define PG8_WAIT_L(n) asm volatile("s_waitcnt lgkmcnt(" #n ")" ::: "memory")
; #define PG8_BAR __builtin_amdgcn_s_barrier()
; #define PG8_SCHED __builtin_amdgcn_sched_barrier(0)
;     ...
;         const char* nA = has_next ? (const char*)g.A + (size_t)nxt.pm * tstep : cA; const char* nB = has_next ? (const char*)g.Bt + (size_t)nxt.pn * tstep : cB;
;         for (int t = 0; t < nt; t += 2) {
;             const bool last = (t == nt - 2);
;             const char* a1 = cA + (size_t)(t + 1) * kstep;
;             const char* a2 = last ? nA : cA + (size_t)(t + 2) * kstep; const char* b2 = last ? nB : cB + (size_t)(t + 2) * kstep;
;             const char* a3 = a2 + kstep; const char* b3 = b2 + kstep;
;             if (last && has_next) S.a_ready(nxt);
;             if constexpr (SP2) {
;             PG8_LDB(B0, 0, 0); PG8_LDB(B1, 0, 1); PG8_SCHED; PG8_LDA(At, 0, 0); PG8_STAGE(PG8_SA(1, 1), a1 + hstep, voffA);
;             PG8_WAIT_V(8); PG8_WAIT_L(0); PG8_BAR; PG8_MMAF(0, 0, At, B0); PG8_MMAF(0, 1, At, B1); PG8_BAR; PG8_SCHED;
;             const bool fin = last && !has_next;
;             PG8_LDA(At, 0, 1); if (!fin) { PG8_STAGE(PG8_SB(0, 0), b2, voffB); PG8_STAGE(PG8_SB(0, 1), b2 + hstep, voffB); PG8_STAGE(PG8_SA(0, 0), a2, voffA); }
;             if (!fin) PG8_WAIT_V(8); else PG8_WAIT_V(2); PG8_WAIT_L(0); PG8_BAR; PG8_MMAF(1, 0, At, B0); PG8_MMAF(1, 1, At, B1); PG8_BAR; PG8_SCHED;
.LBB0_748:
	s_ashr_i32 s47, s46, 31
	s_lshl_b64 s[8:9], s[46:47], 19
	s_add_u32 s48, s12, s8
	s_addc_u32 s49, s13, s9
	s_and_b64 s[8:9], exec, s[4:5]
	s_waitcnt lgkmcnt(0)
	ds_read_b128 v[2:5], v222
	ds_read_b128 v[6:9], v222 offset:1024
	ds_read_b128 v[10:13], v222 offset:2048
	ds_read_b128 v[14:17], v222 offset:3072
	ds_read_b128 v[18:21], v223
	ds_read_b128 v[22:25], v223 offset:1024
	ds_read_b128 v[26:29], v223 offset:2048
	ds_read_b128 v[30:33], v223 offset:3072
	s_cselect_b32 s47, s31, s49
	s_cselect_b32 s55, s30, s48
	s_ashr_i32 s45, s44, 31
	s_lshl_b64 s[8:9], s[44:45], 19
	s_add_u32 s50, s90, s8
	s_addc_u32 s51, s91, s9
	s_and_b64 s[8:9], exec, s[4:5]
	s_cselect_b32 s45, s7, s51
	s_cselect_b32 s58, s6, s50
	s_add_u32 s56, s30, 0x100
	s_addc_u32 s57, s31, 0
	s_add_u32 s26, s6, 0x100
	s_addc_u32 s27, s7, 0
	s_add_u32 s8, s30, 0x180
	s_addc_u32 s9, s31, 0
	ds_read_b128 v[34:37], v224
	ds_read_b128 v[38:41], v224 offset:1024
	ds_read_b128 v[42:45], v224 offset:2048
	ds_read_b128 v[46:49], v224 offset:3072
	ds_read_b128 v[50:53], v224 offset:4096
	ds_read_b128 v[54:57], v224 offset:5120
	ds_read_b128 v[58:61], v224 offset:6144
	ds_read_b128 v[62:65], v224 offset:7168
	s_add_u32 s24, s6, 0x180
	s_addc_u32 s25, s7, 0
	s_add_u32 s60, s30, 0x40080
	s_addc_u32 s61, s31, 0
	s_add_u32 m0, s14, 0xc000
	s_nop 0
	global_load_lds_dwordx4 v1, s[60:61]
	s_nop 0
	s_add_u32 m0, s14, 0xe000
	s_nop 0
	global_load_lds_dwordx4 v213, s[60:61]
	s_waitcnt vmcnt(8)
	s_waitcnt lgkmcnt(0)
	s_barrier
	v_mfma_f32_16x16x32_f16 v[66:69], v[2:5], v[34:37], 0
	s_setprio 1
	v_mfma_f32_16x16x32_f16 v[70:73], v[10:13], v[34:37], 0
	s_waitcnt lgkmcnt(5)
	v_mfma_f32_16x16x32_f16 v[78:81], v[10:13], v[42:45], 0
	s_waitcnt lgkmcnt(3)
	v_mfma_f32_16x16x32_f16 v[82:85], v[2:5], v[50:53], 0
	s_waitcnt lgkmcnt(1)
	v_mfma_f32_16x16x32_f16 v[90:93], v[2:5], v[58:61], 0
	v_mfma_f32_16x16x32_f16 v[94:97], v[10:13], v[58:61], 0
	v_mfma_f32_16x16x32_f16 v[66:69], v[6:9], v[38:41], v[66:69]
	v_mfma_f32_16x16x32_f16 v[70:73], v[14:17], v[38:41], v[70:73]
	v_mfma_f32_16x16x32_f16 v[74:77], v[2:5], v[42:45], 0
	v_mfma_f32_16x16x32_f16 v[78:81], v[14:17], v[46:49], v[78:81]
	v_mfma_f32_16x16x32_f16 v[82:85], v[6:9], v[54:57], v[82:85]
	v_mfma_f32_16x16x32_f16 v[86:89], v[10:13], v[50:53], 0
	s_waitcnt lgkmcnt(0)
	v_mfma_f32_16x16x32_f16 v[90:93], v[6:9], v[62:65], v[90:93]
	v_mfma_f32_16x16x32_f16 v[94:97], v[14:17], v[62:65], v[94:97]
	v_mfma_f32_16x16x32_f16 v[74:77], v[6:9], v[46:49], v[74:77]
	v_mfma_f32_16x16x32_f16 v[86:89], v[14:17], v[54:57], v[86:89]
	v_mfma_f32_16x16x32_f16 v[98:101], v[18:21], v[34:37], 0
	v_mfma_f32_16x16x32_f16 v[34:37], v[26:29], v[34:37], 0
	v_mfma_f32_16x16x32_f16 v[98:101], v[22:25], v[38:41], v[98:101]
	v_mfma_f32_16x16x32_f16 v[34:37], v[30:33], v[38:41], v[34:37]
	v_mfma_f32_16x16x32_f16 v[38:41], v[18:21], v[42:45], 0
	v_mfma_f32_16x16x32_f16 v[42:45], v[26:29], v[42:45], 0
	v_mfma_f32_16x16x32_f16 v[38:41], v[22:25], v[46:49], v[38:41]
	v_mfma_f32_16x16x32_f16 v[42:45], v[30:33], v[46:49], v[42:45]
	v_mfma_f32_16x16x32_f16 v[46:49], v[18:21], v[50:53], 0
	v_mfma_f32_16x16x32_f16 v[50:53], v[26:29], v[50:53], 0
	v_mfma_f32_16x16x32_f16 v[46:49], v[22:25], v[54:57], v[46:49]
	v_mfma_f32_16x16x32_f16 v[50:53], v[30:33], v[54:57], v[50:53]
	v_mfma_f32_16x16x32_f16 v[54:57], v[18:21], v[58:61], 0
	v_mfma_f32_16x16x32_f16 v[58:61], v[26:29], v[58:61], 0
	v_mfma_f32_16x16x32_f16 v[54:57], v[22:25], v[62:65], v[54:57]
	v_mfma_f32_16x16x32_f16 v[58:61], v[30:33], v[62:65], v[58:61]
	s_barrier
	s_setprio 0
	ds_read_b128 v[62:65], v224 offset:16384
	ds_read_b128 v[102:105], v224 offset:17408
	ds_read_b128 v[106:109], v224 offset:18432
	ds_read_b128 v[110:113], v224 offset:19456
	ds_read_b128 v[114:117], v224 offset:20480
	ds_read_b128 v[118:121], v224 offset:21504
	ds_read_b128 v[122:125], v224 offset:22528
	ds_read_b128 v[126:129], v224 offset:23552
	s_add_u32 m0, s14, 0x10000
	s_nop 0
	global_load_lds_dwordx4 v209, s[26:27]
	s_nop 0
	s_add_u32 m0, s14, 0x12000
	s_nop 0
	global_load_lds_dwordx4 v219, s[26:27]
	s_add_u32 s26, s6, 0x40100
	s_addc_u32 s27, s7, 0
	s_add_u32 m0, s14, 0x14000
	s_nop 0
	global_load_lds_dwordx4 v209, s[26:27]
	s_nop 0
	s_add_u32 m0, s14, 0x16000
	s_nop 0
	global_load_lds_dwordx4 v219, s[26:27]
	s_nop 0
	s_add_u32 m0, s14, 0
	s_nop 0
	global_load_lds_dwordx4 v1, s[56:57]
	s_nop 0
	s_add_u32 m0, s14, 0x2000
	s_nop 0
	global_load_lds_dwordx4 v213, s[56:57]
	s_waitcnt vmcnt(8)
	s_waitcnt lgkmcnt(0)
	s_barrier
	v_mfma_f32_16x16x32_f16 v[130:133], v[2:5], v[62:65], 0
	s_setprio 1
	s_waitcnt lgkmcnt(6)
	v_mfma_f32_16x16x32_f16 v[134:137], v[6:9], v[102:105], v[130:133]
	v_mfma_f32_16x16x32_f16 v[130:133], v[10:13], v[62:65], 0
	v_mfma_f32_16x16x32_f16 v[146:149], v[14:17], v[102:105], v[130:133]
	s_waitcnt lgkmcnt(5)
	v_mfma_f32_16x16x32_f16 v[130:133], v[2:5], v[106:109], 0
	s_waitcnt lgkmcnt(4)
	v_mfma_f32_16x16x32_f16 v[158:161], v[6:9], v[110:113], v[130:133]
	v_mfma_f32_16x16x32_f16 v[130:133], v[10:13], v[106:109], 0
	v_mfma_f32_16x16x32_f16 v[162:165], v[14:17], v[110:113], v[130:133]
	s_waitcnt lgkmcnt(3)
	v_mfma_f32_16x16x32_f16 v[130:133], v[2:5], v[114:117], 0
	s_waitcnt lgkmcnt(1)
	v_mfma_f32_16x16x32_f16 v[2:5], v[2:5], v[122:125], 0
	v_mfma_f32_16x16x32_f16 v[166:169], v[6:9], v[118:121], v[130:133]
	s_waitcnt lgkmcnt(0)
	v_mfma_f32_16x16x32_f16 v[2:5], v[6:9], v[126:129], v[2:5]
	v_mfma_f32_16x16x32_f16 v[6:9], v[10:13], v[122:125], 0
	v_mfma_f32_16x16x32_f16 v[130:133], v[10:13], v[114:117], 0
	v_mfma_f32_16x16x32_f16 v[6:9], v[14:17], v[126:129], v[6:9]
	v_mfma_f32_16x16x32_f16 v[170:173], v[14:17], v[118:121], v[130:133]
	v_mfma_f32_16x16x32_f16 v[10:13], v[18:21], v[62:65], 0
	v_mfma_f32_16x16x32_f16 v[174:177], v[22:25], v[102:105], v[10:13]
	v_mfma_f32_16x16x32_f16 v[10:13], v[26:29], v[62:65], 0
	v_mfma_f32_16x16x32_f16 v[178:181], v[30:33], v[102:105], v[10:13]
	v_mfma_f32_16x16x32_f16 v[10:13], v[18:21], v[106:109], 0
	v_mfma_f32_16x16x32_f16 v[182:185], v[22:25], v[110:113], v[10:13]
	v_mfma_f32_16x16x32_f16 v[10:13], v[26:29], v[106:109], 0
	v_mfma_f32_16x16x32_f16 v[110:113], v[30:33], v[110:113], v[10:13]
	v_mfma_f32_16x16x32_f16 v[10:13], v[18:21], v[114:117], 0
	v_mfma_f32_16x16x32_f16 v[186:189], v[22:25], v[118:121], v[10:13]
	v_mfma_f32_16x16x32_f16 v[10:13], v[26:29], v[114:117], 0
	v_mfma_f32_16x16x32_f16 v[190:193], v[30:33], v[118:121], v[10:13]
	v_mfma_f32_16x16x32_f16 v[10:13], v[18:21], v[122:125], 0
	v_mfma_f32_16x16x32_f16 v[194:197], v[22:25], v[126:129], v[10:13]
	v_mfma_f32_16x16x32_f16 v[10:13], v[26:29], v[122:125], 0
	v_mfma_f32_16x16x32_f16 v[122:125], v[30:33], v[126:129], v[10:13]
	s_barrier
; #define PG8_STAGE(bufoff, gbase, voff) do { if constexpr (ABL & 1) break; glds16s<(bufoff)>((voff)[0], (const void*)(gbase), ldsbw); glds16s<(bufoff) + 8192>((voff)[1], (const void*)(gbase), ldsbw); } while (0)
; #define PG8_LDA(dst, b, h) do { if constexpr (ABL & 4) break; _Pragma("unroll") for (int m = 0; m < 4; ++m) _Pragma("unroll") for (int k = 0; k < 2; ++k) dst[m][k] = *(const LAS f16x8*)(lds + PG8_SA(b, h) + aoff + m * 2048 + k * 1024); } while (0)
; #define PG8_LDB(dst, b, h) do { if constexpr (ABL & 4) break; _Pragma("unroll") for (int n = 0; n < 2; ++n) _Pragma("unroll") for (int k = 0; k < 2; ++k) dst[n][k] = *(const LAS f16x8*)(lds + PG8_SB(b, h) + boff + n * 2048 + k * 1024); } while (0)
; #define PG8_MMA(ai, bj, At, Bt) do { if constexpr (ABL & 2) break; __builtin_amdgcn_s_setprio(1); _Pragma("unroll") for (int m = 0; m < 4; ++m) _Pragma("unroll") for (int n = 0; n < 2; ++n) _Pragma("unroll") for (int k = 0; k < 2; ++k) \
;         acc[ai][bj][m][n] = __builtin_amdgcn_mfma_f32_16x16x32_f16(Bt[n][k], At[m][k], acc[ai][bj][m][n], 0, 0, 0); __builtin_amdgcn_s_setprio(0); } while (0)
; #define PG8_MMAF(ai, bj, At, Bt) do { if (t == 0) PG8_MMA0(ai, bj, At, Bt); else PG8_MMA(ai, bj, At, Bt); } while (0)
; #define PG8_WAIT_V(n) asm volatile("s_waitcnt vmcnt(" #n ")" ::: "memory")
; #define PG8_WAIT_L(n) asm volatile("s_waitcnt lgkmcnt(" #n ")" ::: "memory")
; #define PG8_BAR __builtin_amdgcn_s_barrier()
; #define PG8_SCHED __builtin_amdgcn_sched_barrier(0)
;     ...
;             if (!fin) PG8_WAIT_V(8); else PG8_WAIT_V(2); PG8_WAIT_L(0); PG8_BAR; PG8_MMAF(1, 0, At, B0); PG8_MMAF(1, 1, At, B1); PG8_BAR; PG8_SCHED;
;             PG8_LDB(B0, 1, 0); PG8_LDB(B1, 1, 1); PG8_SCHED; PG8_LDA(At, 1, 0); if (!fin) PG8_STAGE(PG8_SA(0, 1), a2 + hstep, voffA);
;             if (!fin) PG8_WAIT_V(8); else PG8_WAIT_V(0); PG8_WAIT_L(0); PG8_BAR; PG8_MMA(0, 0, At, B0); PG8_MMA(0, 1, At, B1); PG8_BAR; PG8_SCHED;
;             PG8_LDA(At, 1, 1); if (!fin) { PG8_STAGE(PG8_SB(1, 0), b3, voffB); PG8_STAGE(PG8_SB(1, 1), b3 + hstep, voffB); PG8_STAGE(PG8_SA(1, 0), a3, voffA); }
;             if (!fin) PG8_WAIT_V(8); PG8_WAIT_L(0); PG8_BAR; PG8_MMA(1, 0, At, B0); PG8_MMA(1, 1, At, B1); PG8_BAR; PG8_SCHED;
	s_setprio 0
	s_nop 4
	ds_read_b128 v[10:13], v225
	ds_read_b128 v[14:17], v225 offset:1024
	ds_read_b128 v[18:21], v225 offset:2048
	ds_read_b128 v[22:25], v225 offset:3072
	ds_read_b128 v[198:201], v226
	ds_read_b128 v[214:217], v226 offset:1024
	ds_read_b128 v[228:231], v226 offset:2048
	ds_read_b128 v[232:235], v226 offset:3072
	ds_read_b128 v[26:29], v224 offset:32768
	ds_read_b128 v[30:33], v224 offset:33792
	ds_read_b128 v[62:65], v224 offset:34816
	ds_read_b128 v[114:117], v224 offset:35840
	ds_read_b128 v[236:239], v224 offset:36864
	ds_read_b128 v[240:243], v224 offset:37888
	ds_read_b128 v[244:247], v224 offset:38912
	ds_read_b128 v[248:251], v224 offset:39936
	s_add_u32 s26, s30, 0x40100
	s_addc_u32 s27, s31, 0
	s_add_u32 m0, s14, 0x4000
	s_nop 0
	global_load_lds_dwordx4 v1, s[26:27]
	s_nop 0
	s_add_u32 m0, s14, 0x6000
	s_nop 0
	global_load_lds_dwordx4 v213, s[26:27]
	s_waitcnt vmcnt(8)
	s_waitcnt lgkmcnt(0)
	s_barrier
	v_mfma_f32_16x16x32_f16 v[66:69], v[10:13], v[26:29], v[66:69]
	s_setprio 1
	s_waitcnt lgkmcnt(6)
	v_mfma_f32_16x16x32_f16 v[154:157], v[14:17], v[30:33], v[66:69]
	v_mfma_f32_16x16x32_f16 v[66:69], v[18:21], v[26:29], v[70:73]
	v_mfma_f32_16x16x32_f16 v[150:153], v[22:25], v[30:33], v[66:69]
	s_waitcnt lgkmcnt(5)
	v_mfma_f32_16x16x32_f16 v[66:69], v[10:13], v[62:65], v[74:77]
	s_waitcnt lgkmcnt(4)
	v_mfma_f32_16x16x32_f16 v[130:133], v[14:17], v[114:117], v[66:69]
	v_mfma_f32_16x16x32_f16 v[66:69], v[18:21], v[62:65], v[78:81]
	v_mfma_f32_16x16x32_f16 v[126:129], v[22:25], v[114:117], v[66:69]
	s_waitcnt lgkmcnt(3)
	v_mfma_f32_16x16x32_f16 v[66:69], v[10:13], v[236:239], v[82:85]
	s_waitcnt lgkmcnt(2)
	v_mfma_f32_16x16x32_f16 v[106:109], v[14:17], v[240:243], v[66:69]
	v_mfma_f32_16x16x32_f16 v[66:69], v[18:21], v[236:239], v[86:89]
	v_mfma_f32_16x16x32_f16 v[102:105], v[22:25], v[240:243], v[66:69]
	s_waitcnt lgkmcnt(1)
	v_mfma_f32_16x16x32_f16 v[66:69], v[10:13], v[244:247], v[90:93]
	s_waitcnt lgkmcnt(0)
	v_mfma_f32_16x16x32_f16 v[82:85], v[14:17], v[248:251], v[66:69]
	v_mfma_f32_16x16x32_f16 v[66:69], v[18:21], v[244:247], v[94:97]
	v_mfma_f32_16x16x32_f16 v[78:81], v[22:25], v[248:251], v[66:69]
	v_mfma_f32_16x16x32_f16 v[66:69], v[198:201], v[26:29], v[98:101]
	v_mfma_f32_16x16x32_f16 v[26:29], v[228:231], v[26:29], v[34:37]
	v_mfma_f32_16x16x32_f16 v[138:141], v[232:235], v[30:33], v[26:29]
	v_mfma_f32_16x16x32_f16 v[26:29], v[198:201], v[62:65], v[38:41]
	v_mfma_f32_16x16x32_f16 v[118:121], v[214:217], v[114:117], v[26:29]
	v_mfma_f32_16x16x32_f16 v[26:29], v[228:231], v[62:65], v[42:45]
	v_mfma_f32_16x16x32_f16 v[114:117], v[232:235], v[114:117], v[26:29]
	v_mfma_f32_16x16x32_f16 v[26:29], v[198:201], v[236:239], v[46:49]
	v_mfma_f32_16x16x32_f16 v[94:97], v[214:217], v[240:243], v[26:29]
	v_mfma_f32_16x16x32_f16 v[26:29], v[228:231], v[236:239], v[50:53]
	v_mfma_f32_16x16x32_f16 v[90:93], v[232:235], v[240:243], v[26:29]
	v_mfma_f32_16x16x32_f16 v[26:29], v[198:201], v[244:247], v[54:57]
	v_mfma_f32_16x16x32_f16 v[70:73], v[214:217], v[248:251], v[26:29]
	v_mfma_f32_16x16x32_f16 v[26:29], v[228:231], v[244:247], v[58:61]
	v_mfma_f32_16x16x32_f16 v[142:145], v[214:217], v[30:33], v[66:69]
	v_mfma_f32_16x16x32_f16 v[66:69], v[232:235], v[248:251], v[26:29]
	s_barrier
	s_setprio 0
	ds_read_b128 v[34:37], v224 offset:49152
	ds_read_b128 v[38:41], v224 offset:50176
	ds_read_b128 v[74:77], v224 offset:51200
	ds_read_b128 v[86:89], v224 offset:52224
	ds_read_b128 v[98:101], v224 offset:53248
	ds_read_b128 v[236:239], v224 offset:54272
	ds_read_b128 v[240:243], v224 offset:55296
	ds_read_b128 v[244:247], v224 offset:56320
	s_add_u32 m0, s14, 0x18000
	s_nop 0
	global_load_lds_dwordx4 v209, s[24:25]
	s_nop 0
	s_add_u32 m0, s14, 0x1a000
	s_nop 0
	global_load_lds_dwordx4 v219, s[24:25]
	s_add_u32 s24, s6, 0x40180
	s_addc_u32 s25, s7, 0
	s_add_u32 m0, s14, 0x1c000
	s_nop 0
	global_load_lds_dwordx4 v209, s[24:25]
	s_nop 0
	s_add_u32 m0, s14, 0x1e000
	s_nop 0
	global_load_lds_dwordx4 v219, s[24:25]
	s_nop 0
	s_add_u32 m0, s14, 0x8000
	s_nop 0
	global_load_lds_dwordx4 v1, s[8:9]
	s_nop 0
	s_add_u32 m0, s14, 0xa000
	s_nop 0
	global_load_lds_dwordx4 v213, s[8:9]
	s_waitcnt vmcnt(8)
	s_waitcnt lgkmcnt(0)
	s_barrier
	v_mfma_f32_16x16x32_f16 v[26:29], v[10:13], v[34:37], v[134:137]
	s_setprio 1
	s_waitcnt lgkmcnt(6)
	v_mfma_f32_16x16x32_f16 v[62:65], v[14:17], v[38:41], v[26:29]
	v_mfma_f32_16x16x32_f16 v[26:29], v[18:21], v[34:37], v[146:149]
	v_mfma_f32_16x16x32_f16 v[58:61], v[22:25], v[38:41], v[26:29]
	s_waitcnt lgkmcnt(5)
	v_mfma_f32_16x16x32_f16 v[26:29], v[10:13], v[74:77], v[158:161]
	s_waitcnt lgkmcnt(4)
	v_mfma_f32_16x16x32_f16 v[46:49], v[14:17], v[86:89], v[26:29]
	v_mfma_f32_16x16x32_f16 v[26:29], v[18:21], v[74:77], v[162:165]
	v_mfma_f32_16x16x32_f16 v[42:45], v[22:25], v[86:89], v[26:29]
	s_waitcnt lgkmcnt(3)
	v_mfma_f32_16x16x32_f16 v[26:29], v[10:13], v[98:101], v[166:169]
	s_waitcnt lgkmcnt(1)
	v_mfma_f32_16x16x32_f16 v[2:5], v[10:13], v[240:243], v[2:5]
	v_mfma_f32_16x16x32_f16 v[30:33], v[14:17], v[236:239], v[26:29]
	v_mfma_f32_16x16x32_f16 v[26:29], v[18:21], v[98:101], v[170:173]
	s_waitcnt lgkmcnt(0)
	v_mfma_f32_16x16x32_f16 v[14:17], v[14:17], v[244:247], v[2:5]
	v_mfma_f32_16x16x32_f16 v[2:5], v[18:21], v[240:243], v[6:9]
	v_mfma_f32_16x16x32_f16 v[26:29], v[22:25], v[236:239], v[26:29]
	v_mfma_f32_16x16x32_f16 v[10:13], v[22:25], v[244:247], v[2:5]
	v_mfma_f32_16x16x32_f16 v[2:5], v[198:201], v[34:37], v[174:177]
	v_mfma_f32_16x16x32_f16 v[54:57], v[214:217], v[38:41], v[2:5]
	v_mfma_f32_16x16x32_f16 v[2:5], v[228:231], v[34:37], v[178:181]
	v_mfma_f32_16x16x32_f16 v[50:53], v[232:235], v[38:41], v[2:5]
	v_mfma_f32_16x16x32_f16 v[2:5], v[198:201], v[74:77], v[182:185]
	v_mfma_f32_16x16x32_f16 v[38:41], v[214:217], v[86:89], v[2:5]
	v_mfma_f32_16x16x32_f16 v[2:5], v[228:231], v[74:77], v[110:113]
	v_mfma_f32_16x16x32_f16 v[34:37], v[232:235], v[86:89], v[2:5]
	v_mfma_f32_16x16x32_f16 v[2:5], v[198:201], v[98:101], v[186:189]
	v_mfma_f32_16x16x32_f16 v[22:25], v[214:217], v[236:239], v[2:5]
	v_mfma_f32_16x16x32_f16 v[2:5], v[228:231], v[98:101], v[190:193]
	v_mfma_f32_16x16x32_f16 v[18:21], v[232:235], v[236:239], v[2:5]
	v_mfma_f32_16x16x32_f16 v[2:5], v[198:201], v[240:243], v[194:197]
	v_mfma_f32_16x16x32_f16 v[6:9], v[214:217], v[244:247], v[2:5]
	v_mfma_f32_16x16x32_f16 v[2:5], v[228:231], v[240:243], v[122:125]
	v_mfma_f32_16x16x32_f16 v[2:5], v[232:235], v[244:247], v[2:5]
	s_barrier
	s_setprio 0
	s_add_u32 s30, s6, 0x200
	s_addc_u32 s31, s7, 0
	s_mov_b32 s59, 0
	s_branch .LBB0_750
; #define PG8_STAGE(bufoff, gbase, voff) do { if constexpr (ABL & 1) break; glds16s<(bufoff)>((voff)[0], (const void*)(gbase), ldsbw); glds16s<(bufoff) + 8192>((voff)[1], (const void*)(gbase), ldsbw); } while (0)
; #define PG8_LDA(dst, b, h) do { if constexpr (ABL & 4) break; _Pragma("unroll") for (int m = 0; m < 4; ++m) _Pragma("unroll") for (int k = 0; k < 2; ++k) dst[m][k] = *(const LAS f16x8*)(lds + PG8_SA(b, h) + aoff + m * 2048 + k * 1024); } while (0)
; #define PG8_LDB(dst, b, h) do { if constexpr (ABL & 4) break; _Pragma("unroll") for (int n = 0; n < 2; ++n) _Pragma("unroll") for (int k = 0; k < 2; ++k) dst[n][k] = *(const LAS f16x8*)(lds + PG8_SB(b, h) + boff + n * 2048 + k * 1024); } while (0)
; #define PG8_WAIT_V(n) asm volatile("s_waitcnt vmcnt(" #n ")" ::: "memory")
;     ...
;             const bool last = (t == nt - 2);
;             const char* a1 = cA + (size_t)(t + 1) * kstep;
;             const char* a2 = last ? nA : cA + (size_t)(t + 2) * kstep; const char* b2 = last ? nB : cB + (size_t)(t + 2) * kstep;
;             const char* a3 = a2 + kstep; const char* b3 = b2 + kstep;
;             if (last && has_next) S.a_ready(nxt);
;             if constexpr (SP2) {
;             PG8_LDB(B0, 0, 0); PG8_LDB(B1, 0, 1); PG8_SCHED; PG8_LDA(At, 0, 0); PG8_STAGE(PG8_SA(1, 1), a1 + hstep, voffA);
;             PG8_WAIT_V(8); PG8_WAIT_L(0); PG8_BAR; PG8_MMAF(0, 0, At, B0); PG8_MMAF(0, 1, At, B1); PG8_BAR; PG8_SCHED;
;             const bool fin = last && !has_next;
;             PG8_LDA(At, 0, 1); if (!fin) { PG8_STAGE(PG8_SB(0, 0), b2, voffB); PG8_STAGE(PG8_SB(0, 1), b2 + hstep, voffB); PG8_STAGE(PG8_SA(0, 0), a2, voffA); }
;             if (!fin) PG8_WAIT_V(8); else PG8_WAIT_V(2); PG8_WAIT_L(0); PG8_BAR; PG8_MMAF(1, 0, At, B0); PG8_MMAF(1, 1, At, B1); PG8_BAR; PG8_SCHED;
;             PG8_LDB(B0, 1, 0); PG8_LDB(B1, 1, 1); PG8_SCHED; PG8_LDA(At, 1, 0); if (!fin) PG8_STAGE(PG8_SA(0, 1), a2 + hstep, voffA);
;             if (!fin) PG8_WAIT_V(8); else PG8_WAIT_V(0); PG8_WAIT_L(0); PG8_BAR; PG8_MMA(0, 0, At, B0); PG8_MMA(0, 1, At, B1); PG8_BAR; PG8_SCHED;
;             PG8_LDA(At, 1, 1); if (!fin) { PG8_STAGE(PG8_SB(1, 0), b3, voffB); PG8_STAGE(PG8_SB(1, 1), b3 + hstep, voffB); PG8_STAGE(PG8_SA(1, 0), a3, voffA); }
;             if (!fin) PG8_WAIT_V(8); PG8_WAIT_L(0); PG8_BAR; PG8_MMA(1, 0, At, B0); PG8_MMA(1, 1, At, B1); PG8_BAR; PG8_SCHED;
.LBB0_749:
	s_waitcnt lgkmcnt(0)
	s_barrier
	v_mfma_f32_16x16x32_f16 v[62:65], v[162:165], v[186:189], v[62:65]
	s_setprio 1
	v_mfma_f32_16x16x32_f16 v[58:61], v[146:149], v[186:189], v[58:61]
	s_waitcnt lgkmcnt(5)
	v_mfma_f32_16x16x32_f16 v[46:49], v[162:165], v[178:181], v[46:49]
	v_mfma_f32_16x16x32_f16 v[42:45], v[146:149], v[178:181], v[42:45]
	s_waitcnt lgkmcnt(3)
	v_mfma_f32_16x16x32_f16 v[30:33], v[162:165], v[170:173], v[30:33]
	v_mfma_f32_16x16x32_f16 v[26:29], v[146:149], v[170:173], v[26:29]
	s_waitcnt lgkmcnt(1)
	v_mfma_f32_16x16x32_f16 v[14:17], v[162:165], v[122:125], v[14:17]
	v_mfma_f32_16x16x32_f16 v[10:13], v[146:149], v[122:125], v[10:13]
	v_mfma_f32_16x16x32_f16 v[62:65], v[166:169], v[190:193], v[62:65]
	v_mfma_f32_16x16x32_f16 v[58:61], v[158:161], v[190:193], v[58:61]
	v_mfma_f32_16x16x32_f16 v[46:49], v[166:169], v[182:185], v[46:49]
	v_mfma_f32_16x16x32_f16 v[42:45], v[158:161], v[182:185], v[42:45]
	v_mfma_f32_16x16x32_f16 v[30:33], v[166:169], v[174:177], v[30:33]
	v_mfma_f32_16x16x32_f16 v[26:29], v[158:161], v[174:177], v[26:29]
	s_waitcnt lgkmcnt(0)
	v_mfma_f32_16x16x32_f16 v[14:17], v[166:169], v[134:137], v[14:17]
	v_mfma_f32_16x16x32_f16 v[10:13], v[158:161], v[134:137], v[10:13]
	v_mfma_f32_16x16x32_f16 v[54:57], v[98:101], v[186:189], v[54:57]
	v_mfma_f32_16x16x32_f16 v[50:53], v[74:77], v[186:189], v[50:53]
	v_mfma_f32_16x16x32_f16 v[38:41], v[98:101], v[178:181], v[38:41]
	v_mfma_f32_16x16x32_f16 v[34:37], v[74:77], v[178:181], v[34:37]
	v_mfma_f32_16x16x32_f16 v[22:25], v[98:101], v[170:173], v[22:25]
	v_mfma_f32_16x16x32_f16 v[18:21], v[74:77], v[170:173], v[18:21]
	v_mfma_f32_16x16x32_f16 v[6:9], v[98:101], v[122:125], v[6:9]
	v_mfma_f32_16x16x32_f16 v[2:5], v[74:77], v[122:125], v[2:5]
	v_mfma_f32_16x16x32_f16 v[54:57], v[110:113], v[190:193], v[54:57]
	v_mfma_f32_16x16x32_f16 v[50:53], v[86:89], v[190:193], v[50:53]
	v_mfma_f32_16x16x32_f16 v[38:41], v[110:113], v[182:185], v[38:41]
	v_mfma_f32_16x16x32_f16 v[34:37], v[86:89], v[182:185], v[34:37]
	v_mfma_f32_16x16x32_f16 v[22:25], v[110:113], v[174:177], v[22:25]
	v_mfma_f32_16x16x32_f16 v[18:21], v[86:89], v[174:177], v[18:21]
	v_mfma_f32_16x16x32_f16 v[6:9], v[110:113], v[134:137], v[6:9]
	v_mfma_f32_16x16x32_f16 v[2:5], v[86:89], v[134:137], v[2:5]
	s_barrier
	s_setprio 0
	s_add_i32 s59, s59, 2
	s_add_u32 s30, s30, 0x100
	s_addc_u32 s31, s31, 0
	s_cmp_gt_u32 s59, 13
	s_cbranch_scc1 .LBB0_760
.LBB0_750:
	ds_read_b128 v[146:149], v222
	ds_read_b128 v[158:161], v222 offset:1024
	ds_read_b128 v[162:165], v222 offset:2048
	ds_read_b128 v[166:169], v222 offset:3072
	ds_read_b128 v[74:77], v223
	ds_read_b128 v[86:89], v223 offset:1024
	ds_read_b128 v[98:101], v223 offset:2048
	ds_read_b128 v[110:113], v223 offset:3072
	s_mov_b64 s[6:7], s[56:57]
	s_add_u32 s56, s6, 0x100
	s_addc_u32 s57, s7, 0
	s_cmp_eq_u32 s59, 12
	s_cselect_b64 s[26:27], -1, 0
	s_and_b64 s[8:9], s[26:27], exec
	s_cselect_b32 s25, s47, s57
	s_cselect_b32 s24, s55, s56
	s_cselect_b32 s9, s45, s31
	s_cselect_b32 s8, s58, s30
	ds_read_b128 v[170:173], v224
	ds_read_b128 v[174:177], v224 offset:1024
	ds_read_b128 v[178:181], v224 offset:2048
	ds_read_b128 v[182:185], v224 offset:3072
	ds_read_b128 v[186:189], v224 offset:4096
	ds_read_b128 v[190:193], v224 offset:5120
	ds_read_b128 v[194:197], v224 offset:6144
	ds_read_b128 v[198:201], v224 offset:7168
	s_add_u32 s6, s6, 0x40080
	s_addc_u32 s7, s7, 0
	s_add_u32 m0, s14, 0xc000
	s_nop 0
	global_load_lds_dwordx4 v1, s[6:7]
	s_nop 0
	s_add_u32 m0, s14, 0xe000
	s_nop 0
	global_load_lds_dwordx4 v213, s[6:7]
	s_waitcnt vmcnt(8)
	s_waitcnt lgkmcnt(0)
	s_barrier
	v_mfma_f32_16x16x32_f16 v[122:125], v[146:149], v[170:173], v[154:157]
	s_setprio 1
	v_mfma_f32_16x16x32_f16 v[134:137], v[162:165], v[170:173], v[150:153]
	s_waitcnt lgkmcnt(5)
	v_mfma_f32_16x16x32_f16 v[130:133], v[146:149], v[178:181], v[130:133]
	v_mfma_f32_16x16x32_f16 v[126:129], v[162:165], v[178:181], v[126:129]
	s_waitcnt lgkmcnt(3)
	v_mfma_f32_16x16x32_f16 v[106:109], v[146:149], v[186:189], v[106:109]
	v_mfma_f32_16x16x32_f16 v[102:105], v[162:165], v[186:189], v[102:105]
	s_waitcnt lgkmcnt(1)
	v_mfma_f32_16x16x32_f16 v[82:85], v[146:149], v[194:197], v[82:85]
	v_mfma_f32_16x16x32_f16 v[78:81], v[162:165], v[194:197], v[78:81]
	v_mfma_f32_16x16x32_f16 v[122:125], v[158:161], v[174:177], v[122:125]
	v_mfma_f32_16x16x32_f16 v[134:137], v[166:169], v[174:177], v[134:137]
	v_mfma_f32_16x16x32_f16 v[130:133], v[158:161], v[182:185], v[130:133]
	v_mfma_f32_16x16x32_f16 v[126:129], v[166:169], v[182:185], v[126:129]
	v_mfma_f32_16x16x32_f16 v[106:109], v[158:161], v[190:193], v[106:109]
	v_mfma_f32_16x16x32_f16 v[102:105], v[166:169], v[190:193], v[102:105]
	s_waitcnt lgkmcnt(0)
	v_mfma_f32_16x16x32_f16 v[82:85], v[158:161], v[198:201], v[82:85]
	v_mfma_f32_16x16x32_f16 v[78:81], v[166:169], v[198:201], v[78:81]
	v_mfma_f32_16x16x32_f16 v[142:145], v[74:77], v[170:173], v[142:145]
	v_mfma_f32_16x16x32_f16 v[138:141], v[98:101], v[170:173], v[138:141]
	v_mfma_f32_16x16x32_f16 v[118:121], v[74:77], v[178:181], v[118:121]
	v_mfma_f32_16x16x32_f16 v[114:117], v[98:101], v[178:181], v[114:117]
	v_mfma_f32_16x16x32_f16 v[94:97], v[74:77], v[186:189], v[94:97]
	v_mfma_f32_16x16x32_f16 v[90:93], v[98:101], v[186:189], v[90:93]
	v_mfma_f32_16x16x32_f16 v[70:73], v[74:77], v[194:197], v[70:73]
	v_mfma_f32_16x16x32_f16 v[66:69], v[98:101], v[194:197], v[66:69]
	v_mfma_f32_16x16x32_f16 v[142:145], v[86:89], v[174:177], v[142:145]
	v_mfma_f32_16x16x32_f16 v[138:141], v[110:113], v[174:177], v[138:141]
	v_mfma_f32_16x16x32_f16 v[118:121], v[86:89], v[182:185], v[118:121]
	v_mfma_f32_16x16x32_f16 v[114:117], v[110:113], v[182:185], v[114:117]
	v_mfma_f32_16x16x32_f16 v[94:97], v[86:89], v[190:193], v[94:97]
	v_mfma_f32_16x16x32_f16 v[90:93], v[110:113], v[190:193], v[90:93]
	v_mfma_f32_16x16x32_f16 v[70:73], v[86:89], v[198:201], v[70:73]
	v_mfma_f32_16x16x32_f16 v[66:69], v[110:113], v[198:201], v[66:69]
	s_barrier
	s_setprio 0
	ds_read_b128 v[186:189], v224 offset:16384
	ds_read_b128 v[190:193], v224 offset:17408
	ds_read_b128 v[178:181], v224 offset:18432
	ds_read_b128 v[182:185], v224 offset:19456
	ds_read_b128 v[170:173], v224 offset:20480
	ds_read_b128 v[174:177], v224 offset:21504
	ds_read_b128 v[150:153], v224 offset:22528
	ds_read_b128 v[154:157], v224 offset:23552
	s_and_b64 s[6:7], s[4:5], s[26:27]
	s_mov_b64 s[26:27], -1
	s_and_b64 vcc, exec, s[6:7]
	s_cbranch_vccnz .LBB0_752
	s_add_u32 m0, s14, 0x10000
	s_nop 0
	global_load_lds_dwordx4 v209, s[8:9]
	s_nop 0
	s_add_u32 m0, s14, 0x12000
	s_nop 0
	global_load_lds_dwordx4 v219, s[8:9]
	s_add_u32 s26, s8, 0x40000
	s_addc_u32 s27, s9, 0
	s_add_u32 m0, s14, 0x14000
	s_nop 0
	global_load_lds_dwordx4 v209, s[26:27]
	s_nop 0
	s_add_u32 m0, s14, 0x16000
	s_nop 0
	global_load_lds_dwordx4 v219, s[26:27]
	s_mov_b64 s[26:27], 0
	s_add_u32 m0, s14, 0
	s_nop 0
	global_load_lds_dwordx4 v1, s[24:25]
	s_nop 0
	s_add_u32 m0, s14, 0x2000
	s_nop 0
	global_load_lds_dwordx4 v213, s[24:25]
	s_waitcnt vmcnt(8)

; #define PG8_STAGE(bufoff, gbase, voff) do { if constexpr (ABL & 1) break; glds16s<(bufoff)>((voff)[0], (const void*)(gbase), ldsbw); glds16s<(bufoff) + 8192>((voff)[1], (const void*)(gbase), ldsbw); } while (0)
; #define PG8_LDA(dst, b, h) do { if constexpr (ABL & 4) break; _Pragma("unroll") for (int m = 0; m < 4; ++m) _Pragma("unroll") for (int k = 0; k < 2; ++k) dst[m][k] = *(const LAS f16x8*)(lds + PG8_SA(b, h) + aoff + m * 2048 + k * 1024); } while (0)
; #define PG8_LDB(dst, b, h) do { if constexpr (ABL & 4) break; _Pragma("unroll") for (int n = 0; n < 2; ++n) _Pragma("unroll") for (int k = 0; k < 2; ++k) dst[n][k] = *(const LAS f16x8*)(lds + PG8_SB(b, h) + boff + n * 2048 + k * 1024); } while (0)
; #define PG8_MMA(ai, bj, At, Bt) do { if constexpr (ABL & 2) break; __builtin_amdgcn_s_setprio(1); _Pragma("unroll") for (int m = 0; m < 4; ++m) _Pragma("unroll") for (int n = 0; n < 2; ++n) _Pragma("unroll") for (int k = 0; k < 2; ++k) \
;         acc[ai][bj][m][n] = __builtin_amdgcn_mfma_f32_16x16x32_f16(Bt[n][k], At[m][k], acc[ai][bj][m][n], 0, 0, 0); __builtin_amdgcn_s_setprio(0); } while (0)
; #define PG8_MMAF(ai, bj, At, Bt) do { if (t == 0) PG8_MMA0(ai, bj, At, Bt); else PG8_MMA(ai, bj, At, Bt); } while (0)
; #define PG8_WAIT_V(n) asm volatile("s_waitcnt vmcnt(" #n ")" ::: "memory")
; #define PG8_WAIT_L(n) asm volatile("s_waitcnt lgkmcnt(" #n ")" ::: "memory")
; #define PG8_BAR __builtin_amdgcn_s_barrier()
; #define PG8_SCHED __builtin_amdgcn_sched_barrier(0)
;     ...
;             if (!fin) PG8_WAIT_V(8); else PG8_WAIT_V(2); PG8_WAIT_L(0); PG8_BAR; PG8_MMAF(1, 0, At, B0); PG8_MMAF(1, 1, At, B1); PG8_BAR; PG8_SCHED;
;             PG8_LDB(B0, 1, 0); PG8_LDB(B1, 1, 1); PG8_SCHED; PG8_LDA(At, 1, 0); if (!fin) PG8_STAGE(PG8_SA(0, 1), a2 + hstep, voffA);
;             if (!fin) PG8_WAIT_V(8); else PG8_WAIT_V(0); PG8_WAIT_L(0); PG8_BAR; PG8_MMA(0, 0, At, B0); PG8_MMA(0, 1, At, B1); PG8_BAR; PG8_SCHED;
.LBB0_754:
	s_waitcnt lgkmcnt(0)
	s_xor_b64 s[26:27], s[6:7], -1
	s_barrier
	v_mfma_f32_16x16x32_f16 v[62:65], v[146:149], v[186:189], v[62:65]
	s_setprio 1
	v_mfma_f32_16x16x32_f16 v[58:61], v[162:165], v[186:189], v[58:61]
	s_waitcnt lgkmcnt(5)
	v_mfma_f32_16x16x32_f16 v[46:49], v[146:149], v[178:181], v[46:49]
	v_mfma_f32_16x16x32_f16 v[42:45], v[162:165], v[178:181], v[42:45]
	s_waitcnt lgkmcnt(3)
	v_mfma_f32_16x16x32_f16 v[30:33], v[146:149], v[170:173], v[30:33]
	v_mfma_f32_16x16x32_f16 v[26:29], v[162:165], v[170:173], v[26:29]
	s_waitcnt lgkmcnt(1)
	v_mfma_f32_16x16x32_f16 v[14:17], v[146:149], v[150:153], v[14:17]
	v_mfma_f32_16x16x32_f16 v[10:13], v[162:165], v[150:153], v[10:13]
	v_mfma_f32_16x16x32_f16 v[62:65], v[158:161], v[190:193], v[62:65]
	v_mfma_f32_16x16x32_f16 v[58:61], v[166:169], v[190:193], v[58:61]
	v_mfma_f32_16x16x32_f16 v[46:49], v[158:161], v[182:185], v[46:49]
	v_mfma_f32_16x16x32_f16 v[42:45], v[166:169], v[182:185], v[42:45]
	v_mfma_f32_16x16x32_f16 v[30:33], v[158:161], v[174:177], v[30:33]
	v_mfma_f32_16x16x32_f16 v[26:29], v[166:169], v[174:177], v[26:29]
	s_waitcnt lgkmcnt(0)
	v_mfma_f32_16x16x32_f16 v[14:17], v[158:161], v[154:157], v[14:17]
	v_mfma_f32_16x16x32_f16 v[10:13], v[166:169], v[154:157], v[10:13]
	v_mfma_f32_16x16x32_f16 v[54:57], v[74:77], v[186:189], v[54:57]
	v_mfma_f32_16x16x32_f16 v[50:53], v[98:101], v[186:189], v[50:53]
	v_mfma_f32_16x16x32_f16 v[38:41], v[74:77], v[178:181], v[38:41]
	v_mfma_f32_16x16x32_f16 v[34:37], v[98:101], v[178:181], v[34:37]
	v_mfma_f32_16x16x32_f16 v[22:25], v[74:77], v[170:173], v[22:25]
	v_mfma_f32_16x16x32_f16 v[18:21], v[98:101], v[170:173], v[18:21]
	v_mfma_f32_16x16x32_f16 v[6:9], v[74:77], v[150:153], v[6:9]
	v_mfma_f32_16x16x32_f16 v[2:5], v[98:101], v[150:153], v[2:5]
	v_mfma_f32_16x16x32_f16 v[54:57], v[86:89], v[190:193], v[54:57]
	v_mfma_f32_16x16x32_f16 v[50:53], v[110:113], v[190:193], v[50:53]
	v_mfma_f32_16x16x32_f16 v[38:41], v[86:89], v[182:185], v[38:41]
	v_mfma_f32_16x16x32_f16 v[34:37], v[110:113], v[182:185], v[34:37]
	v_mfma_f32_16x16x32_f16 v[22:25], v[86:89], v[174:177], v[22:25]
	v_mfma_f32_16x16x32_f16 v[18:21], v[110:113], v[174:177], v[18:21]
	v_mfma_f32_16x16x32_f16 v[6:9], v[86:89], v[154:157], v[6:9]
	v_mfma_f32_16x16x32_f16 v[2:5], v[110:113], v[154:157], v[2:5]
	s_barrier
	s_setprio 0
	ds_read_b128 v[162:165], v225
	ds_read_b128 v[166:169], v225 offset:1024
	ds_read_b128 v[146:149], v225 offset:2048
	ds_read_b128 v[158:161], v225 offset:3072
	ds_read_b128 v[98:101], v226
	ds_read_b128 v[110:113], v226 offset:1024
	ds_read_b128 v[74:77], v226 offset:2048
	ds_read_b128 v[86:89], v226 offset:3072
	ds_read_b128 v[194:197], v224 offset:32768
	ds_read_b128 v[198:201], v224 offset:33792
	ds_read_b128 v[186:189], v224 offset:34816
	ds_read_b128 v[190:193], v224 offset:35840
	ds_read_b128 v[178:181], v224 offset:36864
	ds_read_b128 v[182:185], v224 offset:37888
	ds_read_b128 v[170:173], v224 offset:38912
	ds_read_b128 v[174:177], v224 offset:39936
	v_cndmask_b32_e64 v150, 0, 1, s[26:27]
	v_cmp_ne_u32_e64 s[6:7], 1, v150
	s_andn2_b64 vcc, exec, s[26:27]
	s_mov_b64 s[26:27], -1
	s_cbranch_vccnz .LBB0_756
	s_add_u32 s26, s24, 0x40000
	s_addc_u32 s27, s25, 0
	s_add_u32 m0, s14, 0x4000
	s_nop 0
	global_load_lds_dwordx4 v1, s[26:27]
	s_nop 0
	s_add_u32 m0, s14, 0x6000
	s_nop 0
	global_load_lds_dwordx4 v213, s[26:27]
	s_waitcnt vmcnt(8)
	s_mov_b64 s[26:27], 0

; #define PG8_STAGE(bufoff, gbase, voff) do { if constexpr (ABL & 1) break; glds16s<(bufoff)>((voff)[0], (const void*)(gbase), ldsbw); glds16s<(bufoff) + 8192>((voff)[1], (const void*)(gbase), ldsbw); } while (0)
; #define PG8_LDA(dst, b, h) do { if constexpr (ABL & 4) break; _Pragma("unroll") for (int m = 0; m < 4; ++m) _Pragma("unroll") for (int k = 0; k < 2; ++k) dst[m][k] = *(const LAS f16x8*)(lds + PG8_SA(b, h) + aoff + m * 2048 + k * 1024); } while (0)
; #define PG8_MMA(ai, bj, At, Bt) do { if constexpr (ABL & 2) break; __builtin_amdgcn_s_setprio(1); _Pragma("unroll") for (int m = 0; m < 4; ++m) _Pragma("unroll") for (int n = 0; n < 2; ++n) _Pragma("unroll") for (int k = 0; k < 2; ++k) \
;         acc[ai][bj][m][n] = __builtin_amdgcn_mfma_f32_16x16x32_f16(Bt[n][k], At[m][k], acc[ai][bj][m][n], 0, 0, 0); __builtin_amdgcn_s_setprio(0); } while (0)
; #define PG8_WAIT_V(n) asm volatile("s_waitcnt vmcnt(" #n ")" ::: "memory")
; #define PG8_WAIT_L(n) asm volatile("s_waitcnt lgkmcnt(" #n ")" ::: "memory")
; #define PG8_BAR __builtin_amdgcn_s_barrier()
; #define PG8_SCHED __builtin_amdgcn_sched_barrier(0)
;     ...
;             if (!fin) PG8_WAIT_V(8); else PG8_WAIT_V(0); PG8_WAIT_L(0); PG8_BAR; PG8_MMA(0, 0, At, B0); PG8_MMA(0, 1, At, B1); PG8_BAR; PG8_SCHED;
;             PG8_LDA(At, 1, 1); if (!fin) { PG8_STAGE(PG8_SB(1, 0), b3, voffB); PG8_STAGE(PG8_SB(1, 1), b3 + hstep, voffB); PG8_STAGE(PG8_SA(1, 0), a3, voffA); }
;             if (!fin) PG8_WAIT_V(8); PG8_WAIT_L(0); PG8_BAR; PG8_MMA(1, 0, At, B0); PG8_MMA(1, 1, At, B1); PG8_BAR; PG8_SCHED;
.LBB0_758:
	s_waitcnt lgkmcnt(0)
	s_barrier
	v_mfma_f32_16x16x32_f16 v[122:125], v[162:165], v[194:197], v[122:125]
	s_setprio 1
	s_waitcnt lgkmcnt(6)
	v_mfma_f32_16x16x32_f16 v[154:157], v[166:169], v[198:201], v[122:125]
	v_mfma_f32_16x16x32_f16 v[122:125], v[146:149], v[194:197], v[134:137]
	v_mfma_f32_16x16x32_f16 v[150:153], v[158:161], v[198:201], v[122:125]
	s_waitcnt lgkmcnt(5)
	v_mfma_f32_16x16x32_f16 v[122:125], v[162:165], v[186:189], v[130:133]
	s_waitcnt lgkmcnt(4)
	v_mfma_f32_16x16x32_f16 v[130:133], v[166:169], v[190:193], v[122:125]
	v_mfma_f32_16x16x32_f16 v[122:125], v[146:149], v[186:189], v[126:129]
	s_waitcnt lgkmcnt(3)
	v_mfma_f32_16x16x32_f16 v[106:109], v[162:165], v[178:181], v[106:109]
	v_mfma_f32_16x16x32_f16 v[102:105], v[146:149], v[178:181], v[102:105]
	s_waitcnt lgkmcnt(1)
	v_mfma_f32_16x16x32_f16 v[82:85], v[162:165], v[170:173], v[82:85]
	v_mfma_f32_16x16x32_f16 v[78:81], v[146:149], v[170:173], v[78:81]
	v_mfma_f32_16x16x32_f16 v[126:129], v[158:161], v[190:193], v[122:125]
	v_mfma_f32_16x16x32_f16 v[106:109], v[166:169], v[182:185], v[106:109]
	v_mfma_f32_16x16x32_f16 v[102:105], v[158:161], v[182:185], v[102:105]
	s_waitcnt lgkmcnt(0)
	v_mfma_f32_16x16x32_f16 v[82:85], v[166:169], v[174:177], v[82:85]
	v_mfma_f32_16x16x32_f16 v[78:81], v[158:161], v[174:177], v[78:81]
	v_mfma_f32_16x16x32_f16 v[122:125], v[98:101], v[194:197], v[142:145]
	v_mfma_f32_16x16x32_f16 v[142:145], v[110:113], v[198:201], v[122:125]
	v_mfma_f32_16x16x32_f16 v[122:125], v[74:77], v[194:197], v[138:141]
	v_mfma_f32_16x16x32_f16 v[118:121], v[98:101], v[186:189], v[118:121]
	v_mfma_f32_16x16x32_f16 v[114:117], v[74:77], v[186:189], v[114:117]
	v_mfma_f32_16x16x32_f16 v[94:97], v[98:101], v[178:181], v[94:97]
	v_mfma_f32_16x16x32_f16 v[90:93], v[74:77], v[178:181], v[90:93]
	v_mfma_f32_16x16x32_f16 v[70:73], v[98:101], v[170:173], v[70:73]
	v_mfma_f32_16x16x32_f16 v[66:69], v[74:77], v[170:173], v[66:69]
	v_mfma_f32_16x16x32_f16 v[138:141], v[86:89], v[198:201], v[122:125]
	v_mfma_f32_16x16x32_f16 v[118:121], v[110:113], v[190:193], v[118:121]
	v_mfma_f32_16x16x32_f16 v[114:117], v[86:89], v[190:193], v[114:117]
	v_mfma_f32_16x16x32_f16 v[94:97], v[110:113], v[182:185], v[94:97]
	v_mfma_f32_16x16x32_f16 v[90:93], v[86:89], v[182:185], v[90:93]
	v_mfma_f32_16x16x32_f16 v[70:73], v[110:113], v[174:177], v[70:73]
	v_mfma_f32_16x16x32_f16 v[66:69], v[86:89], v[174:177], v[66:69]
	s_barrier
	s_setprio 0
	ds_read_b128 v[186:189], v224 offset:49152
	ds_read_b128 v[190:193], v224 offset:50176
	ds_read_b128 v[178:181], v224 offset:51200
	ds_read_b128 v[182:185], v224 offset:52224
	ds_read_b128 v[170:173], v224 offset:53248
	ds_read_b128 v[174:177], v224 offset:54272
	ds_read_b128 v[122:125], v224 offset:55296
	ds_read_b128 v[134:137], v224 offset:56320
	s_and_b64 vcc, exec, s[6:7]
	s_cbranch_vccnz .LBB0_749
	s_add_u32 s6, s24, 0x80
	s_addc_u32 s7, s25, 0
	s_add_u32 s24, s8, 0x80
	s_addc_u32 s25, s9, 0
	s_add_u32 m0, s14, 0x18000
	s_nop 0
	global_load_lds_dwordx4 v209, s[24:25]
	s_nop 0
	s_add_u32 m0, s14, 0x1a000
	s_nop 0
	global_load_lds_dwordx4 v219, s[24:25]
	s_add_u32 s8, s8, 0x40080
	s_addc_u32 s9, s9, 0
	s_add_u32 m0, s14, 0x1c000
	s_nop 0
	global_load_lds_dwordx4 v209, s[8:9]
	s_nop 0
	s_add_u32 m0, s14, 0x1e000
	s_nop 0
	global_load_lds_dwordx4 v219, s[8:9]
	s_nop 0
	s_add_u32 m0, s14, 0x8000
	s_nop 0
	global_load_lds_dwordx4 v1, s[6:7]
	s_nop 0
	s_add_u32 m0, s14, 0xa000
	s_nop 0
	global_load_lds_dwordx4 v213, s[6:7]
	s_waitcnt vmcnt(8)
	s_branch .LBB0_749

; #define PG8_STAGE(bufoff, gbase, voff) do { if constexpr (ABL & 1) break; glds16s<(bufoff)>((voff)[0], (const void*)(gbase), ldsbw); glds16s<(bufoff) + 8192>((voff)[1], (const void*)(gbase), ldsbw); } while (0)
; #define PG8_LDA(dst, b, h) do { if constexpr (ABL & 4) break; _Pragma("unroll") for (int m = 0; m < 4; ++m) _Pragma("unroll") for (int k = 0; k < 2; ++k) dst[m][k] = *(const LAS f16x8*)(lds + PG8_SA(b, h) + aoff + m * 2048 + k * 1024); } while (0)
; #define PG8_LDB(dst, b, h) do { if constexpr (ABL & 4) break; _Pragma("unroll") for (int n = 0; n < 2; ++n) _Pragma("unroll") for (int k = 0; k < 2; ++k) dst[n][k] = *(const LAS f16x8*)(lds + PG8_SB(b, h) + boff + n * 2048 + k * 1024); } while (0)
; #define PG8_MMAF(ai, bj, At, Bt) do { if (t == 0) PG8_MMA0(ai, bj, At, Bt); else PG8_MMA(ai, bj, At, Bt); } while (0)
; #define PG8_WAIT_V(n) asm volatile("s_waitcnt vmcnt(" #n ")" ::: "memory")
; #define PG8_WAIT_L(n) asm volatile("s_waitcnt lgkmcnt(" #n ")" ::: "memory")
; #define PG8_BAR __builtin_amdgcn_s_barrier()
; #define PG8_SCHED __builtin_amdgcn_sched_barrier(0)
;     ...
;         const char* nA = has_next ? (const char*)g.A + (size_t)nxt.pm * tstep : cA; const char* nB = has_next ? (const char*)g.Bt + (size_t)nxt.pn * tstep : cB;
;         for (int t = 0; t < nt; t += 2) {
;             const bool last = (t == nt - 2);
;             const char* a1 = cA + (size_t)(t + 1) * kstep;
;             const char* a2 = last ? nA : cA + (size_t)(t + 2) * kstep; const char* b2 = last ? nB : cB + (size_t)(t + 2) * kstep;
;             const char* a3 = a2 + kstep; const char* b3 = b2 + kstep;
;             if (last && has_next) S.a_ready(nxt);
;             if constexpr (SP2) {
;             PG8_LDB(B0, 0, 0); PG8_LDB(B1, 0, 1); PG8_SCHED; PG8_LDA(At, 0, 0); PG8_STAGE(PG8_SA(1, 1), a1 + hstep, voffA);
;             PG8_WAIT_V(8); PG8_WAIT_L(0); PG8_BAR; PG8_MMAF(0, 0, At, B0); PG8_MMAF(0, 1, At, B1); PG8_BAR; PG8_SCHED;
;             const bool fin = last && !has_next;
;             PG8_LDA(At, 0, 1); if (!fin) { PG8_STAGE(PG8_SB(0, 0), b2, voffB); PG8_STAGE(PG8_SB(0, 1), b2 + hstep, voffB); PG8_STAGE(PG8_SA(0, 0), a2, voffA); }
;             if (!fin) PG8_WAIT_V(8); else PG8_WAIT_V(2); PG8_WAIT_L(0); PG8_BAR; PG8_MMAF(1, 0, At, B0); PG8_MMAF(1, 1, At, B1); PG8_BAR; PG8_SCHED;
.LBB0_841:
	s_ashr_i32 s41, s40, 31
	s_lshl_b64 s[24:25], s[40:41], 19
	s_add_u32 s42, s74, s24
	s_addc_u32 s43, s75, s25
	s_and_b64 s[24:25], exec, s[4:5]
	ds_read_b128 v[2:5], v210
	ds_read_b128 v[6:9], v210 offset:1024
	ds_read_b128 v[10:13], v210 offset:2048
	ds_read_b128 v[14:17], v210 offset:3072
	ds_read_b128 v[18:21], v211
	ds_read_b128 v[22:25], v211 offset:1024
	ds_read_b128 v[26:29], v211 offset:2048
	ds_read_b128 v[30:33], v211 offset:3072
	s_cselect_b32 s41, s9, s43
	s_cselect_b32 s51, s8, s42
	s_ashr_i32 s39, s38, 31
	s_lshl_b64 s[24:25], s[38:39], 19
	s_add_u32 s44, s58, s24
	s_addc_u32 s45, s59, s25
	s_and_b64 s[24:25], exec, s[4:5]
	s_cselect_b32 s39, s7, s45
	s_cselect_b32 s52, s6, s44
	s_add_u32 s48, s8, 0x100
	s_addc_u32 s49, s9, 0
	s_add_u32 s54, s6, 0x100
	s_addc_u32 s55, s7, 0
	s_add_u32 s24, s8, 0x180
	s_addc_u32 s25, s9, 0
	ds_read_b128 v[34:37], v212
	ds_read_b128 v[38:41], v212 offset:1024
	ds_read_b128 v[42:45], v212 offset:2048
	ds_read_b128 v[46:49], v212 offset:3072
	ds_read_b128 v[50:53], v212 offset:4096
	ds_read_b128 v[54:57], v212 offset:5120
	ds_read_b128 v[58:61], v212 offset:6144
	ds_read_b128 v[62:65], v212 offset:7168
	s_add_u32 s26, s6, 0x180
	s_addc_u32 s27, s7, 0
	s_add_u32 s56, s8, 0x40080
	s_addc_u32 s57, s9, 0
	s_add_u32 m0, s14, 0xc000
	s_nop 0
	global_load_lds_dwordx4 v206, s[56:57]
	s_nop 0
	s_add_u32 m0, s14, 0xe000
	s_nop 0
	global_load_lds_dwordx4 v208, s[56:57]
	s_waitcnt vmcnt(8)
	s_waitcnt lgkmcnt(0)
	s_barrier
	v_mfma_f32_16x16x32_f16 v[90:93], v[2:5], v[58:61], 0
	s_setprio 1
	v_mfma_f32_16x16x32_f16 v[66:69], v[2:5], v[34:37], 0
	v_mfma_f32_16x16x32_f16 v[70:73], v[10:13], v[34:37], 0
	v_mfma_f32_16x16x32_f16 v[74:77], v[2:5], v[42:45], 0
	v_mfma_f32_16x16x32_f16 v[78:81], v[10:13], v[42:45], 0
	v_mfma_f32_16x16x32_f16 v[82:85], v[2:5], v[50:53], 0
	v_mfma_f32_16x16x32_f16 v[86:89], v[10:13], v[50:53], 0
	s_waitcnt lgkmcnt(0)
	v_mfma_f32_16x16x32_f16 v[94:97], v[6:9], v[62:65], v[90:93]
	v_mfma_f32_16x16x32_f16 v[90:93], v[10:13], v[58:61], 0
	v_mfma_f32_16x16x32_f16 v[66:69], v[6:9], v[38:41], v[66:69]
	v_mfma_f32_16x16x32_f16 v[70:73], v[14:17], v[38:41], v[70:73]
	v_mfma_f32_16x16x32_f16 v[74:77], v[6:9], v[46:49], v[74:77]
	v_mfma_f32_16x16x32_f16 v[78:81], v[14:17], v[46:49], v[78:81]
	v_mfma_f32_16x16x32_f16 v[82:85], v[6:9], v[54:57], v[82:85]
	v_mfma_f32_16x16x32_f16 v[86:89], v[14:17], v[54:57], v[86:89]
	v_mfma_f32_16x16x32_f16 v[102:105], v[14:17], v[62:65], v[90:93]
	v_mfma_f32_16x16x32_f16 v[90:93], v[18:21], v[34:37], 0
	v_mfma_f32_16x16x32_f16 v[34:37], v[26:29], v[34:37], 0
	v_mfma_f32_16x16x32_f16 v[118:121], v[22:25], v[38:41], v[90:93]
	v_mfma_f32_16x16x32_f16 v[34:37], v[30:33], v[38:41], v[34:37]
	v_mfma_f32_16x16x32_f16 v[38:41], v[18:21], v[42:45], 0
	v_mfma_f32_16x16x32_f16 v[42:45], v[26:29], v[42:45], 0
	v_mfma_f32_16x16x32_f16 v[38:41], v[22:25], v[46:49], v[38:41]
	v_mfma_f32_16x16x32_f16 v[42:45], v[30:33], v[46:49], v[42:45]
	v_mfma_f32_16x16x32_f16 v[46:49], v[18:21], v[50:53], 0
	v_mfma_f32_16x16x32_f16 v[50:53], v[26:29], v[50:53], 0
	v_mfma_f32_16x16x32_f16 v[46:49], v[22:25], v[54:57], v[46:49]
	v_mfma_f32_16x16x32_f16 v[50:53], v[30:33], v[54:57], v[50:53]
	v_mfma_f32_16x16x32_f16 v[54:57], v[18:21], v[58:61], 0
	v_mfma_f32_16x16x32_f16 v[58:61], v[26:29], v[58:61], 0
	v_mfma_f32_16x16x32_f16 v[54:57], v[22:25], v[62:65], v[54:57]
	v_mfma_f32_16x16x32_f16 v[58:61], v[30:33], v[62:65], v[58:61]
	s_barrier
	s_setprio 0
	ds_read_b128 v[62:65], v212 offset:16384
	ds_read_b128 v[90:93], v212 offset:17408
	ds_read_b128 v[98:101], v212 offset:18432
	ds_read_b128 v[106:109], v212 offset:19456
	ds_read_b128 v[110:113], v212 offset:20480
	ds_read_b128 v[114:117], v212 offset:21504
	ds_read_b128 v[122:125], v212 offset:22528
	ds_read_b128 v[126:129], v212 offset:23552
	s_add_u32 m0, s14, 0x10000
	s_nop 0
	global_load_lds_dwordx4 v207, s[54:55]
	s_nop 0
	s_add_u32 m0, s14, 0x12000
	s_nop 0
	global_load_lds_dwordx4 v209, s[54:55]
	s_add_u32 s54, s6, 0x40100
	s_addc_u32 s55, s7, 0
	s_add_u32 m0, s14, 0x14000
	s_nop 0
	global_load_lds_dwordx4 v207, s[54:55]
	s_nop 0
	s_add_u32 m0, s14, 0x16000
	s_nop 0
	global_load_lds_dwordx4 v209, s[54:55]
	s_nop 0
	s_add_u32 m0, s14, 0
	s_nop 0
	global_load_lds_dwordx4 v206, s[48:49]
	s_nop 0
	s_add_u32 m0, s14, 0x2000
	s_nop 0
	global_load_lds_dwordx4 v208, s[48:49]
	s_waitcnt vmcnt(8)
	s_waitcnt lgkmcnt(0)
	s_barrier
	v_mfma_f32_16x16x32_f16 v[130:133], v[2:5], v[62:65], 0
	s_setprio 1
	s_waitcnt lgkmcnt(5)
	v_mfma_f32_16x16x32_f16 v[138:141], v[2:5], v[98:101], 0
	s_waitcnt lgkmcnt(3)
	v_mfma_f32_16x16x32_f16 v[146:149], v[2:5], v[110:113], 0
	s_waitcnt lgkmcnt(1)
	v_mfma_f32_16x16x32_f16 v[2:5], v[2:5], v[122:125], 0
	v_mfma_f32_16x16x32_f16 v[130:133], v[6:9], v[90:93], v[130:133]
	v_mfma_f32_16x16x32_f16 v[138:141], v[6:9], v[106:109], v[138:141]
	v_mfma_f32_16x16x32_f16 v[146:149], v[6:9], v[114:117], v[146:149]
	s_waitcnt lgkmcnt(0)
	v_mfma_f32_16x16x32_f16 v[2:5], v[6:9], v[126:129], v[2:5]
	v_mfma_f32_16x16x32_f16 v[6:9], v[10:13], v[122:125], 0
	v_mfma_f32_16x16x32_f16 v[134:137], v[10:13], v[62:65], 0
	v_mfma_f32_16x16x32_f16 v[142:145], v[10:13], v[98:101], 0
	v_mfma_f32_16x16x32_f16 v[150:153], v[10:13], v[110:113], 0
	v_mfma_f32_16x16x32_f16 v[6:9], v[14:17], v[126:129], v[6:9]
	v_mfma_f32_16x16x32_f16 v[134:137], v[14:17], v[90:93], v[134:137]
	v_mfma_f32_16x16x32_f16 v[142:145], v[14:17], v[106:109], v[142:145]
	v_mfma_f32_16x16x32_f16 v[150:153], v[14:17], v[114:117], v[150:153]
	v_mfma_f32_16x16x32_f16 v[10:13], v[18:21], v[62:65], 0
	v_mfma_f32_16x16x32_f16 v[14:17], v[22:25], v[90:93], v[10:13]
	v_mfma_f32_16x16x32_f16 v[10:13], v[26:29], v[62:65], 0
	v_mfma_f32_16x16x32_f16 v[154:157], v[30:33], v[90:93], v[10:13]
	v_mfma_f32_16x16x32_f16 v[10:13], v[18:21], v[98:101], 0
	v_mfma_f32_16x16x32_f16 v[158:161], v[22:25], v[106:109], v[10:13]
	v_mfma_f32_16x16x32_f16 v[10:13], v[26:29], v[98:101], 0
	v_mfma_f32_16x16x32_f16 v[162:165], v[30:33], v[106:109], v[10:13]
	v_mfma_f32_16x16x32_f16 v[10:13], v[18:21], v[110:113], 0
	v_mfma_f32_16x16x32_f16 v[166:169], v[22:25], v[114:117], v[10:13]
	v_mfma_f32_16x16x32_f16 v[10:13], v[26:29], v[110:113], 0
	v_mfma_f32_16x16x32_f16 v[170:173], v[30:33], v[114:117], v[10:13]
	v_mfma_f32_16x16x32_f16 v[10:13], v[18:21], v[122:125], 0
	v_mfma_f32_16x16x32_f16 v[174:177], v[22:25], v[126:129], v[10:13]
	v_mfma_f32_16x16x32_f16 v[10:13], v[26:29], v[122:125], 0
	v_mfma_f32_16x16x32_f16 v[178:181], v[30:33], v[126:129], v[10:13]
	s_barrier
; #define PG8_STAGE(bufoff, gbase, voff) do { if constexpr (ABL & 1) break; glds16s<(bufoff)>((voff)[0], (const void*)(gbase), ldsbw); glds16s<(bufoff) + 8192>((voff)[1], (const void*)(gbase), ldsbw); } while (0)
; #define PG8_LDA(dst, b, h) do { if constexpr (ABL & 4) break; _Pragma("unroll") for (int m = 0; m < 4; ++m) _Pragma("unroll") for (int k = 0; k < 2; ++k) dst[m][k] = *(const LAS f16x8*)(lds + PG8_SA(b, h) + aoff + m * 2048 + k * 1024); } while (0)
; #define PG8_LDB(dst, b, h) do { if constexpr (ABL & 4) break; _Pragma("unroll") for (int n = 0; n < 2; ++n) _Pragma("unroll") for (int k = 0; k < 2; ++k) dst[n][k] = *(const LAS f16x8*)(lds + PG8_SB(b, h) + boff + n * 2048 + k * 1024); } while (0)
; #define PG8_MMA(ai, bj, At, Bt) do { if constexpr (ABL & 2) break; __builtin_amdgcn_s_setprio(1); _Pragma("unroll") for (int m = 0; m < 4; ++m) _Pragma("unroll") for (int n = 0; n < 2; ++n) _Pragma("unroll") for (int k = 0; k < 2; ++k) \
;         acc[ai][bj][m][n] = __builtin_amdgcn_mfma_f32_16x16x32_f16(Bt[n][k], At[m][k], acc[ai][bj][m][n], 0, 0, 0); __builtin_amdgcn_s_setprio(0); } while (0)
; #define PG8_MMAF(ai, bj, At, Bt) do { if (t == 0) PG8_MMA0(ai, bj, At, Bt); else PG8_MMA(ai, bj, At, Bt); } while (0)
; #define PG8_WAIT_V(n) asm volatile("s_waitcnt vmcnt(" #n ")" ::: "memory")
; #define PG8_WAIT_L(n) asm volatile("s_waitcnt lgkmcnt(" #n ")" ::: "memory")
; #define PG8_BAR __builtin_amdgcn_s_barrier()
; #define PG8_SCHED __builtin_amdgcn_sched_barrier(0)
;     ...
;             if (!fin) PG8_WAIT_V(8); else PG8_WAIT_V(2); PG8_WAIT_L(0); PG8_BAR; PG8_MMAF(1, 0, At, B0); PG8_MMAF(1, 1, At, B1); PG8_BAR; PG8_SCHED;
;             PG8_LDB(B0, 1, 0); PG8_LDB(B1, 1, 1); PG8_SCHED; PG8_LDA(At, 1, 0); if (!fin) PG8_STAGE(PG8_SA(0, 1), a2 + hstep, voffA);
;             if (!fin) PG8_WAIT_V(8); else PG8_WAIT_V(0); PG8_WAIT_L(0); PG8_BAR; PG8_MMA(0, 0, At, B0); PG8_MMA(0, 1, At, B1); PG8_BAR; PG8_SCHED;
;             PG8_LDA(At, 1, 1); if (!fin) { PG8_STAGE(PG8_SB(1, 0), b3, voffB); PG8_STAGE(PG8_SB(1, 1), b3 + hstep, voffB); PG8_STAGE(PG8_SA(1, 0), a3, voffA); }
;             if (!fin) PG8_WAIT_V(8); PG8_WAIT_L(0); PG8_BAR; PG8_MMA(1, 0, At, B0); PG8_MMA(1, 1, At, B1); PG8_BAR; PG8_SCHED;
	s_setprio 0
	s_nop 4
	ds_read_b128 v[10:13], v213
	ds_read_b128 v[22:25], v213 offset:1024
	ds_read_b128 v[30:33], v213 offset:2048
	ds_read_b128 v[182:185], v213 offset:3072
	ds_read_b128 v[186:189], v214
	ds_read_b128 v[190:193], v214 offset:1024
	ds_read_b128 v[216:219], v214 offset:2048
	ds_read_b128 v[220:223], v214 offset:3072
	ds_read_b128 v[18:21], v212 offset:32768
	ds_read_b128 v[26:29], v212 offset:33792
	ds_read_b128 v[224:227], v212 offset:34816
	ds_read_b128 v[228:231], v212 offset:35840
	ds_read_b128 v[232:235], v212 offset:36864
	ds_read_b128 v[236:239], v212 offset:37888
	ds_read_b128 v[240:243], v212 offset:38912
	ds_read_b128 v[244:247], v212 offset:39936
	s_add_u32 s8, s8, 0x40100
	s_addc_u32 s9, s9, 0
	s_add_u32 m0, s14, 0x4000
	s_nop 0
	global_load_lds_dwordx4 v206, s[8:9]
	s_nop 0
	s_add_u32 m0, s14, 0x6000
	s_nop 0
	global_load_lds_dwordx4 v208, s[8:9]
	s_waitcnt vmcnt(8)
	s_waitcnt lgkmcnt(0)
	s_barrier
	v_mfma_f32_16x16x32_f16 v[62:65], v[10:13], v[18:21], v[66:69]
	s_setprio 1
	s_waitcnt lgkmcnt(6)
	v_mfma_f32_16x16x32_f16 v[114:117], v[22:25], v[26:29], v[62:65]
	v_mfma_f32_16x16x32_f16 v[62:65], v[30:33], v[18:21], v[70:73]
	v_mfma_f32_16x16x32_f16 v[110:113], v[182:185], v[26:29], v[62:65]
	s_waitcnt lgkmcnt(5)
	v_mfma_f32_16x16x32_f16 v[62:65], v[10:13], v[224:227], v[74:77]
	s_waitcnt lgkmcnt(4)
	v_mfma_f32_16x16x32_f16 v[106:109], v[22:25], v[228:231], v[62:65]
	v_mfma_f32_16x16x32_f16 v[62:65], v[30:33], v[224:227], v[78:81]
	v_mfma_f32_16x16x32_f16 v[98:101], v[182:185], v[228:231], v[62:65]
	s_waitcnt lgkmcnt(3)
	v_mfma_f32_16x16x32_f16 v[62:65], v[10:13], v[232:235], v[82:85]
	s_waitcnt lgkmcnt(2)
	v_mfma_f32_16x16x32_f16 v[90:93], v[22:25], v[236:239], v[62:65]
	v_mfma_f32_16x16x32_f16 v[62:65], v[30:33], v[232:235], v[86:89]
	v_mfma_f32_16x16x32_f16 v[82:85], v[182:185], v[236:239], v[62:65]
	s_waitcnt lgkmcnt(1)
	v_mfma_f32_16x16x32_f16 v[62:65], v[10:13], v[240:243], v[94:97]
	s_waitcnt lgkmcnt(0)
	v_mfma_f32_16x16x32_f16 v[74:77], v[22:25], v[244:247], v[62:65]
	v_mfma_f32_16x16x32_f16 v[62:65], v[30:33], v[240:243], v[102:105]
	v_mfma_f32_16x16x32_f16 v[62:65], v[182:185], v[244:247], v[62:65]
	v_mfma_f32_16x16x32_f16 v[66:69], v[186:189], v[18:21], v[118:121]
	v_mfma_f32_16x16x32_f16 v[18:21], v[216:219], v[18:21], v[34:37]
	v_mfma_f32_16x16x32_f16 v[122:125], v[220:223], v[26:29], v[18:21]
	v_mfma_f32_16x16x32_f16 v[18:21], v[186:189], v[224:227], v[38:41]
	v_mfma_f32_16x16x32_f16 v[118:121], v[190:193], v[228:231], v[18:21]
	v_mfma_f32_16x16x32_f16 v[18:21], v[216:219], v[224:227], v[42:45]
	v_mfma_f32_16x16x32_f16 v[102:105], v[220:223], v[228:231], v[18:21]
	v_mfma_f32_16x16x32_f16 v[18:21], v[186:189], v[232:235], v[46:49]
	v_mfma_f32_16x16x32_f16 v[94:97], v[190:193], v[236:239], v[18:21]
	v_mfma_f32_16x16x32_f16 v[18:21], v[216:219], v[232:235], v[50:53]
	v_mfma_f32_16x16x32_f16 v[86:89], v[220:223], v[236:239], v[18:21]
	v_mfma_f32_16x16x32_f16 v[18:21], v[186:189], v[240:243], v[54:57]
	v_mfma_f32_16x16x32_f16 v[78:81], v[190:193], v[244:247], v[18:21]
	v_mfma_f32_16x16x32_f16 v[18:21], v[216:219], v[240:243], v[58:61]
	v_mfma_f32_16x16x32_f16 v[126:129], v[190:193], v[26:29], v[66:69]
	v_mfma_f32_16x16x32_f16 v[70:73], v[220:223], v[244:247], v[18:21]
	s_barrier
	s_setprio 0
	ds_read_b128 v[38:41], v212 offset:49152
	ds_read_b128 v[46:49], v212 offset:50176
	ds_read_b128 v[224:227], v212 offset:51200
	ds_read_b128 v[228:231], v212 offset:52224
	ds_read_b128 v[232:235], v212 offset:53248
	ds_read_b128 v[236:239], v212 offset:54272
	ds_read_b128 v[240:243], v212 offset:55296
	ds_read_b128 v[244:247], v212 offset:56320
	s_add_u32 m0, s14, 0x18000
	s_nop 0
	global_load_lds_dwordx4 v207, s[26:27]
	s_nop 0
	s_add_u32 m0, s14, 0x1a000
	s_nop 0
	global_load_lds_dwordx4 v209, s[26:27]
	s_add_u32 s8, s6, 0x40180
	s_addc_u32 s9, s7, 0
	s_add_u32 m0, s14, 0x1c000
	s_nop 0
	global_load_lds_dwordx4 v207, s[8:9]
	s_nop 0
	s_add_u32 m0, s14, 0x1e000
	s_nop 0
	global_load_lds_dwordx4 v209, s[8:9]
	s_nop 0
	s_add_u32 m0, s14, 0x8000
	s_nop 0
	global_load_lds_dwordx4 v206, s[24:25]
	s_nop 0
	s_add_u32 m0, s14, 0xa000
	s_nop 0
	global_load_lds_dwordx4 v208, s[24:25]
	s_waitcnt vmcnt(8)
	s_waitcnt lgkmcnt(0)
	s_barrier
	v_mfma_f32_16x16x32_f16 v[18:21], v[10:13], v[38:41], v[130:133]
	s_setprio 1
	s_waitcnt lgkmcnt(6)
	v_mfma_f32_16x16x32_f16 v[58:61], v[22:25], v[46:49], v[18:21]
	v_mfma_f32_16x16x32_f16 v[18:21], v[30:33], v[38:41], v[134:137]
	v_mfma_f32_16x16x32_f16 v[50:53], v[182:185], v[46:49], v[18:21]
	s_waitcnt lgkmcnt(5)
	v_mfma_f32_16x16x32_f16 v[18:21], v[10:13], v[224:227], v[138:141]
	s_waitcnt lgkmcnt(4)
	v_mfma_f32_16x16x32_f16 v[42:45], v[22:25], v[228:231], v[18:21]
	v_mfma_f32_16x16x32_f16 v[18:21], v[30:33], v[224:227], v[142:145]
	v_mfma_f32_16x16x32_f16 v[34:37], v[182:185], v[228:231], v[18:21]
	s_waitcnt lgkmcnt(3)
	v_mfma_f32_16x16x32_f16 v[18:21], v[10:13], v[232:235], v[146:149]
	s_waitcnt lgkmcnt(1)
	v_mfma_f32_16x16x32_f16 v[2:5], v[10:13], v[240:243], v[2:5]
	v_mfma_f32_16x16x32_f16 v[26:29], v[22:25], v[236:239], v[18:21]
	v_mfma_f32_16x16x32_f16 v[18:21], v[30:33], v[232:235], v[150:153]
	s_waitcnt lgkmcnt(0)
	v_mfma_f32_16x16x32_f16 v[10:13], v[22:25], v[244:247], v[2:5]
	v_mfma_f32_16x16x32_f16 v[2:5], v[30:33], v[240:243], v[6:9]
	v_mfma_f32_16x16x32_f16 v[18:21], v[182:185], v[236:239], v[18:21]
	v_mfma_f32_16x16x32_f16 v[2:5], v[182:185], v[244:247], v[2:5]
	v_mfma_f32_16x16x32_f16 v[6:9], v[186:189], v[38:41], v[14:17]
	v_mfma_f32_16x16x32_f16 v[66:69], v[190:193], v[46:49], v[6:9]
	v_mfma_f32_16x16x32_f16 v[6:9], v[216:219], v[38:41], v[154:157]
	v_mfma_f32_16x16x32_f16 v[54:57], v[220:223], v[46:49], v[6:9]
	v_mfma_f32_16x16x32_f16 v[6:9], v[186:189], v[224:227], v[158:161]
	v_mfma_f32_16x16x32_f16 v[46:49], v[190:193], v[228:231], v[6:9]
	v_mfma_f32_16x16x32_f16 v[6:9], v[216:219], v[224:227], v[162:165]
	v_mfma_f32_16x16x32_f16 v[38:41], v[220:223], v[228:231], v[6:9]
	v_mfma_f32_16x16x32_f16 v[6:9], v[186:189], v[232:235], v[166:169]
	v_mfma_f32_16x16x32_f16 v[30:33], v[190:193], v[236:239], v[6:9]
	v_mfma_f32_16x16x32_f16 v[6:9], v[216:219], v[232:235], v[170:173]
	v_mfma_f32_16x16x32_f16 v[22:25], v[220:223], v[236:239], v[6:9]
	v_mfma_f32_16x16x32_f16 v[6:9], v[186:189], v[240:243], v[174:177]
	v_mfma_f32_16x16x32_f16 v[14:17], v[190:193], v[244:247], v[6:9]
	v_mfma_f32_16x16x32_f16 v[6:9], v[216:219], v[240:243], v[178:181]
	v_mfma_f32_16x16x32_f16 v[6:9], v[220:223], v[244:247], v[6:9]
	s_barrier
	s_setprio 0
	s_add_u32 s53, s6, 0x200
	s_addc_u32 s54, s7, 0
	s_mov_b32 s55, 0
	s_branch .LBB0_843
; #define PG8_MMA(ai, bj, At, Bt) do { if constexpr (ABL & 2) break; __builtin_amdgcn_s_setprio(1); _Pragma("unroll") for (int m = 0; m < 4; ++m) _Pragma("unroll") for (int n = 0; n < 2; ++n) _Pragma("unroll") for (int k = 0; k < 2; ++k) \
;         acc[ai][bj][m][n] = __builtin_amdgcn_mfma_f32_16x16x32_f16(Bt[n][k], At[m][k], acc[ai][bj][m][n], 0, 0, 0); __builtin_amdgcn_s_setprio(0); } while (0)
; #define PG8_WAIT_V(n) asm volatile("s_waitcnt vmcnt(" #n ")" ::: "memory")
; #define PG8_WAIT_L(n) asm volatile("s_waitcnt lgkmcnt(" #n ")" ::: "memory")
; #define PG8_BAR __builtin_amdgcn_s_barrier()
; #define PG8_SCHED __builtin_amdgcn_sched_barrier(0)
;     ...
;         for (int t = 0; t < nt; t += 2) {
;     ...
;             if (!fin) PG8_WAIT_V(8); PG8_WAIT_L(0); PG8_BAR; PG8_MMA(1, 0, At, B0); PG8_MMA(1, 1, At, B1); PG8_BAR; PG8_SCHED;
.LBB0_842:
	s_waitcnt lgkmcnt(0)
	s_barrier
	v_mfma_f32_16x16x32_f16 v[58:61], v[146:149], v[186:189], v[58:61]
	s_setprio 1
	v_mfma_f32_16x16x32_f16 v[50:53], v[154:157], v[186:189], v[50:53]
	s_waitcnt lgkmcnt(5)
	v_mfma_f32_16x16x32_f16 v[42:45], v[146:149], v[178:181], v[42:45]
	v_mfma_f32_16x16x32_f16 v[34:37], v[154:157], v[178:181], v[34:37]
	s_waitcnt lgkmcnt(3)
	v_mfma_f32_16x16x32_f16 v[26:29], v[146:149], v[170:173], v[26:29]
	v_mfma_f32_16x16x32_f16 v[18:21], v[154:157], v[170:173], v[18:21]
	s_waitcnt lgkmcnt(1)
	v_mfma_f32_16x16x32_f16 v[10:13], v[146:149], v[162:165], v[10:13]
	v_mfma_f32_16x16x32_f16 v[2:5], v[154:157], v[162:165], v[2:5]
	v_mfma_f32_16x16x32_f16 v[58:61], v[150:153], v[190:193], v[58:61]
	v_mfma_f32_16x16x32_f16 v[50:53], v[158:161], v[190:193], v[50:53]
	v_mfma_f32_16x16x32_f16 v[42:45], v[150:153], v[182:185], v[42:45]
	v_mfma_f32_16x16x32_f16 v[34:37], v[158:161], v[182:185], v[34:37]
	v_mfma_f32_16x16x32_f16 v[26:29], v[150:153], v[174:177], v[26:29]
	v_mfma_f32_16x16x32_f16 v[18:21], v[158:161], v[174:177], v[18:21]
	s_waitcnt lgkmcnt(0)
	v_mfma_f32_16x16x32_f16 v[10:13], v[150:153], v[166:169], v[10:13]
	v_mfma_f32_16x16x32_f16 v[2:5], v[158:161], v[166:169], v[2:5]
	v_mfma_f32_16x16x32_f16 v[66:69], v[130:133], v[186:189], v[66:69]
	v_mfma_f32_16x16x32_f16 v[54:57], v[138:141], v[186:189], v[54:57]
	v_mfma_f32_16x16x32_f16 v[46:49], v[130:133], v[178:181], v[46:49]
	v_mfma_f32_16x16x32_f16 v[38:41], v[138:141], v[178:181], v[38:41]
	v_mfma_f32_16x16x32_f16 v[30:33], v[130:133], v[170:173], v[30:33]
	v_mfma_f32_16x16x32_f16 v[22:25], v[138:141], v[170:173], v[22:25]
	v_mfma_f32_16x16x32_f16 v[14:17], v[130:133], v[162:165], v[14:17]
	v_mfma_f32_16x16x32_f16 v[6:9], v[138:141], v[162:165], v[6:9]
	v_mfma_f32_16x16x32_f16 v[66:69], v[134:137], v[190:193], v[66:69]
	v_mfma_f32_16x16x32_f16 v[54:57], v[142:145], v[190:193], v[54:57]
	v_mfma_f32_16x16x32_f16 v[46:49], v[134:137], v[182:185], v[46:49]
	v_mfma_f32_16x16x32_f16 v[38:41], v[142:145], v[182:185], v[38:41]
	v_mfma_f32_16x16x32_f16 v[30:33], v[134:137], v[174:177], v[30:33]
	v_mfma_f32_16x16x32_f16 v[22:25], v[142:145], v[174:177], v[22:25]
	v_mfma_f32_16x16x32_f16 v[14:17], v[134:137], v[166:169], v[14:17]
	v_mfma_f32_16x16x32_f16 v[6:9], v[142:145], v[166:169], v[6:9]
	s_barrier
	s_setprio 0
	s_add_i32 s55, s55, 2
	s_add_u32 s53, s53, 0x100
	s_addc_u32 s54, s54, 0
	s_cmp_gt_u32 s55, 13
	s_cbranch_scc1 .LBB0_853
; #define PG8_STAGE(bufoff, gbase, voff) do { if constexpr (ABL & 1) break; glds16s<(bufoff)>((voff)[0], (const void*)(gbase), ldsbw); glds16s<(bufoff) + 8192>((voff)[1], (const void*)(gbase), ldsbw); } while (0)
; #define PG8_LDA(dst, b, h) do { if constexpr (ABL & 4) break; _Pragma("unroll") for (int m = 0; m < 4; ++m) _Pragma("unroll") for (int k = 0; k < 2; ++k) dst[m][k] = *(const LAS f16x8*)(lds + PG8_SA(b, h) + aoff + m * 2048 + k * 1024); } while (0)
; #define PG8_LDB(dst, b, h) do { if constexpr (ABL & 4) break; _Pragma("unroll") for (int n = 0; n < 2; ++n) _Pragma("unroll") for (int k = 0; k < 2; ++k) dst[n][k] = *(const LAS f16x8*)(lds + PG8_SB(b, h) + boff + n * 2048 + k * 1024); } while (0)
; #define PG8_MMAF(ai, bj, At, Bt) do { if (t == 0) PG8_MMA0(ai, bj, At, Bt); else PG8_MMA(ai, bj, At, Bt); } while (0)
; #define PG8_WAIT_V(n) asm volatile("s_waitcnt vmcnt(" #n ")" ::: "memory")
; #define PG8_WAIT_L(n) asm volatile("s_waitcnt lgkmcnt(" #n ")" ::: "memory")
; #define PG8_BAR __builtin_amdgcn_s_barrier()
; #define PG8_SCHED __builtin_amdgcn_sched_barrier(0)
;     ...
;             const bool last = (t == nt - 2);
;             const char* a1 = cA + (size_t)(t + 1) * kstep;
;             const char* a2 = last ? nA : cA + (size_t)(t + 2) * kstep; const char* b2 = last ? nB : cB + (size_t)(t + 2) * kstep;
;             const char* a3 = a2 + kstep; const char* b3 = b2 + kstep;
;             if (last && has_next) S.a_ready(nxt);
;             if constexpr (SP2) {
;             PG8_LDB(B0, 0, 0); PG8_LDB(B1, 0, 1); PG8_SCHED; PG8_LDA(At, 0, 0); PG8_STAGE(PG8_SA(1, 1), a1 + hstep, voffA);
;             PG8_WAIT_V(8); PG8_WAIT_L(0); PG8_BAR; PG8_MMAF(0, 0, At, B0); PG8_MMAF(0, 1, At, B1); PG8_BAR; PG8_SCHED;
;             const bool fin = last && !has_next;
;             PG8_LDA(At, 0, 1); if (!fin) { PG8_STAGE(PG8_SB(0, 0), b2, voffB); PG8_STAGE(PG8_SB(0, 1), b2 + hstep, voffB); PG8_STAGE(PG8_SA(0, 0), a2, voffA); }
.LBB0_843:
	ds_read_b128 v[146:149], v210
	ds_read_b128 v[150:153], v210 offset:1024
	ds_read_b128 v[154:157], v210 offset:2048
	ds_read_b128 v[158:161], v210 offset:3072
	ds_read_b128 v[130:133], v211
	ds_read_b128 v[134:137], v211 offset:1024
	ds_read_b128 v[138:141], v211 offset:2048
	ds_read_b128 v[142:145], v211 offset:3072
	s_mov_b64 s[6:7], s[48:49]
	s_add_u32 s48, s6, 0x100
	s_addc_u32 s49, s7, 0
	s_cmp_eq_u32 s55, 12
	s_cselect_b64 s[26:27], -1, 0
	s_and_b64 s[8:9], s[26:27], exec
	s_cselect_b32 s25, s41, s49
	s_cselect_b32 s24, s51, s48
	s_cselect_b32 s9, s39, s54
	s_cselect_b32 s8, s52, s53
	ds_read_b128 v[162:165], v212
	ds_read_b128 v[166:169], v212 offset:1024
	ds_read_b128 v[170:173], v212 offset:2048
	ds_read_b128 v[174:177], v212 offset:3072
	ds_read_b128 v[178:181], v212 offset:4096
	ds_read_b128 v[182:185], v212 offset:5120
	ds_read_b128 v[186:189], v212 offset:6144
	ds_read_b128 v[190:193], v212 offset:7168
	s_add_u32 s6, s6, 0x40080
	s_addc_u32 s7, s7, 0
	s_add_u32 m0, s14, 0xc000
	s_nop 0
	global_load_lds_dwordx4 v206, s[6:7]
	s_nop 0
	s_add_u32 m0, s14, 0xe000
	s_nop 0
	global_load_lds_dwordx4 v208, s[6:7]
	s_waitcnt vmcnt(8)
	s_waitcnt lgkmcnt(0)
	s_barrier
	v_mfma_f32_16x16x32_f16 v[114:117], v[146:149], v[162:165], v[114:117]
	s_setprio 1
	v_mfma_f32_16x16x32_f16 v[110:113], v[154:157], v[162:165], v[110:113]
	s_waitcnt lgkmcnt(5)
	v_mfma_f32_16x16x32_f16 v[106:109], v[146:149], v[170:173], v[106:109]
	v_mfma_f32_16x16x32_f16 v[98:101], v[154:157], v[170:173], v[98:101]
	s_waitcnt lgkmcnt(3)
	v_mfma_f32_16x16x32_f16 v[90:93], v[146:149], v[178:181], v[90:93]
	v_mfma_f32_16x16x32_f16 v[82:85], v[154:157], v[178:181], v[82:85]
	s_waitcnt lgkmcnt(1)
	v_mfma_f32_16x16x32_f16 v[74:77], v[146:149], v[186:189], v[74:77]
	v_mfma_f32_16x16x32_f16 v[62:65], v[154:157], v[186:189], v[62:65]
	v_mfma_f32_16x16x32_f16 v[114:117], v[150:153], v[166:169], v[114:117]
	v_mfma_f32_16x16x32_f16 v[110:113], v[158:161], v[166:169], v[110:113]
	v_mfma_f32_16x16x32_f16 v[106:109], v[150:153], v[174:177], v[106:109]
	v_mfma_f32_16x16x32_f16 v[98:101], v[158:161], v[174:177], v[98:101]
	v_mfma_f32_16x16x32_f16 v[90:93], v[150:153], v[182:185], v[90:93]
	v_mfma_f32_16x16x32_f16 v[82:85], v[158:161], v[182:185], v[82:85]
	s_waitcnt lgkmcnt(0)
	v_mfma_f32_16x16x32_f16 v[74:77], v[150:153], v[190:193], v[74:77]
	v_mfma_f32_16x16x32_f16 v[62:65], v[158:161], v[190:193], v[62:65]
	v_mfma_f32_16x16x32_f16 v[126:129], v[130:133], v[162:165], v[126:129]
	v_mfma_f32_16x16x32_f16 v[122:125], v[138:141], v[162:165], v[122:125]
	v_mfma_f32_16x16x32_f16 v[118:121], v[130:133], v[170:173], v[118:121]
	v_mfma_f32_16x16x32_f16 v[102:105], v[138:141], v[170:173], v[102:105]
	v_mfma_f32_16x16x32_f16 v[94:97], v[130:133], v[178:181], v[94:97]
	v_mfma_f32_16x16x32_f16 v[86:89], v[138:141], v[178:181], v[86:89]
	v_mfma_f32_16x16x32_f16 v[78:81], v[130:133], v[186:189], v[78:81]
	v_mfma_f32_16x16x32_f16 v[70:73], v[138:141], v[186:189], v[70:73]
	v_mfma_f32_16x16x32_f16 v[126:129], v[134:137], v[166:169], v[126:129]
	v_mfma_f32_16x16x32_f16 v[122:125], v[142:145], v[166:169], v[122:125]
	v_mfma_f32_16x16x32_f16 v[118:121], v[134:137], v[174:177], v[118:121]
	v_mfma_f32_16x16x32_f16 v[102:105], v[142:145], v[174:177], v[102:105]
	v_mfma_f32_16x16x32_f16 v[94:97], v[134:137], v[182:185], v[94:97]
	v_mfma_f32_16x16x32_f16 v[86:89], v[142:145], v[182:185], v[86:89]
	v_mfma_f32_16x16x32_f16 v[78:81], v[134:137], v[190:193], v[78:81]
	v_mfma_f32_16x16x32_f16 v[70:73], v[142:145], v[190:193], v[70:73]
	s_barrier
	s_setprio 0
	ds_read_b128 v[186:189], v212 offset:16384
	ds_read_b128 v[190:193], v212 offset:17408
	ds_read_b128 v[178:181], v212 offset:18432
	ds_read_b128 v[182:185], v212 offset:19456
	ds_read_b128 v[170:173], v212 offset:20480
	ds_read_b128 v[174:177], v212 offset:21504
	ds_read_b128 v[162:165], v212 offset:22528
	ds_read_b128 v[166:169], v212 offset:23552
	s_and_b64 s[6:7], s[4:5], s[26:27]
	s_mov_b64 s[26:27], -1
	s_and_b64 vcc, exec, s[6:7]
	s_cbranch_vccnz .LBB0_845
	s_add_u32 m0, s14, 0x10000
	s_nop 0
	global_load_lds_dwordx4 v207, s[8:9]
	s_nop 0
	s_add_u32 m0, s14, 0x12000
	s_nop 0
	global_load_lds_dwordx4 v209, s[8:9]
	s_add_u32 s26, s8, 0x40000
	s_addc_u32 s27, s9, 0
	s_add_u32 m0, s14, 0x14000
	s_nop 0
	global_load_lds_dwordx4 v207, s[26:27]
	s_nop 0
	s_add_u32 m0, s14, 0x16000
	s_nop 0
	global_load_lds_dwordx4 v209, s[26:27]
	s_mov_b64 s[26:27], 0
	s_add_u32 m0, s14, 0
	s_nop 0
	global_load_lds_dwordx4 v206, s[24:25]
	s_nop 0
	s_add_u32 m0, s14, 0x2000
	s_nop 0
	global_load_lds_dwordx4 v208, s[24:25]
	s_waitcnt vmcnt(8)

; #define PG8_STAGE(bufoff, gbase, voff) do { if constexpr (ABL & 1) break; glds16s<(bufoff)>((voff)[0], (const void*)(gbase), ldsbw); glds16s<(bufoff) + 8192>((voff)[1], (const void*)(gbase), ldsbw); } while (0)
; #define PG8_LDA(dst, b, h) do { if constexpr (ABL & 4) break; _Pragma("unroll") for (int m = 0; m < 4; ++m) _Pragma("unroll") for (int k = 0; k < 2; ++k) dst[m][k] = *(const LAS f16x8*)(lds + PG8_SA(b, h) + aoff + m * 2048 + k * 1024); } while (0)
; #define PG8_LDB(dst, b, h) do { if constexpr (ABL & 4) break; _Pragma("unroll") for (int n = 0; n < 2; ++n) _Pragma("unroll") for (int k = 0; k < 2; ++k) dst[n][k] = *(const LAS f16x8*)(lds + PG8_SB(b, h) + boff + n * 2048 + k * 1024); } while (0)
; #define PG8_MMA(ai, bj, At, Bt) do { if constexpr (ABL & 2) break; __builtin_amdgcn_s_setprio(1); _Pragma("unroll") for (int m = 0; m < 4; ++m) _Pragma("unroll") for (int n = 0; n < 2; ++n) _Pragma("unroll") for (int k = 0; k < 2; ++k) \
;         acc[ai][bj][m][n] = __builtin_amdgcn_mfma_f32_16x16x32_f16(Bt[n][k], At[m][k], acc[ai][bj][m][n], 0, 0, 0); __builtin_amdgcn_s_setprio(0); } while (0)
; #define PG8_MMAF(ai, bj, At, Bt) do { if (t == 0) PG8_MMA0(ai, bj, At, Bt); else PG8_MMA(ai, bj, At, Bt); } while (0)
; #define PG8_WAIT_V(n) asm volatile("s_waitcnt vmcnt(" #n ")" ::: "memory")
; #define PG8_WAIT_L(n) asm volatile("s_waitcnt lgkmcnt(" #n ")" ::: "memory")
; #define PG8_BAR __builtin_amdgcn_s_barrier()
; #define PG8_SCHED __builtin_amdgcn_sched_barrier(0)
;     ...
;             if (!fin) PG8_WAIT_V(8); else PG8_WAIT_V(2); PG8_WAIT_L(0); PG8_BAR; PG8_MMAF(1, 0, At, B0); PG8_MMAF(1, 1, At, B1); PG8_BAR; PG8_SCHED;
;             PG8_LDB(B0, 1, 0); PG8_LDB(B1, 1, 1); PG8_SCHED; PG8_LDA(At, 1, 0); if (!fin) PG8_STAGE(PG8_SA(0, 1), a2 + hstep, voffA);
;             if (!fin) PG8_WAIT_V(8); else PG8_WAIT_V(0); PG8_WAIT_L(0); PG8_BAR; PG8_MMA(0, 0, At, B0); PG8_MMA(0, 1, At, B1); PG8_BAR; PG8_SCHED;
.LBB0_847:
	s_waitcnt lgkmcnt(0)
	s_xor_b64 s[26:27], s[6:7], -1
	s_barrier
	v_mfma_f32_16x16x32_f16 v[58:61], v[146:149], v[186:189], v[58:61]
	s_setprio 1
	v_mfma_f32_16x16x32_f16 v[50:53], v[154:157], v[186:189], v[50:53]
	s_waitcnt lgkmcnt(5)
	v_mfma_f32_16x16x32_f16 v[42:45], v[146:149], v[178:181], v[42:45]
	v_mfma_f32_16x16x32_f16 v[34:37], v[154:157], v[178:181], v[34:37]
	s_waitcnt lgkmcnt(3)
	v_mfma_f32_16x16x32_f16 v[26:29], v[146:149], v[170:173], v[26:29]
	v_mfma_f32_16x16x32_f16 v[18:21], v[154:157], v[170:173], v[18:21]
	s_waitcnt lgkmcnt(1)
	v_mfma_f32_16x16x32_f16 v[10:13], v[146:149], v[162:165], v[10:13]
	v_mfma_f32_16x16x32_f16 v[2:5], v[154:157], v[162:165], v[2:5]
	v_mfma_f32_16x16x32_f16 v[58:61], v[150:153], v[190:193], v[58:61]
	v_mfma_f32_16x16x32_f16 v[50:53], v[158:161], v[190:193], v[50:53]
	v_mfma_f32_16x16x32_f16 v[42:45], v[150:153], v[182:185], v[42:45]
	v_mfma_f32_16x16x32_f16 v[34:37], v[158:161], v[182:185], v[34:37]
	v_mfma_f32_16x16x32_f16 v[26:29], v[150:153], v[174:177], v[26:29]
	v_mfma_f32_16x16x32_f16 v[18:21], v[158:161], v[174:177], v[18:21]
	s_waitcnt lgkmcnt(0)
	v_mfma_f32_16x16x32_f16 v[10:13], v[150:153], v[166:169], v[10:13]
	v_mfma_f32_16x16x32_f16 v[2:5], v[158:161], v[166:169], v[2:5]
	v_mfma_f32_16x16x32_f16 v[66:69], v[130:133], v[186:189], v[66:69]
	v_mfma_f32_16x16x32_f16 v[54:57], v[138:141], v[186:189], v[54:57]
	v_mfma_f32_16x16x32_f16 v[46:49], v[130:133], v[178:181], v[46:49]
	v_mfma_f32_16x16x32_f16 v[38:41], v[138:141], v[178:181], v[38:41]
	v_mfma_f32_16x16x32_f16 v[30:33], v[130:133], v[170:173], v[30:33]
	v_mfma_f32_16x16x32_f16 v[22:25], v[138:141], v[170:173], v[22:25]
	v_mfma_f32_16x16x32_f16 v[14:17], v[130:133], v[162:165], v[14:17]
	v_mfma_f32_16x16x32_f16 v[6:9], v[138:141], v[162:165], v[6:9]
	v_mfma_f32_16x16x32_f16 v[66:69], v[134:137], v[190:193], v[66:69]
	v_mfma_f32_16x16x32_f16 v[54:57], v[142:145], v[190:193], v[54:57]
	v_mfma_f32_16x16x32_f16 v[46:49], v[134:137], v[182:185], v[46:49]
	v_mfma_f32_16x16x32_f16 v[38:41], v[142:145], v[182:185], v[38:41]
	v_mfma_f32_16x16x32_f16 v[30:33], v[134:137], v[174:177], v[30:33]
	v_mfma_f32_16x16x32_f16 v[22:25], v[142:145], v[174:177], v[22:25]
	v_mfma_f32_16x16x32_f16 v[14:17], v[134:137], v[166:169], v[14:17]
	v_mfma_f32_16x16x32_f16 v[6:9], v[142:145], v[166:169], v[6:9]
	s_barrier
	s_setprio 0
	ds_read_b128 v[146:149], v213
	ds_read_b128 v[150:153], v213 offset:1024
	ds_read_b128 v[154:157], v213 offset:2048
	ds_read_b128 v[158:161], v213 offset:3072
	ds_read_b128 v[130:133], v214
	ds_read_b128 v[134:137], v214 offset:1024
	ds_read_b128 v[138:141], v214 offset:2048
	ds_read_b128 v[142:145], v214 offset:3072
	ds_read_b128 v[186:189], v212 offset:32768
	ds_read_b128 v[190:193], v212 offset:33792
	ds_read_b128 v[178:181], v212 offset:34816
	ds_read_b128 v[182:185], v212 offset:35840
	ds_read_b128 v[170:173], v212 offset:36864
	ds_read_b128 v[174:177], v212 offset:37888
	ds_read_b128 v[162:165], v212 offset:38912
	ds_read_b128 v[166:169], v212 offset:39936
	v_cndmask_b32_e64 v216, 0, 1, s[26:27]
	v_cmp_ne_u32_e64 s[6:7], 1, v216
	s_andn2_b64 vcc, exec, s[26:27]
	s_mov_b64 s[26:27], -1
	s_cbranch_vccnz .LBB0_849
	s_add_u32 s26, s24, 0x40000
	s_addc_u32 s27, s25, 0
	s_add_u32 m0, s14, 0x4000
	s_nop 0
	global_load_lds_dwordx4 v206, s[26:27]
	s_nop 0
	s_add_u32 m0, s14, 0x6000
	s_nop 0
	global_load_lds_dwordx4 v208, s[26:27]
	s_waitcnt vmcnt(8)
	s_mov_b64 s[26:27], 0

; #define PG8_STAGE(bufoff, gbase, voff) do { if constexpr (ABL & 1) break; glds16s<(bufoff)>((voff)[0], (const void*)(gbase), ldsbw); glds16s<(bufoff) + 8192>((voff)[1], (const void*)(gbase), ldsbw); } while (0)
; #define PG8_LDA(dst, b, h) do { if constexpr (ABL & 4) break; _Pragma("unroll") for (int m = 0; m < 4; ++m) _Pragma("unroll") for (int k = 0; k < 2; ++k) dst[m][k] = *(const LAS f16x8*)(lds + PG8_SA(b, h) + aoff + m * 2048 + k * 1024); } while (0)
; #define PG8_MMA(ai, bj, At, Bt) do { if constexpr (ABL & 2) break; __builtin_amdgcn_s_setprio(1); _Pragma("unroll") for (int m = 0; m < 4; ++m) _Pragma("unroll") for (int n = 0; n < 2; ++n) _Pragma("unroll") for (int k = 0; k < 2; ++k) \
;         acc[ai][bj][m][n] = __builtin_amdgcn_mfma_f32_16x16x32_f16(Bt[n][k], At[m][k], acc[ai][bj][m][n], 0, 0, 0); __builtin_amdgcn_s_setprio(0); } while (0)
; #define PG8_WAIT_V(n) asm volatile("s_waitcnt vmcnt(" #n ")" ::: "memory")
; #define PG8_WAIT_L(n) asm volatile("s_waitcnt lgkmcnt(" #n ")" ::: "memory")
; #define PG8_BAR __builtin_amdgcn_s_barrier()
; #define PG8_SCHED __builtin_amdgcn_sched_barrier(0)
;     ...
;             if (!fin) PG8_WAIT_V(8); else PG8_WAIT_V(0); PG8_WAIT_L(0); PG8_BAR; PG8_MMA(0, 0, At, B0); PG8_MMA(0, 1, At, B1); PG8_BAR; PG8_SCHED;
;             PG8_LDA(At, 1, 1); if (!fin) { PG8_STAGE(PG8_SB(1, 0), b3, voffB); PG8_STAGE(PG8_SB(1, 1), b3 + hstep, voffB); PG8_STAGE(PG8_SA(1, 0), a3, voffA); }
;             if (!fin) PG8_WAIT_V(8); PG8_WAIT_L(0); PG8_BAR; PG8_MMA(1, 0, At, B0); PG8_MMA(1, 1, At, B1); PG8_BAR; PG8_SCHED;
.LBB0_851:
	s_waitcnt lgkmcnt(0)
	s_barrier
	v_mfma_f32_16x16x32_f16 v[114:117], v[146:149], v[186:189], v[114:117]
	s_setprio 1
	v_mfma_f32_16x16x32_f16 v[110:113], v[154:157], v[186:189], v[110:113]
	s_waitcnt lgkmcnt(5)
	v_mfma_f32_16x16x32_f16 v[106:109], v[146:149], v[178:181], v[106:109]
	v_mfma_f32_16x16x32_f16 v[98:101], v[154:157], v[178:181], v[98:101]
	s_waitcnt lgkmcnt(3)
	v_mfma_f32_16x16x32_f16 v[90:93], v[146:149], v[170:173], v[90:93]
	v_mfma_f32_16x16x32_f16 v[82:85], v[154:157], v[170:173], v[82:85]
	s_waitcnt lgkmcnt(1)
	v_mfma_f32_16x16x32_f16 v[74:77], v[146:149], v[162:165], v[74:77]
	v_mfma_f32_16x16x32_f16 v[62:65], v[154:157], v[162:165], v[62:65]
	v_mfma_f32_16x16x32_f16 v[114:117], v[150:153], v[190:193], v[114:117]
	v_mfma_f32_16x16x32_f16 v[110:113], v[158:161], v[190:193], v[110:113]
	v_mfma_f32_16x16x32_f16 v[106:109], v[150:153], v[182:185], v[106:109]
	v_mfma_f32_16x16x32_f16 v[98:101], v[158:161], v[182:185], v[98:101]
	v_mfma_f32_16x16x32_f16 v[90:93], v[150:153], v[174:177], v[90:93]
	v_mfma_f32_16x16x32_f16 v[82:85], v[158:161], v[174:177], v[82:85]
	s_waitcnt lgkmcnt(0)
	v_mfma_f32_16x16x32_f16 v[74:77], v[150:153], v[166:169], v[74:77]
	v_mfma_f32_16x16x32_f16 v[62:65], v[158:161], v[166:169], v[62:65]
	v_mfma_f32_16x16x32_f16 v[126:129], v[130:133], v[186:189], v[126:129]
	v_mfma_f32_16x16x32_f16 v[122:125], v[138:141], v[186:189], v[122:125]
	v_mfma_f32_16x16x32_f16 v[118:121], v[130:133], v[178:181], v[118:121]
	v_mfma_f32_16x16x32_f16 v[102:105], v[138:141], v[178:181], v[102:105]
	v_mfma_f32_16x16x32_f16 v[94:97], v[130:133], v[170:173], v[94:97]
	v_mfma_f32_16x16x32_f16 v[86:89], v[138:141], v[170:173], v[86:89]
	v_mfma_f32_16x16x32_f16 v[78:81], v[130:133], v[162:165], v[78:81]
	v_mfma_f32_16x16x32_f16 v[70:73], v[138:141], v[162:165], v[70:73]
	v_mfma_f32_16x16x32_f16 v[126:129], v[134:137], v[190:193], v[126:129]
	v_mfma_f32_16x16x32_f16 v[122:125], v[142:145], v[190:193], v[122:125]
	v_mfma_f32_16x16x32_f16 v[118:121], v[134:137], v[182:185], v[118:121]
	v_mfma_f32_16x16x32_f16 v[102:105], v[142:145], v[182:185], v[102:105]
	v_mfma_f32_16x16x32_f16 v[94:97], v[134:137], v[174:177], v[94:97]
	v_mfma_f32_16x16x32_f16 v[86:89], v[142:145], v[174:177], v[86:89]
	v_mfma_f32_16x16x32_f16 v[78:81], v[134:137], v[166:169], v[78:81]
	v_mfma_f32_16x16x32_f16 v[70:73], v[142:145], v[166:169], v[70:73]
	s_barrier
	s_setprio 0
	ds_read_b128 v[186:189], v212 offset:49152
	ds_read_b128 v[190:193], v212 offset:50176
	ds_read_b128 v[178:181], v212 offset:51200
	ds_read_b128 v[182:185], v212 offset:52224
	ds_read_b128 v[170:173], v212 offset:53248
	ds_read_b128 v[174:177], v212 offset:54272
	ds_read_b128 v[162:165], v212 offset:55296
	ds_read_b128 v[166:169], v212 offset:56320
	s_and_b64 vcc, exec, s[6:7]
	s_cbranch_vccnz .LBB0_842
	s_add_u32 s6, s24, 0x80
	s_addc_u32 s7, s25, 0
	s_add_u32 s24, s8, 0x80
	s_addc_u32 s25, s9, 0
	s_add_u32 m0, s14, 0x18000
	s_nop 0
	global_load_lds_dwordx4 v207, s[24:25]
	s_nop 0
	s_add_u32 m0, s14, 0x1a000
	s_nop 0
	global_load_lds_dwordx4 v209, s[24:25]
	s_add_u32 s8, s8, 0x40080
	s_addc_u32 s9, s9, 0
	s_add_u32 m0, s14, 0x1c000
	s_nop 0
	global_load_lds_dwordx4 v207, s[8:9]
	s_nop 0
	s_add_u32 m0, s14, 0x1e000
	s_nop 0
	global_load_lds_dwordx4 v209, s[8:9]
	s_nop 0
	s_add_u32 m0, s14, 0x8000
	s_nop 0
	global_load_lds_dwordx4 v206, s[6:7]
	s_nop 0
	s_add_u32 m0, s14, 0xa000
	s_nop 0
	global_load_lds_dwordx4 v208, s[6:7]
	s_waitcnt vmcnt(8)
	s_branch .LBB0_842

; #define PG8_STAGE(bufoff, gbase, voff) do { if constexpr (ABL & 1) break; glds16s<(bufoff)>((voff)[0], (const void*)(gbase), ldsbw); glds16s<(bufoff) + 8192>((voff)[1], (const void*)(gbase), ldsbw); } while (0)
; #define PG8_LDA(dst, b, h) do { if constexpr (ABL & 4) break; _Pragma("unroll") for (int m = 0; m < 4; ++m) _Pragma("unroll") for (int k = 0; k < 2; ++k) dst[m][k] = *(const LAS f16x8*)(lds + PG8_SA(b, h) + aoff + m * 2048 + k * 1024); } while (0)
; #define PG8_LDB(dst, b, h) do { if constexpr (ABL & 4) break; _Pragma("unroll") for (int n = 0; n < 2; ++n) _Pragma("unroll") for (int k = 0; k < 2; ++k) dst[n][k] = *(const LAS f16x8*)(lds + PG8_SB(b, h) + boff + n * 2048 + k * 1024); } while (0)
; #define PG8_MMAF(ai, bj, At, Bt) do { if (t == 0) PG8_MMA0(ai, bj, At, Bt); else PG8_MMA(ai, bj, At, Bt); } while (0)
; #define PG8_WAIT_V(n) asm volatile("s_waitcnt vmcnt(" #n ")" ::: "memory")
; #define PG8_WAIT_L(n) asm volatile("s_waitcnt lgkmcnt(" #n ")" ::: "memory")
; #define PG8_BAR __builtin_amdgcn_s_barrier()
; #define PG8_SCHED __builtin_amdgcn_sched_barrier(0)
;     ...
;         const char* nA = has_next ? (const char*)g.A + (size_t)nxt.pm * tstep : cA; const char* nB = has_next ? (const char*)g.Bt + (size_t)nxt.pn * tstep : cB;
;         for (int t = 0; t < nt; t += 2) {
;             const bool last = (t == nt - 2);
;             const char* a1 = cA + (size_t)(t + 1) * kstep;
;             const char* a2 = last ? nA : cA + (size_t)(t + 2) * kstep; const char* b2 = last ? nB : cB + (size_t)(t + 2) * kstep;
;             const char* a3 = a2 + kstep; const char* b3 = b2 + kstep;
;             if (last && has_next) S.a_ready(nxt);
;             if constexpr (SP2) {
;             PG8_LDB(B0, 0, 0); PG8_LDB(B1, 0, 1); PG8_SCHED; PG8_LDA(At, 0, 0); PG8_STAGE(PG8_SA(1, 1), a1 + hstep, voffA);
;             PG8_WAIT_V(8); PG8_WAIT_L(0); PG8_BAR; PG8_MMAF(0, 0, At, B0); PG8_MMAF(0, 1, At, B1); PG8_BAR; PG8_SCHED;
;             const bool fin = last && !has_next;
;             PG8_LDA(At, 0, 1); if (!fin) { PG8_STAGE(PG8_SB(0, 0), b2, voffB); PG8_STAGE(PG8_SB(0, 1), b2 + hstep, voffB); PG8_STAGE(PG8_SA(0, 0), a2, voffA); }
;             if (!fin) PG8_WAIT_V(8); else PG8_WAIT_V(2); PG8_WAIT_L(0); PG8_BAR; PG8_MMAF(1, 0, At, B0); PG8_MMAF(1, 1, At, B1); PG8_BAR; PG8_SCHED;
.LBB0_878:
	s_ashr_i32 s45, s44, 31
	s_lshl_b64 s[8:9], s[44:45], 17
	s_add_u32 s48, s86, s8
	ds_read_b128 v[2:5], v1
	ds_read_b128 v[6:9], v1 offset:1024
	ds_read_b128 v[10:13], v1 offset:2048
	ds_read_b128 v[14:17], v1 offset:3072
	ds_read_b128 v[18:21], v234
	ds_read_b128 v[22:25], v234 offset:1024
	ds_read_b128 v[26:29], v234 offset:2048
	ds_read_b128 v[30:33], v234 offset:3072
	s_addc_u32 s49, s87, s9
	s_ashr_i32 s43, s42, 31
	s_lshl_b64 s[8:9], s[42:43], 17
	s_add_u32 s50, s70, s8
	s_addc_u32 s51, s71, s9
	s_add_u32 s26, s52, 0x100
	s_addc_u32 s27, s53, 0
	s_add_u32 s60, s54, 0x100
	s_addc_u32 s61, s55, 0
	s_add_u32 s8, s52, 0x180
	s_addc_u32 s9, s53, 0
	ds_read_b128 v[34:37], v235
	ds_read_b128 v[38:41], v235 offset:1024
	ds_read_b128 v[42:45], v235 offset:2048
	ds_read_b128 v[46:49], v235 offset:3072
	ds_read_b128 v[50:53], v235 offset:4096
	ds_read_b128 v[54:57], v235 offset:5120
	ds_read_b128 v[58:61], v235 offset:6144
	ds_read_b128 v[62:65], v235 offset:7168
	s_add_u32 s24, s54, 0x180
	s_addc_u32 s25, s55, 0
	s_add_u32 s62, s52, 0x10080
	s_addc_u32 s63, s53, 0
	s_add_u32 m0, s14, 0xc000
	s_nop 0
	global_load_lds_dwordx4 v230, s[62:63]
	s_nop 0
	s_add_u32 m0, s14, 0xe000
	s_nop 0
	global_load_lds_dwordx4 v232, s[62:63]
	s_waitcnt vmcnt(8)
	s_waitcnt lgkmcnt(0)
	s_barrier
	v_mfma_f32_16x16x32_f16 v[66:69], v[2:5], v[34:37], 0
	s_setprio 1
	v_mfma_f32_16x16x32_f16 v[70:73], v[10:13], v[34:37], 0
	s_waitcnt lgkmcnt(3)
	v_mfma_f32_16x16x32_f16 v[82:85], v[2:5], v[50:53], 0
	v_mfma_f32_16x16x32_f16 v[86:89], v[10:13], v[50:53], 0
	s_waitcnt lgkmcnt(1)
	v_mfma_f32_16x16x32_f16 v[90:93], v[2:5], v[58:61], 0
	v_mfma_f32_16x16x32_f16 v[94:97], v[10:13], v[58:61], 0
	v_mfma_f32_16x16x32_f16 v[66:69], v[6:9], v[38:41], v[66:69]
	v_mfma_f32_16x16x32_f16 v[70:73], v[14:17], v[38:41], v[70:73]
	v_mfma_f32_16x16x32_f16 v[74:77], v[2:5], v[42:45], 0
	v_mfma_f32_16x16x32_f16 v[78:81], v[10:13], v[42:45], 0
	v_mfma_f32_16x16x32_f16 v[82:85], v[6:9], v[54:57], v[82:85]
	v_mfma_f32_16x16x32_f16 v[86:89], v[14:17], v[54:57], v[86:89]
	s_waitcnt lgkmcnt(0)
	v_mfma_f32_16x16x32_f16 v[90:93], v[6:9], v[62:65], v[90:93]
	v_mfma_f32_16x16x32_f16 v[94:97], v[14:17], v[62:65], v[94:97]
	v_mfma_f32_16x16x32_f16 v[74:77], v[6:9], v[46:49], v[74:77]
	v_mfma_f32_16x16x32_f16 v[78:81], v[14:17], v[46:49], v[78:81]
	v_mfma_f32_16x16x32_f16 v[98:101], v[18:21], v[34:37], 0
	v_mfma_f32_16x16x32_f16 v[34:37], v[26:29], v[34:37], 0
	v_mfma_f32_16x16x32_f16 v[98:101], v[22:25], v[38:41], v[98:101]
	v_mfma_f32_16x16x32_f16 v[34:37], v[30:33], v[38:41], v[34:37]
	v_mfma_f32_16x16x32_f16 v[38:41], v[18:21], v[42:45], 0
	v_mfma_f32_16x16x32_f16 v[42:45], v[26:29], v[42:45], 0
	v_mfma_f32_16x16x32_f16 v[38:41], v[22:25], v[46:49], v[38:41]
	v_mfma_f32_16x16x32_f16 v[42:45], v[30:33], v[46:49], v[42:45]
	v_mfma_f32_16x16x32_f16 v[46:49], v[18:21], v[50:53], 0
	v_mfma_f32_16x16x32_f16 v[50:53], v[26:29], v[50:53], 0
	v_mfma_f32_16x16x32_f16 v[46:49], v[22:25], v[54:57], v[46:49]
	v_mfma_f32_16x16x32_f16 v[50:53], v[30:33], v[54:57], v[50:53]
	v_mfma_f32_16x16x32_f16 v[54:57], v[18:21], v[58:61], 0
	v_mfma_f32_16x16x32_f16 v[58:61], v[26:29], v[58:61], 0
	v_mfma_f32_16x16x32_f16 v[54:57], v[22:25], v[62:65], v[54:57]
	v_mfma_f32_16x16x32_f16 v[58:61], v[30:33], v[62:65], v[58:61]
	s_barrier
	s_setprio 0
	ds_read_b128 v[62:65], v235 offset:16384
	ds_read_b128 v[102:105], v235 offset:17408
	ds_read_b128 v[106:109], v235 offset:18432
	ds_read_b128 v[110:113], v235 offset:19456
	ds_read_b128 v[114:117], v235 offset:20480
	ds_read_b128 v[118:121], v235 offset:21504
	ds_read_b128 v[122:125], v235 offset:22528
	ds_read_b128 v[126:129], v235 offset:23552
	s_add_u32 m0, s14, 0x10000
	s_nop 0
	global_load_lds_dwordx4 v231, s[60:61]
	s_nop 0
	s_add_u32 m0, s14, 0x12000
	s_nop 0
	global_load_lds_dwordx4 v233, s[60:61]
	s_add_u32 s60, s54, 0x10100
	s_addc_u32 s61, s55, 0
	s_add_u32 m0, s14, 0x14000
	s_nop 0
	global_load_lds_dwordx4 v231, s[60:61]
	s_nop 0
	s_add_u32 m0, s14, 0x16000
	s_nop 0
	global_load_lds_dwordx4 v233, s[60:61]
	s_nop 0
	s_add_u32 m0, s14, 0
	s_nop 0
	global_load_lds_dwordx4 v230, s[26:27]
	s_nop 0
	s_add_u32 m0, s14, 0x2000
	s_nop 0
	global_load_lds_dwordx4 v232, s[26:27]
	s_waitcnt vmcnt(8)
	s_waitcnt lgkmcnt(0)
	s_barrier
	v_mfma_f32_16x16x32_f16 v[130:133], v[2:5], v[62:65], 0
	s_setprio 1
	s_waitcnt lgkmcnt(5)
	v_mfma_f32_16x16x32_f16 v[138:141], v[2:5], v[106:109], 0
	s_waitcnt lgkmcnt(3)
	v_mfma_f32_16x16x32_f16 v[146:149], v[2:5], v[114:117], 0
	s_waitcnt lgkmcnt(1)
	v_mfma_f32_16x16x32_f16 v[2:5], v[2:5], v[122:125], 0
	v_mfma_f32_16x16x32_f16 v[130:133], v[6:9], v[102:105], v[130:133]
	v_mfma_f32_16x16x32_f16 v[134:137], v[10:13], v[62:65], 0
	v_mfma_f32_16x16x32_f16 v[138:141], v[6:9], v[110:113], v[138:141]
	v_mfma_f32_16x16x32_f16 v[142:145], v[10:13], v[106:109], 0
	v_mfma_f32_16x16x32_f16 v[146:149], v[6:9], v[118:121], v[146:149]
	v_mfma_f32_16x16x32_f16 v[150:153], v[10:13], v[114:117], 0
	s_waitcnt lgkmcnt(0)
	v_mfma_f32_16x16x32_f16 v[2:5], v[6:9], v[126:129], v[2:5]
	v_mfma_f32_16x16x32_f16 v[6:9], v[10:13], v[122:125], 0
	v_mfma_f32_16x16x32_f16 v[134:137], v[14:17], v[102:105], v[134:137]
	v_mfma_f32_16x16x32_f16 v[142:145], v[14:17], v[110:113], v[142:145]
	v_mfma_f32_16x16x32_f16 v[150:153], v[14:17], v[118:121], v[150:153]
	v_mfma_f32_16x16x32_f16 v[6:9], v[14:17], v[126:129], v[6:9]
	v_mfma_f32_16x16x32_f16 v[10:13], v[18:21], v[62:65], 0
	v_mfma_f32_16x16x32_f16 v[14:17], v[26:29], v[62:65], 0
	v_mfma_f32_16x16x32_f16 v[10:13], v[22:25], v[102:105], v[10:13]
	v_mfma_f32_16x16x32_f16 v[14:17], v[30:33], v[102:105], v[14:17]
	v_mfma_f32_16x16x32_f16 v[102:105], v[26:29], v[106:109], 0
	v_mfma_f32_16x16x32_f16 v[62:65], v[18:21], v[106:109], 0
	v_mfma_f32_16x16x32_f16 v[154:157], v[30:33], v[110:113], v[102:105]
	v_mfma_f32_16x16x32_f16 v[102:105], v[18:21], v[114:117], 0
	v_mfma_f32_16x16x32_f16 v[18:21], v[18:21], v[122:125], 0
	v_mfma_f32_16x16x32_f16 v[62:65], v[22:25], v[110:113], v[62:65]
	v_mfma_f32_16x16x32_f16 v[158:161], v[22:25], v[118:121], v[102:105]
	v_mfma_f32_16x16x32_f16 v[102:105], v[26:29], v[114:117], 0
	v_mfma_f32_16x16x32_f16 v[18:21], v[22:25], v[126:129], v[18:21]
	v_mfma_f32_16x16x32_f16 v[22:25], v[26:29], v[122:125], 0
	v_mfma_f32_16x16x32_f16 v[162:165], v[30:33], v[118:121], v[102:105]
	v_mfma_f32_16x16x32_f16 v[22:25], v[30:33], v[126:129], v[22:25]
	s_barrier
; #define PG8_STAGE(bufoff, gbase, voff) do { if constexpr (ABL & 1) break; glds16s<(bufoff)>((voff)[0], (const void*)(gbase), ldsbw); glds16s<(bufoff) + 8192>((voff)[1], (const void*)(gbase), ldsbw); } while (0)
; #define PG8_LDA(dst, b, h) do { if constexpr (ABL & 4) break; _Pragma("unroll") for (int m = 0; m < 4; ++m) _Pragma("unroll") for (int k = 0; k < 2; ++k) dst[m][k] = *(const LAS f16x8*)(lds + PG8_SA(b, h) + aoff + m * 2048 + k * 1024); } while (0)
; #define PG8_LDB(dst, b, h) do { if constexpr (ABL & 4) break; _Pragma("unroll") for (int n = 0; n < 2; ++n) _Pragma("unroll") for (int k = 0; k < 2; ++k) dst[n][k] = *(const LAS f16x8*)(lds + PG8_SB(b, h) + boff + n * 2048 + k * 1024); } while (0)
; #define PG8_MMA(ai, bj, At, Bt) do { if constexpr (ABL & 2) break; __builtin_amdgcn_s_setprio(1); _Pragma("unroll") for (int m = 0; m < 4; ++m) _Pragma("unroll") for (int n = 0; n < 2; ++n) _Pragma("unroll") for (int k = 0; k < 2; ++k) \
;         acc[ai][bj][m][n] = __builtin_amdgcn_mfma_f32_16x16x32_f16(Bt[n][k], At[m][k], acc[ai][bj][m][n], 0, 0, 0); __builtin_amdgcn_s_setprio(0); } while (0)
; #define PG8_MMAF(ai, bj, At, Bt) do { if (t == 0) PG8_MMA0(ai, bj, At, Bt); else PG8_MMA(ai, bj, At, Bt); } while (0)
; #define PG8_WAIT_V(n) asm volatile("s_waitcnt vmcnt(" #n ")" ::: "memory")
; #define PG8_WAIT_L(n) asm volatile("s_waitcnt lgkmcnt(" #n ")" ::: "memory")
; #define PG8_BAR __builtin_amdgcn_s_barrier()
; #define PG8_SCHED __builtin_amdgcn_sched_barrier(0)
;     ...
;             if (!fin) PG8_WAIT_V(8); else PG8_WAIT_V(2); PG8_WAIT_L(0); PG8_BAR; PG8_MMAF(1, 0, At, B0); PG8_MMAF(1, 1, At, B1); PG8_BAR; PG8_SCHED;
;             PG8_LDB(B0, 1, 0); PG8_LDB(B1, 1, 1); PG8_SCHED; PG8_LDA(At, 1, 0); if (!fin) PG8_STAGE(PG8_SA(0, 1), a2 + hstep, voffA);
;             if (!fin) PG8_WAIT_V(8); else PG8_WAIT_V(0); PG8_WAIT_L(0); PG8_BAR; PG8_MMA(0, 0, At, B0); PG8_MMA(0, 1, At, B1); PG8_BAR; PG8_SCHED;
;             PG8_LDA(At, 1, 1); if (!fin) { PG8_STAGE(PG8_SB(1, 0), b3, voffB); PG8_STAGE(PG8_SB(1, 1), b3 + hstep, voffB); PG8_STAGE(PG8_SA(1, 0), a3, voffA); }
;             if (!fin) PG8_WAIT_V(8); PG8_WAIT_L(0); PG8_BAR; PG8_MMA(1, 0, At, B0); PG8_MMA(1, 1, At, B1); PG8_BAR; PG8_SCHED;
	s_setprio 0
	ds_read_b128 v[26:29], v236
	ds_read_b128 v[30:33], v236 offset:1024
	ds_read_b128 v[102:105], v236 offset:2048
	ds_read_b128 v[106:109], v236 offset:3072
	ds_read_b128 v[166:169], v237
	ds_read_b128 v[170:173], v237 offset:1024
	ds_read_b128 v[174:177], v237 offset:2048
	ds_read_b128 v[178:181], v237 offset:3072
	ds_read_b128 v[110:113], v235 offset:32768
	ds_read_b128 v[114:117], v235 offset:33792
	ds_read_b128 v[118:121], v235 offset:34816
	ds_read_b128 v[122:125], v235 offset:35840
	ds_read_b128 v[126:129], v235 offset:36864
	ds_read_b128 v[182:185], v235 offset:37888
	ds_read_b128 v[186:189], v235 offset:38912
	ds_read_b128 v[190:193], v235 offset:39936
	s_add_u32 s26, s52, 0x10100
	s_addc_u32 s27, s53, 0
	s_add_u32 m0, s14, 0x4000
	s_nop 0
	global_load_lds_dwordx4 v230, s[26:27]
	s_nop 0
	s_add_u32 m0, s14, 0x6000
	s_nop 0
	global_load_lds_dwordx4 v232, s[26:27]
	s_waitcnt vmcnt(8)
	s_waitcnt lgkmcnt(0)
	s_barrier
	v_mfma_f32_16x16x32_f16 v[82:85], v[26:29], v[126:129], v[82:85]
	s_setprio 1
	s_waitcnt lgkmcnt(2)
	v_mfma_f32_16x16x32_f16 v[194:197], v[30:33], v[182:185], v[82:85]
	v_mfma_f32_16x16x32_f16 v[82:85], v[102:105], v[126:129], v[86:89]
	v_mfma_f32_16x16x32_f16 v[66:69], v[26:29], v[110:113], v[66:69]
	v_mfma_f32_16x16x32_f16 v[70:73], v[102:105], v[110:113], v[70:73]
	v_mfma_f32_16x16x32_f16 v[198:201], v[106:109], v[182:185], v[82:85]
	s_waitcnt lgkmcnt(1)
	v_mfma_f32_16x16x32_f16 v[82:85], v[26:29], v[186:189], v[90:93]
	v_mfma_f32_16x16x32_f16 v[66:69], v[30:33], v[114:117], v[66:69]
	v_mfma_f32_16x16x32_f16 v[70:73], v[106:109], v[114:117], v[70:73]
	v_mfma_f32_16x16x32_f16 v[74:77], v[26:29], v[118:121], v[74:77]
	v_mfma_f32_16x16x32_f16 v[78:81], v[102:105], v[118:121], v[78:81]
	s_waitcnt lgkmcnt(0)
	v_mfma_f32_16x16x32_f16 v[202:205], v[30:33], v[190:193], v[82:85]
	v_mfma_f32_16x16x32_f16 v[82:85], v[102:105], v[186:189], v[94:97]
	v_mfma_f32_16x16x32_f16 v[74:77], v[30:33], v[122:125], v[74:77]
	v_mfma_f32_16x16x32_f16 v[78:81], v[106:109], v[122:125], v[78:81]
	v_mfma_f32_16x16x32_f16 v[206:209], v[106:109], v[190:193], v[82:85]
	v_mfma_f32_16x16x32_f16 v[34:37], v[174:177], v[110:113], v[34:37]
	v_mfma_f32_16x16x32_f16 v[214:217], v[178:181], v[114:117], v[34:37]
	v_mfma_f32_16x16x32_f16 v[34:37], v[166:169], v[118:121], v[38:41]
	v_mfma_f32_16x16x32_f16 v[218:221], v[170:173], v[122:125], v[34:37]
	v_mfma_f32_16x16x32_f16 v[34:37], v[174:177], v[118:121], v[42:45]
	v_mfma_f32_16x16x32_f16 v[222:225], v[178:181], v[122:125], v[34:37]
	v_mfma_f32_16x16x32_f16 v[34:37], v[166:169], v[126:129], v[46:49]
	v_mfma_f32_16x16x32_f16 v[238:241], v[170:173], v[182:185], v[34:37]
	v_mfma_f32_16x16x32_f16 v[34:37], v[174:177], v[126:129], v[50:53]
	v_mfma_f32_16x16x32_f16 v[182:185], v[178:181], v[182:185], v[34:37]
	v_mfma_f32_16x16x32_f16 v[34:37], v[166:169], v[186:189], v[54:57]
	v_mfma_f32_16x16x32_f16 v[242:245], v[170:173], v[190:193], v[34:37]
	v_mfma_f32_16x16x32_f16 v[34:37], v[174:177], v[186:189], v[58:61]
	v_mfma_f32_16x16x32_f16 v[82:85], v[166:169], v[110:113], v[98:101]
	v_mfma_f32_16x16x32_f16 v[186:189], v[178:181], v[190:193], v[34:37]
	v_mfma_f32_16x16x32_f16 v[210:213], v[170:173], v[114:117], v[82:85]
	s_barrier
	s_setprio 0
	ds_read_b128 v[42:45], v235 offset:49152
	ds_read_b128 v[46:49], v235 offset:50176
	ds_read_b128 v[50:53], v235 offset:51200
	ds_read_b128 v[54:57], v235 offset:52224
	ds_read_b128 v[58:61], v235 offset:53248
	ds_read_b128 v[126:129], v235 offset:54272
	ds_read_b128 v[190:193], v235 offset:55296
	ds_read_b128 v[246:249], v235 offset:56320
	s_add_u32 m0, s14, 0x18000
	s_nop 0
	global_load_lds_dwordx4 v231, s[24:25]
	s_nop 0
	s_add_u32 m0, s14, 0x1a000
	s_nop 0
	global_load_lds_dwordx4 v233, s[24:25]
	s_add_u32 s24, s54, 0x10180
	s_addc_u32 s25, s55, 0
	s_add_u32 m0, s14, 0x1c000
	s_nop 0
	global_load_lds_dwordx4 v231, s[24:25]
	s_nop 0
	s_add_u32 m0, s14, 0x1e000
	s_nop 0
	global_load_lds_dwordx4 v233, s[24:25]
	s_nop 0
	s_add_u32 m0, s14, 0x8000
	s_nop 0
	global_load_lds_dwordx4 v230, s[8:9]
	s_nop 0
	s_add_u32 m0, s14, 0xa000
	s_nop 0
	global_load_lds_dwordx4 v232, s[8:9]
	s_waitcnt vmcnt(8)
	s_waitcnt lgkmcnt(0)
	s_barrier
; #define PG8_STAGE(bufoff, gbase, voff) do { if constexpr (ABL & 1) break; glds16s<(bufoff)>((voff)[0], (const void*)(gbase), ldsbw); glds16s<(bufoff) + 8192>((voff)[1], (const void*)(gbase), ldsbw); } while (0)
; #define PG8_LDA(dst, b, h) do { if constexpr (ABL & 4) break; _Pragma("unroll") for (int m = 0; m < 4; ++m) _Pragma("unroll") for (int k = 0; k < 2; ++k) dst[m][k] = *(const LAS f16x8*)(lds + PG8_SA(b, h) + aoff + m * 2048 + k * 1024); } while (0)
; #define PG8_LDB(dst, b, h) do { if constexpr (ABL & 4) break; _Pragma("unroll") for (int n = 0; n < 2; ++n) _Pragma("unroll") for (int k = 0; k < 2; ++k) dst[n][k] = *(const LAS f16x8*)(lds + PG8_SB(b, h) + boff + n * 2048 + k * 1024); } while (0)
; #define PG8_MMA(ai, bj, At, Bt) do { if constexpr (ABL & 2) break; __builtin_amdgcn_s_setprio(1); _Pragma("unroll") for (int m = 0; m < 4; ++m) _Pragma("unroll") for (int n = 0; n < 2; ++n) _Pragma("unroll") for (int k = 0; k < 2; ++k) \
;         acc[ai][bj][m][n] = __builtin_amdgcn_mfma_f32_16x16x32_f16(Bt[n][k], At[m][k], acc[ai][bj][m][n], 0, 0, 0); __builtin_amdgcn_s_setprio(0); } while (0)
; #define PG8_WAIT_V(n) asm volatile("s_waitcnt vmcnt(" #n ")" ::: "memory")
;     ...
;             PG8_LDB(B0, 0, 0); PG8_LDB(B1, 0, 1); PG8_SCHED; PG8_LDA(At, 0, 0); PG8_STAGE(PG8_SA(1, 1), a1 + hstep, voffA);
;             PG8_WAIT_V(8); PG8_WAIT_L(0); PG8_BAR; PG8_MMAF(0, 0, At, B0); PG8_MMAF(0, 1, At, B1); PG8_BAR; PG8_SCHED;
;             const bool fin = last && !has_next;
;             PG8_LDA(At, 0, 1); if (!fin) { PG8_STAGE(PG8_SB(0, 0), b2, voffB); PG8_STAGE(PG8_SB(0, 1), b2 + hstep, voffB); PG8_STAGE(PG8_SA(0, 0), a2, voffA); }
;             if (!fin) PG8_WAIT_V(8); else PG8_WAIT_V(2); PG8_WAIT_L(0); PG8_BAR; PG8_MMAF(1, 0, At, B0); PG8_MMAF(1, 1, At, B1); PG8_BAR; PG8_SCHED;
;             PG8_LDB(B0, 1, 0); PG8_LDB(B1, 1, 1); PG8_SCHED; PG8_LDA(At, 1, 0); if (!fin) PG8_STAGE(PG8_SA(0, 1), a2 + hstep, voffA);
;             if (!fin) PG8_WAIT_V(8); else PG8_WAIT_V(0); PG8_WAIT_L(0); PG8_BAR; PG8_MMA(0, 0, At, B0); PG8_MMA(0, 1, At, B1); PG8_BAR; PG8_SCHED;
;             PG8_LDA(At, 1, 1); if (!fin) { PG8_STAGE(PG8_SB(1, 0), b3, voffB); PG8_STAGE(PG8_SB(1, 1), b3 + hstep, voffB); PG8_STAGE(PG8_SA(1, 0), a3, voffA); }
;             if (!fin) PG8_WAIT_V(8); PG8_WAIT_L(0); PG8_BAR; PG8_MMA(1, 0, At, B0); PG8_MMA(1, 1, At, B1); PG8_BAR; PG8_SCHED;
	v_mfma_f32_16x16x32_f16 v[2:5], v[26:29], v[190:193], v[2:5]
	s_setprio 1
	v_mfma_f32_16x16x32_f16 v[34:37], v[26:29], v[42:45], v[130:133]
	v_mfma_f32_16x16x32_f16 v[38:41], v[102:105], v[42:45], v[134:137]
	v_mfma_f32_16x16x32_f16 v[82:85], v[26:29], v[50:53], v[138:141]
	v_mfma_f32_16x16x32_f16 v[86:89], v[102:105], v[50:53], v[142:145]
	v_mfma_f32_16x16x32_f16 v[90:93], v[26:29], v[58:61], v[146:149]
	v_mfma_f32_16x16x32_f16 v[94:97], v[102:105], v[58:61], v[150:153]
	s_waitcnt lgkmcnt(0)
	v_mfma_f32_16x16x32_f16 v[98:101], v[30:33], v[246:249], v[2:5]
	v_mfma_f32_16x16x32_f16 v[2:5], v[102:105], v[190:193], v[6:9]
	v_mfma_f32_16x16x32_f16 v[34:37], v[30:33], v[46:49], v[34:37]
	v_mfma_f32_16x16x32_f16 v[38:41], v[106:109], v[46:49], v[38:41]
	v_mfma_f32_16x16x32_f16 v[82:85], v[30:33], v[54:57], v[82:85]
	v_mfma_f32_16x16x32_f16 v[86:89], v[106:109], v[54:57], v[86:89]
	v_mfma_f32_16x16x32_f16 v[90:93], v[30:33], v[126:129], v[90:93]
	v_mfma_f32_16x16x32_f16 v[94:97], v[106:109], v[126:129], v[94:97]
	v_mfma_f32_16x16x32_f16 v[102:105], v[106:109], v[246:249], v[2:5]
	v_mfma_f32_16x16x32_f16 v[2:5], v[166:169], v[42:45], v[10:13]
	v_mfma_f32_16x16x32_f16 v[106:109], v[170:173], v[46:49], v[2:5]
	v_mfma_f32_16x16x32_f16 v[2:5], v[174:177], v[42:45], v[14:17]
	v_mfma_f32_16x16x32_f16 v[110:113], v[178:181], v[46:49], v[2:5]
	v_mfma_f32_16x16x32_f16 v[2:5], v[166:169], v[50:53], v[62:65]
	v_mfma_f32_16x16x32_f16 v[114:117], v[170:173], v[54:57], v[2:5]
	v_mfma_f32_16x16x32_f16 v[2:5], v[174:177], v[50:53], v[154:157]
	v_mfma_f32_16x16x32_f16 v[118:121], v[178:181], v[54:57], v[2:5]
	v_mfma_f32_16x16x32_f16 v[2:5], v[166:169], v[58:61], v[158:161]
	v_mfma_f32_16x16x32_f16 v[122:125], v[170:173], v[126:129], v[2:5]
	v_mfma_f32_16x16x32_f16 v[2:5], v[174:177], v[58:61], v[162:165]
	v_mfma_f32_16x16x32_f16 v[126:129], v[178:181], v[126:129], v[2:5]
	v_mfma_f32_16x16x32_f16 v[2:5], v[166:169], v[190:193], v[18:21]
	v_mfma_f32_16x16x32_f16 v[130:133], v[170:173], v[246:249], v[2:5]
	v_mfma_f32_16x16x32_f16 v[2:5], v[174:177], v[190:193], v[22:25]
	v_mfma_f32_16x16x32_f16 v[134:137], v[178:181], v[246:249], v[2:5]
	s_barrier
	s_setprio 0
	ds_read_b128 v[154:157], v1
	ds_read_b128 v[158:161], v1 offset:1024
	ds_read_b128 v[162:165], v1 offset:2048
	ds_read_b128 v[166:169], v1 offset:3072
	ds_read_b128 v[138:141], v234
	ds_read_b128 v[142:145], v234 offset:1024
	ds_read_b128 v[146:149], v234 offset:2048
	ds_read_b128 v[150:153], v234 offset:3072
	ds_read_b128 v[46:49], v235
	ds_read_b128 v[50:53], v235 offset:1024
	ds_read_b128 v[54:57], v235 offset:2048
	ds_read_b128 v[58:61], v235 offset:3072
	ds_read_b128 v[62:65], v235 offset:4096
	ds_read_b128 v[170:173], v235 offset:5120
	ds_read_b128 v[174:177], v235 offset:6144
	ds_read_b128 v[178:181], v235 offset:7168
	s_add_u32 s8, s52, 0x10180
	s_addc_u32 s9, s53, 0
	s_add_u32 m0, s14, 0xc000
	s_nop 0
	global_load_lds_dwordx4 v230, s[8:9]
	s_nop 0
	s_add_u32 m0, s14, 0xe000
	s_nop 0
	global_load_lds_dwordx4 v232, s[8:9]
	s_waitcnt vmcnt(8)
	s_waitcnt lgkmcnt(0)
	s_barrier
	v_mfma_f32_16x16x32_f16 v[2:5], v[154:157], v[46:49], v[66:69]
	s_setprio 1
	v_mfma_f32_16x16x32_f16 v[6:9], v[162:165], v[46:49], v[70:73]
	s_waitcnt lgkmcnt(5)
	v_mfma_f32_16x16x32_f16 v[10:13], v[154:157], v[54:57], v[74:77]
	v_mfma_f32_16x16x32_f16 v[14:17], v[162:165], v[54:57], v[78:81]
	s_waitcnt lgkmcnt(3)
	v_mfma_f32_16x16x32_f16 v[18:21], v[154:157], v[62:65], v[194:197]
	v_mfma_f32_16x16x32_f16 v[22:25], v[162:165], v[62:65], v[198:201]
	s_waitcnt lgkmcnt(1)
	v_mfma_f32_16x16x32_f16 v[26:29], v[154:157], v[174:177], v[202:205]
	v_mfma_f32_16x16x32_f16 v[30:33], v[162:165], v[174:177], v[206:209]
	v_mfma_f32_16x16x32_f16 v[2:5], v[158:161], v[50:53], v[2:5]
	v_mfma_f32_16x16x32_f16 v[6:9], v[166:169], v[50:53], v[6:9]
	v_mfma_f32_16x16x32_f16 v[10:13], v[158:161], v[58:61], v[10:13]
	v_mfma_f32_16x16x32_f16 v[14:17], v[166:169], v[58:61], v[14:17]
	v_mfma_f32_16x16x32_f16 v[18:21], v[158:161], v[170:173], v[18:21]
	v_mfma_f32_16x16x32_f16 v[22:25], v[166:169], v[170:173], v[22:25]
	s_waitcnt lgkmcnt(0)
	v_mfma_f32_16x16x32_f16 v[26:29], v[158:161], v[178:181], v[26:29]
	v_mfma_f32_16x16x32_f16 v[30:33], v[166:169], v[178:181], v[30:33]
	v_mfma_f32_16x16x32_f16 v[42:45], v[138:141], v[46:49], v[210:213]
	v_mfma_f32_16x16x32_f16 v[46:49], v[146:149], v[46:49], v[214:217]
	v_mfma_f32_16x16x32_f16 v[42:45], v[142:145], v[50:53], v[42:45]
	v_mfma_f32_16x16x32_f16 v[46:49], v[150:153], v[50:53], v[46:49]
	v_mfma_f32_16x16x32_f16 v[50:53], v[138:141], v[54:57], v[218:221]
	v_mfma_f32_16x16x32_f16 v[54:57], v[146:149], v[54:57], v[222:225]
	v_mfma_f32_16x16x32_f16 v[50:53], v[142:145], v[58:61], v[50:53]
	v_mfma_f32_16x16x32_f16 v[54:57], v[150:153], v[58:61], v[54:57]
	v_mfma_f32_16x16x32_f16 v[58:61], v[138:141], v[62:65], v[238:241]
	v_mfma_f32_16x16x32_f16 v[62:65], v[146:149], v[62:65], v[182:185]
	v_mfma_f32_16x16x32_f16 v[66:69], v[138:141], v[174:177], v[242:245]
	v_mfma_f32_16x16x32_f16 v[70:73], v[146:149], v[174:177], v[186:189]
	v_mfma_f32_16x16x32_f16 v[58:61], v[142:145], v[170:173], v[58:61]
	v_mfma_f32_16x16x32_f16 v[62:65], v[150:153], v[170:173], v[62:65]
	v_mfma_f32_16x16x32_f16 v[66:69], v[142:145], v[178:181], v[66:69]
	v_mfma_f32_16x16x32_f16 v[70:73], v[150:153], v[178:181], v[70:73]
	s_barrier
	s_setprio 0
	ds_read_b128 v[194:197], v235 offset:16384
	ds_read_b128 v[198:201], v235 offset:17408
	ds_read_b128 v[186:189], v235 offset:18432
	ds_read_b128 v[190:193], v235 offset:19456
	ds_read_b128 v[178:181], v235 offset:20480
	ds_read_b128 v[182:185], v235 offset:21504
	ds_read_b128 v[170:173], v235 offset:22528
	ds_read_b128 v[174:177], v235 offset:23552
	s_mov_b64 s[8:9], -1
	s_and_b64 vcc, exec, s[4:5]
	s_cbranch_vccz .LBB0_880
	s_waitcnt vmcnt(2)
	s_mov_b64 s[8:9], 0

; #define PG8_STAGE(bufoff, gbase, voff) do { if constexpr (ABL & 1) break; glds16s<(bufoff)>((voff)[0], (const void*)(gbase), ldsbw); glds16s<(bufoff) + 8192>((voff)[1], (const void*)(gbase), ldsbw); } while (0)
; #define PG8_LDA(dst, b, h) do { if constexpr (ABL & 4) break; _Pragma("unroll") for (int m = 0; m < 4; ++m) _Pragma("unroll") for (int k = 0; k < 2; ++k) dst[m][k] = *(const LAS f16x8*)(lds + PG8_SA(b, h) + aoff + m * 2048 + k * 1024); } while (0)
; #define PG8_LDB(dst, b, h) do { if constexpr (ABL & 4) break; _Pragma("unroll") for (int n = 0; n < 2; ++n) _Pragma("unroll") for (int k = 0; k < 2; ++k) dst[n][k] = *(const LAS f16x8*)(lds + PG8_SB(b, h) + boff + n * 2048 + k * 1024); } while (0)
; #define PG8_MMAF(ai, bj, At, Bt) do { if (t == 0) PG8_MMA0(ai, bj, At, Bt); else PG8_MMA(ai, bj, At, Bt); } while (0)
; #define PG8_WAIT_V(n) asm volatile("s_waitcnt vmcnt(" #n ")" ::: "memory")
; #define PG8_WAIT_L(n) asm volatile("s_waitcnt lgkmcnt(" #n ")" ::: "memory")
; #define PG8_BAR __builtin_amdgcn_s_barrier()
; #define PG8_SCHED __builtin_amdgcn_sched_barrier(0)
;     ...
;             if (!fin) PG8_WAIT_V(8); else PG8_WAIT_V(2); PG8_WAIT_L(0); PG8_BAR; PG8_MMAF(1, 0, At, B0); PG8_MMAF(1, 1, At, B1); PG8_BAR; PG8_SCHED;
;             PG8_LDB(B0, 1, 0); PG8_LDB(B1, 1, 1); PG8_SCHED; PG8_LDA(At, 1, 0); if (!fin) PG8_STAGE(PG8_SA(0, 1), a2 + hstep, voffA);
.LBB0_882:
	s_waitcnt lgkmcnt(0)
	s_barrier
	v_mfma_f32_16x16x32_f16 v[34:37], v[154:157], v[194:197], v[34:37]
	s_setprio 1
	s_waitcnt lgkmcnt(6)
	v_mfma_f32_16x16x32_f16 v[74:77], v[158:161], v[198:201], v[34:37]
	v_mfma_f32_16x16x32_f16 v[34:37], v[162:165], v[194:197], v[38:41]
	v_mfma_f32_16x16x32_f16 v[78:81], v[166:169], v[198:201], v[34:37]
	s_waitcnt lgkmcnt(5)
	v_mfma_f32_16x16x32_f16 v[34:37], v[154:157], v[186:189], v[82:85]
	s_waitcnt lgkmcnt(4)
	v_mfma_f32_16x16x32_f16 v[82:85], v[158:161], v[190:193], v[34:37]
	v_mfma_f32_16x16x32_f16 v[34:37], v[162:165], v[186:189], v[86:89]
	v_mfma_f32_16x16x32_f16 v[86:89], v[166:169], v[190:193], v[34:37]
	s_waitcnt lgkmcnt(3)
	v_mfma_f32_16x16x32_f16 v[34:37], v[154:157], v[178:181], v[90:93]
	s_waitcnt lgkmcnt(2)
	v_mfma_f32_16x16x32_f16 v[90:93], v[158:161], v[182:185], v[34:37]
	v_mfma_f32_16x16x32_f16 v[34:37], v[162:165], v[178:181], v[94:97]
	v_mfma_f32_16x16x32_f16 v[94:97], v[166:169], v[182:185], v[34:37]
	s_waitcnt lgkmcnt(1)
	v_mfma_f32_16x16x32_f16 v[34:37], v[154:157], v[170:173], v[98:101]
	s_waitcnt lgkmcnt(0)
	v_mfma_f32_16x16x32_f16 v[98:101], v[158:161], v[174:177], v[34:37]
	v_mfma_f32_16x16x32_f16 v[34:37], v[162:165], v[170:173], v[102:105]
	v_mfma_f32_16x16x32_f16 v[102:105], v[166:169], v[174:177], v[34:37]
	v_mfma_f32_16x16x32_f16 v[34:37], v[138:141], v[194:197], v[106:109]
	v_mfma_f32_16x16x32_f16 v[106:109], v[142:145], v[198:201], v[34:37]
	v_mfma_f32_16x16x32_f16 v[34:37], v[146:149], v[194:197], v[110:113]
	v_mfma_f32_16x16x32_f16 v[110:113], v[150:153], v[198:201], v[34:37]
	v_mfma_f32_16x16x32_f16 v[34:37], v[138:141], v[186:189], v[114:117]
	v_mfma_f32_16x16x32_f16 v[114:117], v[142:145], v[190:193], v[34:37]
	v_mfma_f32_16x16x32_f16 v[34:37], v[146:149], v[186:189], v[118:121]
	v_mfma_f32_16x16x32_f16 v[118:121], v[150:153], v[190:193], v[34:37]
	v_mfma_f32_16x16x32_f16 v[34:37], v[138:141], v[178:181], v[122:125]
	v_mfma_f32_16x16x32_f16 v[122:125], v[142:145], v[182:185], v[34:37]
	v_mfma_f32_16x16x32_f16 v[34:37], v[146:149], v[178:181], v[126:129]
	v_mfma_f32_16x16x32_f16 v[126:129], v[150:153], v[182:185], v[34:37]
	v_mfma_f32_16x16x32_f16 v[34:37], v[138:141], v[170:173], v[130:133]
	v_mfma_f32_16x16x32_f16 v[130:133], v[142:145], v[174:177], v[34:37]
	v_mfma_f32_16x16x32_f16 v[34:37], v[146:149], v[170:173], v[134:137]
	v_mfma_f32_16x16x32_f16 v[134:137], v[150:153], v[174:177], v[34:37]
	s_barrier
	s_setprio 0
	ds_read_b128 v[170:173], v236
	ds_read_b128 v[174:177], v236 offset:1024
	ds_read_b128 v[178:181], v236 offset:2048
	ds_read_b128 v[182:185], v236 offset:3072
	ds_read_b128 v[146:149], v237
	ds_read_b128 v[150:153], v237 offset:1024
	ds_read_b128 v[154:157], v237 offset:2048
	ds_read_b128 v[158:161], v237 offset:3072
	ds_read_b128 v[162:165], v235 offset:32768
	ds_read_b128 v[206:209], v235 offset:33792
	ds_read_b128 v[166:169], v235 offset:34816
	ds_read_b128 v[218:221], v235 offset:35840
	ds_read_b128 v[210:213], v235 offset:36864
	ds_read_b128 v[214:217], v235 offset:37888
	ds_read_b128 v[194:197], v235 offset:38912
	ds_read_b128 v[198:201], v235 offset:39936
	s_mov_b64 s[8:9], -1
	s_and_b64 vcc, exec, s[4:5]
	s_cbranch_vccz .LBB0_884
	s_waitcnt vmcnt(0)
	s_mov_b64 s[8:9], 0

; #define PG8_STAGE(bufoff, gbase, voff) do { if constexpr (ABL & 1) break; glds16s<(bufoff)>((voff)[0], (const void*)(gbase), ldsbw); glds16s<(bufoff) + 8192>((voff)[1], (const void*)(gbase), ldsbw); } while (0)
; #define PG8_LDA(dst, b, h) do { if constexpr (ABL & 4) break; _Pragma("unroll") for (int m = 0; m < 4; ++m) _Pragma("unroll") for (int k = 0; k < 2; ++k) dst[m][k] = *(const LAS f16x8*)(lds + PG8_SA(b, h) + aoff + m * 2048 + k * 1024); } while (0)
; #define PG8_LDB(dst, b, h) do { if constexpr (ABL & 4) break; _Pragma("unroll") for (int n = 0; n < 2; ++n) _Pragma("unroll") for (int k = 0; k < 2; ++k) dst[n][k] = *(const LAS f16x8*)(lds + PG8_SB(b, h) + boff + n * 2048 + k * 1024); } while (0)
; #define PG8_MMA(ai, bj, At, Bt) do { if constexpr (ABL & 2) break; __builtin_amdgcn_s_setprio(1); _Pragma("unroll") for (int m = 0; m < 4; ++m) _Pragma("unroll") for (int n = 0; n < 2; ++n) _Pragma("unroll") for (int k = 0; k < 2; ++k) \
;         acc[ai][bj][m][n] = __builtin_amdgcn_mfma_f32_16x16x32_f16(Bt[n][k], At[m][k], acc[ai][bj][m][n], 0, 0, 0); __builtin_amdgcn_s_setprio(0); } while (0)
; #define PG8_WAIT_V(n) asm volatile("s_waitcnt vmcnt(" #n ")" ::: "memory")
; #define PG8_WAIT_L(n) asm volatile("s_waitcnt lgkmcnt(" #n ")" ::: "memory")
; #define PG8_BAR __builtin_amdgcn_s_barrier()
; #define PG8_SCHED __builtin_amdgcn_sched_barrier(0)
;     ...
;             PG8_LDB(B0, 1, 0); PG8_LDB(B1, 1, 1); PG8_SCHED; PG8_LDA(At, 1, 0); if (!fin) PG8_STAGE(PG8_SA(0, 1), a2 + hstep, voffA);
;             if (!fin) PG8_WAIT_V(8); else PG8_WAIT_V(0); PG8_WAIT_L(0); PG8_BAR; PG8_MMA(0, 0, At, B0); PG8_MMA(0, 1, At, B1); PG8_BAR; PG8_SCHED;
;             PG8_LDA(At, 1, 1); if (!fin) { PG8_STAGE(PG8_SB(1, 0), b3, voffB); PG8_STAGE(PG8_SB(1, 1), b3 + hstep, voffB); PG8_STAGE(PG8_SA(1, 0), a3, voffA); }
;             if (!fin) PG8_WAIT_V(8); PG8_WAIT_L(0); PG8_BAR; PG8_MMA(1, 0, At, B0); PG8_MMA(1, 1, At, B1); PG8_BAR; PG8_SCHED;
;     ...
;         if constexpr (ALIGN_EPI) { if (wr == 0) PG8_BAR; }
.LBB0_886:
	s_waitcnt lgkmcnt(0)
	s_barrier
	v_mfma_f32_16x16x32_f16 v[2:5], v[170:173], v[162:165], v[2:5]
	s_setprio 1
	s_waitcnt lgkmcnt(6)
	v_mfma_f32_16x16x32_f16 v[186:189], v[174:177], v[206:209], v[2:5]
	v_mfma_f32_16x16x32_f16 v[2:5], v[178:181], v[162:165], v[6:9]
	v_mfma_f32_16x16x32_f16 v[190:193], v[182:185], v[206:209], v[2:5]
	s_waitcnt lgkmcnt(5)
	v_mfma_f32_16x16x32_f16 v[2:5], v[170:173], v[166:169], v[10:13]
	s_waitcnt lgkmcnt(4)
	v_mfma_f32_16x16x32_f16 v[138:141], v[174:177], v[218:221], v[2:5]
	v_mfma_f32_16x16x32_f16 v[2:5], v[178:181], v[166:169], v[14:17]
	v_mfma_f32_16x16x32_f16 v[142:145], v[182:185], v[218:221], v[2:5]
	s_waitcnt lgkmcnt(3)
	v_mfma_f32_16x16x32_f16 v[2:5], v[170:173], v[210:213], v[18:21]
	s_waitcnt lgkmcnt(2)
	v_mfma_f32_16x16x32_f16 v[34:37], v[174:177], v[214:217], v[2:5]
	v_mfma_f32_16x16x32_f16 v[2:5], v[178:181], v[210:213], v[22:25]
	v_mfma_f32_16x16x32_f16 v[38:41], v[182:185], v[214:217], v[2:5]
	s_waitcnt lgkmcnt(1)
	v_mfma_f32_16x16x32_f16 v[2:5], v[170:173], v[194:197], v[26:29]
	v_mfma_f32_16x16x32_f16 v[6:9], v[178:181], v[194:197], v[30:33]
	s_waitcnt lgkmcnt(0)
	v_mfma_f32_16x16x32_f16 v[2:5], v[174:177], v[198:201], v[2:5]
	v_mfma_f32_16x16x32_f16 v[6:9], v[182:185], v[198:201], v[6:9]
	v_mfma_f32_16x16x32_f16 v[10:13], v[146:149], v[162:165], v[42:45]
	v_mfma_f32_16x16x32_f16 v[202:205], v[150:153], v[206:209], v[10:13]
	v_mfma_f32_16x16x32_f16 v[10:13], v[154:157], v[162:165], v[46:49]
	v_mfma_f32_16x16x32_f16 v[206:209], v[158:161], v[206:209], v[10:13]
	v_mfma_f32_16x16x32_f16 v[10:13], v[146:149], v[166:169], v[50:53]
	v_mfma_f32_16x16x32_f16 v[162:165], v[150:153], v[218:221], v[10:13]
	v_mfma_f32_16x16x32_f16 v[10:13], v[154:157], v[166:169], v[54:57]
	v_mfma_f32_16x16x32_f16 v[166:169], v[158:161], v[218:221], v[10:13]
	v_mfma_f32_16x16x32_f16 v[10:13], v[146:149], v[210:213], v[58:61]
	v_mfma_f32_16x16x32_f16 v[50:53], v[150:153], v[214:217], v[10:13]
	v_mfma_f32_16x16x32_f16 v[10:13], v[154:157], v[210:213], v[62:65]
	v_mfma_f32_16x16x32_f16 v[54:57], v[158:161], v[214:217], v[10:13]
	v_mfma_f32_16x16x32_f16 v[10:13], v[146:149], v[194:197], v[66:69]
	v_mfma_f32_16x16x32_f16 v[18:21], v[150:153], v[198:201], v[10:13]
	v_mfma_f32_16x16x32_f16 v[10:13], v[154:157], v[194:197], v[70:73]
	v_mfma_f32_16x16x32_f16 v[22:25], v[158:161], v[198:201], v[10:13]
	s_barrier
	s_setprio 0
	ds_read_b128 v[218:221], v235 offset:49152
	ds_read_b128 v[222:225], v235 offset:50176
	ds_read_b128 v[58:61], v235 offset:51200
	ds_read_b128 v[214:217], v235 offset:52224
	ds_read_b128 v[26:29], v235 offset:53248
	ds_read_b128 v[62:65], v235 offset:54272
	ds_read_b128 v[30:33], v235 offset:55296
	ds_read_b128 v[210:213], v235 offset:56320
	v_cndmask_b32_e64 v10, 0, 1, s[2:3]
	v_cmp_ne_u32_e64 s[4:5], 1, v10
	s_andn2_b64 vcc, exec, s[2:3]
	s_cbranch_vccnz .LBB0_888
	s_and_b64 s[2:3], s[2:3], exec
	s_cselect_b32 s2, s48, s52
	s_cselect_b32 s3, s49, s53
	s_cselect_b32 s9, s51, s55
	s_cselect_b32 s8, s50, s54
	s_add_u32 s2, s2, 0x80
	s_addc_u32 s3, s3, 0
	s_add_u32 s8, s8, 0x80
	s_addc_u32 s9, s9, 0
	s_add_u32 m0, s14, 0x18000
	s_nop 0
	global_load_lds_dwordx4 v231, s[8:9]
	s_nop 0
	s_add_u32 m0, s14, 0x1a000
	s_nop 0
	global_load_lds_dwordx4 v233, s[8:9]
	s_add_u32 s8, s50, 0x10080
	s_addc_u32 s9, s51, 0
	s_add_u32 m0, s14, 0x1c000
	s_nop 0
	global_load_lds_dwordx4 v231, s[8:9]
	s_nop 0
	s_add_u32 m0, s14, 0x1e000
	s_nop 0
	global_load_lds_dwordx4 v233, s[8:9]
	s_nop 0
	s_add_u32 m0, s14, 0x8000
	s_nop 0
	global_load_lds_dwordx4 v230, s[2:3]
	s_nop 0
	s_add_u32 m0, s14, 0xa000
	s_nop 0
	global_load_lds_dwordx4 v232, s[2:3]
	s_waitcnt vmcnt(8)
.LBB0_888:
	s_waitcnt lgkmcnt(0)
	s_barrier
	v_mfma_f32_16x16x32_f16 v[10:13], v[170:173], v[218:221], v[74:77]
	s_setprio 1
	s_waitcnt lgkmcnt(6)
	v_mfma_f32_16x16x32_f16 v[194:197], v[174:177], v[222:225], v[10:13]
	v_mfma_f32_16x16x32_f16 v[10:13], v[178:181], v[218:221], v[78:81]
	v_mfma_f32_16x16x32_f16 v[198:201], v[182:185], v[222:225], v[10:13]
	s_waitcnt lgkmcnt(5)
	v_mfma_f32_16x16x32_f16 v[10:13], v[170:173], v[58:61], v[82:85]
	s_waitcnt lgkmcnt(4)
	v_mfma_f32_16x16x32_f16 v[66:69], v[174:177], v[214:217], v[10:13]
	v_mfma_f32_16x16x32_f16 v[10:13], v[178:181], v[58:61], v[86:89]
	v_mfma_f32_16x16x32_f16 v[70:73], v[182:185], v[214:217], v[10:13]
	s_waitcnt lgkmcnt(3)
	v_mfma_f32_16x16x32_f16 v[10:13], v[170:173], v[26:29], v[90:93]
	s_waitcnt lgkmcnt(2)
	v_mfma_f32_16x16x32_f16 v[42:45], v[174:177], v[62:65], v[10:13]
	v_mfma_f32_16x16x32_f16 v[10:13], v[178:181], v[26:29], v[94:97]
	v_mfma_f32_16x16x32_f16 v[46:49], v[182:185], v[62:65], v[10:13]
	s_waitcnt lgkmcnt(1)
	v_mfma_f32_16x16x32_f16 v[10:13], v[170:173], v[30:33], v[98:101]
	v_mfma_f32_16x16x32_f16 v[14:17], v[178:181], v[30:33], v[102:105]
	s_waitcnt lgkmcnt(0)
	v_mfma_f32_16x16x32_f16 v[10:13], v[174:177], v[210:213], v[10:13]
	v_mfma_f32_16x16x32_f16 v[14:17], v[182:185], v[210:213], v[14:17]
	v_mfma_f32_16x16x32_f16 v[74:77], v[146:149], v[218:221], v[106:109]
	v_mfma_f32_16x16x32_f16 v[82:85], v[150:153], v[222:225], v[74:77]
	v_mfma_f32_16x16x32_f16 v[74:77], v[154:157], v[218:221], v[110:113]
	v_mfma_f32_16x16x32_f16 v[86:89], v[158:161], v[222:225], v[74:77]
	v_mfma_f32_16x16x32_f16 v[74:77], v[146:149], v[58:61], v[114:117]
	v_mfma_f32_16x16x32_f16 v[58:61], v[154:157], v[58:61], v[118:121]
	v_mfma_f32_16x16x32_f16 v[78:81], v[158:161], v[214:217], v[58:61]
	v_mfma_f32_16x16x32_f16 v[58:61], v[146:149], v[26:29], v[122:125]
	v_mfma_f32_16x16x32_f16 v[26:29], v[154:157], v[26:29], v[126:129]
	v_mfma_f32_16x16x32_f16 v[58:61], v[150:153], v[62:65], v[58:61]
	v_mfma_f32_16x16x32_f16 v[62:65], v[158:161], v[62:65], v[26:29]
	v_mfma_f32_16x16x32_f16 v[26:29], v[146:149], v[30:33], v[130:133]
	v_mfma_f32_16x16x32_f16 v[30:33], v[154:157], v[30:33], v[134:137]
	v_mfma_f32_16x16x32_f16 v[74:77], v[150:153], v[214:217], v[74:77]
	v_mfma_f32_16x16x32_f16 v[26:29], v[150:153], v[210:213], v[26:29]
	v_mfma_f32_16x16x32_f16 v[30:33], v[158:161], v[210:213], v[30:33]
	s_barrier
	s_setprio 0
	s_andn2_b64 vcc, exec, s[6:7]
	s_cbranch_vccnz .LBB0_890
	s_barrier

; #define PG8_STAGE(bufoff, gbase, voff) do { if constexpr (ABL & 1) break; glds16s<(bufoff)>((voff)[0], (const void*)(gbase), ldsbw); glds16s<(bufoff) + 8192>((voff)[1], (const void*)(gbase), ldsbw); } while (0)
; #define PG8_LDA(dst, b, h) do { if constexpr (ABL & 4) break; _Pragma("unroll") for (int m = 0; m < 4; ++m) _Pragma("unroll") for (int k = 0; k < 2; ++k) dst[m][k] = *(const LAS f16x8*)(lds + PG8_SA(b, h) + aoff + m * 2048 + k * 1024); } while (0)
; #define PG8_LDB(dst, b, h) do { if constexpr (ABL & 4) break; _Pragma("unroll") for (int n = 0; n < 2; ++n) _Pragma("unroll") for (int k = 0; k < 2; ++k) dst[n][k] = *(const LAS f16x8*)(lds + PG8_SB(b, h) + boff + n * 2048 + k * 1024); } while (0)
; #define PG8_MMAF(ai, bj, At, Bt) do { if (t == 0) PG8_MMA0(ai, bj, At, Bt); else PG8_MMA(ai, bj, At, Bt); } while (0)
; #define PG8_WAIT_V(n) asm volatile("s_waitcnt vmcnt(" #n ")" ::: "memory")
; #define PG8_WAIT_L(n) asm volatile("s_waitcnt lgkmcnt(" #n ")" ::: "memory")
; #define PG8_BAR __builtin_amdgcn_s_barrier()
; #define PG8_SCHED __builtin_amdgcn_sched_barrier(0)
;     ...
;         const char* nA = has_next ? (const char*)g.A + (size_t)nxt.pm * tstep : cA; const char* nB = has_next ? (const char*)g.Bt + (size_t)nxt.pn * tstep : cB;
;         for (int t = 0; t < nt; t += 2) {
;             const bool last = (t == nt - 2);
;             const char* a1 = cA + (size_t)(t + 1) * kstep;
;             const char* a2 = last ? nA : cA + (size_t)(t + 2) * kstep; const char* b2 = last ? nB : cB + (size_t)(t + 2) * kstep;
;             const char* a3 = a2 + kstep; const char* b3 = b2 + kstep;
;             if (last && has_next) S.a_ready(nxt);
;             if constexpr (SP2) {
;             PG8_LDB(B0, 0, 0); PG8_LDB(B1, 0, 1); PG8_SCHED; PG8_LDA(At, 0, 0); PG8_STAGE(PG8_SA(1, 1), a1 + hstep, voffA);
;             PG8_WAIT_V(8); PG8_WAIT_L(0); PG8_BAR; PG8_MMAF(0, 0, At, B0); PG8_MMAF(0, 1, At, B1); PG8_BAR; PG8_SCHED;
;             const bool fin = last && !has_next;
;             PG8_LDA(At, 0, 1); if (!fin) { PG8_STAGE(PG8_SB(0, 0), b2, voffB); PG8_STAGE(PG8_SB(0, 1), b2 + hstep, voffB); PG8_STAGE(PG8_SA(0, 0), a2, voffA); }
;             if (!fin) PG8_WAIT_V(8); else PG8_WAIT_V(2); PG8_WAIT_L(0); PG8_BAR; PG8_MMAF(1, 0, At, B0); PG8_MMAF(1, 1, At, B1); PG8_BAR; PG8_SCHED;
.LBB0_987:
	s_waitcnt lgkmcnt(0)
	ds_read_b128 v[2:5], v213
	ds_read_b128 v[6:9], v213 offset:1024
	ds_read_b128 v[10:13], v213 offset:2048
	ds_read_b128 v[14:17], v213 offset:3072
	ds_read_b128 v[18:21], v214
	ds_read_b128 v[22:25], v214 offset:1024
	ds_read_b128 v[26:29], v214 offset:2048
	ds_read_b128 v[30:33], v214 offset:3072
	s_add_u32 s50, s54, 0x100
	s_addc_u32 s51, s55, 0
	s_add_u32 s24, s52, 0x100
	s_addc_u32 s25, s53, 0
	s_add_u32 s6, s54, 0x180
	s_addc_u32 s7, s55, 0
	ds_read_b128 v[34:37], v215
	ds_read_b128 v[38:41], v215 offset:1024
	ds_read_b128 v[42:45], v215 offset:2048
	ds_read_b128 v[46:49], v215 offset:3072
	ds_read_b128 v[50:53], v215 offset:4096
	ds_read_b128 v[54:57], v215 offset:5120
	ds_read_b128 v[58:61], v215 offset:6144
	ds_read_b128 v[62:65], v215 offset:7168
	s_add_u32 s8, s52, 0x180
	s_addc_u32 s9, s53, 0
	s_add_u32 s26, s54, 0xb0080
	s_addc_u32 s27, s55, 0
	s_add_u32 m0, s28, 0xc000
	s_nop 0
	global_load_lds_dwordx4 v1, s[26:27]
	s_nop 0
	s_add_u32 m0, s28, 0xe000
	s_nop 0
	global_load_lds_dwordx4 v211, s[26:27]
	s_waitcnt vmcnt(8)
	s_waitcnt lgkmcnt(0)
	s_barrier
	v_mfma_f32_16x16x32_f16 v[70:73], v[10:13], v[34:37], 0
	s_setprio 1
	s_waitcnt lgkmcnt(5)
	v_mfma_f32_16x16x32_f16 v[74:77], v[2:5], v[42:45], 0
	s_waitcnt lgkmcnt(3)
	v_mfma_f32_16x16x32_f16 v[82:85], v[2:5], v[50:53], 0
	v_mfma_f32_16x16x32_f16 v[86:89], v[10:13], v[50:53], 0
	s_waitcnt lgkmcnt(1)
	v_mfma_f32_16x16x32_f16 v[94:97], v[10:13], v[58:61], 0
	v_mfma_f32_16x16x32_f16 v[66:69], v[2:5], v[34:37], 0
	v_mfma_f32_16x16x32_f16 v[70:73], v[14:17], v[38:41], v[70:73]
	v_mfma_f32_16x16x32_f16 v[74:77], v[6:9], v[46:49], v[74:77]
	v_mfma_f32_16x16x32_f16 v[78:81], v[10:13], v[42:45], 0
	v_mfma_f32_16x16x32_f16 v[82:85], v[6:9], v[54:57], v[82:85]
	v_mfma_f32_16x16x32_f16 v[86:89], v[14:17], v[54:57], v[86:89]
	v_mfma_f32_16x16x32_f16 v[90:93], v[2:5], v[58:61], 0
	s_waitcnt lgkmcnt(0)
	v_mfma_f32_16x16x32_f16 v[94:97], v[14:17], v[62:65], v[94:97]
	v_mfma_f32_16x16x32_f16 v[66:69], v[6:9], v[38:41], v[66:69]
	v_mfma_f32_16x16x32_f16 v[78:81], v[14:17], v[46:49], v[78:81]
	v_mfma_f32_16x16x32_f16 v[90:93], v[6:9], v[62:65], v[90:93]
	v_mfma_f32_16x16x32_f16 v[98:101], v[18:21], v[34:37], 0
	v_mfma_f32_16x16x32_f16 v[34:37], v[26:29], v[34:37], 0
	v_mfma_f32_16x16x32_f16 v[98:101], v[22:25], v[38:41], v[98:101]
	v_mfma_f32_16x16x32_f16 v[34:37], v[30:33], v[38:41], v[34:37]
	v_mfma_f32_16x16x32_f16 v[38:41], v[18:21], v[42:45], 0
	v_mfma_f32_16x16x32_f16 v[42:45], v[26:29], v[42:45], 0
	v_mfma_f32_16x16x32_f16 v[38:41], v[22:25], v[46:49], v[38:41]
	v_mfma_f32_16x16x32_f16 v[42:45], v[30:33], v[46:49], v[42:45]
	v_mfma_f32_16x16x32_f16 v[46:49], v[18:21], v[50:53], 0
	v_mfma_f32_16x16x32_f16 v[50:53], v[26:29], v[50:53], 0
	v_mfma_f32_16x16x32_f16 v[46:49], v[22:25], v[54:57], v[46:49]
	v_mfma_f32_16x16x32_f16 v[50:53], v[30:33], v[54:57], v[50:53]
	v_mfma_f32_16x16x32_f16 v[54:57], v[18:21], v[58:61], 0
	v_mfma_f32_16x16x32_f16 v[58:61], v[26:29], v[58:61], 0
	v_mfma_f32_16x16x32_f16 v[54:57], v[22:25], v[62:65], v[54:57]
	v_mfma_f32_16x16x32_f16 v[58:61], v[30:33], v[62:65], v[58:61]
	s_barrier
	s_setprio 0
	ds_read_b128 v[62:65], v215 offset:16384
	ds_read_b128 v[102:105], v215 offset:17408
	ds_read_b128 v[106:109], v215 offset:18432
	ds_read_b128 v[110:113], v215 offset:19456
	ds_read_b128 v[114:117], v215 offset:20480
	ds_read_b128 v[118:121], v215 offset:21504
	ds_read_b128 v[122:125], v215 offset:22528
	ds_read_b128 v[126:129], v215 offset:23552
	s_add_u32 m0, s28, 0x10000
	s_nop 0
	global_load_lds_dwordx4 v210, s[24:25]
	s_nop 0
	s_add_u32 m0, s28, 0x12000
	s_nop 0
	global_load_lds_dwordx4 v212, s[24:25]
	s_add_u32 s24, s52, 0xb0100
	s_addc_u32 s25, s53, 0
	s_add_u32 m0, s28, 0x14000
	s_nop 0
	global_load_lds_dwordx4 v210, s[24:25]
	s_nop 0
	s_add_u32 m0, s28, 0x16000
	s_nop 0
	global_load_lds_dwordx4 v212, s[24:25]
	s_nop 0
	s_add_u32 m0, s28, 0
	s_nop 0
	global_load_lds_dwordx4 v1, s[50:51]
	s_nop 0
	s_add_u32 m0, s28, 0x2000
	s_nop 0
	global_load_lds_dwordx4 v211, s[50:51]
	s_waitcnt vmcnt(8)
	s_waitcnt lgkmcnt(0)
	s_barrier
	v_mfma_f32_16x16x32_f16 v[130:133], v[2:5], v[62:65], 0
	s_setprio 1
	s_waitcnt lgkmcnt(6)
	v_mfma_f32_16x16x32_f16 v[138:141], v[6:9], v[102:105], v[130:133]
	v_mfma_f32_16x16x32_f16 v[130:133], v[10:13], v[62:65], 0
	v_mfma_f32_16x16x32_f16 v[158:161], v[14:17], v[102:105], v[130:133]
	s_waitcnt lgkmcnt(5)
	v_mfma_f32_16x16x32_f16 v[130:133], v[2:5], v[106:109], 0
	s_waitcnt lgkmcnt(4)
	v_mfma_f32_16x16x32_f16 v[162:165], v[6:9], v[110:113], v[130:133]
	v_mfma_f32_16x16x32_f16 v[130:133], v[10:13], v[106:109], 0
	v_mfma_f32_16x16x32_f16 v[166:169], v[14:17], v[110:113], v[130:133]
	s_waitcnt lgkmcnt(3)
	v_mfma_f32_16x16x32_f16 v[130:133], v[2:5], v[114:117], 0
	s_waitcnt lgkmcnt(1)
	v_mfma_f32_16x16x32_f16 v[2:5], v[2:5], v[122:125], 0
	v_mfma_f32_16x16x32_f16 v[170:173], v[6:9], v[118:121], v[130:133]
	s_waitcnt lgkmcnt(0)
	v_mfma_f32_16x16x32_f16 v[2:5], v[6:9], v[126:129], v[2:5]
	v_mfma_f32_16x16x32_f16 v[6:9], v[10:13], v[122:125], 0
	v_mfma_f32_16x16x32_f16 v[130:133], v[10:13], v[114:117], 0
	v_mfma_f32_16x16x32_f16 v[6:9], v[14:17], v[126:129], v[6:9]
	v_mfma_f32_16x16x32_f16 v[174:177], v[14:17], v[118:121], v[130:133]
	v_mfma_f32_16x16x32_f16 v[10:13], v[18:21], v[62:65], 0
	v_mfma_f32_16x16x32_f16 v[178:181], v[22:25], v[102:105], v[10:13]
	v_mfma_f32_16x16x32_f16 v[10:13], v[26:29], v[62:65], 0
	v_mfma_f32_16x16x32_f16 v[102:105], v[30:33], v[102:105], v[10:13]
	v_mfma_f32_16x16x32_f16 v[10:13], v[18:21], v[106:109], 0
	v_mfma_f32_16x16x32_f16 v[182:185], v[22:25], v[110:113], v[10:13]
	v_mfma_f32_16x16x32_f16 v[10:13], v[26:29], v[106:109], 0
	v_mfma_f32_16x16x32_f16 v[186:189], v[30:33], v[110:113], v[10:13]
	v_mfma_f32_16x16x32_f16 v[10:13], v[18:21], v[114:117], 0
	v_mfma_f32_16x16x32_f16 v[190:193], v[22:25], v[118:121], v[10:13]
	v_mfma_f32_16x16x32_f16 v[10:13], v[26:29], v[114:117], 0
	v_mfma_f32_16x16x32_f16 v[114:117], v[30:33], v[118:121], v[10:13]
	v_mfma_f32_16x16x32_f16 v[10:13], v[18:21], v[122:125], 0
	v_mfma_f32_16x16x32_f16 v[194:197], v[22:25], v[126:129], v[10:13]
	v_mfma_f32_16x16x32_f16 v[10:13], v[26:29], v[122:125], 0
	v_mfma_f32_16x16x32_f16 v[126:129], v[30:33], v[126:129], v[10:13]
	s_barrier
; #define PG8_STAGE(bufoff, gbase, voff) do { if constexpr (ABL & 1) break; glds16s<(bufoff)>((voff)[0], (const void*)(gbase), ldsbw); glds16s<(bufoff) + 8192>((voff)[1], (const void*)(gbase), ldsbw); } while (0)
; #define PG8_LDA(dst, b, h) do { if constexpr (ABL & 4) break; _Pragma("unroll") for (int m = 0; m < 4; ++m) _Pragma("unroll") for (int k = 0; k < 2; ++k) dst[m][k] = *(const LAS f16x8*)(lds + PG8_SA(b, h) + aoff + m * 2048 + k * 1024); } while (0)
; #define PG8_LDB(dst, b, h) do { if constexpr (ABL & 4) break; _Pragma("unroll") for (int n = 0; n < 2; ++n) _Pragma("unroll") for (int k = 0; k < 2; ++k) dst[n][k] = *(const LAS f16x8*)(lds + PG8_SB(b, h) + boff + n * 2048 + k * 1024); } while (0)
; #define PG8_MMA(ai, bj, At, Bt) do { if constexpr (ABL & 2) break; __builtin_amdgcn_s_setprio(1); _Pragma("unroll") for (int m = 0; m < 4; ++m) _Pragma("unroll") for (int n = 0; n < 2; ++n) _Pragma("unroll") for (int k = 0; k < 2; ++k) \
;         acc[ai][bj][m][n] = __builtin_amdgcn_mfma_f32_16x16x32_f16(Bt[n][k], At[m][k], acc[ai][bj][m][n], 0, 0, 0); __builtin_amdgcn_s_setprio(0); } while (0)
; #define PG8_WAIT_V(n) asm volatile("s_waitcnt vmcnt(" #n ")" ::: "memory")
; #define PG8_WAIT_L(n) asm volatile("s_waitcnt lgkmcnt(" #n ")" ::: "memory")
; #define PG8_BAR __builtin_amdgcn_s_barrier()
; #define PG8_SCHED __builtin_amdgcn_sched_barrier(0)
;     ...
;             PG8_LDB(B0, 1, 0); PG8_LDB(B1, 1, 1); PG8_SCHED; PG8_LDA(At, 1, 0); if (!fin) PG8_STAGE(PG8_SA(0, 1), a2 + hstep, voffA);
;             if (!fin) PG8_WAIT_V(8); else PG8_WAIT_V(0); PG8_WAIT_L(0); PG8_BAR; PG8_MMA(0, 0, At, B0); PG8_MMA(0, 1, At, B1); PG8_BAR; PG8_SCHED;
;             PG8_LDA(At, 1, 1); if (!fin) { PG8_STAGE(PG8_SB(1, 0), b3, voffB); PG8_STAGE(PG8_SB(1, 1), b3 + hstep, voffB); PG8_STAGE(PG8_SA(1, 0), a3, voffA); }
;             if (!fin) PG8_WAIT_V(8); PG8_WAIT_L(0); PG8_BAR; PG8_MMA(1, 0, At, B0); PG8_MMA(1, 1, At, B1); PG8_BAR; PG8_SCHED;
	s_setprio 0
	s_nop 4
	ds_read_b128 v[10:13], v216
	ds_read_b128 v[14:17], v216 offset:1024
	ds_read_b128 v[18:21], v216 offset:2048
	ds_read_b128 v[22:25], v216 offset:3072
	ds_read_b128 v[198:201], v217
	ds_read_b128 v[202:205], v217 offset:1024
	ds_read_b128 v[220:223], v217 offset:2048
	ds_read_b128 v[224:227], v217 offset:3072
	ds_read_b128 v[26:29], v215 offset:32768
	ds_read_b128 v[30:33], v215 offset:33792
	ds_read_b128 v[62:65], v215 offset:34816
	ds_read_b128 v[118:121], v215 offset:35840
	ds_read_b128 v[228:231], v215 offset:36864
	ds_read_b128 v[232:235], v215 offset:37888
	ds_read_b128 v[236:239], v215 offset:38912
	ds_read_b128 v[240:243], v215 offset:39936
	s_add_u32 s24, s54, 0xb0100
	s_addc_u32 s25, s55, 0
	s_add_u32 m0, s28, 0x4000
	s_nop 0
	global_load_lds_dwordx4 v1, s[24:25]
	s_nop 0
	s_add_u32 m0, s28, 0x6000
	s_nop 0
	global_load_lds_dwordx4 v211, s[24:25]
	s_waitcnt vmcnt(8)
	s_waitcnt lgkmcnt(0)
	s_barrier
	v_mfma_f32_16x16x32_f16 v[66:69], v[10:13], v[26:29], v[66:69]
	s_setprio 1
	s_waitcnt lgkmcnt(6)
	v_mfma_f32_16x16x32_f16 v[154:157], v[14:17], v[30:33], v[66:69]
	v_mfma_f32_16x16x32_f16 v[66:69], v[18:21], v[26:29], v[70:73]
	v_mfma_f32_16x16x32_f16 v[150:153], v[22:25], v[30:33], v[66:69]
	s_waitcnt lgkmcnt(5)
	v_mfma_f32_16x16x32_f16 v[66:69], v[10:13], v[62:65], v[74:77]
	s_waitcnt lgkmcnt(4)
	v_mfma_f32_16x16x32_f16 v[134:137], v[14:17], v[118:121], v[66:69]
	v_mfma_f32_16x16x32_f16 v[66:69], v[18:21], v[62:65], v[78:81]
	v_mfma_f32_16x16x32_f16 v[130:133], v[22:25], v[118:121], v[66:69]
	s_waitcnt lgkmcnt(3)
	v_mfma_f32_16x16x32_f16 v[66:69], v[10:13], v[228:231], v[82:85]
	s_waitcnt lgkmcnt(2)
	v_mfma_f32_16x16x32_f16 v[110:113], v[14:17], v[232:235], v[66:69]
	v_mfma_f32_16x16x32_f16 v[66:69], v[18:21], v[228:231], v[86:89]
	v_mfma_f32_16x16x32_f16 v[106:109], v[22:25], v[232:235], v[66:69]
	s_waitcnt lgkmcnt(1)
	v_mfma_f32_16x16x32_f16 v[66:69], v[10:13], v[236:239], v[90:93]
	s_waitcnt lgkmcnt(0)
	v_mfma_f32_16x16x32_f16 v[86:89], v[14:17], v[240:243], v[66:69]
	v_mfma_f32_16x16x32_f16 v[66:69], v[18:21], v[236:239], v[94:97]
	v_mfma_f32_16x16x32_f16 v[82:85], v[22:25], v[240:243], v[66:69]
	v_mfma_f32_16x16x32_f16 v[66:69], v[198:201], v[26:29], v[98:101]
	v_mfma_f32_16x16x32_f16 v[26:29], v[220:223], v[26:29], v[34:37]
	v_mfma_f32_16x16x32_f16 v[142:145], v[224:227], v[30:33], v[26:29]
	v_mfma_f32_16x16x32_f16 v[26:29], v[198:201], v[62:65], v[38:41]
	v_mfma_f32_16x16x32_f16 v[122:125], v[202:205], v[118:121], v[26:29]
	v_mfma_f32_16x16x32_f16 v[26:29], v[220:223], v[62:65], v[42:45]
	v_mfma_f32_16x16x32_f16 v[118:121], v[224:227], v[118:121], v[26:29]
	v_mfma_f32_16x16x32_f16 v[26:29], v[198:201], v[228:231], v[46:49]
	v_mfma_f32_16x16x32_f16 v[98:101], v[202:205], v[232:235], v[26:29]
	v_mfma_f32_16x16x32_f16 v[26:29], v[220:223], v[228:231], v[50:53]
	v_mfma_f32_16x16x32_f16 v[94:97], v[224:227], v[232:235], v[26:29]
	v_mfma_f32_16x16x32_f16 v[26:29], v[198:201], v[236:239], v[54:57]
	v_mfma_f32_16x16x32_f16 v[74:77], v[202:205], v[240:243], v[26:29]
	v_mfma_f32_16x16x32_f16 v[26:29], v[220:223], v[236:239], v[58:61]
	v_mfma_f32_16x16x32_f16 v[146:149], v[202:205], v[30:33], v[66:69]
	v_mfma_f32_16x16x32_f16 v[70:73], v[224:227], v[240:243], v[26:29]
	s_barrier
	s_setprio 0
	ds_read_b128 v[34:37], v215 offset:49152
	ds_read_b128 v[38:41], v215 offset:50176
	ds_read_b128 v[66:69], v215 offset:51200
	ds_read_b128 v[78:81], v215 offset:52224
	ds_read_b128 v[90:93], v215 offset:53248
	ds_read_b128 v[228:231], v215 offset:54272
	ds_read_b128 v[232:235], v215 offset:55296
	ds_read_b128 v[236:239], v215 offset:56320
	s_add_u32 m0, s28, 0x18000
	s_nop 0
	global_load_lds_dwordx4 v210, s[8:9]
	s_nop 0
	s_add_u32 m0, s28, 0x1a000
	s_nop 0
	global_load_lds_dwordx4 v212, s[8:9]
	s_add_u32 s8, s52, 0xb0180
	s_addc_u32 s9, s53, 0
	s_add_u32 m0, s28, 0x1c000
	s_nop 0
	global_load_lds_dwordx4 v210, s[8:9]
	s_nop 0
	s_add_u32 m0, s28, 0x1e000
	s_nop 0
	global_load_lds_dwordx4 v212, s[8:9]
	s_nop 0
	s_add_u32 m0, s28, 0x8000
	s_nop 0
	global_load_lds_dwordx4 v1, s[6:7]
	s_nop 0
	s_add_u32 m0, s28, 0xa000
	s_nop 0
	global_load_lds_dwordx4 v211, s[6:7]
	s_waitcnt vmcnt(8)
	s_waitcnt lgkmcnt(0)
	s_barrier
	v_mfma_f32_16x16x32_f16 v[26:29], v[10:13], v[34:37], v[138:141]
	s_setprio 1
	s_waitcnt lgkmcnt(6)
	v_mfma_f32_16x16x32_f16 v[62:65], v[14:17], v[38:41], v[26:29]
	v_mfma_f32_16x16x32_f16 v[26:29], v[18:21], v[34:37], v[158:161]
	v_mfma_f32_16x16x32_f16 v[58:61], v[22:25], v[38:41], v[26:29]
	s_waitcnt lgkmcnt(5)
	v_mfma_f32_16x16x32_f16 v[26:29], v[10:13], v[66:69], v[162:165]
	s_waitcnt lgkmcnt(4)
	v_mfma_f32_16x16x32_f16 v[46:49], v[14:17], v[78:81], v[26:29]
	v_mfma_f32_16x16x32_f16 v[26:29], v[18:21], v[66:69], v[166:169]
	v_mfma_f32_16x16x32_f16 v[42:45], v[22:25], v[78:81], v[26:29]
	s_waitcnt lgkmcnt(3)
	v_mfma_f32_16x16x32_f16 v[26:29], v[10:13], v[90:93], v[170:173]
	s_waitcnt lgkmcnt(1)
	v_mfma_f32_16x16x32_f16 v[2:5], v[10:13], v[232:235], v[2:5]
	v_mfma_f32_16x16x32_f16 v[30:33], v[14:17], v[228:231], v[26:29]
	v_mfma_f32_16x16x32_f16 v[26:29], v[18:21], v[90:93], v[174:177]
	s_waitcnt lgkmcnt(0)
	v_mfma_f32_16x16x32_f16 v[14:17], v[14:17], v[236:239], v[2:5]
	v_mfma_f32_16x16x32_f16 v[2:5], v[18:21], v[232:235], v[6:9]
	v_mfma_f32_16x16x32_f16 v[26:29], v[22:25], v[228:231], v[26:29]
	v_mfma_f32_16x16x32_f16 v[10:13], v[22:25], v[236:239], v[2:5]
	v_mfma_f32_16x16x32_f16 v[2:5], v[198:201], v[34:37], v[178:181]
	v_mfma_f32_16x16x32_f16 v[54:57], v[202:205], v[38:41], v[2:5]
	v_mfma_f32_16x16x32_f16 v[2:5], v[220:223], v[34:37], v[102:105]
	v_mfma_f32_16x16x32_f16 v[50:53], v[224:227], v[38:41], v[2:5]
	v_mfma_f32_16x16x32_f16 v[2:5], v[198:201], v[66:69], v[182:185]
	v_mfma_f32_16x16x32_f16 v[38:41], v[202:205], v[78:81], v[2:5]
	v_mfma_f32_16x16x32_f16 v[2:5], v[220:223], v[66:69], v[186:189]
	v_mfma_f32_16x16x32_f16 v[34:37], v[224:227], v[78:81], v[2:5]
	v_mfma_f32_16x16x32_f16 v[2:5], v[198:201], v[90:93], v[190:193]
	v_mfma_f32_16x16x32_f16 v[22:25], v[202:205], v[228:231], v[2:5]
	v_mfma_f32_16x16x32_f16 v[2:5], v[220:223], v[90:93], v[114:117]
	v_mfma_f32_16x16x32_f16 v[18:21], v[224:227], v[228:231], v[2:5]
	v_mfma_f32_16x16x32_f16 v[2:5], v[198:201], v[232:235], v[194:197]
	v_mfma_f32_16x16x32_f16 v[6:9], v[202:205], v[236:239], v[2:5]
	v_mfma_f32_16x16x32_f16 v[2:5], v[220:223], v[232:235], v[126:129]
	v_mfma_f32_16x16x32_f16 v[2:5], v[224:227], v[236:239], v[2:5]
	s_barrier
	s_setprio 0
	s_add_u32 s52, s52, 0x200
	s_addc_u32 s53, s53, 0
	s_mov_b32 s54, 0
	s_branch .LBB0_989
; #define PG8_STAGE(bufoff, gbase, voff) do { if constexpr (ABL & 1) break; glds16s<(bufoff)>((voff)[0], (const void*)(gbase), ldsbw); glds16s<(bufoff) + 8192>((voff)[1], (const void*)(gbase), ldsbw); } while (0)
; #define PG8_LDA(dst, b, h) do { if constexpr (ABL & 4) break; _Pragma("unroll") for (int m = 0; m < 4; ++m) _Pragma("unroll") for (int k = 0; k < 2; ++k) dst[m][k] = *(const LAS f16x8*)(lds + PG8_SA(b, h) + aoff + m * 2048 + k * 1024); } while (0)
; #define PG8_LDB(dst, b, h) do { if constexpr (ABL & 4) break; _Pragma("unroll") for (int n = 0; n < 2; ++n) _Pragma("unroll") for (int k = 0; k < 2; ++k) dst[n][k] = *(const LAS f16x8*)(lds + PG8_SB(b, h) + boff + n * 2048 + k * 1024); } while (0)
; #define PG8_BAR __builtin_amdgcn_s_barrier()
;     ...
;         for (int t = 0; t < nt; t += 2) {
;             const bool last = (t == nt - 2);
;             const char* a1 = cA + (size_t)(t + 1) * kstep;
;             const char* a2 = last ? nA : cA + (size_t)(t + 2) * kstep; const char* b2 = last ? nB : cB + (size_t)(t + 2) * kstep;
;             const char* a3 = a2 + kstep; const char* b3 = b2 + kstep;
;             if (last && has_next) S.a_ready(nxt);
;             if constexpr (SP2) {
;             PG8_LDB(B0, 0, 0); PG8_LDB(B1, 0, 1); PG8_SCHED; PG8_LDA(At, 0, 0); PG8_STAGE(PG8_SA(1, 1), a1 + hstep, voffA);
;             PG8_WAIT_V(8); PG8_WAIT_L(0); PG8_BAR; PG8_MMAF(0, 0, At, B0); PG8_MMAF(0, 1, At, B1); PG8_BAR; PG8_SCHED;
;             const bool fin = last && !has_next;
;             PG8_LDA(At, 0, 1); if (!fin) { PG8_STAGE(PG8_SB(0, 0), b2, voffB); PG8_STAGE(PG8_SB(0, 1), b2 + hstep, voffB); PG8_STAGE(PG8_SA(0, 0), a2, voffA); }
;             if (!fin) PG8_WAIT_V(8); else PG8_WAIT_V(2); PG8_WAIT_L(0); PG8_BAR; PG8_MMAF(1, 0, At, B0); PG8_MMAF(1, 1, At, B1); PG8_BAR; PG8_SCHED;
;             PG8_LDB(B0, 1, 0); PG8_LDB(B1, 1, 1); PG8_SCHED; PG8_LDA(At, 1, 0); if (!fin) PG8_STAGE(PG8_SA(0, 1), a2 + hstep, voffA);
;             if (!fin) PG8_WAIT_V(8); else PG8_WAIT_V(0); PG8_WAIT_L(0); PG8_BAR; PG8_MMA(0, 0, At, B0); PG8_MMA(0, 1, At, B1); PG8_BAR; PG8_SCHED;
;             PG8_LDA(At, 1, 1); if (!fin) { PG8_STAGE(PG8_SB(1, 0), b3, voffB); PG8_STAGE(PG8_SB(1, 1), b3 + hstep, voffB); PG8_STAGE(PG8_SA(1, 0), a3, voffA); }
;             if (!fin) PG8_WAIT_V(8); PG8_WAIT_L(0); PG8_BAR; PG8_MMA(1, 0, At, B0); PG8_MMA(1, 1, At, B1); PG8_BAR; PG8_SCHED;
.LBB0_988:
	s_waitcnt lgkmcnt(0)
	s_barrier
	v_mfma_f32_16x16x32_f16 v[62:65], v[166:169], v[186:189], v[62:65]
	s_setprio 1
	v_mfma_f32_16x16x32_f16 v[58:61], v[158:161], v[186:189], v[58:61]
	s_waitcnt lgkmcnt(5)
	v_mfma_f32_16x16x32_f16 v[46:49], v[166:169], v[178:181], v[46:49]
	v_mfma_f32_16x16x32_f16 v[42:45], v[158:161], v[178:181], v[42:45]
	s_waitcnt lgkmcnt(3)
	v_mfma_f32_16x16x32_f16 v[30:33], v[166:169], v[138:141], v[30:33]
	v_mfma_f32_16x16x32_f16 v[26:29], v[158:161], v[138:141], v[26:29]
	s_waitcnt lgkmcnt(1)
	v_mfma_f32_16x16x32_f16 v[14:17], v[166:169], v[114:117], v[14:17]
	v_mfma_f32_16x16x32_f16 v[10:13], v[158:161], v[114:117], v[10:13]
	v_mfma_f32_16x16x32_f16 v[62:65], v[170:173], v[190:193], v[62:65]
	v_mfma_f32_16x16x32_f16 v[58:61], v[162:165], v[190:193], v[58:61]
	v_mfma_f32_16x16x32_f16 v[46:49], v[170:173], v[182:185], v[46:49]
	v_mfma_f32_16x16x32_f16 v[42:45], v[162:165], v[182:185], v[42:45]
	v_mfma_f32_16x16x32_f16 v[30:33], v[170:173], v[174:177], v[30:33]
	v_mfma_f32_16x16x32_f16 v[26:29], v[162:165], v[174:177], v[26:29]
	s_waitcnt lgkmcnt(0)
	v_mfma_f32_16x16x32_f16 v[14:17], v[170:173], v[126:129], v[14:17]
	v_mfma_f32_16x16x32_f16 v[10:13], v[162:165], v[126:129], v[10:13]
	v_mfma_f32_16x16x32_f16 v[54:57], v[90:93], v[186:189], v[54:57]
	v_mfma_f32_16x16x32_f16 v[50:53], v[66:69], v[186:189], v[50:53]
	v_mfma_f32_16x16x32_f16 v[38:41], v[90:93], v[178:181], v[38:41]
	v_mfma_f32_16x16x32_f16 v[34:37], v[66:69], v[178:181], v[34:37]
	v_mfma_f32_16x16x32_f16 v[22:25], v[90:93], v[138:141], v[22:25]
	v_mfma_f32_16x16x32_f16 v[18:21], v[66:69], v[138:141], v[18:21]
	v_mfma_f32_16x16x32_f16 v[6:9], v[90:93], v[114:117], v[6:9]
	v_mfma_f32_16x16x32_f16 v[2:5], v[66:69], v[114:117], v[2:5]
	v_mfma_f32_16x16x32_f16 v[54:57], v[102:105], v[190:193], v[54:57]
	v_mfma_f32_16x16x32_f16 v[50:53], v[78:81], v[190:193], v[50:53]
	v_mfma_f32_16x16x32_f16 v[38:41], v[102:105], v[182:185], v[38:41]
	v_mfma_f32_16x16x32_f16 v[34:37], v[78:81], v[182:185], v[34:37]
	v_mfma_f32_16x16x32_f16 v[22:25], v[102:105], v[174:177], v[22:25]
	v_mfma_f32_16x16x32_f16 v[18:21], v[78:81], v[174:177], v[18:21]
	v_mfma_f32_16x16x32_f16 v[6:9], v[102:105], v[126:129], v[6:9]
	v_mfma_f32_16x16x32_f16 v[2:5], v[78:81], v[126:129], v[2:5]
	s_barrier
	s_setprio 0
	s_add_i32 s54, s54, 2
	s_add_u32 s52, s52, 0x100
	s_addc_u32 s53, s53, 0
	s_cmp_gt_u32 s54, 41
	s_cbranch_scc1 .LBB0_999
.LBB0_989:
	ds_read_b128 v[158:161], v213
	ds_read_b128 v[162:165], v213 offset:1024
	ds_read_b128 v[166:169], v213 offset:2048
	ds_read_b128 v[170:173], v213 offset:3072
	ds_read_b128 v[66:69], v214
	ds_read_b128 v[78:81], v214 offset:1024
	ds_read_b128 v[90:93], v214 offset:2048
	ds_read_b128 v[102:105], v214 offset:3072
	s_mov_b64 s[6:7], s[50:51]
	s_add_u32 s50, s6, 0x100
	s_addc_u32 s51, s7, 0
	s_cmp_eq_u32 s54, 40
	s_cselect_b64 s[26:27], -1, 0
	s_and_b64 s[8:9], s[26:27], exec
	s_cselect_b32 s25, s47, s51
	s_cselect_b32 s24, s46, s50
	s_cselect_b32 s9, s49, s53
	s_cselect_b32 s8, s48, s52
	ds_read_b128 v[174:177], v215
	ds_read_b128 v[178:181], v215 offset:1024
	ds_read_b128 v[182:185], v215 offset:2048
	ds_read_b128 v[186:189], v215 offset:3072
	ds_read_b128 v[190:193], v215 offset:4096
	ds_read_b128 v[194:197], v215 offset:5120
	ds_read_b128 v[198:201], v215 offset:6144
	ds_read_b128 v[202:205], v215 offset:7168
	s_add_u32 s6, s6, 0xb0080
	s_addc_u32 s7, s7, 0
	s_add_u32 m0, s28, 0xc000
	s_nop 0
	global_load_lds_dwordx4 v1, s[6:7]
	s_nop 0
	s_add_u32 m0, s28, 0xe000
	s_nop 0
	global_load_lds_dwordx4 v211, s[6:7]
	s_waitcnt vmcnt(8)
	s_waitcnt lgkmcnt(0)
	s_barrier
	v_mfma_f32_16x16x32_f16 v[114:117], v[158:161], v[174:177], v[154:157]
	s_setprio 1
	v_mfma_f32_16x16x32_f16 v[126:129], v[166:169], v[174:177], v[150:153]
	s_waitcnt lgkmcnt(5)
	v_mfma_f32_16x16x32_f16 v[134:137], v[158:161], v[182:185], v[134:137]
	v_mfma_f32_16x16x32_f16 v[130:133], v[166:169], v[182:185], v[130:133]
	s_waitcnt lgkmcnt(3)
	v_mfma_f32_16x16x32_f16 v[110:113], v[158:161], v[190:193], v[110:113]
	v_mfma_f32_16x16x32_f16 v[106:109], v[166:169], v[190:193], v[106:109]
	s_waitcnt lgkmcnt(1)
	v_mfma_f32_16x16x32_f16 v[86:89], v[158:161], v[198:201], v[86:89]
	v_mfma_f32_16x16x32_f16 v[82:85], v[166:169], v[198:201], v[82:85]
	v_mfma_f32_16x16x32_f16 v[114:117], v[162:165], v[178:181], v[114:117]
	v_mfma_f32_16x16x32_f16 v[126:129], v[170:173], v[178:181], v[126:129]
	v_mfma_f32_16x16x32_f16 v[134:137], v[162:165], v[186:189], v[134:137]
	v_mfma_f32_16x16x32_f16 v[130:133], v[170:173], v[186:189], v[130:133]
	v_mfma_f32_16x16x32_f16 v[110:113], v[162:165], v[194:197], v[110:113]
	v_mfma_f32_16x16x32_f16 v[106:109], v[170:173], v[194:197], v[106:109]
	s_waitcnt lgkmcnt(0)
	v_mfma_f32_16x16x32_f16 v[86:89], v[162:165], v[202:205], v[86:89]
	v_mfma_f32_16x16x32_f16 v[82:85], v[170:173], v[202:205], v[82:85]
	v_mfma_f32_16x16x32_f16 v[138:141], v[66:69], v[174:177], v[146:149]
	v_mfma_f32_16x16x32_f16 v[142:145], v[90:93], v[174:177], v[142:145]
	v_mfma_f32_16x16x32_f16 v[122:125], v[66:69], v[182:185], v[122:125]
	v_mfma_f32_16x16x32_f16 v[118:121], v[90:93], v[182:185], v[118:121]
	v_mfma_f32_16x16x32_f16 v[98:101], v[66:69], v[190:193], v[98:101]
	v_mfma_f32_16x16x32_f16 v[94:97], v[90:93], v[190:193], v[94:97]
	v_mfma_f32_16x16x32_f16 v[74:77], v[66:69], v[198:201], v[74:77]
	v_mfma_f32_16x16x32_f16 v[70:73], v[90:93], v[198:201], v[70:73]
	v_mfma_f32_16x16x32_f16 v[138:141], v[78:81], v[178:181], v[138:141]
	v_mfma_f32_16x16x32_f16 v[142:145], v[102:105], v[178:181], v[142:145]
	v_mfma_f32_16x16x32_f16 v[122:125], v[78:81], v[186:189], v[122:125]
	v_mfma_f32_16x16x32_f16 v[118:121], v[102:105], v[186:189], v[118:121]
	v_mfma_f32_16x16x32_f16 v[98:101], v[78:81], v[194:197], v[98:101]
	v_mfma_f32_16x16x32_f16 v[94:97], v[102:105], v[194:197], v[94:97]
	v_mfma_f32_16x16x32_f16 v[74:77], v[78:81], v[202:205], v[74:77]
	v_mfma_f32_16x16x32_f16 v[70:73], v[102:105], v[202:205], v[70:73]
	s_barrier
	s_setprio 0
	ds_read_b128 v[186:189], v215 offset:16384
	ds_read_b128 v[190:193], v215 offset:17408
	ds_read_b128 v[178:181], v215 offset:18432
	ds_read_b128 v[182:185], v215 offset:19456
	ds_read_b128 v[154:157], v215 offset:20480
	ds_read_b128 v[174:177], v215 offset:21504
	ds_read_b128 v[146:149], v215 offset:22528
	ds_read_b128 v[150:153], v215 offset:23552
	s_and_b64 s[6:7], s[4:5], s[26:27]
	s_mov_b64 s[26:27], -1
	s_and_b64 vcc, exec, s[6:7]
	s_cbranch_vccnz .LBB0_991
	s_add_u32 m0, s28, 0x10000
	s_nop 0
	global_load_lds_dwordx4 v210, s[8:9]
	s_nop 0
	s_add_u32 m0, s28, 0x12000
	s_nop 0
	global_load_lds_dwordx4 v212, s[8:9]
	s_add_u32 s26, s8, 0xb0000
	s_addc_u32 s27, s9, 0
	s_add_u32 m0, s28, 0x14000
	s_nop 0
	global_load_lds_dwordx4 v210, s[26:27]
	s_nop 0
	s_add_u32 m0, s28, 0x16000
	s_nop 0
	global_load_lds_dwordx4 v212, s[26:27]
	s_mov_b64 s[26:27], 0
	s_add_u32 m0, s28, 0
	s_nop 0
	global_load_lds_dwordx4 v1, s[24:25]
	s_nop 0
	s_add_u32 m0, s28, 0x2000
	s_nop 0
	global_load_lds_dwordx4 v211, s[24:25]
	s_waitcnt vmcnt(8)

; #define PG8_STAGE(bufoff, gbase, voff) do { if constexpr (ABL & 1) break; glds16s<(bufoff)>((voff)[0], (const void*)(gbase), ldsbw); glds16s<(bufoff) + 8192>((voff)[1], (const void*)(gbase), ldsbw); } while (0)
; #define PG8_LDA(dst, b, h) do { if constexpr (ABL & 4) break; _Pragma("unroll") for (int m = 0; m < 4; ++m) _Pragma("unroll") for (int k = 0; k < 2; ++k) dst[m][k] = *(const LAS f16x8*)(lds + PG8_SA(b, h) + aoff + m * 2048 + k * 1024); } while (0)
; #define PG8_LDB(dst, b, h) do { if constexpr (ABL & 4) break; _Pragma("unroll") for (int n = 0; n < 2; ++n) _Pragma("unroll") for (int k = 0; k < 2; ++k) dst[n][k] = *(const LAS f16x8*)(lds + PG8_SB(b, h) + boff + n * 2048 + k * 1024); } while (0)
; #define PG8_MMA(ai, bj, At, Bt) do { if constexpr (ABL & 2) break; __builtin_amdgcn_s_setprio(1); _Pragma("unroll") for (int m = 0; m < 4; ++m) _Pragma("unroll") for (int n = 0; n < 2; ++n) _Pragma("unroll") for (int k = 0; k < 2; ++k) \
;         acc[ai][bj][m][n] = __builtin_amdgcn_mfma_f32_16x16x32_f16(Bt[n][k], At[m][k], acc[ai][bj][m][n], 0, 0, 0); __builtin_amdgcn_s_setprio(0); } while (0)
; #define PG8_MMAF(ai, bj, At, Bt) do { if (t == 0) PG8_MMA0(ai, bj, At, Bt); else PG8_MMA(ai, bj, At, Bt); } while (0)
; #define PG8_WAIT_V(n) asm volatile("s_waitcnt vmcnt(" #n ")" ::: "memory")
; #define PG8_WAIT_L(n) asm volatile("s_waitcnt lgkmcnt(" #n ")" ::: "memory")
; #define PG8_BAR __builtin_amdgcn_s_barrier()
; #define PG8_SCHED __builtin_amdgcn_sched_barrier(0)
;     ...
;             if (!fin) PG8_WAIT_V(8); else PG8_WAIT_V(2); PG8_WAIT_L(0); PG8_BAR; PG8_MMAF(1, 0, At, B0); PG8_MMAF(1, 1, At, B1); PG8_BAR; PG8_SCHED;
;             PG8_LDB(B0, 1, 0); PG8_LDB(B1, 1, 1); PG8_SCHED; PG8_LDA(At, 1, 0); if (!fin) PG8_STAGE(PG8_SA(0, 1), a2 + hstep, voffA);
;             if (!fin) PG8_WAIT_V(8); else PG8_WAIT_V(0); PG8_WAIT_L(0); PG8_BAR; PG8_MMA(0, 0, At, B0); PG8_MMA(0, 1, At, B1); PG8_BAR; PG8_SCHED;
.LBB0_993:
	s_waitcnt lgkmcnt(0)
	s_xor_b64 s[26:27], s[6:7], -1
	s_barrier
	v_mfma_f32_16x16x32_f16 v[62:65], v[158:161], v[186:189], v[62:65]
	s_setprio 1
	v_mfma_f32_16x16x32_f16 v[58:61], v[166:169], v[186:189], v[58:61]
	s_waitcnt lgkmcnt(5)
	v_mfma_f32_16x16x32_f16 v[46:49], v[158:161], v[178:181], v[46:49]
	v_mfma_f32_16x16x32_f16 v[42:45], v[166:169], v[178:181], v[42:45]
	s_waitcnt lgkmcnt(3)
	v_mfma_f32_16x16x32_f16 v[30:33], v[158:161], v[154:157], v[30:33]
	v_mfma_f32_16x16x32_f16 v[26:29], v[166:169], v[154:157], v[26:29]
	s_waitcnt lgkmcnt(1)
	v_mfma_f32_16x16x32_f16 v[14:17], v[158:161], v[146:149], v[14:17]
	v_mfma_f32_16x16x32_f16 v[10:13], v[166:169], v[146:149], v[10:13]
	v_mfma_f32_16x16x32_f16 v[62:65], v[162:165], v[190:193], v[62:65]
	v_mfma_f32_16x16x32_f16 v[58:61], v[170:173], v[190:193], v[58:61]
	v_mfma_f32_16x16x32_f16 v[46:49], v[162:165], v[182:185], v[46:49]
	v_mfma_f32_16x16x32_f16 v[42:45], v[170:173], v[182:185], v[42:45]
	v_mfma_f32_16x16x32_f16 v[30:33], v[162:165], v[174:177], v[30:33]
	v_mfma_f32_16x16x32_f16 v[26:29], v[170:173], v[174:177], v[26:29]
	s_waitcnt lgkmcnt(0)
	v_mfma_f32_16x16x32_f16 v[14:17], v[162:165], v[150:153], v[14:17]
	v_mfma_f32_16x16x32_f16 v[10:13], v[170:173], v[150:153], v[10:13]
	v_mfma_f32_16x16x32_f16 v[54:57], v[66:69], v[186:189], v[54:57]
	v_mfma_f32_16x16x32_f16 v[50:53], v[90:93], v[186:189], v[50:53]
	v_mfma_f32_16x16x32_f16 v[38:41], v[66:69], v[178:181], v[38:41]
	v_mfma_f32_16x16x32_f16 v[34:37], v[90:93], v[178:181], v[34:37]
	v_mfma_f32_16x16x32_f16 v[22:25], v[66:69], v[154:157], v[22:25]
	v_mfma_f32_16x16x32_f16 v[18:21], v[90:93], v[154:157], v[18:21]
	v_mfma_f32_16x16x32_f16 v[6:9], v[66:69], v[146:149], v[6:9]
	v_mfma_f32_16x16x32_f16 v[2:5], v[90:93], v[146:149], v[2:5]
	v_mfma_f32_16x16x32_f16 v[54:57], v[78:81], v[190:193], v[54:57]
	v_mfma_f32_16x16x32_f16 v[50:53], v[102:105], v[190:193], v[50:53]
	v_mfma_f32_16x16x32_f16 v[38:41], v[78:81], v[182:185], v[38:41]
	v_mfma_f32_16x16x32_f16 v[34:37], v[102:105], v[182:185], v[34:37]
	v_mfma_f32_16x16x32_f16 v[22:25], v[78:81], v[174:177], v[22:25]
	v_mfma_f32_16x16x32_f16 v[18:21], v[102:105], v[174:177], v[18:21]
	v_mfma_f32_16x16x32_f16 v[6:9], v[78:81], v[150:153], v[6:9]
	v_mfma_f32_16x16x32_f16 v[2:5], v[102:105], v[150:153], v[2:5]
	s_barrier
	s_setprio 0
	ds_read_b128 v[166:169], v216
	ds_read_b128 v[170:173], v216 offset:1024
	ds_read_b128 v[158:161], v216 offset:2048
	ds_read_b128 v[162:165], v216 offset:3072
	ds_read_b128 v[90:93], v217
	ds_read_b128 v[102:105], v217 offset:1024
	ds_read_b128 v[66:69], v217 offset:2048
	ds_read_b128 v[78:81], v217 offset:3072
	ds_read_b128 v[198:201], v215 offset:32768
	ds_read_b128 v[202:205], v215 offset:33792
	ds_read_b128 v[190:193], v215 offset:34816
	ds_read_b128 v[194:197], v215 offset:35840
	ds_read_b128 v[182:185], v215 offset:36864
	ds_read_b128 v[186:189], v215 offset:37888
	ds_read_b128 v[174:177], v215 offset:38912
	ds_read_b128 v[178:181], v215 offset:39936
	v_cndmask_b32_e64 v146, 0, 1, s[26:27]
	v_cmp_ne_u32_e64 s[6:7], 1, v146
	s_andn2_b64 vcc, exec, s[26:27]
	s_mov_b64 s[26:27], -1
	s_cbranch_vccnz .LBB0_995
	s_add_u32 s26, s24, 0xb0000
	s_addc_u32 s27, s25, 0
	s_add_u32 m0, s28, 0x4000
	s_nop 0
	global_load_lds_dwordx4 v1, s[26:27]
	s_nop 0
	s_add_u32 m0, s28, 0x6000
	s_nop 0
	global_load_lds_dwordx4 v211, s[26:27]
	s_waitcnt vmcnt(8)
	s_mov_b64 s[26:27], 0

; #define PG8_STAGE(bufoff, gbase, voff) do { if constexpr (ABL & 1) break; glds16s<(bufoff)>((voff)[0], (const void*)(gbase), ldsbw); glds16s<(bufoff) + 8192>((voff)[1], (const void*)(gbase), ldsbw); } while (0)
; #define PG8_LDA(dst, b, h) do { if constexpr (ABL & 4) break; _Pragma("unroll") for (int m = 0; m < 4; ++m) _Pragma("unroll") for (int k = 0; k < 2; ++k) dst[m][k] = *(const LAS f16x8*)(lds + PG8_SA(b, h) + aoff + m * 2048 + k * 1024); } while (0)
; #define PG8_MMA(ai, bj, At, Bt) do { if constexpr (ABL & 2) break; __builtin_amdgcn_s_setprio(1); _Pragma("unroll") for (int m = 0; m < 4; ++m) _Pragma("unroll") for (int n = 0; n < 2; ++n) _Pragma("unroll") for (int k = 0; k < 2; ++k) \
;         acc[ai][bj][m][n] = __builtin_amdgcn_mfma_f32_16x16x32_f16(Bt[n][k], At[m][k], acc[ai][bj][m][n], 0, 0, 0); __builtin_amdgcn_s_setprio(0); } while (0)
; #define PG8_WAIT_V(n) asm volatile("s_waitcnt vmcnt(" #n ")" ::: "memory")
; #define PG8_WAIT_L(n) asm volatile("s_waitcnt lgkmcnt(" #n ")" ::: "memory")
; #define PG8_BAR __builtin_amdgcn_s_barrier()
; #define PG8_SCHED __builtin_amdgcn_sched_barrier(0)
;     ...
;             if (!fin) PG8_WAIT_V(8); else PG8_WAIT_V(0); PG8_WAIT_L(0); PG8_BAR; PG8_MMA(0, 0, At, B0); PG8_MMA(0, 1, At, B1); PG8_BAR; PG8_SCHED;
;             PG8_LDA(At, 1, 1); if (!fin) { PG8_STAGE(PG8_SB(1, 0), b3, voffB); PG8_STAGE(PG8_SB(1, 1), b3 + hstep, voffB); PG8_STAGE(PG8_SA(1, 0), a3, voffA); }
;             if (!fin) PG8_WAIT_V(8); PG8_WAIT_L(0); PG8_BAR; PG8_MMA(1, 0, At, B0); PG8_MMA(1, 1, At, B1); PG8_BAR; PG8_SCHED;
.LBB0_997:
	s_waitcnt lgkmcnt(0)
	s_barrier
	v_mfma_f32_16x16x32_f16 v[114:117], v[166:169], v[198:201], v[114:117]
	s_setprio 1
	s_waitcnt lgkmcnt(6)
	v_mfma_f32_16x16x32_f16 v[154:157], v[170:173], v[202:205], v[114:117]
	v_mfma_f32_16x16x32_f16 v[114:117], v[158:161], v[198:201], v[126:129]
	v_mfma_f32_16x16x32_f16 v[150:153], v[162:165], v[202:205], v[114:117]
	s_waitcnt lgkmcnt(5)
	v_mfma_f32_16x16x32_f16 v[114:117], v[166:169], v[190:193], v[134:137]
	s_waitcnt lgkmcnt(4)
	v_mfma_f32_16x16x32_f16 v[134:137], v[170:173], v[194:197], v[114:117]
	v_mfma_f32_16x16x32_f16 v[114:117], v[158:161], v[190:193], v[130:133]
	s_waitcnt lgkmcnt(3)
	v_mfma_f32_16x16x32_f16 v[110:113], v[166:169], v[182:185], v[110:113]
	v_mfma_f32_16x16x32_f16 v[106:109], v[158:161], v[182:185], v[106:109]
	s_waitcnt lgkmcnt(1)
	v_mfma_f32_16x16x32_f16 v[86:89], v[166:169], v[174:177], v[86:89]
	v_mfma_f32_16x16x32_f16 v[82:85], v[158:161], v[174:177], v[82:85]
	v_mfma_f32_16x16x32_f16 v[130:133], v[162:165], v[194:197], v[114:117]
	v_mfma_f32_16x16x32_f16 v[110:113], v[170:173], v[186:189], v[110:113]
	v_mfma_f32_16x16x32_f16 v[106:109], v[162:165], v[186:189], v[106:109]
	s_waitcnt lgkmcnt(0)
	v_mfma_f32_16x16x32_f16 v[86:89], v[170:173], v[178:181], v[86:89]
	v_mfma_f32_16x16x32_f16 v[82:85], v[162:165], v[178:181], v[82:85]
	v_mfma_f32_16x16x32_f16 v[114:117], v[90:93], v[198:201], v[138:141]
	v_mfma_f32_16x16x32_f16 v[146:149], v[102:105], v[202:205], v[114:117]
	v_mfma_f32_16x16x32_f16 v[114:117], v[66:69], v[198:201], v[142:145]
	v_mfma_f32_16x16x32_f16 v[142:145], v[78:81], v[202:205], v[114:117]
	v_mfma_f32_16x16x32_f16 v[114:117], v[90:93], v[190:193], v[122:125]
	v_mfma_f32_16x16x32_f16 v[122:125], v[102:105], v[194:197], v[114:117]
	v_mfma_f32_16x16x32_f16 v[114:117], v[66:69], v[190:193], v[118:121]
	v_mfma_f32_16x16x32_f16 v[98:101], v[90:93], v[182:185], v[98:101]
	v_mfma_f32_16x16x32_f16 v[94:97], v[66:69], v[182:185], v[94:97]
	v_mfma_f32_16x16x32_f16 v[74:77], v[90:93], v[174:177], v[74:77]
	v_mfma_f32_16x16x32_f16 v[70:73], v[66:69], v[174:177], v[70:73]
	v_mfma_f32_16x16x32_f16 v[118:121], v[78:81], v[194:197], v[114:117]
	v_mfma_f32_16x16x32_f16 v[98:101], v[102:105], v[186:189], v[98:101]
	v_mfma_f32_16x16x32_f16 v[94:97], v[78:81], v[186:189], v[94:97]
	v_mfma_f32_16x16x32_f16 v[74:77], v[102:105], v[178:181], v[74:77]
	v_mfma_f32_16x16x32_f16 v[70:73], v[78:81], v[178:181], v[70:73]
	s_barrier
	s_setprio 0
	ds_read_b128 v[186:189], v215 offset:49152
	ds_read_b128 v[190:193], v215 offset:50176
	ds_read_b128 v[178:181], v215 offset:51200
	ds_read_b128 v[182:185], v215 offset:52224
	ds_read_b128 v[138:141], v215 offset:53248
	ds_read_b128 v[174:177], v215 offset:54272
	ds_read_b128 v[114:117], v215 offset:55296
	ds_read_b128 v[126:129], v215 offset:56320
	s_and_b64 vcc, exec, s[6:7]
	s_cbranch_vccnz .LBB0_988
	s_add_u32 s6, s24, 0x80
	s_addc_u32 s7, s25, 0
	s_add_u32 s24, s8, 0x80
	s_addc_u32 s25, s9, 0
	s_add_u32 m0, s28, 0x18000
	s_nop 0
	global_load_lds_dwordx4 v210, s[24:25]
	s_nop 0
	s_add_u32 m0, s28, 0x1a000
	s_nop 0
	global_load_lds_dwordx4 v212, s[24:25]
	s_add_u32 s8, s8, 0xb0080
	s_addc_u32 s9, s9, 0
	s_add_u32 m0, s28, 0x1c000
	s_nop 0
	global_load_lds_dwordx4 v210, s[8:9]
	s_nop 0
	s_add_u32 m0, s28, 0x1e000
	s_nop 0
	global_load_lds_dwordx4 v212, s[8:9]
	s_nop 0
	s_add_u32 m0, s28, 0x8000
	s_nop 0
	global_load_lds_dwordx4 v1, s[6:7]
	s_nop 0
	s_add_u32 m0, s28, 0xa000
	s_nop 0
	global_load_lds_dwordx4 v211, s[6:7]
	s_waitcnt vmcnt(8)
	s_branch .LBB0_988

;     __device__ __forceinline__ bool next(int i, Unit& u) const { if (i >= count) return false; const int L = first + i; u.pm = L / nN; u.pn = L % nN; return true; }
; #define PG8_STAGE(bufoff, gbase, voff) do { if constexpr (ABL & 1) break; glds16s<(bufoff)>((voff)[0], (const void*)(gbase), ldsbw); glds16s<(bufoff) + 8192>((voff)[1], (const void*)(gbase), ldsbw); } while (0)
; #define PG8_LDA(dst, b, h) do { if constexpr (ABL & 4) break; _Pragma("unroll") for (int m = 0; m < 4; ++m) _Pragma("unroll") for (int k = 0; k < 2; ++k) dst[m][k] = *(const LAS f16x8*)(lds + PG8_SA(b, h) + aoff + m * 2048 + k * 1024); } while (0)
; #define PG8_LDB(dst, b, h) do { if constexpr (ABL & 4) break; _Pragma("unroll") for (int n = 0; n < 2; ++n) _Pragma("unroll") for (int k = 0; k < 2; ++k) dst[n][k] = *(const LAS f16x8*)(lds + PG8_SB(b, h) + boff + n * 2048 + k * 1024); } while (0)
; #define PG8_MMAF(ai, bj, At, Bt) do { if (t == 0) PG8_MMA0(ai, bj, At, Bt); else PG8_MMA(ai, bj, At, Bt); } while (0)
; #define PG8_WAIT_V(n) asm volatile("s_waitcnt vmcnt(" #n ")" ::: "memory")
; #define PG8_BAR __builtin_amdgcn_s_barrier()
;     ...
;         const bool has_next = S.next(ui + 1, nxt);
;         const char* nA = has_next ? (const char*)g.A + (size_t)nxt.pm * tstep : cA; const char* nB = has_next ? (const char*)g.Bt + (size_t)nxt.pn * tstep : cB;
;         for (int t = 0; t < nt; t += 2) {
;             const bool last = (t == nt - 2);
;             const char* a1 = cA + (size_t)(t + 1) * kstep;
;             const char* a2 = last ? nA : cA + (size_t)(t + 2) * kstep; const char* b2 = last ? nB : cB + (size_t)(t + 2) * kstep;
;             const char* a3 = a2 + kstep; const char* b3 = b2 + kstep;
;             if (last && has_next) S.a_ready(nxt);
;             if constexpr (SP2) {
;             PG8_LDB(B0, 0, 0); PG8_LDB(B1, 0, 1); PG8_SCHED; PG8_LDA(At, 0, 0); PG8_STAGE(PG8_SA(1, 1), a1 + hstep, voffA);
;             PG8_WAIT_V(8); PG8_WAIT_L(0); PG8_BAR; PG8_MMAF(0, 0, At, B0); PG8_MMAF(0, 1, At, B1); PG8_BAR; PG8_SCHED;
;             const bool fin = last && !has_next;
;             PG8_LDA(At, 0, 1); if (!fin) { PG8_STAGE(PG8_SB(0, 0), b2, voffB); PG8_STAGE(PG8_SB(0, 1), b2 + hstep, voffB); PG8_STAGE(PG8_SA(0, 0), a2, voffA); }
;             if (!fin) PG8_WAIT_V(8); else PG8_WAIT_V(2); PG8_WAIT_L(0); PG8_BAR; PG8_MMAF(1, 0, At, B0); PG8_MMAF(1, 1, At, B1); PG8_BAR; PG8_SCHED;
.LBB0_1111:
	s_ashr_i32 s43, s42, 31
	s_lshl_b64 s[8:9], s[42:43], 19
	s_add_u32 s44, s74, s8
	s_addc_u32 s45, s75, s9
	s_and_b64 s[8:9], exec, s[4:5]
	s_waitcnt lgkmcnt(0)
	ds_read_b128 v[2:5], v201
	ds_read_b128 v[6:9], v201 offset:1024
	ds_read_b128 v[10:13], v201 offset:2048
	ds_read_b128 v[14:17], v201 offset:3072
	ds_read_b128 v[18:21], v202
	ds_read_b128 v[22:25], v202 offset:1024
	ds_read_b128 v[26:29], v202 offset:2048
	ds_read_b128 v[30:33], v202 offset:3072
	s_cselect_b32 s43, s55, s45
	s_cselect_b32 s56, s54, s44
	s_ashr_i32 s41, s40, 31
	s_lshl_b64 s[8:9], s[40:41], 19
	s_add_u32 s46, s94, s8
	s_addc_u32 s47, s95, s9
	s_and_b64 s[8:9], exec, s[4:5]
	s_cselect_b32 s41, s7, s47
	s_cselect_b32 s57, s6, s46
	s_add_u32 s52, s54, 0x100
	s_addc_u32 s53, s55, 0
	s_add_u32 s26, s6, 0x100
	s_addc_u32 s27, s7, 0
	s_add_u32 s8, s54, 0x180
	s_addc_u32 s9, s55, 0
	ds_read_b128 v[34:37], v203
	ds_read_b128 v[38:41], v203 offset:1024
	ds_read_b128 v[42:45], v203 offset:2048
	ds_read_b128 v[46:49], v203 offset:3072
	ds_read_b128 v[50:53], v203 offset:4096
	ds_read_b128 v[54:57], v203 offset:5120
	ds_read_b128 v[58:61], v203 offset:6144
	ds_read_b128 v[62:65], v203 offset:7168
	s_add_u32 s24, s6, 0x180
	s_addc_u32 s25, s7, 0
	s_add_u32 s58, s54, 0x40080
	s_addc_u32 s59, s55, 0
	s_add_u32 m0, s28, 0xc000
	s_nop 0
	global_load_lds_dwordx4 v1, s[58:59]
	s_nop 0
	s_add_u32 m0, s28, 0xe000
	s_nop 0
	global_load_lds_dwordx4 v199, s[58:59]
	s_waitcnt vmcnt(8)
	s_waitcnt lgkmcnt(0)
	s_barrier
	v_mfma_f32_16x16x32_f16 v[90:93], v[2:5], v[58:61], 0
	s_setprio 1
	v_mfma_f32_16x16x32_f16 v[66:69], v[2:5], v[34:37], 0
	v_mfma_f32_16x16x32_f16 v[70:73], v[10:13], v[34:37], 0
	v_mfma_f32_16x16x32_f16 v[74:77], v[2:5], v[42:45], 0
	v_mfma_f32_16x16x32_f16 v[78:81], v[10:13], v[42:45], 0
	v_mfma_f32_16x16x32_f16 v[82:85], v[2:5], v[50:53], 0
	v_mfma_f32_16x16x32_f16 v[86:89], v[10:13], v[50:53], 0
	s_waitcnt lgkmcnt(0)
	v_mfma_f32_16x16x32_f16 v[98:101], v[6:9], v[62:65], v[90:93]
	v_mfma_f32_16x16x32_f16 v[90:93], v[10:13], v[58:61], 0
	v_mfma_f32_16x16x32_f16 v[66:69], v[6:9], v[38:41], v[66:69]
	v_mfma_f32_16x16x32_f16 v[70:73], v[14:17], v[38:41], v[70:73]
	v_mfma_f32_16x16x32_f16 v[74:77], v[6:9], v[46:49], v[74:77]
	v_mfma_f32_16x16x32_f16 v[78:81], v[14:17], v[46:49], v[78:81]
	v_mfma_f32_16x16x32_f16 v[82:85], v[6:9], v[54:57], v[82:85]
	v_mfma_f32_16x16x32_f16 v[86:89], v[14:17], v[54:57], v[86:89]
	v_mfma_f32_16x16x32_f16 v[102:105], v[14:17], v[62:65], v[90:93]
	v_mfma_f32_16x16x32_f16 v[90:93], v[18:21], v[34:37], 0
	v_mfma_f32_16x16x32_f16 v[34:37], v[26:29], v[34:37], 0
	v_mfma_f32_16x16x32_f16 v[114:117], v[22:25], v[38:41], v[90:93]
	v_mfma_f32_16x16x32_f16 v[34:37], v[30:33], v[38:41], v[34:37]
	v_mfma_f32_16x16x32_f16 v[38:41], v[18:21], v[42:45], 0
	v_mfma_f32_16x16x32_f16 v[42:45], v[26:29], v[42:45], 0
	v_mfma_f32_16x16x32_f16 v[38:41], v[22:25], v[46:49], v[38:41]
	v_mfma_f32_16x16x32_f16 v[42:45], v[30:33], v[46:49], v[42:45]
	v_mfma_f32_16x16x32_f16 v[46:49], v[18:21], v[50:53], 0
	v_mfma_f32_16x16x32_f16 v[50:53], v[26:29], v[50:53], 0
	v_mfma_f32_16x16x32_f16 v[46:49], v[22:25], v[54:57], v[46:49]
	v_mfma_f32_16x16x32_f16 v[50:53], v[30:33], v[54:57], v[50:53]
	v_mfma_f32_16x16x32_f16 v[54:57], v[18:21], v[58:61], 0
	v_mfma_f32_16x16x32_f16 v[58:61], v[26:29], v[58:61], 0
	v_mfma_f32_16x16x32_f16 v[54:57], v[22:25], v[62:65], v[54:57]
	v_mfma_f32_16x16x32_f16 v[58:61], v[30:33], v[62:65], v[58:61]
	s_barrier
	s_setprio 0
	ds_read_b128 v[62:65], v203 offset:16384
	ds_read_b128 v[90:93], v203 offset:17408
	ds_read_b128 v[94:97], v203 offset:18432
	ds_read_b128 v[106:109], v203 offset:19456
	ds_read_b128 v[110:113], v203 offset:20480
	ds_read_b128 v[118:121], v203 offset:21504
	ds_read_b128 v[122:125], v203 offset:22528
	ds_read_b128 v[126:129], v203 offset:23552
	s_add_u32 m0, s28, 0x10000
	s_nop 0
	global_load_lds_dwordx4 v198, s[26:27]
	s_nop 0
	s_add_u32 m0, s28, 0x12000
	s_nop 0
	global_load_lds_dwordx4 v200, s[26:27]
	s_add_u32 s26, s6, 0x40100
	s_addc_u32 s27, s7, 0
	s_add_u32 m0, s28, 0x14000
	s_nop 0
	global_load_lds_dwordx4 v198, s[26:27]
	s_nop 0
	s_add_u32 m0, s28, 0x16000
	s_nop 0
	global_load_lds_dwordx4 v200, s[26:27]
	s_nop 0
	s_add_u32 m0, s28, 0
	s_nop 0
	global_load_lds_dwordx4 v1, s[52:53]
	s_nop 0
	s_add_u32 m0, s28, 0x2000
	s_nop 0
	global_load_lds_dwordx4 v199, s[52:53]
	s_waitcnt vmcnt(8)
	s_waitcnt lgkmcnt(0)
	s_barrier
	v_mfma_f32_16x16x32_f16 v[130:133], v[2:5], v[62:65], 0
	s_setprio 1
	s_waitcnt lgkmcnt(5)
	v_mfma_f32_16x16x32_f16 v[138:141], v[2:5], v[94:97], 0
	s_waitcnt lgkmcnt(3)
	v_mfma_f32_16x16x32_f16 v[146:149], v[2:5], v[110:113], 0
	s_waitcnt lgkmcnt(1)
	v_mfma_f32_16x16x32_f16 v[2:5], v[2:5], v[122:125], 0
	v_mfma_f32_16x16x32_f16 v[130:133], v[6:9], v[90:93], v[130:133]
	v_mfma_f32_16x16x32_f16 v[138:141], v[6:9], v[106:109], v[138:141]
	v_mfma_f32_16x16x32_f16 v[146:149], v[6:9], v[118:121], v[146:149]
	s_waitcnt lgkmcnt(0)
	v_mfma_f32_16x16x32_f16 v[2:5], v[6:9], v[126:129], v[2:5]
	v_mfma_f32_16x16x32_f16 v[6:9], v[10:13], v[122:125], 0
	v_mfma_f32_16x16x32_f16 v[134:137], v[10:13], v[62:65], 0
	v_mfma_f32_16x16x32_f16 v[142:145], v[10:13], v[94:97], 0
	v_mfma_f32_16x16x32_f16 v[150:153], v[10:13], v[110:113], 0
	v_mfma_f32_16x16x32_f16 v[6:9], v[14:17], v[126:129], v[6:9]
	v_mfma_f32_16x16x32_f16 v[134:137], v[14:17], v[90:93], v[134:137]
	v_mfma_f32_16x16x32_f16 v[142:145], v[14:17], v[106:109], v[142:145]
	v_mfma_f32_16x16x32_f16 v[150:153], v[14:17], v[118:121], v[150:153]
	v_mfma_f32_16x16x32_f16 v[10:13], v[18:21], v[62:65], 0
	v_mfma_f32_16x16x32_f16 v[154:157], v[22:25], v[90:93], v[10:13]
	v_mfma_f32_16x16x32_f16 v[10:13], v[26:29], v[62:65], 0
	v_mfma_f32_16x16x32_f16 v[158:161], v[30:33], v[90:93], v[10:13]
	v_mfma_f32_16x16x32_f16 v[10:13], v[18:21], v[94:97], 0
	v_mfma_f32_16x16x32_f16 v[162:165], v[22:25], v[106:109], v[10:13]
	v_mfma_f32_16x16x32_f16 v[10:13], v[26:29], v[94:97], 0
	v_mfma_f32_16x16x32_f16 v[166:169], v[30:33], v[106:109], v[10:13]
	v_mfma_f32_16x16x32_f16 v[10:13], v[18:21], v[110:113], 0
	v_mfma_f32_16x16x32_f16 v[170:173], v[22:25], v[118:121], v[10:13]
	v_mfma_f32_16x16x32_f16 v[10:13], v[26:29], v[110:113], 0
	v_mfma_f32_16x16x32_f16 v[174:177], v[30:33], v[118:121], v[10:13]
	v_mfma_f32_16x16x32_f16 v[10:13], v[18:21], v[122:125], 0
	v_mfma_f32_16x16x32_f16 v[178:181], v[22:25], v[126:129], v[10:13]
	v_mfma_f32_16x16x32_f16 v[10:13], v[26:29], v[122:125], 0
	v_mfma_f32_16x16x32_f16 v[182:185], v[30:33], v[126:129], v[10:13]
	s_barrier
; #define PG8_STAGE(bufoff, gbase, voff) do { if constexpr (ABL & 1) break; glds16s<(bufoff)>((voff)[0], (const void*)(gbase), ldsbw); glds16s<(bufoff) + 8192>((voff)[1], (const void*)(gbase), ldsbw); } while (0)
; #define PG8_LDA(dst, b, h) do { if constexpr (ABL & 4) break; _Pragma("unroll") for (int m = 0; m < 4; ++m) _Pragma("unroll") for (int k = 0; k < 2; ++k) dst[m][k] = *(const LAS f16x8*)(lds + PG8_SA(b, h) + aoff + m * 2048 + k * 1024); } while (0)
; #define PG8_LDB(dst, b, h) do { if constexpr (ABL & 4) break; _Pragma("unroll") for (int n = 0; n < 2; ++n) _Pragma("unroll") for (int k = 0; k < 2; ++k) dst[n][k] = *(const LAS f16x8*)(lds + PG8_SB(b, h) + boff + n * 2048 + k * 1024); } while (0)
; #define PG8_MMA(ai, bj, At, Bt) do { if constexpr (ABL & 2) break; __builtin_amdgcn_s_setprio(1); _Pragma("unroll") for (int m = 0; m < 4; ++m) _Pragma("unroll") for (int n = 0; n < 2; ++n) _Pragma("unroll") for (int k = 0; k < 2; ++k) \
;         acc[ai][bj][m][n] = __builtin_amdgcn_mfma_f32_16x16x32_f16(Bt[n][k], At[m][k], acc[ai][bj][m][n], 0, 0, 0); __builtin_amdgcn_s_setprio(0); } while (0)
; #define PG8_WAIT_V(n) asm volatile("s_waitcnt vmcnt(" #n ")" ::: "memory")
; #define PG8_WAIT_L(n) asm volatile("s_waitcnt lgkmcnt(" #n ")" ::: "memory")
; #define PG8_BAR __builtin_amdgcn_s_barrier()
; #define PG8_SCHED __builtin_amdgcn_sched_barrier(0)
;     ...
;             PG8_LDB(B0, 1, 0); PG8_LDB(B1, 1, 1); PG8_SCHED; PG8_LDA(At, 1, 0); if (!fin) PG8_STAGE(PG8_SA(0, 1), a2 + hstep, voffA);
;             if (!fin) PG8_WAIT_V(8); else PG8_WAIT_V(0); PG8_WAIT_L(0); PG8_BAR; PG8_MMA(0, 0, At, B0); PG8_MMA(0, 1, At, B1); PG8_BAR; PG8_SCHED;
;             PG8_LDA(At, 1, 1); if (!fin) { PG8_STAGE(PG8_SB(1, 0), b3, voffB); PG8_STAGE(PG8_SB(1, 1), b3 + hstep, voffB); PG8_STAGE(PG8_SA(1, 0), a3, voffA); }
;             if (!fin) PG8_WAIT_V(8); PG8_WAIT_L(0); PG8_BAR; PG8_MMA(1, 0, At, B0); PG8_MMA(1, 1, At, B1); PG8_BAR; PG8_SCHED;
	s_setprio 0
	s_nop 4
	ds_read_b128 v[10:13], v204
	ds_read_b128 v[14:17], v204 offset:1024
	ds_read_b128 v[18:21], v204 offset:2048
	ds_read_b128 v[22:25], v204 offset:3072
	ds_read_b128 v[186:189], v205
	ds_read_b128 v[190:193], v205 offset:1024
	ds_read_b128 v[210:213], v205 offset:2048
	ds_read_b128 v[214:217], v205 offset:3072
	ds_read_b128 v[26:29], v203 offset:32768
	ds_read_b128 v[30:33], v203 offset:33792
	ds_read_b128 v[62:65], v203 offset:34816
	ds_read_b128 v[218:221], v203 offset:35840
	ds_read_b128 v[222:225], v203 offset:36864
	ds_read_b128 v[226:229], v203 offset:37888
	ds_read_b128 v[230:233], v203 offset:38912
	ds_read_b128 v[234:237], v203 offset:39936
	s_add_u32 s26, s54, 0x40100
	s_addc_u32 s27, s55, 0
	s_add_u32 m0, s28, 0x4000
	s_nop 0
	global_load_lds_dwordx4 v1, s[26:27]
	s_nop 0
	s_add_u32 m0, s28, 0x6000
	s_nop 0
	global_load_lds_dwordx4 v199, s[26:27]
	s_waitcnt vmcnt(8)
	s_waitcnt lgkmcnt(0)
	s_barrier
	v_mfma_f32_16x16x32_f16 v[66:69], v[10:13], v[26:29], v[66:69]
	s_setprio 1
	s_waitcnt lgkmcnt(6)
	v_mfma_f32_16x16x32_f16 v[126:129], v[14:17], v[30:33], v[66:69]
	v_mfma_f32_16x16x32_f16 v[66:69], v[18:21], v[26:29], v[70:73]
	v_mfma_f32_16x16x32_f16 v[122:125], v[22:25], v[30:33], v[66:69]
	s_waitcnt lgkmcnt(5)
	v_mfma_f32_16x16x32_f16 v[66:69], v[10:13], v[62:65], v[74:77]
	s_waitcnt lgkmcnt(4)
	v_mfma_f32_16x16x32_f16 v[110:113], v[14:17], v[218:221], v[66:69]
	v_mfma_f32_16x16x32_f16 v[66:69], v[18:21], v[62:65], v[78:81]
	v_mfma_f32_16x16x32_f16 v[106:109], v[22:25], v[218:221], v[66:69]
	s_waitcnt lgkmcnt(3)
	v_mfma_f32_16x16x32_f16 v[66:69], v[10:13], v[222:225], v[82:85]
	s_waitcnt lgkmcnt(2)
	v_mfma_f32_16x16x32_f16 v[94:97], v[14:17], v[226:229], v[66:69]
	v_mfma_f32_16x16x32_f16 v[66:69], v[18:21], v[222:225], v[86:89]
	v_mfma_f32_16x16x32_f16 v[90:93], v[22:25], v[226:229], v[66:69]
	s_waitcnt lgkmcnt(1)
	v_mfma_f32_16x16x32_f16 v[66:69], v[10:13], v[230:233], v[98:101]
	s_waitcnt lgkmcnt(0)
	v_mfma_f32_16x16x32_f16 v[78:81], v[14:17], v[234:237], v[66:69]
	v_mfma_f32_16x16x32_f16 v[66:69], v[18:21], v[230:233], v[102:105]
	v_mfma_f32_16x16x32_f16 v[74:77], v[22:25], v[234:237], v[66:69]
	v_mfma_f32_16x16x32_f16 v[66:69], v[186:189], v[26:29], v[114:117]
	v_mfma_f32_16x16x32_f16 v[26:29], v[210:213], v[26:29], v[34:37]
	v_mfma_f32_16x16x32_f16 v[114:117], v[214:217], v[30:33], v[26:29]
	v_mfma_f32_16x16x32_f16 v[26:29], v[186:189], v[62:65], v[38:41]
	v_mfma_f32_16x16x32_f16 v[102:105], v[190:193], v[218:221], v[26:29]
	v_mfma_f32_16x16x32_f16 v[26:29], v[210:213], v[62:65], v[42:45]
	v_mfma_f32_16x16x32_f16 v[98:101], v[214:217], v[218:221], v[26:29]
	v_mfma_f32_16x16x32_f16 v[26:29], v[186:189], v[222:225], v[46:49]
	v_mfma_f32_16x16x32_f16 v[86:89], v[190:193], v[226:229], v[26:29]
	v_mfma_f32_16x16x32_f16 v[26:29], v[210:213], v[222:225], v[50:53]
	v_mfma_f32_16x16x32_f16 v[82:85], v[214:217], v[226:229], v[26:29]
	v_mfma_f32_16x16x32_f16 v[26:29], v[186:189], v[230:233], v[54:57]
	v_mfma_f32_16x16x32_f16 v[70:73], v[190:193], v[234:237], v[26:29]
	v_mfma_f32_16x16x32_f16 v[26:29], v[210:213], v[230:233], v[58:61]
	v_mfma_f32_16x16x32_f16 v[118:121], v[190:193], v[30:33], v[66:69]
	v_mfma_f32_16x16x32_f16 v[66:69], v[214:217], v[234:237], v[26:29]
	s_barrier
	s_setprio 0
	ds_read_b128 v[34:37], v203 offset:49152
	ds_read_b128 v[38:41], v203 offset:50176
	ds_read_b128 v[218:221], v203 offset:51200
	ds_read_b128 v[222:225], v203 offset:52224
	ds_read_b128 v[226:229], v203 offset:53248
	ds_read_b128 v[230:233], v203 offset:54272
	ds_read_b128 v[234:237], v203 offset:55296
	ds_read_b128 v[238:241], v203 offset:56320
	s_add_u32 m0, s28, 0x18000
	s_nop 0
	global_load_lds_dwordx4 v198, s[24:25]
	s_nop 0
	s_add_u32 m0, s28, 0x1a000
	s_nop 0
	global_load_lds_dwordx4 v200, s[24:25]
	s_add_u32 s24, s6, 0x40180
	s_addc_u32 s25, s7, 0
	s_add_u32 m0, s28, 0x1c000
	s_nop 0
	global_load_lds_dwordx4 v198, s[24:25]
	s_nop 0
	s_add_u32 m0, s28, 0x1e000
	s_nop 0
	global_load_lds_dwordx4 v200, s[24:25]
	s_nop 0
	s_add_u32 m0, s28, 0x8000
	s_nop 0
	global_load_lds_dwordx4 v1, s[8:9]
	s_nop 0
	s_add_u32 m0, s28, 0xa000
	s_nop 0
	global_load_lds_dwordx4 v199, s[8:9]
	s_waitcnt vmcnt(8)
	s_waitcnt lgkmcnt(0)
	s_barrier
	v_mfma_f32_16x16x32_f16 v[26:29], v[10:13], v[34:37], v[130:133]
	s_setprio 1
	s_waitcnt lgkmcnt(6)
	v_mfma_f32_16x16x32_f16 v[62:65], v[14:17], v[38:41], v[26:29]
	v_mfma_f32_16x16x32_f16 v[26:29], v[18:21], v[34:37], v[134:137]
	v_mfma_f32_16x16x32_f16 v[58:61], v[22:25], v[38:41], v[26:29]
	s_waitcnt lgkmcnt(5)
	v_mfma_f32_16x16x32_f16 v[26:29], v[10:13], v[218:221], v[138:141]
	s_waitcnt lgkmcnt(4)
	v_mfma_f32_16x16x32_f16 v[46:49], v[14:17], v[222:225], v[26:29]
	v_mfma_f32_16x16x32_f16 v[26:29], v[18:21], v[218:221], v[142:145]
	v_mfma_f32_16x16x32_f16 v[42:45], v[22:25], v[222:225], v[26:29]
	s_waitcnt lgkmcnt(3)
	v_mfma_f32_16x16x32_f16 v[26:29], v[10:13], v[226:229], v[146:149]
	s_waitcnt lgkmcnt(1)
	v_mfma_f32_16x16x32_f16 v[2:5], v[10:13], v[234:237], v[2:5]
	v_mfma_f32_16x16x32_f16 v[30:33], v[14:17], v[230:233], v[26:29]
	v_mfma_f32_16x16x32_f16 v[26:29], v[18:21], v[226:229], v[150:153]
	s_waitcnt lgkmcnt(0)
	v_mfma_f32_16x16x32_f16 v[14:17], v[14:17], v[238:241], v[2:5]
	v_mfma_f32_16x16x32_f16 v[2:5], v[18:21], v[234:237], v[6:9]
	v_mfma_f32_16x16x32_f16 v[26:29], v[22:25], v[230:233], v[26:29]
	v_mfma_f32_16x16x32_f16 v[10:13], v[22:25], v[238:241], v[2:5]
	v_mfma_f32_16x16x32_f16 v[2:5], v[186:189], v[34:37], v[154:157]
	v_mfma_f32_16x16x32_f16 v[54:57], v[190:193], v[38:41], v[2:5]
	v_mfma_f32_16x16x32_f16 v[2:5], v[210:213], v[34:37], v[158:161]
	v_mfma_f32_16x16x32_f16 v[50:53], v[214:217], v[38:41], v[2:5]
	v_mfma_f32_16x16x32_f16 v[2:5], v[186:189], v[218:221], v[162:165]
	v_mfma_f32_16x16x32_f16 v[38:41], v[190:193], v[222:225], v[2:5]
	v_mfma_f32_16x16x32_f16 v[2:5], v[210:213], v[218:221], v[166:169]
	v_mfma_f32_16x16x32_f16 v[34:37], v[214:217], v[222:225], v[2:5]
	v_mfma_f32_16x16x32_f16 v[2:5], v[186:189], v[226:229], v[170:173]
	v_mfma_f32_16x16x32_f16 v[22:25], v[190:193], v[230:233], v[2:5]
	v_mfma_f32_16x16x32_f16 v[2:5], v[210:213], v[226:229], v[174:177]
	v_mfma_f32_16x16x32_f16 v[18:21], v[214:217], v[230:233], v[2:5]
	v_mfma_f32_16x16x32_f16 v[2:5], v[186:189], v[234:237], v[178:181]
	v_mfma_f32_16x16x32_f16 v[6:9], v[190:193], v[238:241], v[2:5]
	v_mfma_f32_16x16x32_f16 v[2:5], v[210:213], v[234:237], v[182:185]
	v_mfma_f32_16x16x32_f16 v[2:5], v[214:217], v[238:241], v[2:5]
	s_barrier
	s_setprio 0
	s_add_u32 s54, s6, 0x200
	s_addc_u32 s55, s7, 0
	s_mov_b32 s58, 0
	s_branch .LBB0_1113
; #define PG8_STAGE(bufoff, gbase, voff) do { if constexpr (ABL & 1) break; glds16s<(bufoff)>((voff)[0], (const void*)(gbase), ldsbw); glds16s<(bufoff) + 8192>((voff)[1], (const void*)(gbase), ldsbw); } while (0)
; #define PG8_LDA(dst, b, h) do { if constexpr (ABL & 4) break; _Pragma("unroll") for (int m = 0; m < 4; ++m) _Pragma("unroll") for (int k = 0; k < 2; ++k) dst[m][k] = *(const LAS f16x8*)(lds + PG8_SA(b, h) + aoff + m * 2048 + k * 1024); } while (0)
; #define PG8_LDB(dst, b, h) do { if constexpr (ABL & 4) break; _Pragma("unroll") for (int n = 0; n < 2; ++n) _Pragma("unroll") for (int k = 0; k < 2; ++k) dst[n][k] = *(const LAS f16x8*)(lds + PG8_SB(b, h) + boff + n * 2048 + k * 1024); } while (0)
; #define PG8_BAR __builtin_amdgcn_s_barrier()
;     ...
;         for (int t = 0; t < nt; t += 2) {
;             const bool last = (t == nt - 2);
;             const char* a1 = cA + (size_t)(t + 1) * kstep;
;             const char* a2 = last ? nA : cA + (size_t)(t + 2) * kstep; const char* b2 = last ? nB : cB + (size_t)(t + 2) * kstep;
;             const char* a3 = a2 + kstep; const char* b3 = b2 + kstep;
;             if (last && has_next) S.a_ready(nxt);
;             if constexpr (SP2) {
;             PG8_LDB(B0, 0, 0); PG8_LDB(B1, 0, 1); PG8_SCHED; PG8_LDA(At, 0, 0); PG8_STAGE(PG8_SA(1, 1), a1 + hstep, voffA);
;             PG8_WAIT_V(8); PG8_WAIT_L(0); PG8_BAR; PG8_MMAF(0, 0, At, B0); PG8_MMAF(0, 1, At, B1); PG8_BAR; PG8_SCHED;
;             const bool fin = last && !has_next;
;             PG8_LDA(At, 0, 1); if (!fin) { PG8_STAGE(PG8_SB(0, 0), b2, voffB); PG8_STAGE(PG8_SB(0, 1), b2 + hstep, voffB); PG8_STAGE(PG8_SA(0, 0), a2, voffA); }
;             if (!fin) PG8_WAIT_V(8); else PG8_WAIT_V(2); PG8_WAIT_L(0); PG8_BAR; PG8_MMAF(1, 0, At, B0); PG8_MMAF(1, 1, At, B1); PG8_BAR; PG8_SCHED;
;             PG8_LDB(B0, 1, 0); PG8_LDB(B1, 1, 1); PG8_SCHED; PG8_LDA(At, 1, 0); if (!fin) PG8_STAGE(PG8_SA(0, 1), a2 + hstep, voffA);
;             if (!fin) PG8_WAIT_V(8); else PG8_WAIT_V(0); PG8_WAIT_L(0); PG8_BAR; PG8_MMA(0, 0, At, B0); PG8_MMA(0, 1, At, B1); PG8_BAR; PG8_SCHED;
;             PG8_LDA(At, 1, 1); if (!fin) { PG8_STAGE(PG8_SB(1, 0), b3, voffB); PG8_STAGE(PG8_SB(1, 1), b3 + hstep, voffB); PG8_STAGE(PG8_SA(1, 0), a3, voffA); }
;             if (!fin) PG8_WAIT_V(8); PG8_WAIT_L(0); PG8_BAR; PG8_MMA(1, 0, At, B0); PG8_MMA(1, 1, At, B1); PG8_BAR; PG8_SCHED;
.LBB0_1112:
	s_waitcnt lgkmcnt(0)
	s_barrier
	v_mfma_f32_16x16x32_f16 v[62:65], v[146:149], v[186:189], v[62:65]
	s_setprio 1
	v_mfma_f32_16x16x32_f16 v[58:61], v[154:157], v[186:189], v[58:61]
	s_waitcnt lgkmcnt(5)
	v_mfma_f32_16x16x32_f16 v[46:49], v[146:149], v[178:181], v[46:49]
	v_mfma_f32_16x16x32_f16 v[42:45], v[154:157], v[178:181], v[42:45]
	s_waitcnt lgkmcnt(3)
	v_mfma_f32_16x16x32_f16 v[30:33], v[146:149], v[170:173], v[30:33]
	v_mfma_f32_16x16x32_f16 v[26:29], v[154:157], v[170:173], v[26:29]
	s_waitcnt lgkmcnt(1)
	v_mfma_f32_16x16x32_f16 v[14:17], v[146:149], v[162:165], v[14:17]
	v_mfma_f32_16x16x32_f16 v[10:13], v[154:157], v[162:165], v[10:13]
	v_mfma_f32_16x16x32_f16 v[62:65], v[150:153], v[190:193], v[62:65]
	v_mfma_f32_16x16x32_f16 v[58:61], v[158:161], v[190:193], v[58:61]
	v_mfma_f32_16x16x32_f16 v[46:49], v[150:153], v[182:185], v[46:49]
	v_mfma_f32_16x16x32_f16 v[42:45], v[158:161], v[182:185], v[42:45]
	v_mfma_f32_16x16x32_f16 v[30:33], v[150:153], v[174:177], v[30:33]
	v_mfma_f32_16x16x32_f16 v[26:29], v[158:161], v[174:177], v[26:29]
	s_waitcnt lgkmcnt(0)
	v_mfma_f32_16x16x32_f16 v[14:17], v[150:153], v[166:169], v[14:17]
	v_mfma_f32_16x16x32_f16 v[10:13], v[158:161], v[166:169], v[10:13]
	v_mfma_f32_16x16x32_f16 v[54:57], v[130:133], v[186:189], v[54:57]
	v_mfma_f32_16x16x32_f16 v[50:53], v[138:141], v[186:189], v[50:53]
	v_mfma_f32_16x16x32_f16 v[38:41], v[130:133], v[178:181], v[38:41]
	v_mfma_f32_16x16x32_f16 v[34:37], v[138:141], v[178:181], v[34:37]
	v_mfma_f32_16x16x32_f16 v[22:25], v[130:133], v[170:173], v[22:25]
	v_mfma_f32_16x16x32_f16 v[18:21], v[138:141], v[170:173], v[18:21]
	v_mfma_f32_16x16x32_f16 v[6:9], v[130:133], v[162:165], v[6:9]
	v_mfma_f32_16x16x32_f16 v[2:5], v[138:141], v[162:165], v[2:5]
	v_mfma_f32_16x16x32_f16 v[54:57], v[134:137], v[190:193], v[54:57]
	v_mfma_f32_16x16x32_f16 v[50:53], v[142:145], v[190:193], v[50:53]
	v_mfma_f32_16x16x32_f16 v[38:41], v[134:137], v[182:185], v[38:41]
	v_mfma_f32_16x16x32_f16 v[34:37], v[142:145], v[182:185], v[34:37]
	v_mfma_f32_16x16x32_f16 v[22:25], v[134:137], v[174:177], v[22:25]
	v_mfma_f32_16x16x32_f16 v[18:21], v[142:145], v[174:177], v[18:21]
	v_mfma_f32_16x16x32_f16 v[6:9], v[134:137], v[166:169], v[6:9]
	v_mfma_f32_16x16x32_f16 v[2:5], v[142:145], v[166:169], v[2:5]
	s_barrier
	s_setprio 0
	s_add_i32 s58, s58, 2
	s_add_u32 s54, s54, 0x100
	s_addc_u32 s55, s55, 0
	s_cmp_gt_u32 s58, 13
	s_cbranch_scc1 .LBB0_1123
; #define PG8_STAGE(bufoff, gbase, voff) do { if constexpr (ABL & 1) break; glds16s<(bufoff)>((voff)[0], (const void*)(gbase), ldsbw); glds16s<(bufoff) + 8192>((voff)[1], (const void*)(gbase), ldsbw); } while (0)
; #define PG8_LDA(dst, b, h) do { if constexpr (ABL & 4) break; _Pragma("unroll") for (int m = 0; m < 4; ++m) _Pragma("unroll") for (int k = 0; k < 2; ++k) dst[m][k] = *(const LAS f16x8*)(lds + PG8_SA(b, h) + aoff + m * 2048 + k * 1024); } while (0)
; #define PG8_LDB(dst, b, h) do { if constexpr (ABL & 4) break; _Pragma("unroll") for (int n = 0; n < 2; ++n) _Pragma("unroll") for (int k = 0; k < 2; ++k) dst[n][k] = *(const LAS f16x8*)(lds + PG8_SB(b, h) + boff + n * 2048 + k * 1024); } while (0)
; #define PG8_MMAF(ai, bj, At, Bt) do { if (t == 0) PG8_MMA0(ai, bj, At, Bt); else PG8_MMA(ai, bj, At, Bt); } while (0)
; #define PG8_WAIT_V(n) asm volatile("s_waitcnt vmcnt(" #n ")" ::: "memory")
; #define PG8_WAIT_L(n) asm volatile("s_waitcnt lgkmcnt(" #n ")" ::: "memory")
; #define PG8_BAR __builtin_amdgcn_s_barrier()
; #define PG8_SCHED __builtin_amdgcn_sched_barrier(0)
;     ...
;         for (int t = 0; t < nt; t += 2) {
;             const bool last = (t == nt - 2);
;             const char* a1 = cA + (size_t)(t + 1) * kstep;
;             const char* a2 = last ? nA : cA + (size_t)(t + 2) * kstep; const char* b2 = last ? nB : cB + (size_t)(t + 2) * kstep;
;             const char* a3 = a2 + kstep; const char* b3 = b2 + kstep;
;             if (last && has_next) S.a_ready(nxt);
;             if constexpr (SP2) {
;             PG8_LDB(B0, 0, 0); PG8_LDB(B1, 0, 1); PG8_SCHED; PG8_LDA(At, 0, 0); PG8_STAGE(PG8_SA(1, 1), a1 + hstep, voffA);
;             PG8_WAIT_V(8); PG8_WAIT_L(0); PG8_BAR; PG8_MMAF(0, 0, At, B0); PG8_MMAF(0, 1, At, B1); PG8_BAR; PG8_SCHED;
;             const bool fin = last && !has_next;
;             PG8_LDA(At, 0, 1); if (!fin) { PG8_STAGE(PG8_SB(0, 0), b2, voffB); PG8_STAGE(PG8_SB(0, 1), b2 + hstep, voffB); PG8_STAGE(PG8_SA(0, 0), a2, voffA); }
.LBB0_1113:
	ds_read_b128 v[146:149], v201
	ds_read_b128 v[150:153], v201 offset:1024
	ds_read_b128 v[154:157], v201 offset:2048
	ds_read_b128 v[158:161], v201 offset:3072
	ds_read_b128 v[130:133], v202
	ds_read_b128 v[134:137], v202 offset:1024
	ds_read_b128 v[138:141], v202 offset:2048
	ds_read_b128 v[142:145], v202 offset:3072
	s_mov_b64 s[6:7], s[52:53]
	s_add_u32 s52, s6, 0x100
	s_addc_u32 s53, s7, 0
	s_cmp_eq_u32 s58, 12
	s_cselect_b64 s[26:27], -1, 0
	s_and_b64 s[8:9], s[26:27], exec
	s_cselect_b32 s25, s43, s53
	s_cselect_b32 s24, s56, s52
	s_cselect_b32 s9, s41, s55
	s_cselect_b32 s8, s57, s54
	ds_read_b128 v[162:165], v203
	ds_read_b128 v[166:169], v203 offset:1024
	ds_read_b128 v[170:173], v203 offset:2048
	ds_read_b128 v[174:177], v203 offset:3072
	ds_read_b128 v[178:181], v203 offset:4096
	ds_read_b128 v[182:185], v203 offset:5120
	ds_read_b128 v[186:189], v203 offset:6144
	ds_read_b128 v[190:193], v203 offset:7168
	s_add_u32 s6, s6, 0x40080
	s_addc_u32 s7, s7, 0
	s_add_u32 m0, s28, 0xc000
	s_nop 0
	global_load_lds_dwordx4 v1, s[6:7]
	s_nop 0
	s_add_u32 m0, s28, 0xe000
	s_nop 0
	global_load_lds_dwordx4 v199, s[6:7]
	s_waitcnt vmcnt(8)
	s_waitcnt lgkmcnt(0)
	s_barrier
	v_mfma_f32_16x16x32_f16 v[126:129], v[146:149], v[162:165], v[126:129]
	s_setprio 1
	v_mfma_f32_16x16x32_f16 v[122:125], v[154:157], v[162:165], v[122:125]
	s_waitcnt lgkmcnt(5)
	v_mfma_f32_16x16x32_f16 v[110:113], v[146:149], v[170:173], v[110:113]
	v_mfma_f32_16x16x32_f16 v[106:109], v[154:157], v[170:173], v[106:109]
	s_waitcnt lgkmcnt(3)
	v_mfma_f32_16x16x32_f16 v[94:97], v[146:149], v[178:181], v[94:97]
	v_mfma_f32_16x16x32_f16 v[90:93], v[154:157], v[178:181], v[90:93]
	s_waitcnt lgkmcnt(1)
	v_mfma_f32_16x16x32_f16 v[78:81], v[146:149], v[186:189], v[78:81]
	v_mfma_f32_16x16x32_f16 v[74:77], v[154:157], v[186:189], v[74:77]
	v_mfma_f32_16x16x32_f16 v[126:129], v[150:153], v[166:169], v[126:129]
	v_mfma_f32_16x16x32_f16 v[122:125], v[158:161], v[166:169], v[122:125]
	v_mfma_f32_16x16x32_f16 v[110:113], v[150:153], v[174:177], v[110:113]
	v_mfma_f32_16x16x32_f16 v[106:109], v[158:161], v[174:177], v[106:109]
	v_mfma_f32_16x16x32_f16 v[94:97], v[150:153], v[182:185], v[94:97]
	v_mfma_f32_16x16x32_f16 v[90:93], v[158:161], v[182:185], v[90:93]
	s_waitcnt lgkmcnt(0)
	v_mfma_f32_16x16x32_f16 v[78:81], v[150:153], v[190:193], v[78:81]
	v_mfma_f32_16x16x32_f16 v[74:77], v[158:161], v[190:193], v[74:77]
	v_mfma_f32_16x16x32_f16 v[118:121], v[130:133], v[162:165], v[118:121]
	v_mfma_f32_16x16x32_f16 v[114:117], v[138:141], v[162:165], v[114:117]
	v_mfma_f32_16x16x32_f16 v[102:105], v[130:133], v[170:173], v[102:105]
	v_mfma_f32_16x16x32_f16 v[98:101], v[138:141], v[170:173], v[98:101]
	v_mfma_f32_16x16x32_f16 v[86:89], v[130:133], v[178:181], v[86:89]
	v_mfma_f32_16x16x32_f16 v[82:85], v[138:141], v[178:181], v[82:85]
	v_mfma_f32_16x16x32_f16 v[70:73], v[130:133], v[186:189], v[70:73]
	v_mfma_f32_16x16x32_f16 v[66:69], v[138:141], v[186:189], v[66:69]
	v_mfma_f32_16x16x32_f16 v[118:121], v[134:137], v[166:169], v[118:121]
	v_mfma_f32_16x16x32_f16 v[114:117], v[142:145], v[166:169], v[114:117]
	v_mfma_f32_16x16x32_f16 v[102:105], v[134:137], v[174:177], v[102:105]
	v_mfma_f32_16x16x32_f16 v[98:101], v[142:145], v[174:177], v[98:101]
	v_mfma_f32_16x16x32_f16 v[86:89], v[134:137], v[182:185], v[86:89]
	v_mfma_f32_16x16x32_f16 v[82:85], v[142:145], v[182:185], v[82:85]
	v_mfma_f32_16x16x32_f16 v[70:73], v[134:137], v[190:193], v[70:73]
	v_mfma_f32_16x16x32_f16 v[66:69], v[142:145], v[190:193], v[66:69]
	s_barrier
	s_setprio 0
	ds_read_b128 v[186:189], v203 offset:16384
	ds_read_b128 v[190:193], v203 offset:17408
	ds_read_b128 v[178:181], v203 offset:18432
	ds_read_b128 v[182:185], v203 offset:19456
	ds_read_b128 v[170:173], v203 offset:20480
	ds_read_b128 v[174:177], v203 offset:21504
	ds_read_b128 v[162:165], v203 offset:22528
	ds_read_b128 v[166:169], v203 offset:23552
	s_and_b64 s[6:7], s[4:5], s[26:27]
	s_mov_b64 s[26:27], -1
	s_and_b64 vcc, exec, s[6:7]
	s_cbranch_vccnz .LBB0_1115
	s_add_u32 m0, s28, 0x10000
	s_nop 0
	global_load_lds_dwordx4 v198, s[8:9]
	s_nop 0
	s_add_u32 m0, s28, 0x12000
	s_nop 0
	global_load_lds_dwordx4 v200, s[8:9]
	s_add_u32 s26, s8, 0x40000
	s_addc_u32 s27, s9, 0
	s_add_u32 m0, s28, 0x14000
	s_nop 0
	global_load_lds_dwordx4 v198, s[26:27]
	s_nop 0
	s_add_u32 m0, s28, 0x16000
	s_nop 0
	global_load_lds_dwordx4 v200, s[26:27]
	s_mov_b64 s[26:27], 0
	s_add_u32 m0, s28, 0
	s_nop 0
	global_load_lds_dwordx4 v1, s[24:25]
	s_nop 0
	s_add_u32 m0, s28, 0x2000
	s_nop 0
	global_load_lds_dwordx4 v199, s[24:25]
	s_waitcnt vmcnt(8)

; #define PG8_STAGE(bufoff, gbase, voff) do { if constexpr (ABL & 1) break; glds16s<(bufoff)>((voff)[0], (const void*)(gbase), ldsbw); glds16s<(bufoff) + 8192>((voff)[1], (const void*)(gbase), ldsbw); } while (0)
; #define PG8_LDA(dst, b, h) do { if constexpr (ABL & 4) break; _Pragma("unroll") for (int m = 0; m < 4; ++m) _Pragma("unroll") for (int k = 0; k < 2; ++k) dst[m][k] = *(const LAS f16x8*)(lds + PG8_SA(b, h) + aoff + m * 2048 + k * 1024); } while (0)
; #define PG8_LDB(dst, b, h) do { if constexpr (ABL & 4) break; _Pragma("unroll") for (int n = 0; n < 2; ++n) _Pragma("unroll") for (int k = 0; k < 2; ++k) dst[n][k] = *(const LAS f16x8*)(lds + PG8_SB(b, h) + boff + n * 2048 + k * 1024); } while (0)
; #define PG8_MMA(ai, bj, At, Bt) do { if constexpr (ABL & 2) break; __builtin_amdgcn_s_setprio(1); _Pragma("unroll") for (int m = 0; m < 4; ++m) _Pragma("unroll") for (int n = 0; n < 2; ++n) _Pragma("unroll") for (int k = 0; k < 2; ++k) \
;         acc[ai][bj][m][n] = __builtin_amdgcn_mfma_f32_16x16x32_f16(Bt[n][k], At[m][k], acc[ai][bj][m][n], 0, 0, 0); __builtin_amdgcn_s_setprio(0); } while (0)
; #define PG8_MMAF(ai, bj, At, Bt) do { if (t == 0) PG8_MMA0(ai, bj, At, Bt); else PG8_MMA(ai, bj, At, Bt); } while (0)
; #define PG8_WAIT_V(n) asm volatile("s_waitcnt vmcnt(" #n ")" ::: "memory")
; #define PG8_WAIT_L(n) asm volatile("s_waitcnt lgkmcnt(" #n ")" ::: "memory")
; #define PG8_BAR __builtin_amdgcn_s_barrier()
; #define PG8_SCHED __builtin_amdgcn_sched_barrier(0)
;     ...
;             if (!fin) PG8_WAIT_V(8); else PG8_WAIT_V(2); PG8_WAIT_L(0); PG8_BAR; PG8_MMAF(1, 0, At, B0); PG8_MMAF(1, 1, At, B1); PG8_BAR; PG8_SCHED;
;             PG8_LDB(B0, 1, 0); PG8_LDB(B1, 1, 1); PG8_SCHED; PG8_LDA(At, 1, 0); if (!fin) PG8_STAGE(PG8_SA(0, 1), a2 + hstep, voffA);
;             if (!fin) PG8_WAIT_V(8); else PG8_WAIT_V(0); PG8_WAIT_L(0); PG8_BAR; PG8_MMA(0, 0, At, B0); PG8_MMA(0, 1, At, B1); PG8_BAR; PG8_SCHED;
.LBB0_1117:
	s_waitcnt lgkmcnt(0)
	s_xor_b64 s[26:27], s[6:7], -1
	s_barrier
	v_mfma_f32_16x16x32_f16 v[62:65], v[146:149], v[186:189], v[62:65]
	s_setprio 1
	v_mfma_f32_16x16x32_f16 v[58:61], v[154:157], v[186:189], v[58:61]
	s_waitcnt lgkmcnt(5)
	v_mfma_f32_16x16x32_f16 v[46:49], v[146:149], v[178:181], v[46:49]
	v_mfma_f32_16x16x32_f16 v[42:45], v[154:157], v[178:181], v[42:45]
	s_waitcnt lgkmcnt(3)
	v_mfma_f32_16x16x32_f16 v[30:33], v[146:149], v[170:173], v[30:33]
	v_mfma_f32_16x16x32_f16 v[26:29], v[154:157], v[170:173], v[26:29]
	s_waitcnt lgkmcnt(1)
	v_mfma_f32_16x16x32_f16 v[14:17], v[146:149], v[162:165], v[14:17]
	v_mfma_f32_16x16x32_f16 v[10:13], v[154:157], v[162:165], v[10:13]
	v_mfma_f32_16x16x32_f16 v[62:65], v[150:153], v[190:193], v[62:65]
	v_mfma_f32_16x16x32_f16 v[58:61], v[158:161], v[190:193], v[58:61]
	v_mfma_f32_16x16x32_f16 v[46:49], v[150:153], v[182:185], v[46:49]
	v_mfma_f32_16x16x32_f16 v[42:45], v[158:161], v[182:185], v[42:45]
	v_mfma_f32_16x16x32_f16 v[30:33], v[150:153], v[174:177], v[30:33]
	v_mfma_f32_16x16x32_f16 v[26:29], v[158:161], v[174:177], v[26:29]
	s_waitcnt lgkmcnt(0)
	v_mfma_f32_16x16x32_f16 v[14:17], v[150:153], v[166:169], v[14:17]
	v_mfma_f32_16x16x32_f16 v[10:13], v[158:161], v[166:169], v[10:13]
	v_mfma_f32_16x16x32_f16 v[54:57], v[130:133], v[186:189], v[54:57]
	v_mfma_f32_16x16x32_f16 v[50:53], v[138:141], v[186:189], v[50:53]
	v_mfma_f32_16x16x32_f16 v[38:41], v[130:133], v[178:181], v[38:41]
	v_mfma_f32_16x16x32_f16 v[34:37], v[138:141], v[178:181], v[34:37]
	v_mfma_f32_16x16x32_f16 v[22:25], v[130:133], v[170:173], v[22:25]
	v_mfma_f32_16x16x32_f16 v[18:21], v[138:141], v[170:173], v[18:21]
	v_mfma_f32_16x16x32_f16 v[6:9], v[130:133], v[162:165], v[6:9]
	v_mfma_f32_16x16x32_f16 v[2:5], v[138:141], v[162:165], v[2:5]
	v_mfma_f32_16x16x32_f16 v[54:57], v[134:137], v[190:193], v[54:57]
	v_mfma_f32_16x16x32_f16 v[50:53], v[142:145], v[190:193], v[50:53]
	v_mfma_f32_16x16x32_f16 v[38:41], v[134:137], v[182:185], v[38:41]
	v_mfma_f32_16x16x32_f16 v[34:37], v[142:145], v[182:185], v[34:37]
	v_mfma_f32_16x16x32_f16 v[22:25], v[134:137], v[174:177], v[22:25]
	v_mfma_f32_16x16x32_f16 v[18:21], v[142:145], v[174:177], v[18:21]
	v_mfma_f32_16x16x32_f16 v[6:9], v[134:137], v[166:169], v[6:9]
	v_mfma_f32_16x16x32_f16 v[2:5], v[142:145], v[166:169], v[2:5]
	s_barrier
	s_setprio 0
	ds_read_b128 v[146:149], v204
	ds_read_b128 v[150:153], v204 offset:1024
	ds_read_b128 v[154:157], v204 offset:2048
	ds_read_b128 v[158:161], v204 offset:3072
	ds_read_b128 v[130:133], v205
	ds_read_b128 v[134:137], v205 offset:1024
	ds_read_b128 v[138:141], v205 offset:2048
	ds_read_b128 v[142:145], v205 offset:3072
	ds_read_b128 v[186:189], v203 offset:32768
	ds_read_b128 v[190:193], v203 offset:33792
	ds_read_b128 v[178:181], v203 offset:34816
	ds_read_b128 v[182:185], v203 offset:35840
	ds_read_b128 v[170:173], v203 offset:36864
	ds_read_b128 v[174:177], v203 offset:37888
	ds_read_b128 v[162:165], v203 offset:38912
	ds_read_b128 v[166:169], v203 offset:39936
	v_cndmask_b32_e64 v209, 0, 1, s[26:27]
	v_cmp_ne_u32_e64 s[6:7], 1, v209
	s_andn2_b64 vcc, exec, s[26:27]
	s_mov_b64 s[26:27], -1
	s_cbranch_vccnz .LBB0_1119
	s_add_u32 s26, s24, 0x40000
	s_addc_u32 s27, s25, 0
	s_add_u32 m0, s28, 0x4000
	s_nop 0
	global_load_lds_dwordx4 v1, s[26:27]
	s_nop 0
	s_add_u32 m0, s28, 0x6000
	s_nop 0
	global_load_lds_dwordx4 v199, s[26:27]
	s_waitcnt vmcnt(8)
	s_mov_b64 s[26:27], 0

; #define PG8_STAGE(bufoff, gbase, voff) do { if constexpr (ABL & 1) break; glds16s<(bufoff)>((voff)[0], (const void*)(gbase), ldsbw); glds16s<(bufoff) + 8192>((voff)[1], (const void*)(gbase), ldsbw); } while (0)
; #define PG8_LDA(dst, b, h) do { if constexpr (ABL & 4) break; _Pragma("unroll") for (int m = 0; m < 4; ++m) _Pragma("unroll") for (int k = 0; k < 2; ++k) dst[m][k] = *(const LAS f16x8*)(lds + PG8_SA(b, h) + aoff + m * 2048 + k * 1024); } while (0)
; #define PG8_MMA(ai, bj, At, Bt) do { if constexpr (ABL & 2) break; __builtin_amdgcn_s_setprio(1); _Pragma("unroll") for (int m = 0; m < 4; ++m) _Pragma("unroll") for (int n = 0; n < 2; ++n) _Pragma("unroll") for (int k = 0; k < 2; ++k) \
;         acc[ai][bj][m][n] = __builtin_amdgcn_mfma_f32_16x16x32_f16(Bt[n][k], At[m][k], acc[ai][bj][m][n], 0, 0, 0); __builtin_amdgcn_s_setprio(0); } while (0)
; #define PG8_WAIT_V(n) asm volatile("s_waitcnt vmcnt(" #n ")" ::: "memory")
; #define PG8_WAIT_L(n) asm volatile("s_waitcnt lgkmcnt(" #n ")" ::: "memory")
; #define PG8_BAR __builtin_amdgcn_s_barrier()
; #define PG8_SCHED __builtin_amdgcn_sched_barrier(0)
;     ...
;             if (!fin) PG8_WAIT_V(8); else PG8_WAIT_V(0); PG8_WAIT_L(0); PG8_BAR; PG8_MMA(0, 0, At, B0); PG8_MMA(0, 1, At, B1); PG8_BAR; PG8_SCHED;
;             PG8_LDA(At, 1, 1); if (!fin) { PG8_STAGE(PG8_SB(1, 0), b3, voffB); PG8_STAGE(PG8_SB(1, 1), b3 + hstep, voffB); PG8_STAGE(PG8_SA(1, 0), a3, voffA); }
;             if (!fin) PG8_WAIT_V(8); PG8_WAIT_L(0); PG8_BAR; PG8_MMA(1, 0, At, B0); PG8_MMA(1, 1, At, B1); PG8_BAR; PG8_SCHED;
.LBB0_1121:
	s_waitcnt lgkmcnt(0)
	s_barrier
	v_mfma_f32_16x16x32_f16 v[126:129], v[146:149], v[186:189], v[126:129]
	s_setprio 1
	v_mfma_f32_16x16x32_f16 v[122:125], v[154:157], v[186:189], v[122:125]
	s_waitcnt lgkmcnt(5)
	v_mfma_f32_16x16x32_f16 v[110:113], v[146:149], v[178:181], v[110:113]
	v_mfma_f32_16x16x32_f16 v[106:109], v[154:157], v[178:181], v[106:109]
	s_waitcnt lgkmcnt(3)
	v_mfma_f32_16x16x32_f16 v[94:97], v[146:149], v[170:173], v[94:97]
	v_mfma_f32_16x16x32_f16 v[90:93], v[154:157], v[170:173], v[90:93]
	s_waitcnt lgkmcnt(1)
	v_mfma_f32_16x16x32_f16 v[78:81], v[146:149], v[162:165], v[78:81]
	v_mfma_f32_16x16x32_f16 v[74:77], v[154:157], v[162:165], v[74:77]
	v_mfma_f32_16x16x32_f16 v[126:129], v[150:153], v[190:193], v[126:129]
	v_mfma_f32_16x16x32_f16 v[122:125], v[158:161], v[190:193], v[122:125]
	v_mfma_f32_16x16x32_f16 v[110:113], v[150:153], v[182:185], v[110:113]
	v_mfma_f32_16x16x32_f16 v[106:109], v[158:161], v[182:185], v[106:109]
	v_mfma_f32_16x16x32_f16 v[94:97], v[150:153], v[174:177], v[94:97]
	v_mfma_f32_16x16x32_f16 v[90:93], v[158:161], v[174:177], v[90:93]
	s_waitcnt lgkmcnt(0)
	v_mfma_f32_16x16x32_f16 v[78:81], v[150:153], v[166:169], v[78:81]
	v_mfma_f32_16x16x32_f16 v[74:77], v[158:161], v[166:169], v[74:77]
	v_mfma_f32_16x16x32_f16 v[118:121], v[130:133], v[186:189], v[118:121]
	v_mfma_f32_16x16x32_f16 v[114:117], v[138:141], v[186:189], v[114:117]
	v_mfma_f32_16x16x32_f16 v[102:105], v[130:133], v[178:181], v[102:105]
	v_mfma_f32_16x16x32_f16 v[98:101], v[138:141], v[178:181], v[98:101]
	v_mfma_f32_16x16x32_f16 v[86:89], v[130:133], v[170:173], v[86:89]
	v_mfma_f32_16x16x32_f16 v[82:85], v[138:141], v[170:173], v[82:85]
	v_mfma_f32_16x16x32_f16 v[70:73], v[130:133], v[162:165], v[70:73]
	v_mfma_f32_16x16x32_f16 v[66:69], v[138:141], v[162:165], v[66:69]
	v_mfma_f32_16x16x32_f16 v[118:121], v[134:137], v[190:193], v[118:121]
	v_mfma_f32_16x16x32_f16 v[114:117], v[142:145], v[190:193], v[114:117]
	v_mfma_f32_16x16x32_f16 v[102:105], v[134:137], v[182:185], v[102:105]
	v_mfma_f32_16x16x32_f16 v[98:101], v[142:145], v[182:185], v[98:101]
	v_mfma_f32_16x16x32_f16 v[86:89], v[134:137], v[174:177], v[86:89]
	v_mfma_f32_16x16x32_f16 v[82:85], v[142:145], v[174:177], v[82:85]
	v_mfma_f32_16x16x32_f16 v[70:73], v[134:137], v[166:169], v[70:73]
	v_mfma_f32_16x16x32_f16 v[66:69], v[142:145], v[166:169], v[66:69]
	s_barrier
	s_setprio 0
	ds_read_b128 v[186:189], v203 offset:49152
	ds_read_b128 v[190:193], v203 offset:50176
	ds_read_b128 v[178:181], v203 offset:51200
	ds_read_b128 v[182:185], v203 offset:52224
	ds_read_b128 v[170:173], v203 offset:53248
	ds_read_b128 v[174:177], v203 offset:54272
	ds_read_b128 v[162:165], v203 offset:55296
	ds_read_b128 v[166:169], v203 offset:56320
	s_and_b64 vcc, exec, s[6:7]
	s_cbranch_vccnz .LBB0_1112
	s_add_u32 s6, s24, 0x80
	s_addc_u32 s7, s25, 0
	s_add_u32 s24, s8, 0x80
	s_addc_u32 s25, s9, 0
	s_add_u32 m0, s28, 0x18000
	s_nop 0
	global_load_lds_dwordx4 v198, s[24:25]
	s_nop 0
	s_add_u32 m0, s28, 0x1a000
	s_nop 0
	global_load_lds_dwordx4 v200, s[24:25]
	s_add_u32 s8, s8, 0x40080
	s_addc_u32 s9, s9, 0
	s_add_u32 m0, s28, 0x1c000
	s_nop 0
	global_load_lds_dwordx4 v198, s[8:9]
	s_nop 0
	s_add_u32 m0, s28, 0x1e000
	s_nop 0
	global_load_lds_dwordx4 v200, s[8:9]
	s_nop 0
	s_add_u32 m0, s28, 0x8000
	s_nop 0
	global_load_lds_dwordx4 v1, s[6:7]
	s_nop 0
	s_add_u32 m0, s28, 0xa000
	s_nop 0
	global_load_lds_dwordx4 v199, s[6:7]
	s_waitcnt vmcnt(8)
	s_branch .LBB0_1112

;     __device__ __forceinline__ bool next(int i, Unit& u) const { if (i >= count) return false; const int L = first + i; u.pm = L / nN; u.pn = L % nN; return true; }
; #define PG8_STAGE(bufoff, gbase, voff) do { if constexpr (ABL & 1) break; glds16s<(bufoff)>((voff)[0], (const void*)(gbase), ldsbw); glds16s<(bufoff) + 8192>((voff)[1], (const void*)(gbase), ldsbw); } while (0)
; #define PG8_LDA(dst, b, h) do { if constexpr (ABL & 4) break; _Pragma("unroll") for (int m = 0; m < 4; ++m) _Pragma("unroll") for (int k = 0; k < 2; ++k) dst[m][k] = *(const LAS f16x8*)(lds + PG8_SA(b, h) + aoff + m * 2048 + k * 1024); } while (0)
; #define PG8_LDB(dst, b, h) do { if constexpr (ABL & 4) break; _Pragma("unroll") for (int n = 0; n < 2; ++n) _Pragma("unroll") for (int k = 0; k < 2; ++k) dst[n][k] = *(const LAS f16x8*)(lds + PG8_SB(b, h) + boff + n * 2048 + k * 1024); } while (0)
; #define PG8_MMAF(ai, bj, At, Bt) do { if (t == 0) PG8_MMA0(ai, bj, At, Bt); else PG8_MMA(ai, bj, At, Bt); } while (0)
; #define PG8_WAIT_V(n) asm volatile("s_waitcnt vmcnt(" #n ")" ::: "memory")
; #define PG8_BAR __builtin_amdgcn_s_barrier()
;     ...
;         const bool has_next = S.next(ui + 1, nxt);
;         const char* nA = has_next ? (const char*)g.A + (size_t)nxt.pm * tstep : cA; const char* nB = has_next ? (const char*)g.Bt + (size_t)nxt.pn * tstep : cB;
;         for (int t = 0; t < nt; t += 2) {
;             const bool last = (t == nt - 2);
;             const char* a1 = cA + (size_t)(t + 1) * kstep;
;             const char* a2 = last ? nA : cA + (size_t)(t + 2) * kstep; const char* b2 = last ? nB : cB + (size_t)(t + 2) * kstep;
;             const char* a3 = a2 + kstep; const char* b3 = b2 + kstep;
;             if (last && has_next) S.a_ready(nxt);
;             if constexpr (SP2) {
;             PG8_LDB(B0, 0, 0); PG8_LDB(B1, 0, 1); PG8_SCHED; PG8_LDA(At, 0, 0); PG8_STAGE(PG8_SA(1, 1), a1 + hstep, voffA);
;             PG8_WAIT_V(8); PG8_WAIT_L(0); PG8_BAR; PG8_MMAF(0, 0, At, B0); PG8_MMAF(0, 1, At, B1); PG8_BAR; PG8_SCHED;
;             const bool fin = last && !has_next;
;             PG8_LDA(At, 0, 1); if (!fin) { PG8_STAGE(PG8_SB(0, 0), b2, voffB); PG8_STAGE(PG8_SB(0, 1), b2 + hstep, voffB); PG8_STAGE(PG8_SA(0, 0), a2, voffA); }
;             if (!fin) PG8_WAIT_V(8); else PG8_WAIT_V(2); PG8_WAIT_L(0); PG8_BAR; PG8_MMAF(1, 0, At, B0); PG8_MMAF(1, 1, At, B1); PG8_BAR; PG8_SCHED;
.LBB0_1163:
	s_ashr_i32 s49, s48, 31
	s_lshl_b64 s[6:7], s[48:49], 19
	s_add_u32 s50, s74, s6
	s_addc_u32 s51, s75, s7
	s_and_b64 s[6:7], exec, s[2:3]
	ds_read_b128 v[2:5], v213
	ds_read_b128 v[6:9], v213 offset:1024
	ds_read_b128 v[10:13], v213 offset:2048
	ds_read_b128 v[14:17], v213 offset:3072
	ds_read_b128 v[18:21], v214
	ds_read_b128 v[22:25], v214 offset:1024
	ds_read_b128 v[26:29], v214 offset:2048
	ds_read_b128 v[30:33], v214 offset:3072
	s_cselect_b32 s45, s37, s51
	s_cselect_b32 s49, s36, s50
	s_ashr_i32 s47, s46, 31
	s_lshl_b64 s[6:7], s[46:47], 19
	s_add_u32 s52, s94, s6
	s_addc_u32 s53, s95, s7
	s_and_b64 s[6:7], exec, s[2:3]
	s_cselect_b32 s47, s39, s53
	s_cselect_b32 s57, s38, s52
	s_add_u32 s24, s36, 0x100
	s_addc_u32 s25, s37, 0
	s_add_u32 s26, s38, 0x100
	s_addc_u32 s27, s39, 0
	s_add_u32 s6, s36, 0x180
	s_addc_u32 s7, s37, 0
	ds_read_b128 v[34:37], v215
	ds_read_b128 v[38:41], v215 offset:1024
	ds_read_b128 v[42:45], v215 offset:2048
	ds_read_b128 v[46:49], v215 offset:3072
	ds_read_b128 v[50:53], v215 offset:4096
	ds_read_b128 v[54:57], v215 offset:5120
	ds_read_b128 v[58:61], v215 offset:6144
	ds_read_b128 v[62:65], v215 offset:7168
	s_add_u32 s8, s38, 0x180
	s_addc_u32 s9, s39, 0
	s_add_u32 s54, s36, 0x40080
	s_addc_u32 s55, s37, 0
	s_add_u32 m0, s35, 0xc000
	s_nop 0
	global_load_lds_dwordx4 v1, s[54:55]
	s_nop 0
	s_add_u32 m0, s35, 0xe000
	s_nop 0
	global_load_lds_dwordx4 v211, s[54:55]
	s_waitcnt vmcnt(8)
	s_waitcnt lgkmcnt(0)
	s_barrier
	v_mfma_f32_16x16x32_f16 v[90:93], v[2:5], v[58:61], 0
	s_setprio 1
	v_mfma_f32_16x16x32_f16 v[66:69], v[2:5], v[34:37], 0
	v_mfma_f32_16x16x32_f16 v[70:73], v[10:13], v[34:37], 0
	v_mfma_f32_16x16x32_f16 v[74:77], v[2:5], v[42:45], 0
	v_mfma_f32_16x16x32_f16 v[78:81], v[10:13], v[42:45], 0
	v_mfma_f32_16x16x32_f16 v[82:85], v[2:5], v[50:53], 0
	v_mfma_f32_16x16x32_f16 v[86:89], v[10:13], v[50:53], 0
	s_waitcnt lgkmcnt(0)
	v_mfma_f32_16x16x32_f16 v[98:101], v[6:9], v[62:65], v[90:93]
	v_mfma_f32_16x16x32_f16 v[90:93], v[10:13], v[58:61], 0
	v_mfma_f32_16x16x32_f16 v[66:69], v[6:9], v[38:41], v[66:69]
	v_mfma_f32_16x16x32_f16 v[70:73], v[14:17], v[38:41], v[70:73]
	v_mfma_f32_16x16x32_f16 v[74:77], v[6:9], v[46:49], v[74:77]
	v_mfma_f32_16x16x32_f16 v[78:81], v[14:17], v[46:49], v[78:81]
	v_mfma_f32_16x16x32_f16 v[82:85], v[6:9], v[54:57], v[82:85]
	v_mfma_f32_16x16x32_f16 v[86:89], v[14:17], v[54:57], v[86:89]
	v_mfma_f32_16x16x32_f16 v[102:105], v[14:17], v[62:65], v[90:93]
	v_mfma_f32_16x16x32_f16 v[90:93], v[18:21], v[34:37], 0
	v_mfma_f32_16x16x32_f16 v[34:37], v[26:29], v[34:37], 0
	v_mfma_f32_16x16x32_f16 v[114:117], v[22:25], v[38:41], v[90:93]
	v_mfma_f32_16x16x32_f16 v[34:37], v[30:33], v[38:41], v[34:37]
	v_mfma_f32_16x16x32_f16 v[38:41], v[18:21], v[42:45], 0
	v_mfma_f32_16x16x32_f16 v[42:45], v[26:29], v[42:45], 0
	v_mfma_f32_16x16x32_f16 v[38:41], v[22:25], v[46:49], v[38:41]
	v_mfma_f32_16x16x32_f16 v[42:45], v[30:33], v[46:49], v[42:45]
	v_mfma_f32_16x16x32_f16 v[46:49], v[18:21], v[50:53], 0
	v_mfma_f32_16x16x32_f16 v[50:53], v[26:29], v[50:53], 0
	v_mfma_f32_16x16x32_f16 v[46:49], v[22:25], v[54:57], v[46:49]
	v_mfma_f32_16x16x32_f16 v[50:53], v[30:33], v[54:57], v[50:53]
	v_mfma_f32_16x16x32_f16 v[54:57], v[18:21], v[58:61], 0
	v_mfma_f32_16x16x32_f16 v[58:61], v[26:29], v[58:61], 0
	v_mfma_f32_16x16x32_f16 v[54:57], v[22:25], v[62:65], v[54:57]
	v_mfma_f32_16x16x32_f16 v[58:61], v[30:33], v[62:65], v[58:61]
	s_barrier
	s_setprio 0
	ds_read_b128 v[62:65], v215 offset:16384
	ds_read_b128 v[90:93], v215 offset:17408
	ds_read_b128 v[94:97], v215 offset:18432
	ds_read_b128 v[106:109], v215 offset:19456
	ds_read_b128 v[110:113], v215 offset:20480
	ds_read_b128 v[118:121], v215 offset:21504
	ds_read_b128 v[122:125], v215 offset:22528
	ds_read_b128 v[126:129], v215 offset:23552
	s_add_u32 m0, s35, 0x10000
	s_nop 0
	global_load_lds_dwordx4 v210, s[26:27]
	s_nop 0
	s_add_u32 m0, s35, 0x12000
	s_nop 0
	global_load_lds_dwordx4 v212, s[26:27]
	s_add_u32 s26, s38, 0x40100
	s_addc_u32 s27, s39, 0
	s_add_u32 m0, s35, 0x14000
	s_nop 0
	global_load_lds_dwordx4 v210, s[26:27]
	s_nop 0
	s_add_u32 m0, s35, 0x16000
	s_nop 0
	global_load_lds_dwordx4 v212, s[26:27]
	s_nop 0
	s_add_u32 m0, s35, 0
	s_nop 0
	global_load_lds_dwordx4 v1, s[24:25]
	s_nop 0
	s_add_u32 m0, s35, 0x2000
	s_nop 0
	global_load_lds_dwordx4 v211, s[24:25]
	s_waitcnt vmcnt(8)
	s_waitcnt lgkmcnt(0)
	s_barrier
	v_mfma_f32_16x16x32_f16 v[134:137], v[10:13], v[62:65], 0
	s_setprio 1
	s_waitcnt lgkmcnt(6)
	v_mfma_f32_16x16x32_f16 v[146:149], v[14:17], v[90:93], v[134:137]
	s_waitcnt lgkmcnt(5)
	v_mfma_f32_16x16x32_f16 v[134:137], v[2:5], v[94:97], 0
	s_waitcnt lgkmcnt(4)
	v_mfma_f32_16x16x32_f16 v[150:153], v[6:9], v[106:109], v[134:137]
	v_mfma_f32_16x16x32_f16 v[134:137], v[10:13], v[94:97], 0
	v_mfma_f32_16x16x32_f16 v[130:133], v[2:5], v[62:65], 0
	v_mfma_f32_16x16x32_f16 v[154:157], v[14:17], v[106:109], v[134:137]
	s_waitcnt lgkmcnt(3)
	v_mfma_f32_16x16x32_f16 v[134:137], v[2:5], v[110:113], 0
	s_waitcnt lgkmcnt(1)
	v_mfma_f32_16x16x32_f16 v[2:5], v[2:5], v[122:125], 0
	v_mfma_f32_16x16x32_f16 v[130:133], v[6:9], v[90:93], v[130:133]
	v_mfma_f32_16x16x32_f16 v[158:161], v[6:9], v[118:121], v[134:137]
	s_waitcnt lgkmcnt(0)
	v_mfma_f32_16x16x32_f16 v[2:5], v[6:9], v[126:129], v[2:5]
	v_mfma_f32_16x16x32_f16 v[6:9], v[10:13], v[122:125], 0
	v_mfma_f32_16x16x32_f16 v[134:137], v[10:13], v[110:113], 0
	v_mfma_f32_16x16x32_f16 v[6:9], v[14:17], v[126:129], v[6:9]
	v_mfma_f32_16x16x32_f16 v[162:165], v[14:17], v[118:121], v[134:137]
	v_mfma_f32_16x16x32_f16 v[10:13], v[18:21], v[62:65], 0
	v_mfma_f32_16x16x32_f16 v[166:169], v[22:25], v[90:93], v[10:13]
	v_mfma_f32_16x16x32_f16 v[10:13], v[26:29], v[62:65], 0
	v_mfma_f32_16x16x32_f16 v[170:173], v[30:33], v[90:93], v[10:13]
	v_mfma_f32_16x16x32_f16 v[10:13], v[18:21], v[94:97], 0
	v_mfma_f32_16x16x32_f16 v[174:177], v[22:25], v[106:109], v[10:13]
	v_mfma_f32_16x16x32_f16 v[10:13], v[26:29], v[94:97], 0
	v_mfma_f32_16x16x32_f16 v[178:181], v[30:33], v[106:109], v[10:13]
	v_mfma_f32_16x16x32_f16 v[10:13], v[18:21], v[110:113], 0
	v_mfma_f32_16x16x32_f16 v[182:185], v[22:25], v[118:121], v[10:13]
	v_mfma_f32_16x16x32_f16 v[10:13], v[26:29], v[110:113], 0
	v_mfma_f32_16x16x32_f16 v[118:121], v[30:33], v[118:121], v[10:13]
	v_mfma_f32_16x16x32_f16 v[10:13], v[18:21], v[122:125], 0
	v_mfma_f32_16x16x32_f16 v[186:189], v[22:25], v[126:129], v[10:13]
	v_mfma_f32_16x16x32_f16 v[10:13], v[26:29], v[122:125], 0
	v_mfma_f32_16x16x32_f16 v[122:125], v[30:33], v[126:129], v[10:13]
	s_barrier
; #define PG8_STAGE(bufoff, gbase, voff) do { if constexpr (ABL & 1) break; glds16s<(bufoff)>((voff)[0], (const void*)(gbase), ldsbw); glds16s<(bufoff) + 8192>((voff)[1], (const void*)(gbase), ldsbw); } while (0)
; #define PG8_LDA(dst, b, h) do { if constexpr (ABL & 4) break; _Pragma("unroll") for (int m = 0; m < 4; ++m) _Pragma("unroll") for (int k = 0; k < 2; ++k) dst[m][k] = *(const LAS f16x8*)(lds + PG8_SA(b, h) + aoff + m * 2048 + k * 1024); } while (0)
; #define PG8_LDB(dst, b, h) do { if constexpr (ABL & 4) break; _Pragma("unroll") for (int n = 0; n < 2; ++n) _Pragma("unroll") for (int k = 0; k < 2; ++k) dst[n][k] = *(const LAS f16x8*)(lds + PG8_SB(b, h) + boff + n * 2048 + k * 1024); } while (0)
; #define PG8_MMA(ai, bj, At, Bt) do { if constexpr (ABL & 2) break; __builtin_amdgcn_s_setprio(1); _Pragma("unroll") for (int m = 0; m < 4; ++m) _Pragma("unroll") for (int n = 0; n < 2; ++n) _Pragma("unroll") for (int k = 0; k < 2; ++k) \
;         acc[ai][bj][m][n] = __builtin_amdgcn_mfma_f32_16x16x32_f16(Bt[n][k], At[m][k], acc[ai][bj][m][n], 0, 0, 0); __builtin_amdgcn_s_setprio(0); } while (0)
; #define PG8_WAIT_V(n) asm volatile("s_waitcnt vmcnt(" #n ")" ::: "memory")
; #define PG8_WAIT_L(n) asm volatile("s_waitcnt lgkmcnt(" #n ")" ::: "memory")
; #define PG8_BAR __builtin_amdgcn_s_barrier()
; #define PG8_SCHED __builtin_amdgcn_sched_barrier(0)
;     ...
;             PG8_LDB(B0, 1, 0); PG8_LDB(B1, 1, 1); PG8_SCHED; PG8_LDA(At, 1, 0); if (!fin) PG8_STAGE(PG8_SA(0, 1), a2 + hstep, voffA);
;             if (!fin) PG8_WAIT_V(8); else PG8_WAIT_V(0); PG8_WAIT_L(0); PG8_BAR; PG8_MMA(0, 0, At, B0); PG8_MMA(0, 1, At, B1); PG8_BAR; PG8_SCHED;
;             PG8_LDA(At, 1, 1); if (!fin) { PG8_STAGE(PG8_SB(1, 0), b3, voffB); PG8_STAGE(PG8_SB(1, 1), b3 + hstep, voffB); PG8_STAGE(PG8_SA(1, 0), a3, voffA); }
;             if (!fin) PG8_WAIT_V(8); PG8_WAIT_L(0); PG8_BAR; PG8_MMA(1, 0, At, B0); PG8_MMA(1, 1, At, B1); PG8_BAR; PG8_SCHED;
	s_setprio 0
	s_nop 4
	ds_read_b128 v[10:13], v216
	ds_read_b128 v[14:17], v216 offset:1024
	ds_read_b128 v[18:21], v216 offset:2048
	ds_read_b128 v[22:25], v216 offset:3072
	ds_read_b128 v[190:193], v217
	ds_read_b128 v[194:197], v217 offset:1024
	ds_read_b128 v[198:201], v217 offset:2048
	ds_read_b128 v[202:205], v217 offset:3072
	ds_read_b128 v[26:29], v215 offset:32768
	ds_read_b128 v[30:33], v215 offset:33792
	ds_read_b128 v[62:65], v215 offset:34816
	ds_read_b128 v[218:221], v215 offset:35840
	ds_read_b128 v[222:225], v215 offset:36864
	ds_read_b128 v[226:229], v215 offset:37888
	ds_read_b128 v[230:233], v215 offset:38912
	ds_read_b128 v[234:237], v215 offset:39936
	s_add_u32 s24, s36, 0x40100
	s_addc_u32 s25, s37, 0
	s_add_u32 m0, s35, 0x4000
	s_nop 0
	global_load_lds_dwordx4 v1, s[24:25]
	s_nop 0
	s_add_u32 m0, s35, 0x6000
	s_nop 0
	global_load_lds_dwordx4 v211, s[24:25]
	s_waitcnt vmcnt(8)
	s_waitcnt lgkmcnt(0)
	s_barrier
	v_mfma_f32_16x16x32_f16 v[66:69], v[10:13], v[26:29], v[66:69]
	s_setprio 1
	s_waitcnt lgkmcnt(6)
	v_mfma_f32_16x16x32_f16 v[142:145], v[14:17], v[30:33], v[66:69]
	v_mfma_f32_16x16x32_f16 v[66:69], v[18:21], v[26:29], v[70:73]
	v_mfma_f32_16x16x32_f16 v[138:141], v[22:25], v[30:33], v[66:69]
	s_waitcnt lgkmcnt(5)
	v_mfma_f32_16x16x32_f16 v[66:69], v[10:13], v[62:65], v[74:77]
	s_waitcnt lgkmcnt(4)
	v_mfma_f32_16x16x32_f16 v[110:113], v[14:17], v[218:221], v[66:69]
	v_mfma_f32_16x16x32_f16 v[66:69], v[18:21], v[62:65], v[78:81]
	v_mfma_f32_16x16x32_f16 v[106:109], v[22:25], v[218:221], v[66:69]
	s_waitcnt lgkmcnt(3)
	v_mfma_f32_16x16x32_f16 v[66:69], v[10:13], v[222:225], v[82:85]
	s_waitcnt lgkmcnt(2)
	v_mfma_f32_16x16x32_f16 v[94:97], v[14:17], v[226:229], v[66:69]
	v_mfma_f32_16x16x32_f16 v[66:69], v[18:21], v[222:225], v[86:89]
	v_mfma_f32_16x16x32_f16 v[90:93], v[22:25], v[226:229], v[66:69]
	s_waitcnt lgkmcnt(1)
	v_mfma_f32_16x16x32_f16 v[66:69], v[10:13], v[230:233], v[98:101]
	s_waitcnt lgkmcnt(0)
	v_mfma_f32_16x16x32_f16 v[78:81], v[14:17], v[234:237], v[66:69]
	v_mfma_f32_16x16x32_f16 v[66:69], v[18:21], v[230:233], v[102:105]
	v_mfma_f32_16x16x32_f16 v[74:77], v[22:25], v[234:237], v[66:69]
	v_mfma_f32_16x16x32_f16 v[66:69], v[190:193], v[26:29], v[114:117]
	v_mfma_f32_16x16x32_f16 v[26:29], v[198:201], v[26:29], v[34:37]
	v_mfma_f32_16x16x32_f16 v[126:129], v[202:205], v[30:33], v[26:29]
	v_mfma_f32_16x16x32_f16 v[26:29], v[190:193], v[62:65], v[38:41]
	v_mfma_f32_16x16x32_f16 v[102:105], v[194:197], v[218:221], v[26:29]
	v_mfma_f32_16x16x32_f16 v[26:29], v[198:201], v[62:65], v[42:45]
	v_mfma_f32_16x16x32_f16 v[98:101], v[202:205], v[218:221], v[26:29]
	v_mfma_f32_16x16x32_f16 v[26:29], v[190:193], v[222:225], v[46:49]
	v_mfma_f32_16x16x32_f16 v[86:89], v[194:197], v[226:229], v[26:29]
	v_mfma_f32_16x16x32_f16 v[26:29], v[198:201], v[222:225], v[50:53]
	v_mfma_f32_16x16x32_f16 v[82:85], v[202:205], v[226:229], v[26:29]
	v_mfma_f32_16x16x32_f16 v[26:29], v[190:193], v[230:233], v[54:57]
	v_mfma_f32_16x16x32_f16 v[70:73], v[194:197], v[234:237], v[26:29]
	v_mfma_f32_16x16x32_f16 v[26:29], v[198:201], v[230:233], v[58:61]
	v_mfma_f32_16x16x32_f16 v[134:137], v[194:197], v[30:33], v[66:69]
	v_mfma_f32_16x16x32_f16 v[66:69], v[202:205], v[234:237], v[26:29]
	s_barrier
	s_setprio 0
	ds_read_b128 v[34:37], v215 offset:49152
	ds_read_b128 v[38:41], v215 offset:50176
	ds_read_b128 v[114:117], v215 offset:51200
	ds_read_b128 v[218:221], v215 offset:52224
	ds_read_b128 v[222:225], v215 offset:53248
	ds_read_b128 v[226:229], v215 offset:54272
	ds_read_b128 v[230:233], v215 offset:55296
	ds_read_b128 v[234:237], v215 offset:56320
	s_add_u32 m0, s35, 0x18000
	s_nop 0
	global_load_lds_dwordx4 v210, s[8:9]
	s_nop 0
	s_add_u32 m0, s35, 0x1a000
	s_nop 0
	global_load_lds_dwordx4 v212, s[8:9]
	s_add_u32 s8, s38, 0x40180
	s_addc_u32 s9, s39, 0
	s_add_u32 m0, s35, 0x1c000
	s_nop 0
	global_load_lds_dwordx4 v210, s[8:9]
	s_nop 0
	s_add_u32 m0, s35, 0x1e000
	s_nop 0
	global_load_lds_dwordx4 v212, s[8:9]
	s_nop 0
	s_add_u32 m0, s35, 0x8000
	s_nop 0
	global_load_lds_dwordx4 v1, s[6:7]
	s_nop 0
	s_add_u32 m0, s35, 0xa000
	s_nop 0
	global_load_lds_dwordx4 v211, s[6:7]
	s_waitcnt vmcnt(8)
	s_waitcnt lgkmcnt(0)
	s_barrier
	v_mfma_f32_16x16x32_f16 v[26:29], v[10:13], v[34:37], v[130:133]
	s_setprio 1
	s_waitcnt lgkmcnt(6)
	v_mfma_f32_16x16x32_f16 v[62:65], v[14:17], v[38:41], v[26:29]
	v_mfma_f32_16x16x32_f16 v[26:29], v[18:21], v[34:37], v[146:149]
	v_mfma_f32_16x16x32_f16 v[58:61], v[22:25], v[38:41], v[26:29]
	s_waitcnt lgkmcnt(5)
	v_mfma_f32_16x16x32_f16 v[26:29], v[10:13], v[114:117], v[150:153]
	s_waitcnt lgkmcnt(4)
	v_mfma_f32_16x16x32_f16 v[46:49], v[14:17], v[218:221], v[26:29]
	v_mfma_f32_16x16x32_f16 v[26:29], v[18:21], v[114:117], v[154:157]
	v_mfma_f32_16x16x32_f16 v[42:45], v[22:25], v[218:221], v[26:29]
	s_waitcnt lgkmcnt(3)
	v_mfma_f32_16x16x32_f16 v[26:29], v[10:13], v[222:225], v[158:161]
	s_waitcnt lgkmcnt(1)
	v_mfma_f32_16x16x32_f16 v[2:5], v[10:13], v[230:233], v[2:5]
	v_mfma_f32_16x16x32_f16 v[30:33], v[14:17], v[226:229], v[26:29]
	v_mfma_f32_16x16x32_f16 v[26:29], v[18:21], v[222:225], v[162:165]
	s_waitcnt lgkmcnt(0)
	v_mfma_f32_16x16x32_f16 v[14:17], v[14:17], v[234:237], v[2:5]
	v_mfma_f32_16x16x32_f16 v[2:5], v[18:21], v[230:233], v[6:9]
	v_mfma_f32_16x16x32_f16 v[26:29], v[22:25], v[226:229], v[26:29]
	v_mfma_f32_16x16x32_f16 v[10:13], v[22:25], v[234:237], v[2:5]
	v_mfma_f32_16x16x32_f16 v[2:5], v[190:193], v[34:37], v[166:169]
	v_mfma_f32_16x16x32_f16 v[54:57], v[194:197], v[38:41], v[2:5]
	v_mfma_f32_16x16x32_f16 v[2:5], v[198:201], v[34:37], v[170:173]
	v_mfma_f32_16x16x32_f16 v[50:53], v[202:205], v[38:41], v[2:5]
	v_mfma_f32_16x16x32_f16 v[2:5], v[190:193], v[114:117], v[174:177]
	v_mfma_f32_16x16x32_f16 v[38:41], v[194:197], v[218:221], v[2:5]
	v_mfma_f32_16x16x32_f16 v[2:5], v[198:201], v[114:117], v[178:181]
	v_mfma_f32_16x16x32_f16 v[34:37], v[202:205], v[218:221], v[2:5]
	v_mfma_f32_16x16x32_f16 v[2:5], v[190:193], v[222:225], v[182:185]
	v_mfma_f32_16x16x32_f16 v[22:25], v[194:197], v[226:229], v[2:5]
	v_mfma_f32_16x16x32_f16 v[2:5], v[198:201], v[222:225], v[118:121]
	v_mfma_f32_16x16x32_f16 v[18:21], v[202:205], v[226:229], v[2:5]
	v_mfma_f32_16x16x32_f16 v[2:5], v[190:193], v[230:233], v[186:189]
	v_mfma_f32_16x16x32_f16 v[6:9], v[194:197], v[234:237], v[2:5]
	v_mfma_f32_16x16x32_f16 v[2:5], v[198:201], v[230:233], v[122:125]
	v_mfma_f32_16x16x32_f16 v[2:5], v[202:205], v[234:237], v[2:5]
	s_barrier
	s_setprio 0
	s_mov_b32 s58, 0
	s_mov_b64 s[54:55], 0
	s_branch .LBB0_1165
; #define PG8_STAGE(bufoff, gbase, voff) do { if constexpr (ABL & 1) break; glds16s<(bufoff)>((voff)[0], (const void*)(gbase), ldsbw); glds16s<(bufoff) + 8192>((voff)[1], (const void*)(gbase), ldsbw); } while (0)
; #define PG8_LDA(dst, b, h) do { if constexpr (ABL & 4) break; _Pragma("unroll") for (int m = 0; m < 4; ++m) _Pragma("unroll") for (int k = 0; k < 2; ++k) dst[m][k] = *(const LAS f16x8*)(lds + PG8_SA(b, h) + aoff + m * 2048 + k * 1024); } while (0)
; #define PG8_LDB(dst, b, h) do { if constexpr (ABL & 4) break; _Pragma("unroll") for (int n = 0; n < 2; ++n) _Pragma("unroll") for (int k = 0; k < 2; ++k) dst[n][k] = *(const LAS f16x8*)(lds + PG8_SB(b, h) + boff + n * 2048 + k * 1024); } while (0)
; #define PG8_BAR __builtin_amdgcn_s_barrier()
;     ...
;         for (int t = 0; t < nt; t += 2) {
;             const bool last = (t == nt - 2);
;             const char* a1 = cA + (size_t)(t + 1) * kstep;
;             const char* a2 = last ? nA : cA + (size_t)(t + 2) * kstep; const char* b2 = last ? nB : cB + (size_t)(t + 2) * kstep;
;             const char* a3 = a2 + kstep; const char* b3 = b2 + kstep;
;             if (last && has_next) S.a_ready(nxt);
;             if constexpr (SP2) {
;             PG8_LDB(B0, 0, 0); PG8_LDB(B1, 0, 1); PG8_SCHED; PG8_LDA(At, 0, 0); PG8_STAGE(PG8_SA(1, 1), a1 + hstep, voffA);
;             PG8_WAIT_V(8); PG8_WAIT_L(0); PG8_BAR; PG8_MMAF(0, 0, At, B0); PG8_MMAF(0, 1, At, B1); PG8_BAR; PG8_SCHED;
;             const bool fin = last && !has_next;
;             PG8_LDA(At, 0, 1); if (!fin) { PG8_STAGE(PG8_SB(0, 0), b2, voffB); PG8_STAGE(PG8_SB(0, 1), b2 + hstep, voffB); PG8_STAGE(PG8_SA(0, 0), a2, voffA); }
;             if (!fin) PG8_WAIT_V(8); else PG8_WAIT_V(2); PG8_WAIT_L(0); PG8_BAR; PG8_MMAF(1, 0, At, B0); PG8_MMAF(1, 1, At, B1); PG8_BAR; PG8_SCHED;
;             PG8_LDB(B0, 1, 0); PG8_LDB(B1, 1, 1); PG8_SCHED; PG8_LDA(At, 1, 0); if (!fin) PG8_STAGE(PG8_SA(0, 1), a2 + hstep, voffA);
;             if (!fin) PG8_WAIT_V(8); else PG8_WAIT_V(0); PG8_WAIT_L(0); PG8_BAR; PG8_MMA(0, 0, At, B0); PG8_MMA(0, 1, At, B1); PG8_BAR; PG8_SCHED;
;             PG8_LDA(At, 1, 1); if (!fin) { PG8_STAGE(PG8_SB(1, 0), b3, voffB); PG8_STAGE(PG8_SB(1, 1), b3 + hstep, voffB); PG8_STAGE(PG8_SA(1, 0), a3, voffA); }
;             if (!fin) PG8_WAIT_V(8); PG8_WAIT_L(0); PG8_BAR; PG8_MMA(1, 0, At, B0); PG8_MMA(1, 1, At, B1); PG8_BAR; PG8_SCHED;
.LBB0_1164:
	s_waitcnt lgkmcnt(0)
	s_barrier
	v_mfma_f32_16x16x32_f16 v[62:65], v[158:161], v[186:189], v[62:65]
	s_setprio 1
	v_mfma_f32_16x16x32_f16 v[58:61], v[166:169], v[186:189], v[58:61]
	s_waitcnt lgkmcnt(5)
	v_mfma_f32_16x16x32_f16 v[46:49], v[158:161], v[178:181], v[46:49]
	v_mfma_f32_16x16x32_f16 v[42:45], v[166:169], v[178:181], v[42:45]
	s_waitcnt lgkmcnt(3)
	v_mfma_f32_16x16x32_f16 v[30:33], v[158:161], v[122:125], v[30:33]
	v_mfma_f32_16x16x32_f16 v[26:29], v[166:169], v[122:125], v[26:29]
	s_waitcnt lgkmcnt(1)
	v_mfma_f32_16x16x32_f16 v[14:17], v[158:161], v[114:117], v[14:17]
	v_mfma_f32_16x16x32_f16 v[10:13], v[166:169], v[114:117], v[10:13]
	v_mfma_f32_16x16x32_f16 v[62:65], v[162:165], v[190:193], v[62:65]
	v_mfma_f32_16x16x32_f16 v[58:61], v[170:173], v[190:193], v[58:61]
	v_mfma_f32_16x16x32_f16 v[46:49], v[162:165], v[182:185], v[46:49]
	v_mfma_f32_16x16x32_f16 v[42:45], v[170:173], v[182:185], v[42:45]
	v_mfma_f32_16x16x32_f16 v[30:33], v[162:165], v[174:177], v[30:33]
	v_mfma_f32_16x16x32_f16 v[26:29], v[170:173], v[174:177], v[26:29]
	s_waitcnt lgkmcnt(0)
	v_mfma_f32_16x16x32_f16 v[14:17], v[162:165], v[118:121], v[14:17]
	v_mfma_f32_16x16x32_f16 v[10:13], v[170:173], v[118:121], v[10:13]
	v_mfma_f32_16x16x32_f16 v[54:57], v[130:133], v[186:189], v[54:57]
	v_mfma_f32_16x16x32_f16 v[50:53], v[150:153], v[186:189], v[50:53]
	v_mfma_f32_16x16x32_f16 v[38:41], v[130:133], v[178:181], v[38:41]
	v_mfma_f32_16x16x32_f16 v[34:37], v[150:153], v[178:181], v[34:37]
	v_mfma_f32_16x16x32_f16 v[22:25], v[130:133], v[122:125], v[22:25]
	v_mfma_f32_16x16x32_f16 v[18:21], v[150:153], v[122:125], v[18:21]
	v_mfma_f32_16x16x32_f16 v[6:9], v[130:133], v[114:117], v[6:9]
	v_mfma_f32_16x16x32_f16 v[2:5], v[150:153], v[114:117], v[2:5]
	v_mfma_f32_16x16x32_f16 v[54:57], v[146:149], v[190:193], v[54:57]
	v_mfma_f32_16x16x32_f16 v[50:53], v[154:157], v[190:193], v[50:53]
	v_mfma_f32_16x16x32_f16 v[38:41], v[146:149], v[182:185], v[38:41]
	v_mfma_f32_16x16x32_f16 v[34:37], v[154:157], v[182:185], v[34:37]
	v_mfma_f32_16x16x32_f16 v[22:25], v[146:149], v[174:177], v[22:25]
	v_mfma_f32_16x16x32_f16 v[18:21], v[154:157], v[174:177], v[18:21]
	v_mfma_f32_16x16x32_f16 v[6:9], v[146:149], v[118:121], v[6:9]
	v_mfma_f32_16x16x32_f16 v[2:5], v[154:157], v[118:121], v[2:5]
	s_barrier
	s_setprio 0
	s_add_i32 s58, s58, 2
	s_add_u32 s54, s54, 0x100
	s_addc_u32 s55, s55, 0
	s_cmp_gt_u32 s58, 13
	s_cbranch_scc1 .LBB0_1175
; #define PG8_STAGE(bufoff, gbase, voff) do { if constexpr (ABL & 1) break; glds16s<(bufoff)>((voff)[0], (const void*)(gbase), ldsbw); glds16s<(bufoff) + 8192>((voff)[1], (const void*)(gbase), ldsbw); } while (0)
; #define PG8_LDA(dst, b, h) do { if constexpr (ABL & 4) break; _Pragma("unroll") for (int m = 0; m < 4; ++m) _Pragma("unroll") for (int k = 0; k < 2; ++k) dst[m][k] = *(const LAS f16x8*)(lds + PG8_SA(b, h) + aoff + m * 2048 + k * 1024); } while (0)
; #define PG8_LDB(dst, b, h) do { if constexpr (ABL & 4) break; _Pragma("unroll") for (int n = 0; n < 2; ++n) _Pragma("unroll") for (int k = 0; k < 2; ++k) dst[n][k] = *(const LAS f16x8*)(lds + PG8_SB(b, h) + boff + n * 2048 + k * 1024); } while (0)
; #define PG8_MMAF(ai, bj, At, Bt) do { if (t == 0) PG8_MMA0(ai, bj, At, Bt); else PG8_MMA(ai, bj, At, Bt); } while (0)
; #define PG8_WAIT_V(n) asm volatile("s_waitcnt vmcnt(" #n ")" ::: "memory")
; #define PG8_WAIT_L(n) asm volatile("s_waitcnt lgkmcnt(" #n ")" ::: "memory")
; #define PG8_BAR __builtin_amdgcn_s_barrier()
; #define PG8_SCHED __builtin_amdgcn_sched_barrier(0)
;     ...
;         for (int t = 0; t < nt; t += 2) {
;             const bool last = (t == nt - 2);
;             const char* a1 = cA + (size_t)(t + 1) * kstep;
;             const char* a2 = last ? nA : cA + (size_t)(t + 2) * kstep; const char* b2 = last ? nB : cB + (size_t)(t + 2) * kstep;
;             const char* a3 = a2 + kstep; const char* b3 = b2 + kstep;
;             if (last && has_next) S.a_ready(nxt);
;             if constexpr (SP2) {
;             PG8_LDB(B0, 0, 0); PG8_LDB(B1, 0, 1); PG8_SCHED; PG8_LDA(At, 0, 0); PG8_STAGE(PG8_SA(1, 1), a1 + hstep, voffA);
;             PG8_WAIT_V(8); PG8_WAIT_L(0); PG8_BAR; PG8_MMAF(0, 0, At, B0); PG8_MMAF(0, 1, At, B1); PG8_BAR; PG8_SCHED;
;             const bool fin = last && !has_next;
;             PG8_LDA(At, 0, 1); if (!fin) { PG8_STAGE(PG8_SB(0, 0), b2, voffB); PG8_STAGE(PG8_SB(0, 1), b2 + hstep, voffB); PG8_STAGE(PG8_SA(0, 0), a2, voffA); }
.LBB0_1165:
	s_add_u32 s26, s36, s54
	s_addc_u32 s27, s37, s55
	ds_read_b128 v[158:161], v213
	ds_read_b128 v[162:165], v213 offset:1024
	ds_read_b128 v[166:169], v213 offset:2048
	ds_read_b128 v[170:173], v213 offset:3072
	ds_read_b128 v[130:133], v214
	ds_read_b128 v[146:149], v214 offset:1024
	ds_read_b128 v[150:153], v214 offset:2048
	ds_read_b128 v[154:157], v214 offset:3072
	s_add_u32 s24, s26, 0x200
	s_addc_u32 s25, s27, 0
	s_add_u32 s6, s38, s54
	s_addc_u32 s7, s39, s55
	s_add_u32 s59, s6, 0x200
	s_addc_u32 s60, s7, 0
	s_cmp_eq_u32 s58, 12
	s_cselect_b64 s[6:7], -1, 0
	s_and_b64 s[8:9], s[6:7], exec
	s_cselect_b32 s25, s45, s25
	s_cselect_b32 s24, s49, s24
	s_cselect_b32 s9, s47, s60
	s_cselect_b32 s8, s57, s59
	ds_read_b128 v[174:177], v215
	ds_read_b128 v[178:181], v215 offset:1024
	ds_read_b128 v[182:185], v215 offset:2048
	ds_read_b128 v[186:189], v215 offset:3072
	ds_read_b128 v[190:193], v215 offset:4096
	ds_read_b128 v[194:197], v215 offset:5120
	ds_read_b128 v[198:201], v215 offset:6144
	ds_read_b128 v[202:205], v215 offset:7168
	s_add_u32 s26, s26, 0x40180
	s_addc_u32 s27, s27, 0
	s_add_u32 m0, s35, 0xc000
	s_nop 0
	global_load_lds_dwordx4 v1, s[26:27]
	s_nop 0
	s_add_u32 m0, s35, 0xe000
	s_nop 0
	global_load_lds_dwordx4 v211, s[26:27]
	s_waitcnt vmcnt(8)
	s_waitcnt lgkmcnt(0)
	s_barrier
	v_mfma_f32_16x16x32_f16 v[114:117], v[158:161], v[174:177], v[142:145]
	s_setprio 1
	v_mfma_f32_16x16x32_f16 v[118:121], v[166:169], v[174:177], v[138:141]
	s_waitcnt lgkmcnt(5)
	v_mfma_f32_16x16x32_f16 v[110:113], v[158:161], v[182:185], v[110:113]
	v_mfma_f32_16x16x32_f16 v[106:109], v[166:169], v[182:185], v[106:109]
	s_waitcnt lgkmcnt(3)
	v_mfma_f32_16x16x32_f16 v[94:97], v[158:161], v[190:193], v[94:97]
	v_mfma_f32_16x16x32_f16 v[90:93], v[166:169], v[190:193], v[90:93]
	s_waitcnt lgkmcnt(1)
	v_mfma_f32_16x16x32_f16 v[78:81], v[158:161], v[198:201], v[78:81]
	v_mfma_f32_16x16x32_f16 v[74:77], v[166:169], v[198:201], v[74:77]
	v_mfma_f32_16x16x32_f16 v[114:117], v[162:165], v[178:181], v[114:117]
	v_mfma_f32_16x16x32_f16 v[118:121], v[170:173], v[178:181], v[118:121]
	v_mfma_f32_16x16x32_f16 v[110:113], v[162:165], v[186:189], v[110:113]
	v_mfma_f32_16x16x32_f16 v[106:109], v[170:173], v[186:189], v[106:109]
	v_mfma_f32_16x16x32_f16 v[94:97], v[162:165], v[194:197], v[94:97]
	v_mfma_f32_16x16x32_f16 v[90:93], v[170:173], v[194:197], v[90:93]
	s_waitcnt lgkmcnt(0)
	v_mfma_f32_16x16x32_f16 v[78:81], v[162:165], v[202:205], v[78:81]
	v_mfma_f32_16x16x32_f16 v[74:77], v[170:173], v[202:205], v[74:77]
	v_mfma_f32_16x16x32_f16 v[122:125], v[130:133], v[174:177], v[134:137]
	v_mfma_f32_16x16x32_f16 v[126:129], v[150:153], v[174:177], v[126:129]
	v_mfma_f32_16x16x32_f16 v[102:105], v[130:133], v[182:185], v[102:105]
	v_mfma_f32_16x16x32_f16 v[98:101], v[150:153], v[182:185], v[98:101]
	v_mfma_f32_16x16x32_f16 v[86:89], v[130:133], v[190:193], v[86:89]
	v_mfma_f32_16x16x32_f16 v[82:85], v[150:153], v[190:193], v[82:85]
	v_mfma_f32_16x16x32_f16 v[70:73], v[130:133], v[198:201], v[70:73]
	v_mfma_f32_16x16x32_f16 v[66:69], v[150:153], v[198:201], v[66:69]
	v_mfma_f32_16x16x32_f16 v[122:125], v[146:149], v[178:181], v[122:125]
	v_mfma_f32_16x16x32_f16 v[126:129], v[154:157], v[178:181], v[126:129]
	v_mfma_f32_16x16x32_f16 v[102:105], v[146:149], v[186:189], v[102:105]
	v_mfma_f32_16x16x32_f16 v[98:101], v[154:157], v[186:189], v[98:101]
	v_mfma_f32_16x16x32_f16 v[86:89], v[146:149], v[194:197], v[86:89]
	v_mfma_f32_16x16x32_f16 v[82:85], v[154:157], v[194:197], v[82:85]
	v_mfma_f32_16x16x32_f16 v[70:73], v[146:149], v[202:205], v[70:73]
	v_mfma_f32_16x16x32_f16 v[66:69], v[154:157], v[202:205], v[66:69]
	s_barrier
	s_setprio 0
	ds_read_b128 v[186:189], v215 offset:16384
	ds_read_b128 v[190:193], v215 offset:17408
	ds_read_b128 v[178:181], v215 offset:18432
	ds_read_b128 v[182:185], v215 offset:19456
	ds_read_b128 v[142:145], v215 offset:20480
	ds_read_b128 v[174:177], v215 offset:21504
	ds_read_b128 v[134:137], v215 offset:22528
	ds_read_b128 v[138:141], v215 offset:23552
	s_and_b64 s[6:7], s[2:3], s[6:7]
	s_mov_b64 s[26:27], -1
	s_and_b64 vcc, exec, s[6:7]
	s_cbranch_vccnz .LBB0_1167
	s_add_u32 m0, s35, 0x10000
	s_nop 0
	global_load_lds_dwordx4 v210, s[8:9]
	s_nop 0
	s_add_u32 m0, s35, 0x12000
	s_nop 0
	global_load_lds_dwordx4 v212, s[8:9]
	s_add_u32 s26, s8, 0x40000
	s_addc_u32 s27, s9, 0
	s_add_u32 m0, s35, 0x14000
	s_nop 0
	global_load_lds_dwordx4 v210, s[26:27]
	s_nop 0
	s_add_u32 m0, s35, 0x16000
	s_nop 0
	global_load_lds_dwordx4 v212, s[26:27]
	s_mov_b64 s[26:27], 0
	s_add_u32 m0, s35, 0
	s_nop 0
	global_load_lds_dwordx4 v1, s[24:25]
	s_nop 0
	s_add_u32 m0, s35, 0x2000
	s_nop 0
	global_load_lds_dwordx4 v211, s[24:25]
	s_waitcnt vmcnt(8)

; #define PG8_STAGE(bufoff, gbase, voff) do { if constexpr (ABL & 1) break; glds16s<(bufoff)>((voff)[0], (const void*)(gbase), ldsbw); glds16s<(bufoff) + 8192>((voff)[1], (const void*)(gbase), ldsbw); } while (0)
; #define PG8_LDA(dst, b, h) do { if constexpr (ABL & 4) break; _Pragma("unroll") for (int m = 0; m < 4; ++m) _Pragma("unroll") for (int k = 0; k < 2; ++k) dst[m][k] = *(const LAS f16x8*)(lds + PG8_SA(b, h) + aoff + m * 2048 + k * 1024); } while (0)
; #define PG8_LDB(dst, b, h) do { if constexpr (ABL & 4) break; _Pragma("unroll") for (int n = 0; n < 2; ++n) _Pragma("unroll") for (int k = 0; k < 2; ++k) dst[n][k] = *(const LAS f16x8*)(lds + PG8_SB(b, h) + boff + n * 2048 + k * 1024); } while (0)
; #define PG8_MMA(ai, bj, At, Bt) do { if constexpr (ABL & 2) break; __builtin_amdgcn_s_setprio(1); _Pragma("unroll") for (int m = 0; m < 4; ++m) _Pragma("unroll") for (int n = 0; n < 2; ++n) _Pragma("unroll") for (int k = 0; k < 2; ++k) \
;         acc[ai][bj][m][n] = __builtin_amdgcn_mfma_f32_16x16x32_f16(Bt[n][k], At[m][k], acc[ai][bj][m][n], 0, 0, 0); __builtin_amdgcn_s_setprio(0); } while (0)
; #define PG8_MMAF(ai, bj, At, Bt) do { if (t == 0) PG8_MMA0(ai, bj, At, Bt); else PG8_MMA(ai, bj, At, Bt); } while (0)
; #define PG8_WAIT_V(n) asm volatile("s_waitcnt vmcnt(" #n ")" ::: "memory")
; #define PG8_WAIT_L(n) asm volatile("s_waitcnt lgkmcnt(" #n ")" ::: "memory")
; #define PG8_BAR __builtin_amdgcn_s_barrier()
; #define PG8_SCHED __builtin_amdgcn_sched_barrier(0)
;     ...
;             if (!fin) PG8_WAIT_V(8); else PG8_WAIT_V(2); PG8_WAIT_L(0); PG8_BAR; PG8_MMAF(1, 0, At, B0); PG8_MMAF(1, 1, At, B1); PG8_BAR; PG8_SCHED;
;             PG8_LDB(B0, 1, 0); PG8_LDB(B1, 1, 1); PG8_SCHED; PG8_LDA(At, 1, 0); if (!fin) PG8_STAGE(PG8_SA(0, 1), a2 + hstep, voffA);
;             if (!fin) PG8_WAIT_V(8); else PG8_WAIT_V(0); PG8_WAIT_L(0); PG8_BAR; PG8_MMA(0, 0, At, B0); PG8_MMA(0, 1, At, B1); PG8_BAR; PG8_SCHED;
.LBB0_1169:
	s_waitcnt lgkmcnt(0)
	s_xor_b64 s[26:27], s[6:7], -1
	s_barrier
	v_mfma_f32_16x16x32_f16 v[62:65], v[158:161], v[186:189], v[62:65]
	s_setprio 1
	v_mfma_f32_16x16x32_f16 v[58:61], v[166:169], v[186:189], v[58:61]
	s_waitcnt lgkmcnt(5)
	v_mfma_f32_16x16x32_f16 v[46:49], v[158:161], v[178:181], v[46:49]
	v_mfma_f32_16x16x32_f16 v[42:45], v[166:169], v[178:181], v[42:45]
	s_waitcnt lgkmcnt(3)
	v_mfma_f32_16x16x32_f16 v[30:33], v[158:161], v[142:145], v[30:33]
	v_mfma_f32_16x16x32_f16 v[26:29], v[166:169], v[142:145], v[26:29]
	s_waitcnt lgkmcnt(1)
	v_mfma_f32_16x16x32_f16 v[14:17], v[158:161], v[134:137], v[14:17]
	v_mfma_f32_16x16x32_f16 v[10:13], v[166:169], v[134:137], v[10:13]
	v_mfma_f32_16x16x32_f16 v[62:65], v[162:165], v[190:193], v[62:65]
	v_mfma_f32_16x16x32_f16 v[58:61], v[170:173], v[190:193], v[58:61]
	v_mfma_f32_16x16x32_f16 v[46:49], v[162:165], v[182:185], v[46:49]
	v_mfma_f32_16x16x32_f16 v[42:45], v[170:173], v[182:185], v[42:45]
	v_mfma_f32_16x16x32_f16 v[30:33], v[162:165], v[174:177], v[30:33]
	v_mfma_f32_16x16x32_f16 v[26:29], v[170:173], v[174:177], v[26:29]
	s_waitcnt lgkmcnt(0)
	v_mfma_f32_16x16x32_f16 v[14:17], v[162:165], v[138:141], v[14:17]
	v_mfma_f32_16x16x32_f16 v[10:13], v[170:173], v[138:141], v[10:13]
	v_mfma_f32_16x16x32_f16 v[54:57], v[130:133], v[186:189], v[54:57]
	v_mfma_f32_16x16x32_f16 v[50:53], v[150:153], v[186:189], v[50:53]
	v_mfma_f32_16x16x32_f16 v[38:41], v[130:133], v[178:181], v[38:41]
	v_mfma_f32_16x16x32_f16 v[34:37], v[150:153], v[178:181], v[34:37]
	v_mfma_f32_16x16x32_f16 v[22:25], v[130:133], v[142:145], v[22:25]
	v_mfma_f32_16x16x32_f16 v[18:21], v[150:153], v[142:145], v[18:21]
	v_mfma_f32_16x16x32_f16 v[6:9], v[130:133], v[134:137], v[6:9]
	v_mfma_f32_16x16x32_f16 v[2:5], v[150:153], v[134:137], v[2:5]
	v_mfma_f32_16x16x32_f16 v[54:57], v[146:149], v[190:193], v[54:57]
	v_mfma_f32_16x16x32_f16 v[50:53], v[154:157], v[190:193], v[50:53]
	v_mfma_f32_16x16x32_f16 v[38:41], v[146:149], v[182:185], v[38:41]
	v_mfma_f32_16x16x32_f16 v[34:37], v[154:157], v[182:185], v[34:37]
	v_mfma_f32_16x16x32_f16 v[22:25], v[146:149], v[174:177], v[22:25]
	v_mfma_f32_16x16x32_f16 v[18:21], v[154:157], v[174:177], v[18:21]
	v_mfma_f32_16x16x32_f16 v[6:9], v[146:149], v[138:141], v[6:9]
	v_mfma_f32_16x16x32_f16 v[2:5], v[154:157], v[138:141], v[2:5]
	s_barrier
	s_setprio 0
	ds_read_b128 v[158:161], v216
	ds_read_b128 v[162:165], v216 offset:1024
	ds_read_b128 v[166:169], v216 offset:2048
	ds_read_b128 v[170:173], v216 offset:3072
	ds_read_b128 v[130:133], v217
	ds_read_b128 v[146:149], v217 offset:1024
	ds_read_b128 v[150:153], v217 offset:2048
	ds_read_b128 v[154:157], v217 offset:3072
	ds_read_b128 v[198:201], v215 offset:32768
	ds_read_b128 v[202:205], v215 offset:33792
	ds_read_b128 v[190:193], v215 offset:34816
	ds_read_b128 v[194:197], v215 offset:35840
	ds_read_b128 v[182:185], v215 offset:36864
	ds_read_b128 v[186:189], v215 offset:37888
	ds_read_b128 v[174:177], v215 offset:38912
	ds_read_b128 v[178:181], v215 offset:39936
	v_cndmask_b32_e64 v134, 0, 1, s[26:27]
	v_cmp_ne_u32_e64 s[6:7], 1, v134
	s_andn2_b64 vcc, exec, s[26:27]
	s_mov_b64 s[26:27], -1
	s_cbranch_vccnz .LBB0_1171
	s_add_u32 s26, s24, 0x40000
	s_addc_u32 s27, s25, 0
	s_add_u32 m0, s35, 0x4000
	s_nop 0
	global_load_lds_dwordx4 v1, s[26:27]
	s_nop 0
	s_add_u32 m0, s35, 0x6000
	s_nop 0
	global_load_lds_dwordx4 v211, s[26:27]
	s_waitcnt vmcnt(8)
	s_mov_b64 s[26:27], 0

; #define PG8_STAGE(bufoff, gbase, voff) do { if constexpr (ABL & 1) break; glds16s<(bufoff)>((voff)[0], (const void*)(gbase), ldsbw); glds16s<(bufoff) + 8192>((voff)[1], (const void*)(gbase), ldsbw); } while (0)
; #define PG8_LDA(dst, b, h) do { if constexpr (ABL & 4) break; _Pragma("unroll") for (int m = 0; m < 4; ++m) _Pragma("unroll") for (int k = 0; k < 2; ++k) dst[m][k] = *(const LAS f16x8*)(lds + PG8_SA(b, h) + aoff + m * 2048 + k * 1024); } while (0)
; #define PG8_MMA(ai, bj, At, Bt) do { if constexpr (ABL & 2) break; __builtin_amdgcn_s_setprio(1); _Pragma("unroll") for (int m = 0; m < 4; ++m) _Pragma("unroll") for (int n = 0; n < 2; ++n) _Pragma("unroll") for (int k = 0; k < 2; ++k) \
;         acc[ai][bj][m][n] = __builtin_amdgcn_mfma_f32_16x16x32_f16(Bt[n][k], At[m][k], acc[ai][bj][m][n], 0, 0, 0); __builtin_amdgcn_s_setprio(0); } while (0)
; #define PG8_WAIT_V(n) asm volatile("s_waitcnt vmcnt(" #n ")" ::: "memory")
; #define PG8_WAIT_L(n) asm volatile("s_waitcnt lgkmcnt(" #n ")" ::: "memory")
; #define PG8_BAR __builtin_amdgcn_s_barrier()
; #define PG8_SCHED __builtin_amdgcn_sched_barrier(0)
;     ...
;             if (!fin) PG8_WAIT_V(8); else PG8_WAIT_V(0); PG8_WAIT_L(0); PG8_BAR; PG8_MMA(0, 0, At, B0); PG8_MMA(0, 1, At, B1); PG8_BAR; PG8_SCHED;
;             PG8_LDA(At, 1, 1); if (!fin) { PG8_STAGE(PG8_SB(1, 0), b3, voffB); PG8_STAGE(PG8_SB(1, 1), b3 + hstep, voffB); PG8_STAGE(PG8_SA(1, 0), a3, voffA); }
;             if (!fin) PG8_WAIT_V(8); PG8_WAIT_L(0); PG8_BAR; PG8_MMA(1, 0, At, B0); PG8_MMA(1, 1, At, B1); PG8_BAR; PG8_SCHED;
.LBB0_1173:
	s_waitcnt lgkmcnt(0)
	s_barrier
	v_mfma_f32_16x16x32_f16 v[114:117], v[158:161], v[198:201], v[114:117]
	s_setprio 1
	s_waitcnt lgkmcnt(6)
	v_mfma_f32_16x16x32_f16 v[142:145], v[162:165], v[202:205], v[114:117]
	v_mfma_f32_16x16x32_f16 v[114:117], v[166:169], v[198:201], v[118:121]
	s_waitcnt lgkmcnt(5)
	v_mfma_f32_16x16x32_f16 v[110:113], v[158:161], v[190:193], v[110:113]
	v_mfma_f32_16x16x32_f16 v[106:109], v[166:169], v[190:193], v[106:109]
	s_waitcnt lgkmcnt(3)
	v_mfma_f32_16x16x32_f16 v[94:97], v[158:161], v[182:185], v[94:97]
	v_mfma_f32_16x16x32_f16 v[90:93], v[166:169], v[182:185], v[90:93]
	s_waitcnt lgkmcnt(1)
	v_mfma_f32_16x16x32_f16 v[78:81], v[158:161], v[174:177], v[78:81]
	v_mfma_f32_16x16x32_f16 v[74:77], v[166:169], v[174:177], v[74:77]
	v_mfma_f32_16x16x32_f16 v[138:141], v[170:173], v[202:205], v[114:117]
	v_mfma_f32_16x16x32_f16 v[110:113], v[162:165], v[194:197], v[110:113]
	v_mfma_f32_16x16x32_f16 v[106:109], v[170:173], v[194:197], v[106:109]
	v_mfma_f32_16x16x32_f16 v[94:97], v[162:165], v[186:189], v[94:97]
	v_mfma_f32_16x16x32_f16 v[90:93], v[170:173], v[186:189], v[90:93]
	s_waitcnt lgkmcnt(0)
	v_mfma_f32_16x16x32_f16 v[78:81], v[162:165], v[178:181], v[78:81]
	v_mfma_f32_16x16x32_f16 v[74:77], v[170:173], v[178:181], v[74:77]
	v_mfma_f32_16x16x32_f16 v[114:117], v[130:133], v[198:201], v[122:125]
	v_mfma_f32_16x16x32_f16 v[134:137], v[146:149], v[202:205], v[114:117]
	v_mfma_f32_16x16x32_f16 v[114:117], v[150:153], v[198:201], v[126:129]
	v_mfma_f32_16x16x32_f16 v[102:105], v[130:133], v[190:193], v[102:105]
	v_mfma_f32_16x16x32_f16 v[98:101], v[150:153], v[190:193], v[98:101]
	v_mfma_f32_16x16x32_f16 v[86:89], v[130:133], v[182:185], v[86:89]
	v_mfma_f32_16x16x32_f16 v[82:85], v[150:153], v[182:185], v[82:85]
	v_mfma_f32_16x16x32_f16 v[70:73], v[130:133], v[174:177], v[70:73]
	v_mfma_f32_16x16x32_f16 v[66:69], v[150:153], v[174:177], v[66:69]
	v_mfma_f32_16x16x32_f16 v[126:129], v[154:157], v[202:205], v[114:117]
	v_mfma_f32_16x16x32_f16 v[102:105], v[146:149], v[194:197], v[102:105]
	v_mfma_f32_16x16x32_f16 v[98:101], v[154:157], v[194:197], v[98:101]
	v_mfma_f32_16x16x32_f16 v[86:89], v[146:149], v[186:189], v[86:89]
	v_mfma_f32_16x16x32_f16 v[82:85], v[154:157], v[186:189], v[82:85]
	v_mfma_f32_16x16x32_f16 v[70:73], v[146:149], v[178:181], v[70:73]
	v_mfma_f32_16x16x32_f16 v[66:69], v[154:157], v[178:181], v[66:69]
	s_barrier
	s_setprio 0
	ds_read_b128 v[186:189], v215 offset:49152
	ds_read_b128 v[190:193], v215 offset:50176
	ds_read_b128 v[178:181], v215 offset:51200
	ds_read_b128 v[182:185], v215 offset:52224
	ds_read_b128 v[122:125], v215 offset:53248
	ds_read_b128 v[174:177], v215 offset:54272
	ds_read_b128 v[114:117], v215 offset:55296
	ds_read_b128 v[118:121], v215 offset:56320
	s_and_b64 vcc, exec, s[6:7]
	s_cbranch_vccnz .LBB0_1164
	s_add_u32 s6, s24, 0x80
	s_addc_u32 s7, s25, 0
	s_add_u32 s24, s8, 0x80
	s_addc_u32 s25, s9, 0
	s_add_u32 m0, s35, 0x18000
	s_nop 0
	global_load_lds_dwordx4 v210, s[24:25]
	s_nop 0
	s_add_u32 m0, s35, 0x1a000
	s_nop 0
	global_load_lds_dwordx4 v212, s[24:25]
	s_add_u32 s8, s8, 0x40080
	s_addc_u32 s9, s9, 0
	s_add_u32 m0, s35, 0x1c000
	s_nop 0
	global_load_lds_dwordx4 v210, s[8:9]
	s_nop 0
	s_add_u32 m0, s35, 0x1e000
	s_nop 0
	global_load_lds_dwordx4 v212, s[8:9]
	s_nop 0
	s_add_u32 m0, s35, 0x8000
	s_nop 0
	global_load_lds_dwordx4 v1, s[6:7]
	s_nop 0
	s_add_u32 m0, s35, 0xa000
	s_nop 0
	global_load_lds_dwordx4 v211, s[6:7]
	s_waitcnt vmcnt(8)
	s_branch .LBB0_1164
